# interleave LDS stores and global prefetch with MFMAs in unrolled GEMM k-steps
# speedup vs baseline: 1.0094x; 1.0094x over previous
.LBB0_263:
	s_lshr_b32 s2, s13, 3
	s_and_b32 s2, s2, 12
	v_readlane_b32 s6, v246, 16
	s_add_i32 s10, s2, s6
	s_and_b32 s2, s13, 3
	s_or_b32 s2, s10, s2
	s_lshl_b32 s6, s2, 7
	s_add_i32 s11, s6, 0xfffff000
	s_lshr_b32 s11, s11, 11
	s_add_i32 s11, s11, 1
	s_cmp_gt_u32 s10, 31
	s_cselect_b32 s11, s11, 0
	v_readlane_b32 s10, v246, 28
	s_add_i32 s11, s11, s10
	s_and_b32 s10, s12, 0x380
	v_mov_b32 v98, v194
	s_mov_b32 s16, 0x10000
	v_ashrrev_i32_e32 v66, 3, v98
	s_waitcnt vmcnt(0) lgkmcnt(0)
	v_add_u32_e32 v2, s10, v66
	v_ashrrev_i32_e32 v3, 31, v2
	v_lshlrev_b64 v[2:3], 11, v[2:3]
	v_lshlrev_b32_e32 v0, 4, v98
	v_lshl_add_u64 v[2:3], s[46:47], 0, v[2:3]
	v_and_b32_e32 v0, 0x70, v0
	s_waitcnt vmcnt(43)
	v_lshl_add_u64 v[154:155], v[2:3], 0, v[0:1]
	v_add_u32_e32 v2, s6, v66
	v_ashrrev_i32_e32 v3, 31, v2
	v_lshlrev_b64 v[2:3], 11, v[2:3]
	v_lshl_add_u64 v[2:3], s[42:43], 0, v[2:3]
	s_waitcnt vmcnt(37)
	v_lshl_add_u64 v[162:163], v[2:3], 0, v[0:1]
	v_add_co_u32_e32 v164, vcc, s16, v162
	s_mov_b32 s18, 0x20000
	s_nop 0
	v_addc_co_u32_e32 v165, vcc, 0, v163, vcc
	s_waitcnt vmcnt(36)
	v_add_co_u32_e32 v166, vcc, s18, v162
	s_mov_b32 s17, 0x30000
	s_waitcnt vmcnt(34)
	v_addc_co_u32_e32 v167, vcc, 0, v163, vcc
	v_add_co_u32_e32 v168, vcc, s17, v162
	s_nop 1
	v_addc_co_u32_e32 v169, vcc, 0, v163, vcc
	v_add_co_u32_e32 v156, vcc, s16, v154
	s_barrier
	s_barrier
	global_load_dwordx4 v[2:5], v[162:163], off
	global_load_dwordx4 v[6:9], v[164:165], off
	global_load_dwordx4 v[10:13], v[166:167], off
	global_load_dwordx4 v[14:17], v[168:169], off
	global_load_dwordx4 v[18:21], v[154:155], off
	v_addc_co_u32_e32 v157, vcc, 0, v155, vcc
	v_add_co_u32_e32 v158, vcc, s18, v154
	global_load_dwordx4 v[22:25], v[156:157], off
	s_nop 0
	v_addc_co_u32_e32 v159, vcc, 0, v155, vcc
	v_add_co_u32_e32 v160, vcc, s17, v154
	global_load_dwordx4 v[26:29], v[158:159], off
	s_nop 0
	v_addc_co_u32_e32 v161, vcc, 0, v155, vcc
	global_load_dwordx4 v[30:33], v[160:161], off
	global_load_dwordx4 v[34:37], v[162:163], off offset:128
	global_load_dwordx4 v[38:41], v[164:165], off offset:128
	global_load_dwordx4 v[42:45], v[166:167], off offset:128
	global_load_dwordx4 v[46:49], v[168:169], off offset:128
	global_load_dwordx4 v[50:53], v[154:155], off offset:128
	global_load_dwordx4 v[54:57], v[156:157], off offset:128
	global_load_dwordx4 v[58:61], v[158:159], off offset:128
	global_load_dwordx4 v[62:65], v[160:161], off offset:128
	global_load_dwordx4 v[78:81], v[162:163], off offset:256
	global_load_dwordx4 v[82:85], v[164:165], off offset:256
	global_load_dwordx4 v[86:89], v[166:167], off offset:256
	global_load_dwordx4 v[90:93], v[168:169], off offset:256
	v_mul_lo_u32 v66, v66, s34
	v_add3_u32 v0, 16, v66, v0
	s_waitcnt vmcnt(52)
	v_add_u32_e32 v173, 0xd800, v0
	s_mov_b32 s14, 0xfffffc0
	s_waitcnt vmcnt(19)
	ds_write_b128 v0, v[2:5]
	s_waitcnt vmcnt(18)
	ds_write_b128 v0, v[6:9] offset:4608
	s_waitcnt vmcnt(17)
	ds_write_b128 v0, v[10:13] offset:9216
	s_waitcnt vmcnt(16)
	ds_write_b128 v0, v[14:17] offset:13824
	s_waitcnt vmcnt(15)
	ds_write_b128 v0, v[18:21] offset:18432
	s_waitcnt vmcnt(14)
	ds_write_b128 v0, v[22:25] offset:23040
	s_waitcnt vmcnt(13)
	ds_write_b128 v0, v[26:29] offset:27648
	s_waitcnt vmcnt(12)
	ds_write_b128 v0, v[30:33] offset:32256
	global_load_dwordx4 v[114:117], v[154:155], off offset:256
	global_load_dwordx4 v[118:121], v[156:157], off offset:256
	global_load_dwordx4 v[122:125], v[158:159], off offset:256
	global_load_dwordx4 v[126:129], v[160:161], off offset:256
	global_load_dwordx4 v[66:69], v[162:163], off offset:384
	global_load_dwordx4 v[70:73], v[164:165], off offset:384
	global_load_dwordx4 v[74:77], v[166:167], off offset:384
	global_load_dwordx4 v[94:97], v[168:169], off offset:384
	s_waitcnt lgkmcnt(0)
	s_barrier
	s_waitcnt vmcnt(19)
	ds_write_b128 v0, v[34:37] offset:36864
	s_waitcnt vmcnt(18)
	ds_write_b128 v0, v[38:41] offset:41472
	s_waitcnt vmcnt(17)
	ds_write_b128 v0, v[42:45] offset:46080
	s_waitcnt vmcnt(16)
	ds_write_b128 v0, v[46:49] offset:50688
	s_waitcnt vmcnt(15)
	ds_write_b128 v0, v[50:53] offset:55296
	s_waitcnt vmcnt(14)
	ds_write_b128 v0, v[54:57] offset:59904
	s_waitcnt vmcnt(13)
	ds_write_b128 v0, v[58:61] offset:64512
	s_waitcnt vmcnt(12)
	ds_write_b128 v173, v[62:65] offset:13824
	v_and_b32_e32 v2, 31, v98
	v_lshrrev_b32_e32 v3, 1, v98
	v_and_b32_e32 v4, 0x5f, v98
	global_load_dwordx4 v[130:133], v[154:155], off offset:384
	global_load_dwordx4 v[134:137], v[156:157], off offset:384
	global_load_dwordx4 v[138:141], v[158:159], off offset:384
	global_load_dwordx4 v[142:145], v[160:161], off offset:384
	global_load_dwordx4 v[98:101], v[162:163], off offset:512
	global_load_dwordx4 v[102:105], v[164:165], off offset:512
	global_load_dwordx4 v[106:109], v[166:167], off offset:512
	global_load_dwordx4 v[110:113], v[168:169], off offset:512
	v_and_or_b32 v2, v3, s14, v2
	v_mul_u32_u24_e32 v4, 0x48, v4
	v_mul_lo_u32 v2, v2, s34
	v_and_b32_e32 v3, 16, v3
	v_add3_u32 v171, 16, v2, v3
	v_lshlrev_b32_e32 v2, 1, v4
	v_add3_u32 v172, 16, v2, v3
	s_setprio 2
	ds_read_b128 v[2:5], v171
	ds_read_b128 v[146:149], v171 offset:32
	ds_read_b128 v[18:21], v171 offset:4608
	ds_read_b128 v[150:153], v171 offset:4640
	ds_read_b128 v[6:9], v172 offset:18432
	ds_read_b128 v[174:177], v172 offset:18464
	ds_read_b128 v[22:25], v172 offset:23040
	ds_read_b128 v[178:181], v172 offset:23072
	s_waitcnt lgkmcnt(3)
	v_mfma_f32_32x32x16_bf16 v[50:65], v[2:5], v[6:9], 0
	s_waitcnt lgkmcnt(1)
	v_mfma_f32_32x32x16_bf16 v[34:49], v[2:5], v[22:25], 0
	v_mfma_f32_32x32x16_bf16 v[2:17], v[18:21], v[6:9], 0
	v_mfma_f32_32x32x16_bf16 v[18:33], v[18:21], v[22:25], 0
	ds_read_b128 v[182:185], v171 offset:64
	ds_read_b128 v[186:189], v171 offset:4672
	ds_read_b128 v[190:193], v172 offset:18496
	ds_read_b128 v[212:215], v172 offset:23104
	s_waitcnt lgkmcnt(4)
	v_mfma_f32_32x32x16_bf16 v[34:49], v[146:149], v[178:181], v[34:49]
	v_mfma_f32_32x32x16_bf16 v[2:17], v[150:153], v[174:177], v[2:17]
	v_mfma_f32_32x32x16_bf16 v[18:33], v[150:153], v[178:181], v[18:33]
	v_mfma_f32_32x32x16_bf16 v[50:65], v[146:149], v[174:177], v[50:65]
	ds_read_b128 v[146:149], v171 offset:96
	ds_read_b128 v[150:153], v171 offset:4704
	ds_read_b128 v[174:177], v172 offset:18528
	ds_read_b128 v[178:181], v172 offset:23136
	s_waitcnt lgkmcnt(4)
	v_mfma_f32_32x32x16_bf16 v[34:49], v[182:185], v[212:215], v[34:49]
	v_mfma_f32_32x32x16_bf16 v[2:17], v[186:189], v[190:193], v[2:17]
	v_mfma_f32_32x32x16_bf16 v[18:33], v[186:189], v[212:215], v[18:33]
	v_mfma_f32_32x32x16_bf16 v[50:65], v[182:185], v[190:193], v[50:65]
	s_waitcnt lgkmcnt(0)
	v_mfma_f32_32x32x16_bf16 v[34:49], v[146:149], v[178:181], v[34:49]
	v_mfma_f32_32x32x16_bf16 v[2:17], v[150:153], v[174:177], v[2:17]
	v_mfma_f32_32x32x16_bf16 v[18:33], v[150:153], v[178:181], v[18:33]
	v_mfma_f32_32x32x16_bf16 v[50:65], v[146:149], v[174:177], v[50:65]
	s_setprio 0
	s_barrier
	s_setprio 2
	s_waitcnt vmcnt(14)
	ds_write_b128 v0, v[118:121] offset:23040
	s_waitcnt vmcnt(12)
	ds_write_b128 v0, v[126:129] offset:32256
	ds_read_b128 v[118:121], v171 offset:36864
	ds_read_b128 v[174:177], v171 offset:41472
	ds_read_b128 v[182:185], v172 offset:55296
	ds_read_b128 v[190:193], v172 offset:59904
	ds_read_b128 v[126:129], v171 offset:36896
	ds_read_b128 v[178:181], v171 offset:41504
	ds_read_b128 v[186:189], v172 offset:55328
	ds_read_b128 v[212:215], v172 offset:59936
	s_waitcnt lgkmcnt(4)
	v_mfma_f32_32x32x16_bf16 v[34:49], v[118:121], v[190:193], v[34:49]
	s_waitcnt vmcnt(19)
	ds_write_b128 v0, v[78:81]
	v_mfma_f32_32x32x16_bf16 v[2:17], v[174:177], v[182:185], v[2:17]
	s_waitcnt vmcnt(18)
	ds_write_b128 v0, v[82:85] offset:4608
	v_mfma_f32_32x32x16_bf16 v[18:33], v[174:177], v[190:193], v[18:33]
	s_waitcnt vmcnt(17)
	ds_write_b128 v0, v[86:89] offset:9216
	v_mfma_f32_32x32x16_bf16 v[50:65], v[118:121], v[182:185], v[50:65]
	s_waitcnt vmcnt(16)
	ds_write_b128 v0, v[90:93] offset:13824
	ds_read_b128 v[118:121], v171 offset:36928
	ds_read_b128 v[174:177], v171 offset:41536
	ds_read_b128 v[182:185], v172 offset:55360
	ds_read_b128 v[190:193], v172 offset:59968
	s_waitcnt lgkmcnt(8)
	v_mfma_f32_32x32x16_bf16 v[34:49], v[126:129], v[212:215], v[34:49]
	s_waitcnt vmcnt(15)
	ds_write_b128 v0, v[114:117] offset:18432
	v_mfma_f32_32x32x16_bf16 v[2:17], v[178:181], v[186:189], v[2:17]
	s_waitcnt vmcnt(13)
	ds_write_b128 v0, v[122:125] offset:27648
	v_mfma_f32_32x32x16_bf16 v[18:33], v[178:181], v[212:215], v[18:33]
	v_mfma_f32_32x32x16_bf16 v[50:65], v[126:129], v[186:189], v[50:65]
	ds_read_b128 v[126:129], v171 offset:36960
	ds_read_b128 v[178:181], v171 offset:41568
	ds_read_b128 v[186:189], v172 offset:55392
	ds_read_b128 v[212:215], v172 offset:60000
	s_waitcnt lgkmcnt(6)
	v_mfma_f32_32x32x16_bf16 v[34:49], v[118:121], v[190:193], v[34:49]
	global_load_dwordx4 v[90:93], v[154:155], off offset:512
	global_load_dwordx4 v[122:125], v[156:157], off offset:512
	v_mfma_f32_32x32x16_bf16 v[2:17], v[174:177], v[182:185], v[2:17]
	global_load_dwordx4 v[146:149], v[158:159], off offset:512
	global_load_dwordx4 v[150:153], v[160:161], off offset:512
	v_mfma_f32_32x32x16_bf16 v[18:33], v[174:177], v[190:193], v[18:33]
	global_load_dwordx4 v[78:81], v[162:163], off offset:640
	global_load_dwordx4 v[82:85], v[164:165], off offset:640
	v_mfma_f32_32x32x16_bf16 v[50:65], v[118:121], v[182:185], v[50:65]
	global_load_dwordx4 v[86:89], v[166:167], off offset:640
	global_load_dwordx4 v[114:117], v[168:169], off offset:640
	s_waitcnt lgkmcnt(0)
	v_mfma_f32_32x32x16_bf16 v[34:49], v[126:129], v[212:215], v[34:49]
	v_mfma_f32_32x32x16_bf16 v[2:17], v[178:181], v[186:189], v[2:17]
	v_mfma_f32_32x32x16_bf16 v[18:33], v[178:181], v[212:215], v[18:33]
	v_mfma_f32_32x32x16_bf16 v[50:65], v[126:129], v[186:189], v[50:65]
	s_waitcnt lgkmcnt(0)
	s_setprio 0
	s_barrier
	s_setprio 2
	s_waitcnt vmcnt(16)
	ds_write_b128 v0, v[94:97] offset:50688
	s_waitcnt vmcnt(12)
	ds_write_b128 v173, v[142:145] offset:13824
	ds_read_b128 v[94:97], v171
	ds_read_b128 v[174:177], v171 offset:4608
	ds_read_b128 v[182:185], v172 offset:18432
	ds_read_b128 v[190:193], v172 offset:23040
	ds_read_b128 v[142:145], v171 offset:32
	ds_read_b128 v[178:181], v171 offset:4640
	ds_read_b128 v[186:189], v172 offset:18464
	ds_read_b128 v[212:215], v172 offset:23072
	s_waitcnt lgkmcnt(4)
	v_mfma_f32_32x32x16_bf16 v[34:49], v[94:97], v[190:193], v[34:49]
	s_waitcnt vmcnt(19)
	ds_write_b128 v0, v[66:69] offset:36864
	v_mfma_f32_32x32x16_bf16 v[2:17], v[174:177], v[182:185], v[2:17]
	s_waitcnt vmcnt(18)
	ds_write_b128 v0, v[70:73] offset:41472
	v_mfma_f32_32x32x16_bf16 v[18:33], v[174:177], v[190:193], v[18:33]
	s_waitcnt vmcnt(17)
	ds_write_b128 v0, v[74:77] offset:46080
	v_mfma_f32_32x32x16_bf16 v[50:65], v[94:97], v[182:185], v[50:65]
	s_waitcnt vmcnt(15)
	ds_write_b128 v0, v[130:133] offset:55296
	ds_read_b128 v[94:97], v171 offset:64
	ds_read_b128 v[174:177], v171 offset:4672
	ds_read_b128 v[182:185], v172 offset:18496
	ds_read_b128 v[190:193], v172 offset:23104
	s_waitcnt lgkmcnt(8)
	v_mfma_f32_32x32x16_bf16 v[34:49], v[142:145], v[212:215], v[34:49]
	s_waitcnt vmcnt(14)
	ds_write_b128 v0, v[134:137] offset:59904
	v_mfma_f32_32x32x16_bf16 v[2:17], v[178:181], v[186:189], v[2:17]
	s_waitcnt vmcnt(13)
	ds_write_b128 v0, v[138:141] offset:64512
	v_mfma_f32_32x32x16_bf16 v[18:33], v[178:181], v[212:215], v[18:33]
	v_mfma_f32_32x32x16_bf16 v[50:65], v[142:145], v[186:189], v[50:65]
	ds_read_b128 v[142:145], v171 offset:96
	ds_read_b128 v[178:181], v171 offset:4704
	ds_read_b128 v[186:189], v172 offset:18528
	ds_read_b128 v[212:215], v172 offset:23136
	s_waitcnt lgkmcnt(6)
	v_mfma_f32_32x32x16_bf16 v[34:49], v[94:97], v[190:193], v[34:49]
	global_load_dwordx4 v[126:129], v[154:155], off offset:640
	global_load_dwordx4 v[130:133], v[156:157], off offset:640
	v_mfma_f32_32x32x16_bf16 v[2:17], v[174:177], v[182:185], v[2:17]
	global_load_dwordx4 v[134:137], v[158:159], off offset:640
	global_load_dwordx4 v[138:141], v[160:161], off offset:640
	v_mfma_f32_32x32x16_bf16 v[18:33], v[174:177], v[190:193], v[18:33]
	global_load_dwordx4 v[66:69], v[162:163], off offset:768
	global_load_dwordx4 v[70:73], v[164:165], off offset:768
	v_mfma_f32_32x32x16_bf16 v[50:65], v[94:97], v[182:185], v[50:65]
	global_load_dwordx4 v[74:77], v[166:167], off offset:768
	global_load_dwordx4 v[118:121], v[168:169], off offset:768
	s_waitcnt lgkmcnt(0)
	v_mfma_f32_32x32x16_bf16 v[34:49], v[142:145], v[212:215], v[34:49]
	v_mfma_f32_32x32x16_bf16 v[2:17], v[178:181], v[186:189], v[2:17]
	v_mfma_f32_32x32x16_bf16 v[18:33], v[178:181], v[212:215], v[18:33]
	v_mfma_f32_32x32x16_bf16 v[50:65], v[142:145], v[186:189], v[50:65]
	s_waitcnt lgkmcnt(0)
	s_setprio 0
	s_barrier
	s_setprio 2
	s_waitcnt vmcnt(17)
	ds_write_b128 v0, v[106:109] offset:9216
	s_waitcnt vmcnt(12)
	ds_write_b128 v0, v[150:153] offset:32256
	ds_read_b128 v[106:109], v171 offset:36864
	ds_read_b128 v[174:177], v171 offset:41472
	ds_read_b128 v[182:185], v172 offset:55296
	ds_read_b128 v[190:193], v172 offset:59904
	ds_read_b128 v[150:153], v171 offset:36896
	ds_read_b128 v[178:181], v171 offset:41504
	ds_read_b128 v[186:189], v172 offset:55328
	ds_read_b128 v[212:215], v172 offset:59936
	s_waitcnt lgkmcnt(4)
	v_mfma_f32_32x32x16_bf16 v[34:49], v[106:109], v[190:193], v[34:49]
	s_waitcnt vmcnt(19)
	ds_write_b128 v0, v[98:101]
	v_mfma_f32_32x32x16_bf16 v[2:17], v[174:177], v[182:185], v[2:17]
	s_waitcnt vmcnt(18)
	ds_write_b128 v0, v[102:105] offset:4608
	v_mfma_f32_32x32x16_bf16 v[18:33], v[174:177], v[190:193], v[18:33]
	s_waitcnt vmcnt(16)
	ds_write_b128 v0, v[110:113] offset:13824
	v_mfma_f32_32x32x16_bf16 v[50:65], v[106:109], v[182:185], v[50:65]
	s_waitcnt vmcnt(15)
	ds_write_b128 v0, v[90:93] offset:18432
	ds_read_b128 v[106:109], v171 offset:36928
	ds_read_b128 v[174:177], v171 offset:41536
	ds_read_b128 v[182:185], v172 offset:55360
	ds_read_b128 v[190:193], v172 offset:59968
	s_waitcnt lgkmcnt(8)
	v_mfma_f32_32x32x16_bf16 v[34:49], v[150:153], v[212:215], v[34:49]
	s_waitcnt vmcnt(14)
	ds_write_b128 v0, v[122:125] offset:23040
	v_mfma_f32_32x32x16_bf16 v[2:17], v[178:181], v[186:189], v[2:17]
	s_waitcnt vmcnt(13)
	ds_write_b128 v0, v[146:149] offset:27648
	v_mfma_f32_32x32x16_bf16 v[18:33], v[178:181], v[212:215], v[18:33]
	v_mfma_f32_32x32x16_bf16 v[50:65], v[150:153], v[186:189], v[50:65]
	ds_read_b128 v[150:153], v171 offset:36960
	ds_read_b128 v[178:181], v171 offset:41568
	ds_read_b128 v[186:189], v172 offset:55392
	ds_read_b128 v[212:215], v172 offset:60000
	s_waitcnt lgkmcnt(6)
	v_mfma_f32_32x32x16_bf16 v[34:49], v[106:109], v[190:193], v[34:49]
	global_load_dwordx4 v[110:113], v[154:155], off offset:768
	global_load_dwordx4 v[122:125], v[156:157], off offset:768
	v_mfma_f32_32x32x16_bf16 v[2:17], v[174:177], v[182:185], v[2:17]
	global_load_dwordx4 v[142:145], v[158:159], off offset:768
	global_load_dwordx4 v[146:149], v[160:161], off offset:768
	v_mfma_f32_32x32x16_bf16 v[18:33], v[174:177], v[190:193], v[18:33]
	global_load_dwordx4 v[90:93], v[162:163], off offset:896
	global_load_dwordx4 v[94:97], v[164:165], off offset:896
	v_mfma_f32_32x32x16_bf16 v[50:65], v[106:109], v[182:185], v[50:65]
	global_load_dwordx4 v[98:101], v[166:167], off offset:896
	global_load_dwordx4 v[102:105], v[168:169], off offset:896
	s_waitcnt lgkmcnt(0)
	v_mfma_f32_32x32x16_bf16 v[34:49], v[150:153], v[212:215], v[34:49]
	v_mfma_f32_32x32x16_bf16 v[2:17], v[178:181], v[186:189], v[2:17]
	v_mfma_f32_32x32x16_bf16 v[18:33], v[178:181], v[212:215], v[18:33]
	v_mfma_f32_32x32x16_bf16 v[50:65], v[150:153], v[186:189], v[50:65]
	s_waitcnt lgkmcnt(0)
	s_setprio 0
	s_barrier
	s_setprio 2
	s_waitcnt vmcnt(12)
	ds_write_b128 v173, v[138:141] offset:13824
	ds_read_b128 v[138:141], v171
	ds_read_b128 v[174:177], v171 offset:4608
	ds_read_b128 v[182:185], v172 offset:18432
	ds_read_b128 v[190:193], v172 offset:23040
	ds_read_b128 v[150:153], v171 offset:32
	ds_read_b128 v[178:181], v171 offset:4640
	ds_read_b128 v[186:189], v172 offset:18464
	ds_read_b128 v[212:215], v172 offset:23072
	s_waitcnt lgkmcnt(4)
	v_mfma_f32_32x32x16_bf16 v[34:49], v[138:141], v[190:193], v[34:49]
	s_waitcnt vmcnt(19)
	ds_write_b128 v0, v[78:81] offset:36864
	v_mfma_f32_32x32x16_bf16 v[2:17], v[174:177], v[182:185], v[2:17]
	s_waitcnt vmcnt(18)
	ds_write_b128 v0, v[82:85] offset:41472
	v_mfma_f32_32x32x16_bf16 v[18:33], v[174:177], v[190:193], v[18:33]
	s_waitcnt vmcnt(17)
	ds_write_b128 v0, v[86:89] offset:46080
	v_mfma_f32_32x32x16_bf16 v[50:65], v[138:141], v[182:185], v[50:65]
	s_waitcnt vmcnt(16)
	ds_write_b128 v0, v[114:117] offset:50688
	ds_read_b128 v[138:141], v171 offset:64
	ds_read_b128 v[174:177], v171 offset:4672
	ds_read_b128 v[182:185], v172 offset:18496
	ds_read_b128 v[190:193], v172 offset:23104
	s_waitcnt lgkmcnt(8)
	v_mfma_f32_32x32x16_bf16 v[34:49], v[150:153], v[212:215], v[34:49]
	s_waitcnt vmcnt(15)
	ds_write_b128 v0, v[126:129] offset:55296
	v_mfma_f32_32x32x16_bf16 v[2:17], v[178:181], v[186:189], v[2:17]
	s_waitcnt vmcnt(14)
	ds_write_b128 v0, v[130:133] offset:59904
	v_mfma_f32_32x32x16_bf16 v[18:33], v[178:181], v[212:215], v[18:33]
	s_waitcnt vmcnt(13)
	ds_write_b128 v0, v[134:137] offset:64512
	v_mfma_f32_32x32x16_bf16 v[50:65], v[150:153], v[186:189], v[50:65]
	ds_read_b128 v[150:153], v171 offset:96
	ds_read_b128 v[178:181], v171 offset:4704
	ds_read_b128 v[186:189], v172 offset:18528
	ds_read_b128 v[212:215], v172 offset:23136
	s_waitcnt lgkmcnt(7)
	v_mfma_f32_32x32x16_bf16 v[34:49], v[138:141], v[190:193], v[34:49]
	global_load_dwordx4 v[114:117], v[154:155], off offset:896
	global_load_dwordx4 v[126:129], v[156:157], off offset:896
	v_mfma_f32_32x32x16_bf16 v[2:17], v[174:177], v[182:185], v[2:17]
	global_load_dwordx4 v[130:133], v[158:159], off offset:896
	global_load_dwordx4 v[134:137], v[160:161], off offset:896
	v_mfma_f32_32x32x16_bf16 v[18:33], v[174:177], v[190:193], v[18:33]
	global_load_dwordx4 v[78:81], v[162:163], off offset:1024
	global_load_dwordx4 v[82:85], v[164:165], off offset:1024
	v_mfma_f32_32x32x16_bf16 v[50:65], v[138:141], v[182:185], v[50:65]
	global_load_dwordx4 v[86:89], v[166:167], off offset:1024
	global_load_dwordx4 v[106:109], v[168:169], off offset:1024
	s_waitcnt lgkmcnt(0)
	v_mfma_f32_32x32x16_bf16 v[34:49], v[150:153], v[212:215], v[34:49]
	v_mfma_f32_32x32x16_bf16 v[2:17], v[178:181], v[186:189], v[2:17]
	v_mfma_f32_32x32x16_bf16 v[18:33], v[178:181], v[212:215], v[18:33]
	v_mfma_f32_32x32x16_bf16 v[50:65], v[150:153], v[186:189], v[50:65]
	s_waitcnt lgkmcnt(0)
	s_setprio 0
	s_barrier
	s_setprio 2
	s_waitcnt vmcnt(12)
	ds_write_b128 v0, v[146:149] offset:32256
	ds_read_b128 v[146:149], v171 offset:36864
	ds_read_b128 v[174:177], v171 offset:41472
	ds_read_b128 v[182:185], v172 offset:55296
	ds_read_b128 v[190:193], v172 offset:59904
	ds_read_b128 v[150:153], v171 offset:36896
	ds_read_b128 v[178:181], v171 offset:41504
	ds_read_b128 v[186:189], v172 offset:55328
	ds_read_b128 v[212:215], v172 offset:59936
	s_waitcnt lgkmcnt(4)
	v_mfma_f32_32x32x16_bf16 v[34:49], v[146:149], v[190:193], v[34:49]
	s_waitcnt vmcnt(19)
	ds_write_b128 v0, v[66:69]
	v_mfma_f32_32x32x16_bf16 v[2:17], v[174:177], v[182:185], v[2:17]
	s_waitcnt vmcnt(18)
	ds_write_b128 v0, v[70:73] offset:4608
	v_mfma_f32_32x32x16_bf16 v[18:33], v[174:177], v[190:193], v[18:33]
	s_waitcnt vmcnt(17)
	ds_write_b128 v0, v[74:77] offset:9216
	v_mfma_f32_32x32x16_bf16 v[50:65], v[146:149], v[182:185], v[50:65]
	s_waitcnt vmcnt(16)
	ds_write_b128 v0, v[118:121] offset:13824
	ds_read_b128 v[146:149], v171 offset:36928
	ds_read_b128 v[174:177], v171 offset:41536
	ds_read_b128 v[182:185], v172 offset:55360
	ds_read_b128 v[190:193], v172 offset:59968
	s_waitcnt lgkmcnt(8)
	v_mfma_f32_32x32x16_bf16 v[34:49], v[150:153], v[212:215], v[34:49]
	s_waitcnt vmcnt(15)
	ds_write_b128 v0, v[110:113] offset:18432
	v_mfma_f32_32x32x16_bf16 v[2:17], v[178:181], v[186:189], v[2:17]
	s_waitcnt vmcnt(14)
	ds_write_b128 v0, v[122:125] offset:23040
	v_mfma_f32_32x32x16_bf16 v[18:33], v[178:181], v[212:215], v[18:33]
	s_waitcnt vmcnt(13)
	ds_write_b128 v0, v[142:145] offset:27648
	v_mfma_f32_32x32x16_bf16 v[50:65], v[150:153], v[186:189], v[50:65]
	ds_read_b128 v[150:153], v171 offset:36960
	ds_read_b128 v[178:181], v171 offset:41568
	ds_read_b128 v[186:189], v172 offset:55392
	ds_read_b128 v[212:215], v172 offset:60000
	s_waitcnt lgkmcnt(7)
	v_mfma_f32_32x32x16_bf16 v[34:49], v[146:149], v[190:193], v[34:49]
	global_load_dwordx4 v[118:121], v[154:155], off offset:1024
	global_load_dwordx4 v[122:125], v[156:157], off offset:1024
	v_mfma_f32_32x32x16_bf16 v[2:17], v[174:177], v[182:185], v[2:17]
	global_load_dwordx4 v[138:141], v[158:159], off offset:1024
	global_load_dwordx4 v[142:145], v[160:161], off offset:1024
	v_mfma_f32_32x32x16_bf16 v[18:33], v[174:177], v[190:193], v[18:33]
	global_load_dwordx4 v[66:69], v[162:163], off offset:1152
	global_load_dwordx4 v[70:73], v[164:165], off offset:1152
	v_mfma_f32_32x32x16_bf16 v[50:65], v[146:149], v[182:185], v[50:65]
	global_load_dwordx4 v[74:77], v[166:167], off offset:1152
	global_load_dwordx4 v[110:113], v[168:169], off offset:1152
	s_waitcnt lgkmcnt(0)
	v_mfma_f32_32x32x16_bf16 v[34:49], v[150:153], v[212:215], v[34:49]
	v_mfma_f32_32x32x16_bf16 v[2:17], v[178:181], v[186:189], v[2:17]
	v_mfma_f32_32x32x16_bf16 v[18:33], v[178:181], v[212:215], v[18:33]
	v_mfma_f32_32x32x16_bf16 v[50:65], v[150:153], v[186:189], v[50:65]
	s_waitcnt lgkmcnt(0)
	s_setprio 0
	s_barrier
	s_setprio 2
	ds_read_b128 v[146:149], v171
	ds_read_b128 v[174:177], v171 offset:4608
	ds_read_b128 v[182:185], v172 offset:18432
	ds_read_b128 v[190:193], v172 offset:23040
	ds_read_b128 v[150:153], v171 offset:32
	ds_read_b128 v[178:181], v171 offset:4640
	ds_read_b128 v[186:189], v172 offset:18464
	ds_read_b128 v[212:215], v172 offset:23072
	s_waitcnt lgkmcnt(4)
	v_mfma_f32_32x32x16_bf16 v[34:49], v[146:149], v[190:193], v[34:49]
	s_waitcnt vmcnt(19)
	ds_write_b128 v0, v[90:93] offset:36864
	v_mfma_f32_32x32x16_bf16 v[2:17], v[174:177], v[182:185], v[2:17]
	s_waitcnt vmcnt(18)
	ds_write_b128 v0, v[94:97] offset:41472
	v_mfma_f32_32x32x16_bf16 v[18:33], v[174:177], v[190:193], v[18:33]
	s_waitcnt vmcnt(17)
	ds_write_b128 v0, v[98:101] offset:46080
	v_mfma_f32_32x32x16_bf16 v[50:65], v[146:149], v[182:185], v[50:65]
	s_waitcnt vmcnt(16)
	ds_write_b128 v0, v[102:105] offset:50688
	ds_read_b128 v[146:149], v171 offset:64
	ds_read_b128 v[174:177], v171 offset:4672
	ds_read_b128 v[182:185], v172 offset:18496
	ds_read_b128 v[190:193], v172 offset:23104
	s_waitcnt lgkmcnt(8)
	v_mfma_f32_32x32x16_bf16 v[34:49], v[150:153], v[212:215], v[34:49]
	s_waitcnt vmcnt(15)
	ds_write_b128 v0, v[114:117] offset:55296
	v_mfma_f32_32x32x16_bf16 v[2:17], v[178:181], v[186:189], v[2:17]
	s_waitcnt vmcnt(14)
	ds_write_b128 v0, v[126:129] offset:59904
	v_mfma_f32_32x32x16_bf16 v[18:33], v[178:181], v[212:215], v[18:33]
	s_waitcnt vmcnt(13)
	ds_write_b128 v0, v[130:133] offset:64512
	v_mfma_f32_32x32x16_bf16 v[50:65], v[150:153], v[186:189], v[50:65]
	s_waitcnt vmcnt(12)
	ds_write_b128 v173, v[134:137] offset:13824
	ds_read_b128 v[150:153], v171 offset:96
	ds_read_b128 v[178:181], v171 offset:4704
	ds_read_b128 v[186:189], v172 offset:18528
	ds_read_b128 v[212:215], v172 offset:23136
	s_waitcnt lgkmcnt(8)
	v_mfma_f32_32x32x16_bf16 v[34:49], v[146:149], v[190:193], v[34:49]
	global_load_dwordx4 v[114:117], v[154:155], off offset:1152
	global_load_dwordx4 v[126:129], v[156:157], off offset:1152
	v_mfma_f32_32x32x16_bf16 v[2:17], v[174:177], v[182:185], v[2:17]
	global_load_dwordx4 v[130:133], v[158:159], off offset:1152
	global_load_dwordx4 v[134:137], v[160:161], off offset:1152
	v_mfma_f32_32x32x16_bf16 v[18:33], v[174:177], v[190:193], v[18:33]
	global_load_dwordx4 v[90:93], v[162:163], off offset:1280
	global_load_dwordx4 v[94:97], v[164:165], off offset:1280
	v_mfma_f32_32x32x16_bf16 v[50:65], v[146:149], v[182:185], v[50:65]
	global_load_dwordx4 v[98:101], v[166:167], off offset:1280
	global_load_dwordx4 v[102:105], v[168:169], off offset:1280
	s_waitcnt lgkmcnt(0)
	v_mfma_f32_32x32x16_bf16 v[34:49], v[150:153], v[212:215], v[34:49]
	v_mfma_f32_32x32x16_bf16 v[2:17], v[178:181], v[186:189], v[2:17]
	v_mfma_f32_32x32x16_bf16 v[18:33], v[178:181], v[212:215], v[18:33]
	v_mfma_f32_32x32x16_bf16 v[50:65], v[150:153], v[186:189], v[50:65]
	s_waitcnt lgkmcnt(0)
	s_setprio 0
	s_barrier
	s_setprio 2
	ds_read_b128 v[146:149], v171 offset:36864
	ds_read_b128 v[174:177], v171 offset:41472
	ds_read_b128 v[182:185], v172 offset:55296
	ds_read_b128 v[190:193], v172 offset:59904
	ds_read_b128 v[150:153], v171 offset:36896
	ds_read_b128 v[178:181], v171 offset:41504
	ds_read_b128 v[186:189], v172 offset:55328
	ds_read_b128 v[212:215], v172 offset:59936
	s_waitcnt lgkmcnt(4)
	v_mfma_f32_32x32x16_bf16 v[34:49], v[146:149], v[190:193], v[34:49]
	s_waitcnt vmcnt(19)
	ds_write_b128 v0, v[78:81]
	v_mfma_f32_32x32x16_bf16 v[2:17], v[174:177], v[182:185], v[2:17]
	s_waitcnt vmcnt(18)
	ds_write_b128 v0, v[82:85] offset:4608
	v_mfma_f32_32x32x16_bf16 v[18:33], v[174:177], v[190:193], v[18:33]
	s_waitcnt vmcnt(17)
	ds_write_b128 v0, v[86:89] offset:9216
	v_mfma_f32_32x32x16_bf16 v[50:65], v[146:149], v[182:185], v[50:65]
	s_waitcnt vmcnt(16)
	ds_write_b128 v0, v[106:109] offset:13824
	ds_read_b128 v[146:149], v171 offset:36928
	ds_read_b128 v[174:177], v171 offset:41536
	ds_read_b128 v[182:185], v172 offset:55360
	ds_read_b128 v[190:193], v172 offset:59968
	s_waitcnt lgkmcnt(8)
	v_mfma_f32_32x32x16_bf16 v[34:49], v[150:153], v[212:215], v[34:49]
	s_waitcnt vmcnt(15)
	ds_write_b128 v0, v[118:121] offset:18432
	v_mfma_f32_32x32x16_bf16 v[2:17], v[178:181], v[186:189], v[2:17]
	s_waitcnt vmcnt(14)
	ds_write_b128 v0, v[122:125] offset:23040
	v_mfma_f32_32x32x16_bf16 v[18:33], v[178:181], v[212:215], v[18:33]
	s_waitcnt vmcnt(13)
	ds_write_b128 v0, v[138:141] offset:27648
	v_mfma_f32_32x32x16_bf16 v[50:65], v[150:153], v[186:189], v[50:65]
	s_waitcnt vmcnt(12)
	ds_write_b128 v0, v[142:145] offset:32256
	ds_read_b128 v[150:153], v171 offset:36960
	ds_read_b128 v[178:181], v171 offset:41568
	ds_read_b128 v[186:189], v172 offset:55392
	ds_read_b128 v[212:215], v172 offset:60000
	s_waitcnt lgkmcnt(8)
	v_mfma_f32_32x32x16_bf16 v[34:49], v[146:149], v[190:193], v[34:49]
	global_load_dwordx4 v[118:121], v[154:155], off offset:1280
	global_load_dwordx4 v[122:125], v[156:157], off offset:1280
	v_mfma_f32_32x32x16_bf16 v[2:17], v[174:177], v[182:185], v[2:17]
	global_load_dwordx4 v[138:141], v[158:159], off offset:1280
	global_load_dwordx4 v[142:145], v[160:161], off offset:1280
	v_mfma_f32_32x32x16_bf16 v[18:33], v[174:177], v[190:193], v[18:33]
	global_load_dwordx4 v[78:81], v[162:163], off offset:1408
	global_load_dwordx4 v[82:85], v[164:165], off offset:1408
	v_mfma_f32_32x32x16_bf16 v[50:65], v[146:149], v[182:185], v[50:65]
	global_load_dwordx4 v[86:89], v[166:167], off offset:1408
	global_load_dwordx4 v[106:109], v[168:169], off offset:1408
	s_waitcnt lgkmcnt(0)
	v_mfma_f32_32x32x16_bf16 v[34:49], v[150:153], v[212:215], v[34:49]
	v_mfma_f32_32x32x16_bf16 v[2:17], v[178:181], v[186:189], v[2:17]
	v_mfma_f32_32x32x16_bf16 v[18:33], v[178:181], v[212:215], v[18:33]
	v_mfma_f32_32x32x16_bf16 v[50:65], v[150:153], v[186:189], v[50:65]
	s_waitcnt lgkmcnt(0)
	s_setprio 0
	s_barrier
	s_setprio 2
	ds_read_b128 v[146:149], v171
	ds_read_b128 v[174:177], v171 offset:4608
	ds_read_b128 v[182:185], v172 offset:18432
	ds_read_b128 v[190:193], v172 offset:23040
	ds_read_b128 v[150:153], v171 offset:32
	ds_read_b128 v[178:181], v171 offset:4640
	ds_read_b128 v[186:189], v172 offset:18464
	ds_read_b128 v[212:215], v172 offset:23072
	s_waitcnt lgkmcnt(4)
	v_mfma_f32_32x32x16_bf16 v[34:49], v[146:149], v[190:193], v[34:49]
	s_waitcnt vmcnt(19)
	ds_write_b128 v0, v[66:69] offset:36864
	v_mfma_f32_32x32x16_bf16 v[2:17], v[174:177], v[182:185], v[2:17]
	s_waitcnt vmcnt(18)
	ds_write_b128 v0, v[70:73] offset:41472
	v_mfma_f32_32x32x16_bf16 v[18:33], v[174:177], v[190:193], v[18:33]
	s_waitcnt vmcnt(17)
	ds_write_b128 v0, v[74:77] offset:46080
	v_mfma_f32_32x32x16_bf16 v[50:65], v[146:149], v[182:185], v[50:65]
	s_waitcnt vmcnt(16)
	ds_write_b128 v0, v[110:113] offset:50688
	ds_read_b128 v[146:149], v171 offset:64
	ds_read_b128 v[174:177], v171 offset:4672
	ds_read_b128 v[182:185], v172 offset:18496
	ds_read_b128 v[190:193], v172 offset:23104
	s_waitcnt lgkmcnt(8)
	v_mfma_f32_32x32x16_bf16 v[34:49], v[150:153], v[212:215], v[34:49]
	s_waitcnt vmcnt(15)
	ds_write_b128 v0, v[114:117] offset:55296
	v_mfma_f32_32x32x16_bf16 v[2:17], v[178:181], v[186:189], v[2:17]
	s_waitcnt vmcnt(14)
	ds_write_b128 v0, v[126:129] offset:59904
	v_mfma_f32_32x32x16_bf16 v[18:33], v[178:181], v[212:215], v[18:33]
	s_waitcnt vmcnt(13)
	ds_write_b128 v0, v[130:133] offset:64512
	v_mfma_f32_32x32x16_bf16 v[50:65], v[150:153], v[186:189], v[50:65]
	s_waitcnt vmcnt(12)
	ds_write_b128 v173, v[134:137] offset:13824
	ds_read_b128 v[150:153], v171 offset:96
	ds_read_b128 v[178:181], v171 offset:4704
	ds_read_b128 v[186:189], v172 offset:18528
	ds_read_b128 v[212:215], v172 offset:23136
	s_waitcnt lgkmcnt(8)
	v_mfma_f32_32x32x16_bf16 v[34:49], v[146:149], v[190:193], v[34:49]
	global_load_dwordx4 v[114:117], v[154:155], off offset:1408
	global_load_dwordx4 v[126:129], v[156:157], off offset:1408
	v_mfma_f32_32x32x16_bf16 v[2:17], v[174:177], v[182:185], v[2:17]
	global_load_dwordx4 v[130:133], v[158:159], off offset:1408
	global_load_dwordx4 v[134:137], v[160:161], off offset:1408
	v_mfma_f32_32x32x16_bf16 v[18:33], v[174:177], v[190:193], v[18:33]
	global_load_dwordx4 v[66:69], v[162:163], off offset:1536
	global_load_dwordx4 v[70:73], v[164:165], off offset:1536
	v_mfma_f32_32x32x16_bf16 v[50:65], v[146:149], v[182:185], v[50:65]
	global_load_dwordx4 v[74:77], v[166:167], off offset:1536
	global_load_dwordx4 v[110:113], v[168:169], off offset:1536
	s_waitcnt lgkmcnt(0)
	v_mfma_f32_32x32x16_bf16 v[34:49], v[150:153], v[212:215], v[34:49]
	v_mfma_f32_32x32x16_bf16 v[2:17], v[178:181], v[186:189], v[2:17]
	v_mfma_f32_32x32x16_bf16 v[18:33], v[178:181], v[212:215], v[18:33]
	v_mfma_f32_32x32x16_bf16 v[50:65], v[150:153], v[186:189], v[50:65]
	s_waitcnt lgkmcnt(0)
	s_setprio 0
	s_barrier
	s_setprio 2
	ds_read_b128 v[146:149], v171 offset:36864
	ds_read_b128 v[174:177], v171 offset:41472
	ds_read_b128 v[182:185], v172 offset:55296
	ds_read_b128 v[190:193], v172 offset:59904
	ds_read_b128 v[150:153], v171 offset:36896
	ds_read_b128 v[178:181], v171 offset:41504
	ds_read_b128 v[186:189], v172 offset:55328
	ds_read_b128 v[212:215], v172 offset:59936
	s_waitcnt lgkmcnt(4)
	v_mfma_f32_32x32x16_bf16 v[34:49], v[146:149], v[190:193], v[34:49]
	s_waitcnt vmcnt(19)
	ds_write_b128 v0, v[90:93]
	v_mfma_f32_32x32x16_bf16 v[2:17], v[174:177], v[182:185], v[2:17]
	s_waitcnt vmcnt(18)
	ds_write_b128 v0, v[94:97] offset:4608
	v_mfma_f32_32x32x16_bf16 v[18:33], v[174:177], v[190:193], v[18:33]
	s_waitcnt vmcnt(17)
	ds_write_b128 v0, v[98:101] offset:9216
	v_mfma_f32_32x32x16_bf16 v[50:65], v[146:149], v[182:185], v[50:65]
	s_waitcnt vmcnt(16)
	ds_write_b128 v0, v[102:105] offset:13824
	ds_read_b128 v[146:149], v171 offset:36928
	ds_read_b128 v[174:177], v171 offset:41536
	ds_read_b128 v[182:185], v172 offset:55360
	ds_read_b128 v[190:193], v172 offset:59968
	s_waitcnt lgkmcnt(8)
	v_mfma_f32_32x32x16_bf16 v[34:49], v[150:153], v[212:215], v[34:49]
	s_waitcnt vmcnt(15)
	ds_write_b128 v0, v[118:121] offset:18432
	v_mfma_f32_32x32x16_bf16 v[2:17], v[178:181], v[186:189], v[2:17]
	s_waitcnt vmcnt(14)
	ds_write_b128 v0, v[122:125] offset:23040
	v_mfma_f32_32x32x16_bf16 v[18:33], v[178:181], v[212:215], v[18:33]
	s_waitcnt vmcnt(13)
	ds_write_b128 v0, v[138:141] offset:27648
	v_mfma_f32_32x32x16_bf16 v[50:65], v[150:153], v[186:189], v[50:65]
	s_waitcnt vmcnt(12)
	ds_write_b128 v0, v[142:145] offset:32256
	ds_read_b128 v[150:153], v171 offset:36960
	ds_read_b128 v[178:181], v171 offset:41568
	ds_read_b128 v[186:189], v172 offset:55392
	ds_read_b128 v[212:215], v172 offset:60000
	s_waitcnt lgkmcnt(8)
	v_mfma_f32_32x32x16_bf16 v[34:49], v[146:149], v[190:193], v[34:49]
	global_load_dwordx4 v[118:121], v[154:155], off offset:1536
	global_load_dwordx4 v[122:125], v[156:157], off offset:1536
	v_mfma_f32_32x32x16_bf16 v[2:17], v[174:177], v[182:185], v[2:17]
	global_load_dwordx4 v[138:141], v[158:159], off offset:1536
	global_load_dwordx4 v[142:145], v[160:161], off offset:1536
	v_mfma_f32_32x32x16_bf16 v[18:33], v[174:177], v[190:193], v[18:33]
	global_load_dwordx4 v[90:93], v[162:163], off offset:1664
	global_load_dwordx4 v[94:97], v[164:165], off offset:1664
	v_mfma_f32_32x32x16_bf16 v[50:65], v[146:149], v[182:185], v[50:65]
	global_load_dwordx4 v[98:101], v[166:167], off offset:1664
	global_load_dwordx4 v[102:105], v[168:169], off offset:1664
	s_waitcnt lgkmcnt(0)
	v_mfma_f32_32x32x16_bf16 v[34:49], v[150:153], v[212:215], v[34:49]
	v_mfma_f32_32x32x16_bf16 v[2:17], v[178:181], v[186:189], v[2:17]
	v_mfma_f32_32x32x16_bf16 v[18:33], v[178:181], v[212:215], v[18:33]
	v_mfma_f32_32x32x16_bf16 v[50:65], v[150:153], v[186:189], v[50:65]
	s_waitcnt lgkmcnt(0)
	s_setprio 0
	s_barrier
	s_setprio 2
	ds_read_b128 v[146:149], v171
	ds_read_b128 v[174:177], v171 offset:4608
	ds_read_b128 v[182:185], v172 offset:18432
	ds_read_b128 v[190:193], v172 offset:23040
	ds_read_b128 v[150:153], v171 offset:32
	ds_read_b128 v[178:181], v171 offset:4640
	ds_read_b128 v[186:189], v172 offset:18464
	ds_read_b128 v[212:215], v172 offset:23072
	s_waitcnt lgkmcnt(4)
	v_mfma_f32_32x32x16_bf16 v[34:49], v[146:149], v[190:193], v[34:49]
	s_waitcnt vmcnt(19)
	ds_write_b128 v0, v[78:81] offset:36864
	v_mfma_f32_32x32x16_bf16 v[2:17], v[174:177], v[182:185], v[2:17]
	s_waitcnt vmcnt(18)
	ds_write_b128 v0, v[82:85] offset:41472
	v_mfma_f32_32x32x16_bf16 v[18:33], v[174:177], v[190:193], v[18:33]
	s_waitcnt vmcnt(17)
	ds_write_b128 v0, v[86:89] offset:46080
	v_mfma_f32_32x32x16_bf16 v[50:65], v[146:149], v[182:185], v[50:65]
	s_waitcnt vmcnt(16)
	ds_write_b128 v0, v[106:109] offset:50688
	ds_read_b128 v[146:149], v171 offset:64
	ds_read_b128 v[174:177], v171 offset:4672
	ds_read_b128 v[182:185], v172 offset:18496
	ds_read_b128 v[190:193], v172 offset:23104
	s_waitcnt lgkmcnt(8)
	v_mfma_f32_32x32x16_bf16 v[34:49], v[150:153], v[212:215], v[34:49]
	s_waitcnt vmcnt(15)
	ds_write_b128 v0, v[114:117] offset:55296
	v_mfma_f32_32x32x16_bf16 v[2:17], v[178:181], v[186:189], v[2:17]
	s_waitcnt vmcnt(14)
	ds_write_b128 v0, v[126:129] offset:59904
	v_mfma_f32_32x32x16_bf16 v[18:33], v[178:181], v[212:215], v[18:33]
	s_waitcnt vmcnt(13)
	ds_write_b128 v0, v[130:133] offset:64512
	v_mfma_f32_32x32x16_bf16 v[50:65], v[150:153], v[186:189], v[50:65]
	s_waitcnt vmcnt(12)
	ds_write_b128 v173, v[134:137] offset:13824
	ds_read_b128 v[150:153], v171 offset:96
	ds_read_b128 v[178:181], v171 offset:4704
	ds_read_b128 v[186:189], v172 offset:18528
	ds_read_b128 v[212:215], v172 offset:23136
	s_waitcnt lgkmcnt(8)
	v_mfma_f32_32x32x16_bf16 v[34:49], v[146:149], v[190:193], v[34:49]
	global_load_dwordx4 v[114:117], v[154:155], off offset:1664
	global_load_dwordx4 v[126:129], v[156:157], off offset:1664
	v_mfma_f32_32x32x16_bf16 v[2:17], v[174:177], v[182:185], v[2:17]
	global_load_dwordx4 v[130:133], v[158:159], off offset:1664
	global_load_dwordx4 v[134:137], v[160:161], off offset:1664
	v_mfma_f32_32x32x16_bf16 v[18:33], v[174:177], v[190:193], v[18:33]
	global_load_dwordx4 v[78:81], v[162:163], off offset:1792
	global_load_dwordx4 v[82:85], v[164:165], off offset:1792
	v_mfma_f32_32x32x16_bf16 v[50:65], v[146:149], v[182:185], v[50:65]
	global_load_dwordx4 v[86:89], v[166:167], off offset:1792
	global_load_dwordx4 v[106:109], v[168:169], off offset:1792
	s_waitcnt lgkmcnt(0)
	v_mfma_f32_32x32x16_bf16 v[34:49], v[150:153], v[212:215], v[34:49]
	v_mfma_f32_32x32x16_bf16 v[2:17], v[178:181], v[186:189], v[2:17]
	v_mfma_f32_32x32x16_bf16 v[18:33], v[178:181], v[212:215], v[18:33]
	v_mfma_f32_32x32x16_bf16 v[50:65], v[150:153], v[186:189], v[50:65]
	s_waitcnt lgkmcnt(0)
	s_setprio 0
	s_barrier
	s_waitcnt vmcnt(19)
	ds_write_b128 v0, v[66:69]
	s_waitcnt vmcnt(18)
	ds_write_b128 v0, v[70:73] offset:4608
	s_waitcnt vmcnt(17)
	ds_write_b128 v0, v[74:77] offset:9216
	s_waitcnt vmcnt(16)
	ds_write_b128 v0, v[110:113] offset:13824
	s_waitcnt vmcnt(15)
	ds_write_b128 v0, v[118:121] offset:18432
	s_waitcnt vmcnt(14)
	ds_write_b128 v0, v[122:125] offset:23040
	s_waitcnt vmcnt(13)
	ds_write_b128 v0, v[138:141] offset:27648
	s_waitcnt vmcnt(12)
	ds_write_b128 v0, v[142:145] offset:32256
	global_load_dwordx4 v[118:121], v[154:155], off offset:1792
	global_load_dwordx4 v[122:125], v[156:157], off offset:1792
	global_load_dwordx4 v[138:141], v[158:159], off offset:1792
	global_load_dwordx4 v[142:145], v[160:161], off offset:1792
	global_load_dwordx4 v[66:69], v[162:163], off offset:1920
	global_load_dwordx4 v[70:73], v[164:165], off offset:1920
	global_load_dwordx4 v[74:77], v[166:167], off offset:1920
	global_load_dwordx4 v[110:113], v[168:169], off offset:1920
	s_setprio 2
	ds_read_b128 v[146:149], v171 offset:36864
	ds_read_b128 v[150:153], v171 offset:36896
	ds_read_b128 v[162:165], v171 offset:41472
	ds_read_b128 v[166:169], v171 offset:41504
	ds_read_b128 v[174:177], v172 offset:55296
	ds_read_b128 v[178:181], v172 offset:55328
	ds_read_b128 v[182:185], v172 offset:59904
	ds_read_b128 v[186:189], v172 offset:59936
	s_waitcnt lgkmcnt(1)
	v_mfma_f32_32x32x16_bf16 v[34:49], v[146:149], v[182:185], v[34:49]
	v_mfma_f32_32x32x16_bf16 v[2:17], v[162:165], v[174:177], v[2:17]
	v_mfma_f32_32x32x16_bf16 v[18:33], v[162:165], v[182:185], v[18:33]
	v_mfma_f32_32x32x16_bf16 v[50:65], v[146:149], v[174:177], v[50:65]
	ds_read_b128 v[146:149], v171 offset:36928
	ds_read_b128 v[162:165], v171 offset:41536
	ds_read_b128 v[174:177], v172 offset:55360
	ds_read_b128 v[182:185], v172 offset:59968
	s_waitcnt lgkmcnt(4)
	v_mfma_f32_32x32x16_bf16 v[34:49], v[150:153], v[186:189], v[34:49]
	v_mfma_f32_32x32x16_bf16 v[2:17], v[166:169], v[178:181], v[2:17]
	v_mfma_f32_32x32x16_bf16 v[18:33], v[166:169], v[186:189], v[18:33]
	v_mfma_f32_32x32x16_bf16 v[50:65], v[150:153], v[178:181], v[50:65]
	ds_read_b128 v[150:153], v171 offset:36960
	ds_read_b128 v[166:169], v171 offset:41568
	ds_read_b128 v[178:181], v172 offset:55392
	ds_read_b128 v[186:189], v172 offset:60000
	s_waitcnt lgkmcnt(4)
	v_mfma_f32_32x32x16_bf16 v[34:49], v[146:149], v[182:185], v[34:49]
	v_mfma_f32_32x32x16_bf16 v[2:17], v[162:165], v[174:177], v[2:17]
	v_mfma_f32_32x32x16_bf16 v[18:33], v[162:165], v[182:185], v[18:33]
	v_mfma_f32_32x32x16_bf16 v[50:65], v[146:149], v[174:177], v[50:65]
	s_waitcnt lgkmcnt(0)
	v_mfma_f32_32x32x16_bf16 v[34:49], v[150:153], v[186:189], v[34:49]
	v_mfma_f32_32x32x16_bf16 v[2:17], v[166:169], v[178:181], v[2:17]
	v_mfma_f32_32x32x16_bf16 v[18:33], v[166:169], v[186:189], v[18:33]
	v_mfma_f32_32x32x16_bf16 v[50:65], v[150:153], v[178:181], v[50:65]
	s_setprio 0
	s_barrier
	s_waitcnt vmcnt(19)
	ds_write_b128 v0, v[90:93] offset:36864
	s_waitcnt vmcnt(18)
	ds_write_b128 v0, v[94:97] offset:41472
	s_waitcnt vmcnt(17)
	ds_write_b128 v0, v[98:101] offset:46080
	s_waitcnt vmcnt(16)
	ds_write_b128 v0, v[102:105] offset:50688
	s_waitcnt vmcnt(15)
	ds_write_b128 v0, v[114:117] offset:55296
	s_waitcnt vmcnt(14)
	ds_write_b128 v0, v[126:129] offset:59904
	s_waitcnt vmcnt(13)
	ds_write_b128 v0, v[130:133] offset:64512
	s_waitcnt vmcnt(12)
	ds_write_b128 v173, v[134:137] offset:13824
	global_load_dwordx4 v[90:93], v[154:155], off offset:1920
	global_load_dwordx4 v[94:97], v[156:157], off offset:1920
	global_load_dwordx4 v[98:101], v[158:159], off offset:1920
	global_load_dwordx4 v[102:105], v[160:161], off offset:1920
	s_setprio 2
	ds_read_b128 v[114:117], v171
	ds_read_b128 v[126:129], v171 offset:32
	ds_read_b128 v[130:133], v171 offset:4608
	ds_read_b128 v[134:137], v171 offset:4640
	ds_read_b128 v[146:149], v172 offset:18432
	ds_read_b128 v[150:153], v172 offset:18464
	ds_read_b128 v[154:157], v172 offset:23040
	ds_read_b128 v[158:161], v172 offset:23072
	s_waitcnt lgkmcnt(1)
	v_mfma_f32_32x32x16_bf16 v[34:49], v[114:117], v[154:157], v[34:49]
	v_mfma_f32_32x32x16_bf16 v[2:17], v[130:133], v[146:149], v[2:17]
	v_mfma_f32_32x32x16_bf16 v[18:33], v[130:133], v[154:157], v[18:33]
	v_mfma_f32_32x32x16_bf16 v[50:65], v[114:117], v[146:149], v[50:65]
	ds_read_b128 v[114:117], v171 offset:64
	ds_read_b128 v[130:133], v171 offset:4672
	ds_read_b128 v[146:149], v172 offset:18496
	ds_read_b128 v[154:157], v172 offset:23104
	s_waitcnt lgkmcnt(4)
	v_mfma_f32_32x32x16_bf16 v[34:49], v[126:129], v[158:161], v[34:49]
	v_mfma_f32_32x32x16_bf16 v[2:17], v[134:137], v[150:153], v[2:17]
	v_mfma_f32_32x32x16_bf16 v[18:33], v[134:137], v[158:161], v[18:33]
	v_mfma_f32_32x32x16_bf16 v[50:65], v[126:129], v[150:153], v[50:65]
	ds_read_b128 v[126:129], v171 offset:96
	ds_read_b128 v[134:137], v171 offset:4704
	ds_read_b128 v[150:153], v172 offset:18528
	ds_read_b128 v[158:161], v172 offset:23136
	s_waitcnt lgkmcnt(4)
	v_mfma_f32_32x32x16_bf16 v[34:49], v[114:117], v[154:157], v[34:49]
	v_mfma_f32_32x32x16_bf16 v[2:17], v[130:133], v[146:149], v[2:17]
	v_mfma_f32_32x32x16_bf16 v[18:33], v[130:133], v[154:157], v[18:33]
	v_mfma_f32_32x32x16_bf16 v[50:65], v[114:117], v[146:149], v[50:65]
	s_waitcnt lgkmcnt(0)
	v_mfma_f32_32x32x16_bf16 v[34:49], v[126:129], v[158:161], v[34:49]
	v_mfma_f32_32x32x16_bf16 v[2:17], v[134:137], v[150:153], v[2:17]
	v_mfma_f32_32x32x16_bf16 v[18:33], v[134:137], v[158:161], v[18:33]
	v_mfma_f32_32x32x16_bf16 v[50:65], v[126:129], v[150:153], v[50:65]
	s_setprio 0
	s_barrier
	s_setprio 2
	s_waitcnt vmcnt(15)
	ds_write_b128 v0, v[78:81]
	s_waitcnt vmcnt(14)
	ds_write_b128 v0, v[82:85] offset:4608
	s_waitcnt vmcnt(13)
	ds_write_b128 v0, v[86:89] offset:9216
	s_waitcnt vmcnt(12)
	ds_write_b128 v0, v[106:109] offset:13824
	s_waitcnt vmcnt(11)
	ds_write_b128 v0, v[118:121] offset:18432
	s_waitcnt vmcnt(10)
	ds_write_b128 v0, v[122:125] offset:23040
	ds_read_b128 v[78:81], v171 offset:36864
	ds_read_b128 v[86:89], v171 offset:41472
	ds_read_b128 v[114:117], v172 offset:55296
	ds_read_b128 v[122:125], v172 offset:59904
	ds_read_b128 v[82:85], v171 offset:36896
	ds_read_b128 v[106:109], v171 offset:41504
	ds_read_b128 v[118:121], v172 offset:55328
	ds_read_b128 v[126:129], v172 offset:59936
	s_waitcnt lgkmcnt(4)
	v_mfma_f32_32x32x16_bf16 v[34:49], v[78:81], v[122:125], v[34:49]
	s_waitcnt vmcnt(9)
	ds_write_b128 v0, v[138:141] offset:27648
	v_mfma_f32_32x32x16_bf16 v[2:17], v[86:89], v[114:117], v[2:17]
	s_waitcnt vmcnt(8)
	ds_write_b128 v0, v[142:145] offset:32256
	v_mfma_f32_32x32x16_bf16 v[18:33], v[86:89], v[122:125], v[18:33]
	v_mfma_f32_32x32x16_bf16 v[50:65], v[78:81], v[114:117], v[50:65]
	ds_read_b128 v[78:81], v171 offset:36928
	ds_read_b128 v[86:89], v171 offset:41536
	ds_read_b128 v[114:117], v172 offset:55360
	ds_read_b128 v[122:125], v172 offset:59968
	s_waitcnt lgkmcnt(6)
	v_mfma_f32_32x32x16_bf16 v[34:49], v[82:85], v[126:129], v[34:49]
	v_mfma_f32_32x32x16_bf16 v[2:17], v[106:109], v[118:121], v[2:17]
	v_mfma_f32_32x32x16_bf16 v[18:33], v[106:109], v[126:129], v[18:33]
	v_mfma_f32_32x32x16_bf16 v[50:65], v[82:85], v[118:121], v[50:65]
	ds_read_b128 v[82:85], v171 offset:36960
	ds_read_b128 v[106:109], v171 offset:41568
	ds_read_b128 v[118:121], v172 offset:55392
	ds_read_b128 v[126:129], v172 offset:60000
	s_waitcnt lgkmcnt(4)
	v_mfma_f32_32x32x16_bf16 v[34:49], v[78:81], v[122:125], v[34:49]
	v_mfma_f32_32x32x16_bf16 v[2:17], v[86:89], v[114:117], v[2:17]
	v_mfma_f32_32x32x16_bf16 v[18:33], v[86:89], v[122:125], v[18:33]
	v_mfma_f32_32x32x16_bf16 v[50:65], v[78:81], v[114:117], v[50:65]
	s_waitcnt lgkmcnt(0)
	v_mfma_f32_32x32x16_bf16 v[34:49], v[82:85], v[126:129], v[34:49]
	v_mfma_f32_32x32x16_bf16 v[2:17], v[106:109], v[118:121], v[2:17]
	v_mfma_f32_32x32x16_bf16 v[18:33], v[106:109], v[126:129], v[18:33]
	v_mfma_f32_32x32x16_bf16 v[50:65], v[82:85], v[118:121], v[50:65]
	s_waitcnt lgkmcnt(0)
	s_setprio 0
	s_barrier
	s_setprio 2
	s_waitcnt vmcnt(7)
	ds_write_b128 v0, v[66:69] offset:36864
	s_waitcnt vmcnt(6)
	ds_write_b128 v0, v[70:73] offset:41472
	s_waitcnt vmcnt(5)
	ds_write_b128 v0, v[74:77] offset:46080
	s_waitcnt vmcnt(3)
	ds_write_b128 v0, v[90:93] offset:55296
	s_waitcnt vmcnt(2)
	ds_write_b128 v0, v[94:97] offset:59904
	ds_read_b128 v[66:69], v171
	ds_read_b128 v[74:77], v171 offset:4608
	ds_read_b128 v[82:85], v172 offset:18432
	ds_read_b128 v[90:93], v172 offset:23040
	ds_read_b128 v[70:73], v171 offset:32
	ds_read_b128 v[78:81], v171 offset:4640
	ds_read_b128 v[86:89], v172 offset:18464
	ds_read_b128 v[94:97], v172 offset:23072
	s_waitcnt lgkmcnt(4)
	v_mfma_f32_32x32x16_bf16 v[34:49], v[66:69], v[90:93], v[34:49]
	s_waitcnt vmcnt(4)
	ds_write_b128 v0, v[110:113] offset:50688
	v_mfma_f32_32x32x16_bf16 v[2:17], v[74:77], v[82:85], v[2:17]
	s_waitcnt vmcnt(1)
	ds_write_b128 v0, v[98:101] offset:64512
	v_mfma_f32_32x32x16_bf16 v[18:33], v[74:77], v[90:93], v[18:33]
	s_waitcnt vmcnt(0)
	ds_write_b128 v173, v[102:105] offset:13824
	v_mfma_f32_32x32x16_bf16 v[50:65], v[66:69], v[82:85], v[50:65]
	ds_read_b128 v[66:69], v171 offset:64
	ds_read_b128 v[74:77], v171 offset:4672
	ds_read_b128 v[82:85], v172 offset:18496
	ds_read_b128 v[90:93], v172 offset:23104
	s_waitcnt lgkmcnt(7)
	v_mfma_f32_32x32x16_bf16 v[34:49], v[70:73], v[94:97], v[34:49]
	v_mfma_f32_32x32x16_bf16 v[2:17], v[78:81], v[86:89], v[2:17]
	v_mfma_f32_32x32x16_bf16 v[18:33], v[78:81], v[94:97], v[18:33]
	v_mfma_f32_32x32x16_bf16 v[50:65], v[70:73], v[86:89], v[50:65]
	ds_read_b128 v[70:73], v171 offset:96
	ds_read_b128 v[78:81], v171 offset:4704
	ds_read_b128 v[86:89], v172 offset:18528
	ds_read_b128 v[94:97], v172 offset:23136
	s_waitcnt lgkmcnt(4)
	v_mfma_f32_32x32x16_bf16 v[34:49], v[66:69], v[90:93], v[34:49]
	v_mfma_f32_32x32x16_bf16 v[2:17], v[74:77], v[82:85], v[2:17]
	v_mfma_f32_32x32x16_bf16 v[18:33], v[74:77], v[90:93], v[18:33]
	v_mfma_f32_32x32x16_bf16 v[50:65], v[66:69], v[82:85], v[50:65]
	s_waitcnt lgkmcnt(0)
	v_mfma_f32_32x32x16_bf16 v[34:49], v[70:73], v[94:97], v[34:49]
	v_mfma_f32_32x32x16_bf16 v[2:17], v[78:81], v[86:89], v[2:17]
	v_mfma_f32_32x32x16_bf16 v[18:33], v[78:81], v[94:97], v[18:33]
	v_mfma_f32_32x32x16_bf16 v[50:65], v[70:73], v[86:89], v[50:65]
	s_waitcnt lgkmcnt(0)
	s_setprio 0
	s_barrier
	s_setprio 2
	ds_read_b128 v[66:69], v171 offset:36864
	ds_read_b128 v[70:73], v171 offset:36896
	ds_read_b128 v[74:77], v171 offset:41472
	ds_read_b128 v[78:81], v171 offset:41504
	ds_read_b128 v[82:85], v172 offset:55296
	ds_read_b128 v[86:89], v172 offset:55328
	ds_read_b128 v[90:93], v172 offset:59904
	ds_read_b128 v[94:97], v172 offset:59936
	s_waitcnt lgkmcnt(1)
	v_mfma_f32_32x32x16_bf16 v[34:49], v[66:69], v[90:93], v[34:49]
	v_mfma_f32_32x32x16_bf16 v[2:17], v[74:77], v[82:85], v[2:17]
	v_mfma_f32_32x32x16_bf16 v[18:33], v[74:77], v[90:93], v[18:33]
	v_mfma_f32_32x32x16_bf16 v[50:65], v[66:69], v[82:85], v[50:65]
	ds_read_b128 v[66:69], v171 offset:36928
	ds_read_b128 v[74:77], v171 offset:41536
	ds_read_b128 v[82:85], v172 offset:55360
	ds_read_b128 v[90:93], v172 offset:59968
	s_waitcnt lgkmcnt(4)
	v_mfma_f32_32x32x16_bf16 v[34:49], v[70:73], v[94:97], v[34:49]
	v_mfma_f32_32x32x16_bf16 v[2:17], v[78:81], v[86:89], v[2:17]
	v_mfma_f32_32x32x16_bf16 v[18:33], v[78:81], v[94:97], v[18:33]
	v_mfma_f32_32x32x16_bf16 v[50:65], v[70:73], v[86:89], v[50:65]
	ds_read_b128 v[70:73], v171 offset:36960
	ds_read_b128 v[78:81], v171 offset:41568
	ds_read_b128 v[86:89], v172 offset:55392
	ds_read_b128 v[94:97], v172 offset:60000
	s_waitcnt lgkmcnt(4)
	v_mfma_f32_32x32x16_bf16 v[34:49], v[66:69], v[90:93], v[34:49]
	v_mfma_f32_32x32x16_bf16 v[2:17], v[74:77], v[82:85], v[2:17]
	v_mfma_f32_32x32x16_bf16 v[18:33], v[74:77], v[90:93], v[18:33]
	v_mfma_f32_32x32x16_bf16 v[50:65], v[66:69], v[82:85], v[50:65]
	s_waitcnt lgkmcnt(0)
	v_mfma_f32_32x32x16_bf16 v[34:49], v[70:73], v[94:97], v[34:49]
	v_mfma_f32_32x32x16_bf16 v[2:17], v[78:81], v[86:89], v[2:17]
	v_mfma_f32_32x32x16_bf16 v[18:33], v[78:81], v[94:97], v[18:33]
	v_mfma_f32_32x32x16_bf16 v[50:65], v[70:73], v[86:89], v[50:65]
	s_setprio 0
	s_barrier
	v_mov_b32 v66, v194
	s_mul_hi_i32 s15, s11, 0x9000
	v_and_b32_e32 v69, 31, v66
	v_bfe_u32 v169, v66, 5, 1
	v_and_or_b32 v171, v66, 64, s10
	v_ashrrev_i32_e32 v66, 1, v66
	v_and_b32_e32 v68, 0xffffffc0, v66
	v_add_u32_e32 v66, s6, v68
	s_mul_i32 s11, s11, 0x9000
	v_ashrrev_i32_e32 v67, 31, v66
	s_add_u32 s14, s8, s11
	v_or_b32_e32 v0, v171, v69
	v_lshlrev_b64 v[66:67], 12, v[66:67]
	s_addc_u32 s15, s9, s15
	v_lshlrev_b32_e32 v0, 2, v0
	v_lshl_add_u64 v[66:67], s[40:41], 0, v[66:67]
	global_load_dword v100, v0, s[14:15]
	global_load_dword v101, v0, s[14:15] offset:128
	v_lshl_add_u64 v[66:67], v[66:67], 0, v[0:1]
	v_lshlrev_b32_e32 v0, 14, v169
	v_lshl_add_u64 v[66:67], v[66:67], 0, v[0:1]
	s_movk_i32 s6, 0x1000
	v_add_co_u32_e32 v72, vcc, s6, v66
	s_movk_i32 s6, 0x2000
	s_nop 0
	v_addc_co_u32_e32 v73, vcc, 0, v67, vcc
	v_add_co_u32_e32 v70, vcc, s6, v66
	s_movk_i32 s6, 0x3000
	s_nop 0
	v_addc_co_u32_e32 v71, vcc, 0, v67, vcc
	v_add_co_u32_e32 v74, vcc, s6, v66
	s_mov_b32 s6, 0x8000
	s_nop 0
	v_addc_co_u32_e32 v75, vcc, 0, v67, vcc
	v_add_co_u32_e32 v78, vcc, s6, v66
	s_mov_b32 s6, 0xa000
	s_nop 0
	v_addc_co_u32_e32 v79, vcc, 0, v67, vcc
	v_add_co_u32_e32 v76, vcc, s31, v66
	global_load_dword v172, v[66:67], off
	global_load_dword v173, v[66:67], off offset:128
	v_addc_co_u32_e32 v77, vcc, 0, v67, vcc
	v_add_co_u32_e32 v82, vcc, s6, v66
	s_mov_b32 s6, 0xb000
	s_nop 0
	v_addc_co_u32_e32 v83, vcc, 0, v67, vcc
	v_add_co_u32_e32 v80, vcc, s6, v66
	s_mov_b32 s6, 0x11000
	s_nop 0
	v_addc_co_u32_e32 v81, vcc, 0, v67, vcc
	v_add_co_u32_e32 v86, vcc, s16, v66
	global_load_dword v167, v[70:71], off offset:-4096
	global_load_dword v168, v[72:73], off offset:128
	global_load_dword v165, v[70:71], off
	global_load_dword v166, v[70:71], off offset:128
	v_addc_co_u32_e32 v87, vcc, 0, v67, vcc
	v_add_co_u32_e32 v84, vcc, s6, v66
	s_mov_b32 s6, 0x13000
	s_nop 0
	v_addc_co_u32_e32 v85, vcc, 0, v67, vcc
	v_add_co_u32_e32 v90, vcc, s30, v66
	global_load_dword v163, v[74:75], off
	global_load_dword v164, v[74:75], off offset:128
	v_addc_co_u32_e32 v91, vcc, 0, v67, vcc
	v_add_co_u32_e32 v88, vcc, s6, v66
	s_mov_b32 s6, 0x18000
	s_nop 0
	v_addc_co_u32_e32 v89, vcc, 0, v67, vcc
	v_add_co_u32_e32 v94, vcc, s6, v66
	s_mov_b32 s6, 0x19000
	s_nop 0
	v_addc_co_u32_e32 v95, vcc, 0, v67, vcc
	v_add_co_u32_e32 v92, vcc, s6, v66
	s_mov_b32 s6, 0x1a000
	s_nop 0
	v_addc_co_u32_e32 v93, vcc, 0, v67, vcc
	v_add_co_u32_e32 v98, vcc, s6, v66
	s_mov_b32 s6, 0x21000
	s_nop 0
	v_addc_co_u32_e32 v99, vcc, 0, v67, vcc
	v_add_co_u32_e32 v96, vcc, s25, v66
	global_load_dword v161, v[76:77], off offset:-4096
	global_load_dword v162, v[78:79], off offset:128
	global_load_dword v157, v[76:77], off
	global_load_dword v159, v[76:77], off offset:128
	v_addc_co_u32_e32 v97, vcc, 0, v67, vcc
	v_add_co_u32_e32 v102, vcc, s18, v66
	global_load_dword v156, v[80:81], off offset:-4096
	global_load_dword v158, v[82:83], off offset:128
	global_load_dword v150, v[80:81], off
	global_load_dword v152, v[80:81], off offset:128
	v_addc_co_u32_e32 v103, vcc, 0, v67, vcc
	v_add_co_u32_e32 v104, vcc, s6, v66
	s_mov_b32 s6, 0x22000
	s_nop 0
	v_addc_co_u32_e32 v105, vcc, 0, v67, vcc
	global_load_dword v149, v[84:85], off offset:-4096
	global_load_dword v160, v[86:87], off offset:128
	global_load_dword v151, v[84:85], off
	global_load_dword v153, v[84:85], off offset:128
	global_load_dword v154, v[88:89], off offset:-4096
	global_load_dword v155, v[90:91], off offset:128
	global_load_dword v147, v[88:89], off
	global_load_dword v148, v[88:89], off offset:128
	global_load_dword v145, v[92:93], off offset:-4096
	global_load_dword v146, v[94:95], off offset:128
	global_load_dword v141, v[92:93], off
	global_load_dword v142, v[92:93], off offset:128
	global_load_dword v143, v[96:97], off offset:-4096
	global_load_dword v144, v[98:99], off offset:128
	global_load_dword v139, v[96:97], off
	global_load_dword v140, v[96:97], off offset:128
	global_load_dword v137, v[104:105], off offset:-4096
	global_load_dword v138, v[102:103], off offset:128
	global_load_dword v134, v[104:105], off
	global_load_dword v136, v[104:105], off offset:128
	v_add_co_u32_e32 v102, vcc, s6, v66
	s_mov_b32 s6, 0x23000
	s_nop 0
	v_addc_co_u32_e32 v103, vcc, 0, v67, vcc
	v_add_co_u32_e32 v104, vcc, s6, v66
	s_mov_b32 s6, 0x28000
	s_nop 0
	v_addc_co_u32_e32 v105, vcc, 0, v67, vcc
	global_load_dword v133, v[104:105], off offset:-4096
	global_load_dword v135, v[102:103], off offset:128
	global_load_dword v128, v[104:105], off
	global_load_dword v130, v[104:105], off offset:128
	v_add_co_u32_e32 v102, vcc, s6, v66
	s_mov_b32 s6, 0x29000
	s_nop 0
	v_addc_co_u32_e32 v103, vcc, 0, v67, vcc
	v_add_co_u32_e32 v104, vcc, s6, v66
	s_mov_b32 s6, 0x2a000
	s_nop 0
	v_addc_co_u32_e32 v105, vcc, 0, v67, vcc
	global_load_dword v131, v[104:105], off offset:-4096
	global_load_dword v132, v[102:103], off offset:128
	global_load_dword v127, v[104:105], off
	global_load_dword v129, v[104:105], off offset:128
	v_add_co_u32_e32 v102, vcc, s6, v66
	s_mov_b32 s6, 0x2b000
	s_nop 0
	v_addc_co_u32_e32 v103, vcc, 0, v67, vcc
	v_add_co_u32_e32 v104, vcc, s6, v66
	s_mov_b32 s6, 0x31000
	s_nop 0
	v_addc_co_u32_e32 v105, vcc, 0, v67, vcc
	global_load_dword v124, v[104:105], off offset:-4096
	global_load_dword v125, v[102:103], off offset:128
	global_load_dword v118, v[104:105], off
	global_load_dword v120, v[104:105], off offset:128
	v_add_co_u32_e32 v102, vcc, s17, v66
	s_nop 1
	v_addc_co_u32_e32 v103, vcc, 0, v67, vcc
	v_add_co_u32_e32 v104, vcc, s6, v66
	s_mov_b32 s6, 0x32000
	s_nop 0
	v_addc_co_u32_e32 v105, vcc, 0, v67, vcc
	global_load_dword v117, v[104:105], off offset:-4096
	global_load_dword v126, v[102:103], off offset:128
	global_load_dword v119, v[104:105], off
	global_load_dword v121, v[104:105], off offset:128
	v_add_co_u32_e32 v102, vcc, s6, v66
	s_mov_b32 s6, 0x33000
	s_nop 0
	v_addc_co_u32_e32 v103, vcc, 0, v67, vcc
	v_add_co_u32_e32 v104, vcc, s6, v66
	s_mov_b32 s6, 0x38000
	s_nop 0
	v_addc_co_u32_e32 v105, vcc, 0, v67, vcc
	global_load_dword v122, v[104:105], off offset:-4096
	global_load_dword v123, v[102:103], off offset:128
	global_load_dword v112, v[104:105], off
	global_load_dword v114, v[104:105], off offset:128
	v_add_co_u32_e32 v102, vcc, s6, v66
	s_mov_b32 s6, 0x39000
	s_nop 0
	v_addc_co_u32_e32 v103, vcc, 0, v67, vcc
	v_add_co_u32_e32 v104, vcc, s6, v66
	s_mov_b32 s6, 0x3a000
	s_nop 0
	v_addc_co_u32_e32 v105, vcc, 0, v67, vcc
	v_add_co_u32_e32 v110, vcc, s6, v66
	s_mov_b32 s6, 0x3b000
	s_nop 0
	v_addc_co_u32_e32 v111, vcc, 0, v67, vcc
	v_add_co_u32_e32 v174, vcc, s6, v66
	global_load_dword v106, v[104:105], off offset:-4096
	global_load_dword v108, v[102:103], off offset:128
	s_nop 0
	global_load_dword v103, v[104:105], off
	s_nop 0
	global_load_dword v104, v[104:105], off offset:128
	v_addc_co_u32_e32 v175, vcc, 0, v67, vcc
	global_load_dword v102, v[174:175], off offset:-4096
	s_nop 0
	global_load_dword v110, v[110:111], off offset:128
	s_nop 0
	global_load_dword v105, v[174:175], off
	global_load_dword v107, v[174:175], off offset:128
	v_and_b32_e32 v109, 64, v200
	v_xor_b32_e32 v0, 16, v200
	v_add_u32_e32 v116, 64, v109
	v_cmp_lt_i32_e32 vcc, v0, v116
	s_waitcnt vmcnt(62)
	v_fmac_f32_e32 v173, v34, v101
	v_fmac_f32_e32 v172, v50, v100
	v_cndmask_b32_e32 v0, v200, v0, vcc
	v_mul_f32_e32 v34, v173, v173
	v_lshlrev_b32_e32 v109, 2, v0
	v_fmac_f32_e32 v34, v172, v172
	s_waitcnt vmcnt(60)
	v_fmac_f32_e32 v168, v35, v101
	ds_bpermute_b32 v35, v109, v34
	v_xor_b32_e32 v0, 8, v200
	v_cmp_lt_i32_e32 vcc, v0, v116
	s_waitcnt vmcnt(58)
	v_fmac_f32_e32 v166, v36, v101
	s_waitcnt vmcnt(56)
	v_fmac_f32_e32 v164, v37, v101
	v_cndmask_b32_e32 v0, v200, v0, vcc
	v_lshlrev_b32_e32 v111, 2, v0
	s_waitcnt lgkmcnt(0)
	v_add_f32_e32 v34, v34, v35
	ds_bpermute_b32 v35, v111, v34
	v_xor_b32_e32 v0, 4, v200
	v_cmp_lt_i32_e32 vcc, v0, v116
	s_waitcnt vmcnt(54)
	v_fmac_f32_e32 v162, v38, v101
	s_lshl_b32 s2, s2, 9
	v_cndmask_b32_e32 v0, v200, v0, vcc
	v_lshlrev_b32_e32 v113, 2, v0
	s_waitcnt lgkmcnt(0)
	v_add_f32_e32 v34, v34, v35
	ds_bpermute_b32 v35, v113, v34
	v_xor_b32_e32 v0, 2, v200
	v_cmp_lt_i32_e32 vcc, v0, v116
	v_lshlrev_b32_e32 v169, 2, v169
	v_fmac_f32_e32 v167, v51, v100
	v_cndmask_b32_e32 v0, v200, v0, vcc
	v_lshlrev_b32_e32 v115, 2, v0
	s_waitcnt lgkmcnt(0)
	v_add_f32_e32 v36, v34, v35
	v_xor_b32_e32 v0, 1, v200
	ds_bpermute_b32 v37, v115, v36
	v_cmp_lt_i32_e32 vcc, v0, v116
	v_fmac_f32_e32 v165, v52, v100
	v_fmac_f32_e32 v163, v53, v100
	v_cndmask_b32_e32 v0, v200, v0, vcc
	v_lshlrev_b32_e32 v116, 2, v0
	v_lshrrev_b32_e32 v0, 6, v171
	v_mul_u32_u24_e32 v0, 0xc000, v0
	v_lshl_add_u64 v[34:35], s[44:45], 0, v[0:1]
	s_waitcnt lgkmcnt(0)
	v_add_f32_e32 v0, v36, v37
	ds_bpermute_b32 v38, v116, v0
	v_cmp_eq_u32_e32 vcc, 0, v69
	v_ashrrev_i32_e32 v69, 31, v68
	v_lshl_add_u64 v[34:35], v[34:35], 0, s[2:3]
	v_fmac_f32_e32 v161, v54, v100
	s_waitcnt vmcnt(53)
	v_fmac_f32_e32 v157, v55, v100
	s_waitcnt vmcnt(52)
	v_fmac_f32_e32 v159, v39, v101
	s_waitcnt vmcnt(51)
	v_fmac_f32_e32 v156, v56, v100
	s_waitcnt vmcnt(50)
	v_fmac_f32_e32 v158, v40, v101
	s_waitcnt vmcnt(49)
	v_fmac_f32_e32 v150, v57, v100
	s_waitcnt vmcnt(48)
	v_fmac_f32_e32 v152, v41, v101
	s_waitcnt vmcnt(47)
	v_fmac_f32_e32 v149, v58, v100
	s_waitcnt vmcnt(46)
	v_fmac_f32_e32 v160, v42, v101
	s_waitcnt vmcnt(45)
	v_fmac_f32_e32 v151, v59, v100
	s_waitcnt vmcnt(44)
	v_fmac_f32_e32 v153, v43, v101
	s_waitcnt vmcnt(43)
	v_fmac_f32_e32 v154, v60, v100
	s_waitcnt vmcnt(42)
	v_fmac_f32_e32 v155, v44, v101
	s_waitcnt vmcnt(41)
	v_fmac_f32_e32 v147, v61, v100
	s_waitcnt vmcnt(40)
	v_fmac_f32_e32 v148, v45, v101
	s_waitcnt vmcnt(39)
	v_fmac_f32_e32 v145, v62, v100
	s_waitcnt vmcnt(38)
	v_fmac_f32_e32 v146, v46, v101
	s_waitcnt vmcnt(37)
	v_fmac_f32_e32 v141, v63, v100
	s_waitcnt vmcnt(36)
	v_fmac_f32_e32 v142, v47, v101
	s_waitcnt vmcnt(35)
	v_fmac_f32_e32 v143, v64, v100
	s_waitcnt vmcnt(34)
	v_fmac_f32_e32 v144, v48, v101
	s_waitcnt vmcnt(33)
	v_fmac_f32_e32 v139, v65, v100
	s_waitcnt vmcnt(32)
	v_fmac_f32_e32 v140, v49, v101
	v_lshl_add_u64 v[34:35], v[68:69], 2, v[34:35]
	v_lshlrev_b32_e32 v36, 2, v169
	global_store_dword v[66:67], v172, off
	global_store_dword v[66:67], v173, off offset:128
	global_store_dword v[70:71], v167, off offset:-4096
	global_store_dword v[72:73], v168, off offset:128
	global_store_dword v[70:71], v165, off
	global_store_dword v[70:71], v166, off offset:128
	global_store_dword v[74:75], v163, off
	global_store_dword v[74:75], v164, off offset:128
	global_store_dword v[76:77], v161, off offset:-4096
	global_store_dword v[78:79], v162, off offset:128
	global_store_dword v[76:77], v157, off
	global_store_dword v[76:77], v159, off offset:128
	global_store_dword v[80:81], v156, off offset:-4096
	global_store_dword v[82:83], v158, off offset:128
	global_store_dword v[80:81], v150, off
	global_store_dword v[80:81], v152, off offset:128
	global_store_dword v[84:85], v149, off offset:-4096
	global_store_dword v[86:87], v160, off offset:128
	global_store_dword v[84:85], v151, off
	global_store_dword v[84:85], v153, off offset:128
	global_store_dword v[88:89], v154, off offset:-4096
	global_store_dword v[90:91], v155, off offset:128
	global_store_dword v[88:89], v147, off
	global_store_dword v[88:89], v148, off offset:128
	global_store_dword v[92:93], v145, off offset:-4096
	global_store_dword v[94:95], v146, off offset:128
	global_store_dword v[92:93], v141, off
	global_store_dword v[92:93], v142, off offset:128
	global_store_dword v[96:97], v143, off offset:-4096
	global_store_dword v[98:99], v144, off offset:128
	global_store_dword v[96:97], v139, off
	global_store_dword v[96:97], v140, off offset:128
	s_and_saveexec_b64 s[10:11], vcc
	s_cbranch_execz .LBB0_265
	v_mov_b32_e32 v37, v1
	v_lshl_add_u64 v[40:41], v[34:35], 0, v[36:37]
	s_waitcnt lgkmcnt(0)
	v_add_f32_e32 v0, v0, v38
	global_store_dword v[40:41], v0, off

.LBB0_1292:
	v_mul_hi_u32 v0, v166, s20
	v_mul_lo_u32 v2, s19, v0
	v_not_b32_e32 v3, v0
	v_mul_lo_u32 v3, s2, v3
	v_add_u32_e32 v2, s20, v2
	v_add_u32_e32 v4, 1, v0
	v_add_u32_e32 v3, s20, v3
	v_cmp_le_u32_e32 vcc, s2, v2
	v_readlane_b32 s6, v246, 16
	v_readlane_b32 s10, v246, 23
	v_cndmask_b32_e32 v0, v0, v4, vcc
	v_cndmask_b32_e32 v2, v2, v3, vcc
	v_add_u32_e32 v3, 1, v0
	v_cmp_le_u32_e32 vcc, s2, v2
	v_readlane_b32 s11, v246, 24
	s_nop 0
	v_cndmask_b32_e32 v0, v0, v3, vcc
	v_mul_lo_u32 v2, s19, v0
	v_add_u32_e32 v168, s20, v2
	v_lshlrev_b32_e32 v0, 2, v0
	v_add_u32_e32 v172, s6, v0
	v_and_b32_e32 v0, 3, v168
	v_lshrrev_b32_e32 v171, 2, v168
	v_or_b32_e32 v0, v172, v0
	v_lshlrev_b32_e32 v167, 7, v0
	v_lshlrev_b32_e32 v169, 7, v171
	s_andn2_b64 vcc, exec, s[10:11]
	s_mov_b64 s[10:11], -1
	s_cbranch_vccnz .LBB0_1387
	v_mov_b32 v66, v194
	s_nop 0
	v_ashrrev_i32_e32 v68, 3, v66
	v_add_u32_e32 v2, v68, v169
	v_ashrrev_i32_e32 v3, 31, v2
	v_lshlrev_b64 v[2:3], 11, v[2:3]
	v_lshlrev_b32_e32 v0, 4, v66
	v_lshl_add_u64 v[2:3], s[50:51], 0, v[2:3]
	v_and_b32_e32 v0, 0x70, v0
	v_lshl_add_u64 v[150:151], v[2:3], 0, v[0:1]
	v_add_u32_e32 v2, v68, v167
	v_ashrrev_i32_e32 v3, 31, v2
	v_lshlrev_b64 v[2:3], 11, v[2:3]
	v_lshl_add_u64 v[2:3], s[52:53], 0, v[2:3]
	v_lshl_add_u64 v[158:159], v[2:3], 0, v[0:1]
	v_add_co_u32_e32 v160, vcc, s12, v158
	s_barrier
	s_nop 0
	v_addc_co_u32_e32 v161, vcc, 0, v159, vcc
	v_add_co_u32_e32 v162, vcc, s23, v158
	s_nop 1
	v_addc_co_u32_e32 v163, vcc, 0, v159, vcc
	v_add_co_u32_e32 v164, vcc, s21, v158
	s_nop 1
	v_addc_co_u32_e32 v165, vcc, 0, v159, vcc
	v_add_co_u32_e32 v152, vcc, s12, v150
	s_barrier
	global_load_dwordx4 v[2:5], v[158:159], off
	global_load_dwordx4 v[6:9], v[160:161], off
	global_load_dwordx4 v[10:13], v[162:163], off
	global_load_dwordx4 v[14:17], v[164:165], off
	global_load_dwordx4 v[18:21], v[150:151], off
	v_addc_co_u32_e32 v153, vcc, 0, v151, vcc
	v_add_co_u32_e32 v154, vcc, s23, v150
	global_load_dwordx4 v[22:25], v[152:153], off
	s_nop 0
	v_addc_co_u32_e32 v155, vcc, 0, v151, vcc
	v_add_co_u32_e32 v156, vcc, s21, v150
	global_load_dwordx4 v[26:29], v[154:155], off
	s_nop 0
	v_addc_co_u32_e32 v157, vcc, 0, v151, vcc
	global_load_dwordx4 v[30:33], v[156:157], off
	global_load_dwordx4 v[34:37], v[158:159], off offset:128
	global_load_dwordx4 v[38:41], v[160:161], off offset:128
	global_load_dwordx4 v[42:45], v[162:163], off offset:128
	global_load_dwordx4 v[46:49], v[164:165], off offset:128
	global_load_dwordx4 v[50:53], v[150:151], off offset:128
	global_load_dwordx4 v[54:57], v[152:153], off offset:128
	global_load_dwordx4 v[58:61], v[154:155], off offset:128
	global_load_dwordx4 v[62:65], v[156:157], off offset:128
	global_load_dwordx4 v[98:101], v[158:159], off offset:256
	global_load_dwordx4 v[102:105], v[160:161], off offset:256
	global_load_dwordx4 v[106:109], v[162:163], off offset:256
	global_load_dwordx4 v[110:113], v[164:165], off offset:256
	v_mul_lo_u32 v68, v68, s34
	v_add3_u32 v0, 16, v68, v0
	v_and_b32_e32 v67, 31, v66
	v_add_u32_e32 v175, 0xd800, v0
	s_waitcnt vmcnt(19)
	ds_write_b128 v0, v[2:5]
	s_waitcnt vmcnt(18)
	ds_write_b128 v0, v[6:9] offset:4608
	s_waitcnt vmcnt(17)
	ds_write_b128 v0, v[10:13] offset:9216
	s_waitcnt vmcnt(16)
	ds_write_b128 v0, v[14:17] offset:13824
	s_waitcnt vmcnt(15)
	ds_write_b128 v0, v[18:21] offset:18432
	s_waitcnt vmcnt(14)
	ds_write_b128 v0, v[22:25] offset:23040
	s_waitcnt vmcnt(13)
	ds_write_b128 v0, v[26:29] offset:27648
	s_waitcnt vmcnt(12)
	ds_write_b128 v0, v[30:33] offset:32256
	global_load_dwordx4 v[122:125], v[150:151], off offset:256
	global_load_dwordx4 v[126:129], v[152:153], off offset:256
	global_load_dwordx4 v[130:133], v[154:155], off offset:256
	global_load_dwordx4 v[134:137], v[156:157], off offset:256
	global_load_dwordx4 v[78:81], v[158:159], off offset:384
	global_load_dwordx4 v[86:89], v[160:161], off offset:384
	global_load_dwordx4 v[90:93], v[162:163], off offset:384
	global_load_dwordx4 v[94:97], v[164:165], off offset:384
	s_waitcnt lgkmcnt(0)
	s_barrier
	v_lshrrev_b32_e32 v2, 1, v66
	s_waitcnt vmcnt(19)
	ds_write_b128 v0, v[34:37] offset:36864
	s_waitcnt vmcnt(18)
	ds_write_b128 v0, v[38:41] offset:41472
	s_waitcnt vmcnt(17)
	ds_write_b128 v0, v[42:45] offset:46080
	s_waitcnt vmcnt(16)
	ds_write_b128 v0, v[46:49] offset:50688
	s_waitcnt vmcnt(15)
	ds_write_b128 v0, v[50:53] offset:55296
	s_waitcnt vmcnt(14)
	ds_write_b128 v0, v[54:57] offset:59904
	s_waitcnt vmcnt(13)
	ds_write_b128 v0, v[58:61] offset:64512
	s_waitcnt vmcnt(12)
	ds_write_b128 v175, v[62:65] offset:13824
	v_and_or_b32 v3, v2, s24, v67
	v_and_b32_e32 v4, 0x5f, v66
	global_load_dwordx4 v[114:117], v[150:151], off offset:384
	global_load_dwordx4 v[118:121], v[152:153], off offset:384
	global_load_dwordx4 v[138:141], v[154:155], off offset:384
	global_load_dwordx4 v[142:145], v[156:157], off offset:384
	global_load_dwordx4 v[66:69], v[158:159], off offset:512
	global_load_dwordx4 v[70:73], v[160:161], off offset:512
	global_load_dwordx4 v[74:77], v[162:163], off offset:512
	global_load_dwordx4 v[82:85], v[164:165], off offset:512
	v_mul_u32_u24_e32 v4, 0x48, v4
	v_mul_lo_u32 v3, v3, s34
	v_and_b32_e32 v2, 16, v2
	v_add3_u32 v173, 16, v3, v2
	v_lshlrev_b32_e32 v3, 1, v4
	v_add3_u32 v174, 16, v3, v2
	s_setprio 2
	ds_read_b128 v[2:5], v173
	ds_read_b128 v[146:149], v173 offset:32
	ds_read_b128 v[34:37], v173 offset:4608
	ds_read_b128 v[176:179], v173 offset:4640
	ds_read_b128 v[6:9], v174 offset:18432
	ds_read_b128 v[180:183], v174 offset:18464
	ds_read_b128 v[38:41], v174 offset:23040
	ds_read_b128 v[184:187], v174 offset:23072
	s_waitcnt lgkmcnt(3)
	v_mfma_f32_32x32x16_bf16 v[18:33], v[2:5], v[6:9], 0
	s_waitcnt lgkmcnt(1)
	v_mfma_f32_32x32x16_bf16 v[50:65], v[2:5], v[38:41], 0
	v_mfma_f32_32x32x16_bf16 v[2:17], v[34:37], v[6:9], 0
	v_mfma_f32_32x32x16_bf16 v[34:49], v[34:37], v[38:41], 0
	ds_read_b128 v[188:191], v173 offset:64
	ds_read_b128 v[212:215], v173 offset:4672
	ds_read_b128 v[216:219], v174 offset:18496
	ds_read_b128 v[220:223], v174 offset:23104
	v_mfma_f32_32x32x16_bf16 v[18:33], v[146:149], v[180:183], v[18:33]
	s_waitcnt lgkmcnt(4)
	v_mfma_f32_32x32x16_bf16 v[50:65], v[146:149], v[184:187], v[50:65]
	v_mfma_f32_32x32x16_bf16 v[2:17], v[176:179], v[180:183], v[2:17]
	v_mfma_f32_32x32x16_bf16 v[34:49], v[176:179], v[184:187], v[34:49]
	ds_read_b128 v[146:149], v173 offset:96
	ds_read_b128 v[176:179], v173 offset:4704
	ds_read_b128 v[180:183], v174 offset:18528
	ds_read_b128 v[184:187], v174 offset:23136
	s_waitcnt lgkmcnt(5)
	v_mfma_f32_32x32x16_bf16 v[18:33], v[188:191], v[216:219], v[18:33]
	s_waitcnt lgkmcnt(4)
	v_mfma_f32_32x32x16_bf16 v[50:65], v[188:191], v[220:223], v[50:65]
	v_mfma_f32_32x32x16_bf16 v[2:17], v[212:215], v[216:219], v[2:17]
	v_mfma_f32_32x32x16_bf16 v[34:49], v[212:215], v[220:223], v[34:49]
	s_waitcnt lgkmcnt(1)
	v_mfma_f32_32x32x16_bf16 v[18:33], v[146:149], v[180:183], v[18:33]
	s_waitcnt lgkmcnt(0)
	v_mfma_f32_32x32x16_bf16 v[50:65], v[146:149], v[184:187], v[50:65]
	v_mfma_f32_32x32x16_bf16 v[2:17], v[176:179], v[180:183], v[2:17]
	v_mfma_f32_32x32x16_bf16 v[34:49], v[176:179], v[184:187], v[34:49]
	s_setprio 0
	s_barrier
	s_setprio 2
	s_waitcnt vmcnt(13)
	ds_write_b128 v0, v[130:133] offset:27648
	ds_read_b128 v[130:133], v173 offset:36864
	ds_read_b128 v[180:183], v173 offset:41472
	ds_read_b128 v[188:191], v174 offset:55296
	ds_read_b128 v[216:219], v174 offset:59904
	ds_read_b128 v[176:179], v173 offset:36896
	ds_read_b128 v[184:187], v173 offset:41504
	ds_read_b128 v[212:215], v174 offset:55328
	ds_read_b128 v[220:223], v174 offset:59936
	s_waitcnt lgkmcnt(5)
	v_mfma_f32_32x32x16_bf16 v[18:33], v[130:133], v[188:191], v[18:33]
	s_waitcnt vmcnt(19)
	ds_write_b128 v0, v[98:101]
	s_waitcnt lgkmcnt(5)
	v_mfma_f32_32x32x16_bf16 v[50:65], v[130:133], v[216:219], v[50:65]
	s_waitcnt vmcnt(18)
	ds_write_b128 v0, v[102:105] offset:4608
	v_mfma_f32_32x32x16_bf16 v[2:17], v[180:183], v[188:191], v[2:17]
	s_waitcnt vmcnt(17)
	ds_write_b128 v0, v[106:109] offset:9216
	v_mfma_f32_32x32x16_bf16 v[34:49], v[180:183], v[216:219], v[34:49]
	s_waitcnt vmcnt(16)
	ds_write_b128 v0, v[110:113] offset:13824
	ds_read_b128 v[130:133], v173 offset:36928
	ds_read_b128 v[180:183], v173 offset:41536
	ds_read_b128 v[188:191], v174 offset:55360
	ds_read_b128 v[216:219], v174 offset:59968
	s_waitcnt lgkmcnt(9)
	v_mfma_f32_32x32x16_bf16 v[18:33], v[176:179], v[212:215], v[18:33]
	s_waitcnt vmcnt(15)
	ds_write_b128 v0, v[122:125] offset:18432
	s_waitcnt lgkmcnt(9)
	v_mfma_f32_32x32x16_bf16 v[50:65], v[176:179], v[220:223], v[50:65]
	s_waitcnt vmcnt(14)
	ds_write_b128 v0, v[126:129] offset:23040
	v_mfma_f32_32x32x16_bf16 v[2:17], v[184:187], v[212:215], v[2:17]
	s_waitcnt vmcnt(12)
	ds_write_b128 v0, v[134:137] offset:32256
	v_mfma_f32_32x32x16_bf16 v[34:49], v[184:187], v[220:223], v[34:49]
	ds_read_b128 v[176:179], v173 offset:36960
	ds_read_b128 v[184:187], v173 offset:41568
	ds_read_b128 v[212:215], v174 offset:55392
	ds_read_b128 v[220:223], v174 offset:60000
	s_waitcnt lgkmcnt(8)
	v_mfma_f32_32x32x16_bf16 v[18:33], v[130:133], v[188:191], v[18:33]
	global_load_dwordx4 v[122:125], v[150:151], off offset:512
	global_load_dwordx4 v[126:129], v[152:153], off offset:512
	s_waitcnt lgkmcnt(7)
	v_mfma_f32_32x32x16_bf16 v[50:65], v[130:133], v[216:219], v[50:65]
	global_load_dwordx4 v[134:137], v[154:155], off offset:512
	global_load_dwordx4 v[146:149], v[156:157], off offset:512
	v_mfma_f32_32x32x16_bf16 v[2:17], v[180:183], v[188:191], v[2:17]
	global_load_dwordx4 v[98:101], v[158:159], off offset:640
	global_load_dwordx4 v[102:105], v[160:161], off offset:640
	v_mfma_f32_32x32x16_bf16 v[34:49], v[180:183], v[216:219], v[34:49]
	global_load_dwordx4 v[106:109], v[162:163], off offset:640
	global_load_dwordx4 v[110:113], v[164:165], off offset:640
	s_waitcnt lgkmcnt(1)
	v_mfma_f32_32x32x16_bf16 v[18:33], v[176:179], v[212:215], v[18:33]
	s_waitcnt lgkmcnt(0)
	v_mfma_f32_32x32x16_bf16 v[50:65], v[176:179], v[220:223], v[50:65]
	v_mfma_f32_32x32x16_bf16 v[2:17], v[184:187], v[212:215], v[2:17]
	v_mfma_f32_32x32x16_bf16 v[34:49], v[184:187], v[220:223], v[34:49]
	s_waitcnt lgkmcnt(0)
	s_setprio 0
	s_barrier
	s_setprio 2
	s_waitcnt vmcnt(14)
	ds_write_b128 v0, v[118:121] offset:59904
	ds_read_b128 v[118:121], v173
	ds_read_b128 v[180:183], v173 offset:4608
	ds_read_b128 v[188:191], v174 offset:18432
	ds_read_b128 v[216:219], v174 offset:23040
	ds_read_b128 v[176:179], v173 offset:32
	ds_read_b128 v[184:187], v173 offset:4640
	ds_read_b128 v[212:215], v174 offset:18464
	ds_read_b128 v[220:223], v174 offset:23072
	s_waitcnt lgkmcnt(5)
	v_mfma_f32_32x32x16_bf16 v[18:33], v[118:121], v[188:191], v[18:33]
	s_waitcnt vmcnt(19)
	ds_write_b128 v0, v[78:81] offset:36864
	s_waitcnt lgkmcnt(5)
	v_mfma_f32_32x32x16_bf16 v[50:65], v[118:121], v[216:219], v[50:65]
	s_waitcnt vmcnt(18)
	ds_write_b128 v0, v[86:89] offset:41472
	v_mfma_f32_32x32x16_bf16 v[2:17], v[180:183], v[188:191], v[2:17]
	s_waitcnt vmcnt(17)
	ds_write_b128 v0, v[90:93] offset:46080
	v_mfma_f32_32x32x16_bf16 v[34:49], v[180:183], v[216:219], v[34:49]
	s_waitcnt vmcnt(16)
	ds_write_b128 v0, v[94:97] offset:50688
	ds_read_b128 v[118:121], v173 offset:64
	ds_read_b128 v[180:183], v173 offset:4672
	ds_read_b128 v[188:191], v174 offset:18496
	ds_read_b128 v[216:219], v174 offset:23104
	s_waitcnt lgkmcnt(9)
	v_mfma_f32_32x32x16_bf16 v[18:33], v[176:179], v[212:215], v[18:33]
	s_waitcnt vmcnt(15)
	ds_write_b128 v0, v[114:117] offset:55296
	s_waitcnt lgkmcnt(9)
	v_mfma_f32_32x32x16_bf16 v[50:65], v[176:179], v[220:223], v[50:65]
	s_waitcnt vmcnt(13)
	ds_write_b128 v0, v[138:141] offset:64512
	v_mfma_f32_32x32x16_bf16 v[2:17], v[184:187], v[212:215], v[2:17]
	s_waitcnt vmcnt(12)
	ds_write_b128 v175, v[142:145] offset:13824
	v_mfma_f32_32x32x16_bf16 v[34:49], v[184:187], v[220:223], v[34:49]
	ds_read_b128 v[176:179], v173 offset:96
	ds_read_b128 v[184:187], v173 offset:4704
	ds_read_b128 v[212:215], v174 offset:18528
	ds_read_b128 v[220:223], v174 offset:23136
	s_waitcnt lgkmcnt(8)
	v_mfma_f32_32x32x16_bf16 v[18:33], v[118:121], v[188:191], v[18:33]
	global_load_dwordx4 v[94:97], v[150:151], off offset:640
	global_load_dwordx4 v[130:133], v[152:153], off offset:640
	s_waitcnt lgkmcnt(7)
	v_mfma_f32_32x32x16_bf16 v[50:65], v[118:121], v[216:219], v[50:65]
	global_load_dwordx4 v[138:141], v[154:155], off offset:640
	global_load_dwordx4 v[142:145], v[156:157], off offset:640
	v_mfma_f32_32x32x16_bf16 v[2:17], v[180:183], v[188:191], v[2:17]
	global_load_dwordx4 v[78:81], v[158:159], off offset:768
	global_load_dwordx4 v[86:89], v[160:161], off offset:768
	v_mfma_f32_32x32x16_bf16 v[34:49], v[180:183], v[216:219], v[34:49]
	global_load_dwordx4 v[90:93], v[162:163], off offset:768
	global_load_dwordx4 v[114:117], v[164:165], off offset:768
	s_waitcnt lgkmcnt(1)
	v_mfma_f32_32x32x16_bf16 v[18:33], v[176:179], v[212:215], v[18:33]
	s_waitcnt lgkmcnt(0)
	v_mfma_f32_32x32x16_bf16 v[50:65], v[176:179], v[220:223], v[50:65]
	v_mfma_f32_32x32x16_bf16 v[2:17], v[184:187], v[212:215], v[2:17]
	v_mfma_f32_32x32x16_bf16 v[34:49], v[184:187], v[220:223], v[34:49]
	s_waitcnt lgkmcnt(0)
	s_setprio 0
	s_barrier
	s_setprio 2
	s_waitcnt vmcnt(16)
	ds_write_b128 v0, v[82:85] offset:13824
	ds_read_b128 v[82:85], v173 offset:36864
	ds_read_b128 v[180:183], v173 offset:41472
	ds_read_b128 v[188:191], v174 offset:55296
	ds_read_b128 v[216:219], v174 offset:59904
	ds_read_b128 v[176:179], v173 offset:36896
	ds_read_b128 v[184:187], v173 offset:41504
	ds_read_b128 v[212:215], v174 offset:55328
	ds_read_b128 v[220:223], v174 offset:59936
	s_waitcnt lgkmcnt(5)
	v_mfma_f32_32x32x16_bf16 v[18:33], v[82:85], v[188:191], v[18:33]
	s_waitcnt vmcnt(19)
	ds_write_b128 v0, v[66:69]
	s_waitcnt lgkmcnt(5)
	v_mfma_f32_32x32x16_bf16 v[50:65], v[82:85], v[216:219], v[50:65]
	s_waitcnt vmcnt(18)
	ds_write_b128 v0, v[70:73] offset:4608
	v_mfma_f32_32x32x16_bf16 v[2:17], v[180:183], v[188:191], v[2:17]
	s_waitcnt vmcnt(17)
	ds_write_b128 v0, v[74:77] offset:9216
	v_mfma_f32_32x32x16_bf16 v[34:49], v[180:183], v[216:219], v[34:49]
	s_waitcnt vmcnt(15)
	ds_write_b128 v0, v[122:125] offset:18432
	ds_read_b128 v[82:85], v173 offset:36928
	ds_read_b128 v[180:183], v173 offset:41536
	ds_read_b128 v[188:191], v174 offset:55360
	ds_read_b128 v[216:219], v174 offset:59968
	s_waitcnt lgkmcnt(9)
	v_mfma_f32_32x32x16_bf16 v[18:33], v[176:179], v[212:215], v[18:33]
	s_waitcnt vmcnt(14)
	ds_write_b128 v0, v[126:129] offset:23040
	s_waitcnt lgkmcnt(9)
	v_mfma_f32_32x32x16_bf16 v[50:65], v[176:179], v[220:223], v[50:65]
	s_waitcnt vmcnt(13)
	ds_write_b128 v0, v[134:137] offset:27648
	v_mfma_f32_32x32x16_bf16 v[2:17], v[184:187], v[212:215], v[2:17]
	s_waitcnt vmcnt(12)
	ds_write_b128 v0, v[146:149] offset:32256
	v_mfma_f32_32x32x16_bf16 v[34:49], v[184:187], v[220:223], v[34:49]
	ds_read_b128 v[176:179], v173 offset:36960
	ds_read_b128 v[184:187], v173 offset:41568
	ds_read_b128 v[212:215], v174 offset:55392
	ds_read_b128 v[220:223], v174 offset:60000
	s_waitcnt lgkmcnt(8)
	v_mfma_f32_32x32x16_bf16 v[18:33], v[82:85], v[188:191], v[18:33]
	global_load_dwordx4 v[122:125], v[150:151], off offset:768
	global_load_dwordx4 v[126:129], v[152:153], off offset:768
	s_waitcnt lgkmcnt(7)
	v_mfma_f32_32x32x16_bf16 v[50:65], v[82:85], v[216:219], v[50:65]
	global_load_dwordx4 v[134:137], v[154:155], off offset:768
	global_load_dwordx4 v[146:149], v[156:157], off offset:768
	v_mfma_f32_32x32x16_bf16 v[2:17], v[180:183], v[188:191], v[2:17]
	global_load_dwordx4 v[66:69], v[158:159], off offset:896
	global_load_dwordx4 v[70:73], v[160:161], off offset:896
	v_mfma_f32_32x32x16_bf16 v[34:49], v[180:183], v[216:219], v[34:49]
	global_load_dwordx4 v[74:77], v[162:163], off offset:896
	global_load_dwordx4 v[118:121], v[164:165], off offset:896
	s_waitcnt lgkmcnt(1)
	v_mfma_f32_32x32x16_bf16 v[18:33], v[176:179], v[212:215], v[18:33]
	s_waitcnt lgkmcnt(0)
	v_mfma_f32_32x32x16_bf16 v[50:65], v[176:179], v[220:223], v[50:65]
	v_mfma_f32_32x32x16_bf16 v[2:17], v[184:187], v[212:215], v[2:17]
	v_mfma_f32_32x32x16_bf16 v[34:49], v[184:187], v[220:223], v[34:49]
	s_waitcnt lgkmcnt(0)
	s_setprio 0
	s_barrier
	s_setprio 2
	s_waitcnt vmcnt(17)
	ds_write_b128 v0, v[106:109] offset:46080
	ds_read_b128 v[106:109], v173
	ds_read_b128 v[180:183], v173 offset:4608
	ds_read_b128 v[188:191], v174 offset:18432
	ds_read_b128 v[216:219], v174 offset:23040
	ds_read_b128 v[176:179], v173 offset:32
	ds_read_b128 v[184:187], v173 offset:4640
	ds_read_b128 v[212:215], v174 offset:18464
	ds_read_b128 v[220:223], v174 offset:23072
	s_waitcnt lgkmcnt(5)
	v_mfma_f32_32x32x16_bf16 v[18:33], v[106:109], v[188:191], v[18:33]
	s_waitcnt vmcnt(19)
	ds_write_b128 v0, v[98:101] offset:36864
	s_waitcnt lgkmcnt(5)
	v_mfma_f32_32x32x16_bf16 v[50:65], v[106:109], v[216:219], v[50:65]
	s_waitcnt vmcnt(18)
	ds_write_b128 v0, v[102:105] offset:41472
	v_mfma_f32_32x32x16_bf16 v[2:17], v[180:183], v[188:191], v[2:17]
	s_waitcnt vmcnt(16)
	ds_write_b128 v0, v[110:113] offset:50688
	v_mfma_f32_32x32x16_bf16 v[34:49], v[180:183], v[216:219], v[34:49]
	s_waitcnt vmcnt(15)
	ds_write_b128 v0, v[94:97] offset:55296
	ds_read_b128 v[106:109], v173 offset:64
	ds_read_b128 v[180:183], v173 offset:4672
	ds_read_b128 v[188:191], v174 offset:18496
	ds_read_b128 v[216:219], v174 offset:23104
	s_waitcnt lgkmcnt(9)
	v_mfma_f32_32x32x16_bf16 v[18:33], v[176:179], v[212:215], v[18:33]
	s_waitcnt vmcnt(14)
	ds_write_b128 v0, v[130:133] offset:59904
	s_waitcnt lgkmcnt(9)
	v_mfma_f32_32x32x16_bf16 v[50:65], v[176:179], v[220:223], v[50:65]
	s_waitcnt vmcnt(13)
	ds_write_b128 v0, v[138:141] offset:64512
	v_mfma_f32_32x32x16_bf16 v[2:17], v[184:187], v[212:215], v[2:17]
	s_waitcnt vmcnt(12)
	ds_write_b128 v175, v[142:145] offset:13824
	v_mfma_f32_32x32x16_bf16 v[34:49], v[184:187], v[220:223], v[34:49]
	ds_read_b128 v[176:179], v173 offset:96
	ds_read_b128 v[184:187], v173 offset:4704
	ds_read_b128 v[212:215], v174 offset:18528
	ds_read_b128 v[220:223], v174 offset:23136
	s_waitcnt lgkmcnt(8)
	v_mfma_f32_32x32x16_bf16 v[18:33], v[106:109], v[188:191], v[18:33]
	global_load_dwordx4 v[110:113], v[150:151], off offset:896
	global_load_dwordx4 v[130:133], v[152:153], off offset:896
	s_waitcnt lgkmcnt(7)
	v_mfma_f32_32x32x16_bf16 v[50:65], v[106:109], v[216:219], v[50:65]
	global_load_dwordx4 v[138:141], v[154:155], off offset:896
	global_load_dwordx4 v[142:145], v[156:157], off offset:896
	v_mfma_f32_32x32x16_bf16 v[2:17], v[180:183], v[188:191], v[2:17]
	global_load_dwordx4 v[82:85], v[158:159], off offset:1024
	global_load_dwordx4 v[94:97], v[160:161], off offset:1024
	v_mfma_f32_32x32x16_bf16 v[34:49], v[180:183], v[216:219], v[34:49]
	global_load_dwordx4 v[98:101], v[162:163], off offset:1024
	global_load_dwordx4 v[102:105], v[164:165], off offset:1024
	s_waitcnt lgkmcnt(1)
	v_mfma_f32_32x32x16_bf16 v[18:33], v[176:179], v[212:215], v[18:33]
	s_waitcnt lgkmcnt(0)
	v_mfma_f32_32x32x16_bf16 v[50:65], v[176:179], v[220:223], v[50:65]
	v_mfma_f32_32x32x16_bf16 v[2:17], v[184:187], v[212:215], v[2:17]
	v_mfma_f32_32x32x16_bf16 v[34:49], v[184:187], v[220:223], v[34:49]
	s_waitcnt lgkmcnt(0)
	s_setprio 0
	s_barrier
	s_setprio 2
	s_waitcnt vmcnt(14)
	ds_write_b128 v0, v[126:129] offset:23040
	ds_read_b128 v[126:129], v173 offset:36864
	ds_read_b128 v[180:183], v173 offset:41472
	ds_read_b128 v[188:191], v174 offset:55296
	ds_read_b128 v[216:219], v174 offset:59904
	ds_read_b128 v[176:179], v173 offset:36896
	ds_read_b128 v[184:187], v173 offset:41504
	ds_read_b128 v[212:215], v174 offset:55328
	ds_read_b128 v[220:223], v174 offset:59936
	s_waitcnt lgkmcnt(5)
	v_mfma_f32_32x32x16_bf16 v[18:33], v[126:129], v[188:191], v[18:33]
	s_waitcnt vmcnt(19)
	ds_write_b128 v0, v[78:81]
	s_waitcnt lgkmcnt(5)
	v_mfma_f32_32x32x16_bf16 v[50:65], v[126:129], v[216:219], v[50:65]
	s_waitcnt vmcnt(18)
	ds_write_b128 v0, v[86:89] offset:4608
	v_mfma_f32_32x32x16_bf16 v[2:17], v[180:183], v[188:191], v[2:17]
	s_waitcnt vmcnt(17)
	ds_write_b128 v0, v[90:93] offset:9216
	v_mfma_f32_32x32x16_bf16 v[34:49], v[180:183], v[216:219], v[34:49]
	s_waitcnt vmcnt(16)
	ds_write_b128 v0, v[114:117] offset:13824
	ds_read_b128 v[126:129], v173 offset:36928
	ds_read_b128 v[180:183], v173 offset:41536
	ds_read_b128 v[188:191], v174 offset:55360
	ds_read_b128 v[216:219], v174 offset:59968
	s_waitcnt lgkmcnt(9)
	v_mfma_f32_32x32x16_bf16 v[18:33], v[176:179], v[212:215], v[18:33]
	s_waitcnt vmcnt(15)
	ds_write_b128 v0, v[122:125] offset:18432
	s_waitcnt lgkmcnt(9)
	v_mfma_f32_32x32x16_bf16 v[50:65], v[176:179], v[220:223], v[50:65]
	s_waitcnt vmcnt(13)
	ds_write_b128 v0, v[134:137] offset:27648
	v_mfma_f32_32x32x16_bf16 v[2:17], v[184:187], v[212:215], v[2:17]
	s_waitcnt vmcnt(12)
	ds_write_b128 v0, v[146:149] offset:32256
	v_mfma_f32_32x32x16_bf16 v[34:49], v[184:187], v[220:223], v[34:49]
	ds_read_b128 v[176:179], v173 offset:36960
	ds_read_b128 v[184:187], v173 offset:41568
	ds_read_b128 v[212:215], v174 offset:55392
	ds_read_b128 v[220:223], v174 offset:60000
	s_waitcnt lgkmcnt(8)
	v_mfma_f32_32x32x16_bf16 v[18:33], v[126:129], v[188:191], v[18:33]
	global_load_dwordx4 v[114:117], v[150:151], off offset:1024
	global_load_dwordx4 v[122:125], v[152:153], off offset:1024
	s_waitcnt lgkmcnt(7)
	v_mfma_f32_32x32x16_bf16 v[50:65], v[126:129], v[216:219], v[50:65]
	global_load_dwordx4 v[134:137], v[154:155], off offset:1024
	global_load_dwordx4 v[146:149], v[156:157], off offset:1024
	v_mfma_f32_32x32x16_bf16 v[2:17], v[180:183], v[188:191], v[2:17]
	global_load_dwordx4 v[78:81], v[158:159], off offset:1152
	global_load_dwordx4 v[86:89], v[160:161], off offset:1152
	v_mfma_f32_32x32x16_bf16 v[34:49], v[180:183], v[216:219], v[34:49]
	global_load_dwordx4 v[90:93], v[162:163], off offset:1152
	global_load_dwordx4 v[106:109], v[164:165], off offset:1152
	s_waitcnt lgkmcnt(1)
	v_mfma_f32_32x32x16_bf16 v[18:33], v[176:179], v[212:215], v[18:33]
	s_waitcnt lgkmcnt(0)
	v_mfma_f32_32x32x16_bf16 v[50:65], v[176:179], v[220:223], v[50:65]
	v_mfma_f32_32x32x16_bf16 v[2:17], v[184:187], v[212:215], v[2:17]
	v_mfma_f32_32x32x16_bf16 v[34:49], v[184:187], v[220:223], v[34:49]
	s_waitcnt lgkmcnt(0)
	s_setprio 0
	s_barrier
	s_setprio 2
	s_waitcnt vmcnt(12)
	ds_write_b128 v175, v[142:145] offset:13824
	ds_read_b128 v[142:145], v173
	ds_read_b128 v[180:183], v173 offset:4608
	ds_read_b128 v[188:191], v174 offset:18432
	ds_read_b128 v[216:219], v174 offset:23040
	ds_read_b128 v[176:179], v173 offset:32
	ds_read_b128 v[184:187], v173 offset:4640
	ds_read_b128 v[212:215], v174 offset:18464
	ds_read_b128 v[220:223], v174 offset:23072
	s_waitcnt lgkmcnt(5)
	v_mfma_f32_32x32x16_bf16 v[18:33], v[142:145], v[188:191], v[18:33]
	s_waitcnt vmcnt(19)
	ds_write_b128 v0, v[66:69] offset:36864
	s_waitcnt lgkmcnt(5)
	v_mfma_f32_32x32x16_bf16 v[50:65], v[142:145], v[216:219], v[50:65]
	s_waitcnt vmcnt(18)
	ds_write_b128 v0, v[70:73] offset:41472
	v_mfma_f32_32x32x16_bf16 v[2:17], v[180:183], v[188:191], v[2:17]
	s_waitcnt vmcnt(17)
	ds_write_b128 v0, v[74:77] offset:46080
	v_mfma_f32_32x32x16_bf16 v[34:49], v[180:183], v[216:219], v[34:49]
	s_waitcnt vmcnt(16)
	ds_write_b128 v0, v[118:121] offset:50688
	ds_read_b128 v[142:145], v173 offset:64
	ds_read_b128 v[180:183], v173 offset:4672
	ds_read_b128 v[188:191], v174 offset:18496
	ds_read_b128 v[216:219], v174 offset:23104
	s_waitcnt lgkmcnt(9)
	v_mfma_f32_32x32x16_bf16 v[18:33], v[176:179], v[212:215], v[18:33]
	s_waitcnt vmcnt(15)
	ds_write_b128 v0, v[110:113] offset:55296
	s_waitcnt lgkmcnt(9)
	v_mfma_f32_32x32x16_bf16 v[50:65], v[176:179], v[220:223], v[50:65]
	s_waitcnt vmcnt(14)
	ds_write_b128 v0, v[130:133] offset:59904
	v_mfma_f32_32x32x16_bf16 v[2:17], v[184:187], v[212:215], v[2:17]
	s_waitcnt vmcnt(13)
	ds_write_b128 v0, v[138:141] offset:64512
	v_mfma_f32_32x32x16_bf16 v[34:49], v[184:187], v[220:223], v[34:49]
	ds_read_b128 v[176:179], v173 offset:96
	ds_read_b128 v[184:187], v173 offset:4704
	ds_read_b128 v[212:215], v174 offset:18528
	ds_read_b128 v[220:223], v174 offset:23136
	s_waitcnt lgkmcnt(8)
	v_mfma_f32_32x32x16_bf16 v[18:33], v[142:145], v[188:191], v[18:33]
	global_load_dwordx4 v[118:121], v[150:151], off offset:1152
	global_load_dwordx4 v[126:129], v[152:153], off offset:1152
	s_waitcnt lgkmcnt(7)
	v_mfma_f32_32x32x16_bf16 v[50:65], v[142:145], v[216:219], v[50:65]
	global_load_dwordx4 v[130:133], v[154:155], off offset:1152
	global_load_dwordx4 v[138:141], v[156:157], off offset:1152
	v_mfma_f32_32x32x16_bf16 v[2:17], v[180:183], v[188:191], v[2:17]
	global_load_dwordx4 v[66:69], v[158:159], off offset:1280
	global_load_dwordx4 v[70:73], v[160:161], off offset:1280
	v_mfma_f32_32x32x16_bf16 v[34:49], v[180:183], v[216:219], v[34:49]
	global_load_dwordx4 v[74:77], v[162:163], off offset:1280
	global_load_dwordx4 v[110:113], v[164:165], off offset:1280
	s_waitcnt lgkmcnt(1)
	v_mfma_f32_32x32x16_bf16 v[18:33], v[176:179], v[212:215], v[18:33]
	s_waitcnt lgkmcnt(0)
	v_mfma_f32_32x32x16_bf16 v[50:65], v[176:179], v[220:223], v[50:65]
	v_mfma_f32_32x32x16_bf16 v[2:17], v[184:187], v[212:215], v[2:17]
	v_mfma_f32_32x32x16_bf16 v[34:49], v[184:187], v[220:223], v[34:49]
	s_waitcnt lgkmcnt(0)
	s_setprio 0
	s_barrier
	s_setprio 2
	s_waitcnt vmcnt(12)
	ds_write_b128 v0, v[146:149] offset:32256
	ds_read_b128 v[146:149], v173 offset:36864
	ds_read_b128 v[180:183], v173 offset:41472
	ds_read_b128 v[188:191], v174 offset:55296
	ds_read_b128 v[216:219], v174 offset:59904
	ds_read_b128 v[176:179], v173 offset:36896
	ds_read_b128 v[184:187], v173 offset:41504
	ds_read_b128 v[212:215], v174 offset:55328
	ds_read_b128 v[220:223], v174 offset:59936
	s_waitcnt lgkmcnt(5)
	v_mfma_f32_32x32x16_bf16 v[18:33], v[146:149], v[188:191], v[18:33]
	s_waitcnt vmcnt(19)
	ds_write_b128 v0, v[82:85]
	s_waitcnt lgkmcnt(5)
	v_mfma_f32_32x32x16_bf16 v[50:65], v[146:149], v[216:219], v[50:65]
	s_waitcnt vmcnt(18)
	ds_write_b128 v0, v[94:97] offset:4608
	v_mfma_f32_32x32x16_bf16 v[2:17], v[180:183], v[188:191], v[2:17]
	s_waitcnt vmcnt(17)
	ds_write_b128 v0, v[98:101] offset:9216
	v_mfma_f32_32x32x16_bf16 v[34:49], v[180:183], v[216:219], v[34:49]
	s_waitcnt vmcnt(16)
	ds_write_b128 v0, v[102:105] offset:13824
	ds_read_b128 v[146:149], v173 offset:36928
	ds_read_b128 v[180:183], v173 offset:41536
	ds_read_b128 v[188:191], v174 offset:55360
	ds_read_b128 v[216:219], v174 offset:59968
	s_waitcnt lgkmcnt(9)
	v_mfma_f32_32x32x16_bf16 v[18:33], v[176:179], v[212:215], v[18:33]
	s_waitcnt vmcnt(15)
	ds_write_b128 v0, v[114:117] offset:18432
	s_waitcnt lgkmcnt(9)
	v_mfma_f32_32x32x16_bf16 v[50:65], v[176:179], v[220:223], v[50:65]
	s_waitcnt vmcnt(14)
	ds_write_b128 v0, v[122:125] offset:23040
	v_mfma_f32_32x32x16_bf16 v[2:17], v[184:187], v[212:215], v[2:17]
	s_waitcnt vmcnt(13)
	ds_write_b128 v0, v[134:137] offset:27648
	v_mfma_f32_32x32x16_bf16 v[34:49], v[184:187], v[220:223], v[34:49]
	ds_read_b128 v[176:179], v173 offset:36960
	ds_read_b128 v[184:187], v173 offset:41568
	ds_read_b128 v[212:215], v174 offset:55392
	ds_read_b128 v[220:223], v174 offset:60000
	s_waitcnt lgkmcnt(8)
	v_mfma_f32_32x32x16_bf16 v[18:33], v[146:149], v[188:191], v[18:33]
	global_load_dwordx4 v[114:117], v[150:151], off offset:1280
	global_load_dwordx4 v[122:125], v[152:153], off offset:1280
	s_waitcnt lgkmcnt(7)
	v_mfma_f32_32x32x16_bf16 v[50:65], v[146:149], v[216:219], v[50:65]
	global_load_dwordx4 v[134:137], v[154:155], off offset:1280
	global_load_dwordx4 v[142:145], v[156:157], off offset:1280
	v_mfma_f32_32x32x16_bf16 v[2:17], v[180:183], v[188:191], v[2:17]
	global_load_dwordx4 v[82:85], v[158:159], off offset:1408
	global_load_dwordx4 v[94:97], v[160:161], off offset:1408
	v_mfma_f32_32x32x16_bf16 v[34:49], v[180:183], v[216:219], v[34:49]
	global_load_dwordx4 v[98:101], v[162:163], off offset:1408
	global_load_dwordx4 v[102:105], v[164:165], off offset:1408
	s_waitcnt lgkmcnt(1)
	v_mfma_f32_32x32x16_bf16 v[18:33], v[176:179], v[212:215], v[18:33]
	s_waitcnt lgkmcnt(0)
	v_mfma_f32_32x32x16_bf16 v[50:65], v[176:179], v[220:223], v[50:65]
	v_mfma_f32_32x32x16_bf16 v[2:17], v[184:187], v[212:215], v[2:17]
	v_mfma_f32_32x32x16_bf16 v[34:49], v[184:187], v[220:223], v[34:49]
	s_waitcnt lgkmcnt(0)
	s_setprio 0
	s_barrier
	s_setprio 2
	ds_read_b128 v[146:149], v173
	ds_read_b128 v[180:183], v173 offset:4608
	ds_read_b128 v[188:191], v174 offset:18432
	ds_read_b128 v[216:219], v174 offset:23040
	ds_read_b128 v[176:179], v173 offset:32
	ds_read_b128 v[184:187], v173 offset:4640
	ds_read_b128 v[212:215], v174 offset:18464
	ds_read_b128 v[220:223], v174 offset:23072
	s_waitcnt lgkmcnt(5)
	v_mfma_f32_32x32x16_bf16 v[18:33], v[146:149], v[188:191], v[18:33]
	s_waitcnt vmcnt(19)
	ds_write_b128 v0, v[78:81] offset:36864
	s_waitcnt lgkmcnt(5)
	v_mfma_f32_32x32x16_bf16 v[50:65], v[146:149], v[216:219], v[50:65]
	s_waitcnt vmcnt(18)
	ds_write_b128 v0, v[86:89] offset:41472
	v_mfma_f32_32x32x16_bf16 v[2:17], v[180:183], v[188:191], v[2:17]
	s_waitcnt vmcnt(17)
	ds_write_b128 v0, v[90:93] offset:46080
	v_mfma_f32_32x32x16_bf16 v[34:49], v[180:183], v[216:219], v[34:49]
	s_waitcnt vmcnt(16)
	ds_write_b128 v0, v[106:109] offset:50688
	ds_read_b128 v[146:149], v173 offset:64
	ds_read_b128 v[180:183], v173 offset:4672
	ds_read_b128 v[188:191], v174 offset:18496
	ds_read_b128 v[216:219], v174 offset:23104
	s_waitcnt lgkmcnt(9)
	v_mfma_f32_32x32x16_bf16 v[18:33], v[176:179], v[212:215], v[18:33]
	s_waitcnt vmcnt(15)
	ds_write_b128 v0, v[118:121] offset:55296
	s_waitcnt lgkmcnt(9)
	v_mfma_f32_32x32x16_bf16 v[50:65], v[176:179], v[220:223], v[50:65]
	s_waitcnt vmcnt(14)
	ds_write_b128 v0, v[126:129] offset:59904
	v_mfma_f32_32x32x16_bf16 v[2:17], v[184:187], v[212:215], v[2:17]
	s_waitcnt vmcnt(13)
	ds_write_b128 v0, v[130:133] offset:64512
	v_mfma_f32_32x32x16_bf16 v[34:49], v[184:187], v[220:223], v[34:49]
	s_waitcnt vmcnt(12)
	ds_write_b128 v175, v[138:141] offset:13824
	ds_read_b128 v[176:179], v173 offset:96
	ds_read_b128 v[184:187], v173 offset:4704
	ds_read_b128 v[212:215], v174 offset:18528
	ds_read_b128 v[220:223], v174 offset:23136
	s_waitcnt lgkmcnt(9)
	v_mfma_f32_32x32x16_bf16 v[18:33], v[146:149], v[188:191], v[18:33]
	global_load_dwordx4 v[118:121], v[150:151], off offset:1408
	global_load_dwordx4 v[126:129], v[152:153], off offset:1408
	s_waitcnt lgkmcnt(8)
	v_mfma_f32_32x32x16_bf16 v[50:65], v[146:149], v[216:219], v[50:65]
	global_load_dwordx4 v[130:133], v[154:155], off offset:1408
	global_load_dwordx4 v[138:141], v[156:157], off offset:1408
	v_mfma_f32_32x32x16_bf16 v[2:17], v[180:183], v[188:191], v[2:17]
	global_load_dwordx4 v[78:81], v[158:159], off offset:1536
	global_load_dwordx4 v[86:89], v[160:161], off offset:1536
	v_mfma_f32_32x32x16_bf16 v[34:49], v[180:183], v[216:219], v[34:49]
	global_load_dwordx4 v[90:93], v[162:163], off offset:1536
	global_load_dwordx4 v[106:109], v[164:165], off offset:1536
	s_waitcnt lgkmcnt(1)
	v_mfma_f32_32x32x16_bf16 v[18:33], v[176:179], v[212:215], v[18:33]
	s_waitcnt lgkmcnt(0)
	v_mfma_f32_32x32x16_bf16 v[50:65], v[176:179], v[220:223], v[50:65]
	v_mfma_f32_32x32x16_bf16 v[2:17], v[184:187], v[212:215], v[2:17]
	v_mfma_f32_32x32x16_bf16 v[34:49], v[184:187], v[220:223], v[34:49]
	s_waitcnt lgkmcnt(0)
	s_setprio 0
	s_barrier
	s_setprio 2
	ds_read_b128 v[146:149], v173 offset:36864
	ds_read_b128 v[180:183], v173 offset:41472
	ds_read_b128 v[188:191], v174 offset:55296
	ds_read_b128 v[216:219], v174 offset:59904
	ds_read_b128 v[176:179], v173 offset:36896
	ds_read_b128 v[184:187], v173 offset:41504
	ds_read_b128 v[212:215], v174 offset:55328
	ds_read_b128 v[220:223], v174 offset:59936
	s_waitcnt lgkmcnt(5)
	v_mfma_f32_32x32x16_bf16 v[18:33], v[146:149], v[188:191], v[18:33]
	s_waitcnt vmcnt(19)
	ds_write_b128 v0, v[66:69]
	s_waitcnt lgkmcnt(5)
	v_mfma_f32_32x32x16_bf16 v[50:65], v[146:149], v[216:219], v[50:65]
	s_waitcnt vmcnt(18)
	ds_write_b128 v0, v[70:73] offset:4608
	v_mfma_f32_32x32x16_bf16 v[2:17], v[180:183], v[188:191], v[2:17]
	s_waitcnt vmcnt(17)
	ds_write_b128 v0, v[74:77] offset:9216
	v_mfma_f32_32x32x16_bf16 v[34:49], v[180:183], v[216:219], v[34:49]
	s_waitcnt vmcnt(16)
	ds_write_b128 v0, v[110:113] offset:13824
	ds_read_b128 v[146:149], v173 offset:36928
	ds_read_b128 v[180:183], v173 offset:41536
	ds_read_b128 v[188:191], v174 offset:55360
	ds_read_b128 v[216:219], v174 offset:59968
	s_waitcnt lgkmcnt(9)
	v_mfma_f32_32x32x16_bf16 v[18:33], v[176:179], v[212:215], v[18:33]
	s_waitcnt vmcnt(15)
	ds_write_b128 v0, v[114:117] offset:18432
	s_waitcnt lgkmcnt(9)
	v_mfma_f32_32x32x16_bf16 v[50:65], v[176:179], v[220:223], v[50:65]
	s_waitcnt vmcnt(14)
	ds_write_b128 v0, v[122:125] offset:23040
	v_mfma_f32_32x32x16_bf16 v[2:17], v[184:187], v[212:215], v[2:17]
	s_waitcnt vmcnt(13)
	ds_write_b128 v0, v[134:137] offset:27648
	v_mfma_f32_32x32x16_bf16 v[34:49], v[184:187], v[220:223], v[34:49]
	s_waitcnt vmcnt(12)
	ds_write_b128 v0, v[142:145] offset:32256
	ds_read_b128 v[176:179], v173 offset:36960
	ds_read_b128 v[184:187], v173 offset:41568
	ds_read_b128 v[212:215], v174 offset:55392
	ds_read_b128 v[220:223], v174 offset:60000
	s_waitcnt lgkmcnt(9)
	v_mfma_f32_32x32x16_bf16 v[18:33], v[146:149], v[188:191], v[18:33]
	global_load_dwordx4 v[114:117], v[150:151], off offset:1536
	global_load_dwordx4 v[122:125], v[152:153], off offset:1536
	s_waitcnt lgkmcnt(8)
	v_mfma_f32_32x32x16_bf16 v[50:65], v[146:149], v[216:219], v[50:65]
	global_load_dwordx4 v[134:137], v[154:155], off offset:1536
	global_load_dwordx4 v[142:145], v[156:157], off offset:1536
	v_mfma_f32_32x32x16_bf16 v[2:17], v[180:183], v[188:191], v[2:17]
	global_load_dwordx4 v[66:69], v[158:159], off offset:1664
	global_load_dwordx4 v[70:73], v[160:161], off offset:1664
	v_mfma_f32_32x32x16_bf16 v[34:49], v[180:183], v[216:219], v[34:49]
	global_load_dwordx4 v[74:77], v[162:163], off offset:1664
	global_load_dwordx4 v[110:113], v[164:165], off offset:1664
	s_waitcnt lgkmcnt(1)
	v_mfma_f32_32x32x16_bf16 v[18:33], v[176:179], v[212:215], v[18:33]
	s_waitcnt lgkmcnt(0)
	v_mfma_f32_32x32x16_bf16 v[50:65], v[176:179], v[220:223], v[50:65]
	v_mfma_f32_32x32x16_bf16 v[2:17], v[184:187], v[212:215], v[2:17]
	v_mfma_f32_32x32x16_bf16 v[34:49], v[184:187], v[220:223], v[34:49]
	s_waitcnt lgkmcnt(0)
	s_setprio 0
	s_barrier
	s_setprio 2
	ds_read_b128 v[146:149], v173
	ds_read_b128 v[180:183], v173 offset:4608
	ds_read_b128 v[188:191], v174 offset:18432
	ds_read_b128 v[216:219], v174 offset:23040
	ds_read_b128 v[176:179], v173 offset:32
	ds_read_b128 v[184:187], v173 offset:4640
	ds_read_b128 v[212:215], v174 offset:18464
	ds_read_b128 v[220:223], v174 offset:23072
	s_waitcnt lgkmcnt(5)
	v_mfma_f32_32x32x16_bf16 v[18:33], v[146:149], v[188:191], v[18:33]
	s_waitcnt vmcnt(19)
	ds_write_b128 v0, v[82:85] offset:36864
	s_waitcnt lgkmcnt(5)
	v_mfma_f32_32x32x16_bf16 v[50:65], v[146:149], v[216:219], v[50:65]
	s_waitcnt vmcnt(18)
	ds_write_b128 v0, v[94:97] offset:41472
	v_mfma_f32_32x32x16_bf16 v[2:17], v[180:183], v[188:191], v[2:17]
	s_waitcnt vmcnt(17)
	ds_write_b128 v0, v[98:101] offset:46080
	v_mfma_f32_32x32x16_bf16 v[34:49], v[180:183], v[216:219], v[34:49]
	s_waitcnt vmcnt(16)
	ds_write_b128 v0, v[102:105] offset:50688
	ds_read_b128 v[146:149], v173 offset:64
	ds_read_b128 v[180:183], v173 offset:4672
	ds_read_b128 v[188:191], v174 offset:18496
	ds_read_b128 v[216:219], v174 offset:23104
	s_waitcnt lgkmcnt(9)
	v_mfma_f32_32x32x16_bf16 v[18:33], v[176:179], v[212:215], v[18:33]
	s_waitcnt vmcnt(15)
	ds_write_b128 v0, v[118:121] offset:55296
	s_waitcnt lgkmcnt(9)
	v_mfma_f32_32x32x16_bf16 v[50:65], v[176:179], v[220:223], v[50:65]
	s_waitcnt vmcnt(14)
	ds_write_b128 v0, v[126:129] offset:59904
	v_mfma_f32_32x32x16_bf16 v[2:17], v[184:187], v[212:215], v[2:17]
	s_waitcnt vmcnt(13)
	ds_write_b128 v0, v[130:133] offset:64512
	v_mfma_f32_32x32x16_bf16 v[34:49], v[184:187], v[220:223], v[34:49]
	s_waitcnt vmcnt(12)
	ds_write_b128 v175, v[138:141] offset:13824
	ds_read_b128 v[176:179], v173 offset:96
	ds_read_b128 v[184:187], v173 offset:4704
	ds_read_b128 v[212:215], v174 offset:18528
	ds_read_b128 v[220:223], v174 offset:23136
	s_waitcnt lgkmcnt(9)
	v_mfma_f32_32x32x16_bf16 v[18:33], v[146:149], v[188:191], v[18:33]
	global_load_dwordx4 v[118:121], v[150:151], off offset:1664
	global_load_dwordx4 v[126:129], v[152:153], off offset:1664
	s_waitcnt lgkmcnt(8)
	v_mfma_f32_32x32x16_bf16 v[50:65], v[146:149], v[216:219], v[50:65]
	global_load_dwordx4 v[130:133], v[154:155], off offset:1664
	global_load_dwordx4 v[138:141], v[156:157], off offset:1664
	v_mfma_f32_32x32x16_bf16 v[2:17], v[180:183], v[188:191], v[2:17]
	global_load_dwordx4 v[82:85], v[158:159], off offset:1792
	global_load_dwordx4 v[94:97], v[160:161], off offset:1792
	v_mfma_f32_32x32x16_bf16 v[34:49], v[180:183], v[216:219], v[34:49]
	global_load_dwordx4 v[98:101], v[162:163], off offset:1792
	global_load_dwordx4 v[102:105], v[164:165], off offset:1792
	s_waitcnt lgkmcnt(1)
	v_mfma_f32_32x32x16_bf16 v[18:33], v[176:179], v[212:215], v[18:33]
	s_waitcnt lgkmcnt(0)
	v_mfma_f32_32x32x16_bf16 v[50:65], v[176:179], v[220:223], v[50:65]
	v_mfma_f32_32x32x16_bf16 v[2:17], v[184:187], v[212:215], v[2:17]
	v_mfma_f32_32x32x16_bf16 v[34:49], v[184:187], v[220:223], v[34:49]
	s_waitcnt lgkmcnt(0)
	s_setprio 0
	s_barrier
	s_waitcnt vmcnt(19)
	ds_write_b128 v0, v[78:81]
	s_waitcnt vmcnt(18)
	ds_write_b128 v0, v[86:89] offset:4608
	s_waitcnt vmcnt(17)
	ds_write_b128 v0, v[90:93] offset:9216
	s_waitcnt vmcnt(16)
	ds_write_b128 v0, v[106:109] offset:13824
	s_waitcnt vmcnt(15)
	ds_write_b128 v0, v[114:117] offset:18432
	s_waitcnt vmcnt(14)
	ds_write_b128 v0, v[122:125] offset:23040
	s_waitcnt vmcnt(13)
	ds_write_b128 v0, v[134:137] offset:27648
	s_waitcnt vmcnt(12)
	ds_write_b128 v0, v[142:145] offset:32256
	global_load_dwordx4 v[114:117], v[150:151], off offset:1792
	global_load_dwordx4 v[122:125], v[152:153], off offset:1792
	global_load_dwordx4 v[134:137], v[154:155], off offset:1792
	global_load_dwordx4 v[142:145], v[156:157], off offset:1792
	global_load_dwordx4 v[78:81], v[158:159], off offset:1920
	global_load_dwordx4 v[86:89], v[160:161], off offset:1920
	global_load_dwordx4 v[90:93], v[162:163], off offset:1920
	global_load_dwordx4 v[106:109], v[164:165], off offset:1920
	s_setprio 2
	ds_read_b128 v[146:149], v173 offset:36864
	ds_read_b128 v[158:161], v173 offset:36896
	ds_read_b128 v[162:165], v173 offset:41472
	ds_read_b128 v[176:179], v173 offset:41504
	ds_read_b128 v[180:183], v174 offset:55296
	ds_read_b128 v[184:187], v174 offset:55328
	ds_read_b128 v[188:191], v174 offset:59904
	ds_read_b128 v[212:215], v174 offset:59936
	s_waitcnt lgkmcnt(3)
	v_mfma_f32_32x32x16_bf16 v[18:33], v[146:149], v[180:183], v[18:33]
	s_waitcnt lgkmcnt(1)
	v_mfma_f32_32x32x16_bf16 v[50:65], v[146:149], v[188:191], v[50:65]
	v_mfma_f32_32x32x16_bf16 v[2:17], v[162:165], v[180:183], v[2:17]
	v_mfma_f32_32x32x16_bf16 v[34:49], v[162:165], v[188:191], v[34:49]
	ds_read_b128 v[146:149], v173 offset:36928
	ds_read_b128 v[162:165], v173 offset:41536
	ds_read_b128 v[180:183], v174 offset:55360
	ds_read_b128 v[188:191], v174 offset:59968
	v_mfma_f32_32x32x16_bf16 v[18:33], v[158:161], v[184:187], v[18:33]
	s_waitcnt lgkmcnt(4)
	v_mfma_f32_32x32x16_bf16 v[50:65], v[158:161], v[212:215], v[50:65]
	v_mfma_f32_32x32x16_bf16 v[2:17], v[176:179], v[184:187], v[2:17]
	v_mfma_f32_32x32x16_bf16 v[34:49], v[176:179], v[212:215], v[34:49]
	ds_read_b128 v[158:161], v173 offset:36960
	ds_read_b128 v[176:179], v173 offset:41568
	ds_read_b128 v[184:187], v174 offset:55392
	ds_read_b128 v[212:215], v174 offset:60000
	s_waitcnt lgkmcnt(5)
	v_mfma_f32_32x32x16_bf16 v[18:33], v[146:149], v[180:183], v[18:33]
	s_waitcnt lgkmcnt(4)
	v_mfma_f32_32x32x16_bf16 v[50:65], v[146:149], v[188:191], v[50:65]
	v_mfma_f32_32x32x16_bf16 v[2:17], v[162:165], v[180:183], v[2:17]
	v_mfma_f32_32x32x16_bf16 v[34:49], v[162:165], v[188:191], v[34:49]
	s_waitcnt lgkmcnt(1)
	v_mfma_f32_32x32x16_bf16 v[18:33], v[158:161], v[184:187], v[18:33]
	s_waitcnt lgkmcnt(0)
	v_mfma_f32_32x32x16_bf16 v[50:65], v[158:161], v[212:215], v[50:65]
	v_mfma_f32_32x32x16_bf16 v[2:17], v[176:179], v[184:187], v[2:17]
	v_mfma_f32_32x32x16_bf16 v[34:49], v[176:179], v[212:215], v[34:49]
	s_setprio 0
	s_barrier
	s_waitcnt vmcnt(19)
	ds_write_b128 v0, v[66:69] offset:36864
	s_waitcnt vmcnt(18)
	ds_write_b128 v0, v[70:73] offset:41472
	s_waitcnt vmcnt(17)
	ds_write_b128 v0, v[74:77] offset:46080
	s_waitcnt vmcnt(16)
	ds_write_b128 v0, v[110:113] offset:50688
	s_waitcnt vmcnt(15)
	ds_write_b128 v0, v[118:121] offset:55296
	s_waitcnt vmcnt(14)
	ds_write_b128 v0, v[126:129] offset:59904
	s_waitcnt vmcnt(13)
	ds_write_b128 v0, v[130:133] offset:64512
	s_waitcnt vmcnt(12)
	ds_write_b128 v175, v[138:141] offset:13824
	global_load_dwordx4 v[66:69], v[150:151], off offset:1920
	global_load_dwordx4 v[70:73], v[152:153], off offset:1920
	global_load_dwordx4 v[74:77], v[154:155], off offset:1920
	global_load_dwordx4 v[110:113], v[156:157], off offset:1920
	s_setprio 2
	ds_read_b128 v[118:121], v173
	ds_read_b128 v[126:129], v173 offset:32
	ds_read_b128 v[130:133], v173 offset:4608
	ds_read_b128 v[138:141], v173 offset:4640
	ds_read_b128 v[146:149], v174 offset:18432
	ds_read_b128 v[150:153], v174 offset:18464
	ds_read_b128 v[154:157], v174 offset:23040
	ds_read_b128 v[158:161], v174 offset:23072
	s_waitcnt lgkmcnt(3)
	v_mfma_f32_32x32x16_bf16 v[18:33], v[118:121], v[146:149], v[18:33]
	s_waitcnt lgkmcnt(1)
	v_mfma_f32_32x32x16_bf16 v[50:65], v[118:121], v[154:157], v[50:65]
	v_mfma_f32_32x32x16_bf16 v[2:17], v[130:133], v[146:149], v[2:17]
	v_mfma_f32_32x32x16_bf16 v[34:49], v[130:133], v[154:157], v[34:49]
	ds_read_b128 v[118:121], v173 offset:64
	ds_read_b128 v[130:133], v173 offset:4672
	ds_read_b128 v[146:149], v174 offset:18496
	ds_read_b128 v[154:157], v174 offset:23104
	v_mfma_f32_32x32x16_bf16 v[18:33], v[126:129], v[150:153], v[18:33]
	s_waitcnt lgkmcnt(4)
	v_mfma_f32_32x32x16_bf16 v[50:65], v[126:129], v[158:161], v[50:65]
	v_mfma_f32_32x32x16_bf16 v[2:17], v[138:141], v[150:153], v[2:17]
	v_mfma_f32_32x32x16_bf16 v[34:49], v[138:141], v[158:161], v[34:49]
	ds_read_b128 v[126:129], v173 offset:96
	ds_read_b128 v[138:141], v173 offset:4704
	ds_read_b128 v[150:153], v174 offset:18528
	ds_read_b128 v[158:161], v174 offset:23136
	s_waitcnt lgkmcnt(5)
	v_mfma_f32_32x32x16_bf16 v[18:33], v[118:121], v[146:149], v[18:33]
	s_waitcnt lgkmcnt(4)
	v_mfma_f32_32x32x16_bf16 v[50:65], v[118:121], v[154:157], v[50:65]
	v_mfma_f32_32x32x16_bf16 v[2:17], v[130:133], v[146:149], v[2:17]
	v_mfma_f32_32x32x16_bf16 v[34:49], v[130:133], v[154:157], v[34:49]
	s_waitcnt lgkmcnt(1)
	v_mfma_f32_32x32x16_bf16 v[18:33], v[126:129], v[150:153], v[18:33]
	s_waitcnt lgkmcnt(0)
	v_mfma_f32_32x32x16_bf16 v[50:65], v[126:129], v[158:161], v[50:65]
	v_mfma_f32_32x32x16_bf16 v[2:17], v[138:141], v[150:153], v[2:17]
	v_mfma_f32_32x32x16_bf16 v[34:49], v[138:141], v[158:161], v[34:49]
	s_setprio 0
	s_barrier
	s_setprio 2
	s_waitcnt vmcnt(15)
	ds_write_b128 v0, v[82:85]
	s_waitcnt vmcnt(14)
	ds_write_b128 v0, v[94:97] offset:4608
	s_waitcnt vmcnt(13)
	ds_write_b128 v0, v[98:101] offset:9216
	s_waitcnt vmcnt(12)
	ds_write_b128 v0, v[102:105] offset:13824
	s_waitcnt vmcnt(11)
	ds_write_b128 v0, v[114:117] offset:18432
	s_waitcnt vmcnt(10)
	ds_write_b128 v0, v[122:125] offset:23040
	ds_read_b128 v[82:85], v173 offset:36864
	ds_read_b128 v[98:101], v173 offset:41472
	ds_read_b128 v[114:117], v174 offset:55296
	ds_read_b128 v[122:125], v174 offset:59904
	ds_read_b128 v[94:97], v173 offset:36896
	ds_read_b128 v[102:105], v173 offset:41504
	ds_read_b128 v[118:121], v174 offset:55328
	ds_read_b128 v[126:129], v174 offset:59936
	s_waitcnt lgkmcnt(5)
	v_mfma_f32_32x32x16_bf16 v[18:33], v[82:85], v[114:117], v[18:33]
	s_waitcnt vmcnt(9)
	ds_write_b128 v0, v[134:137] offset:27648
	s_waitcnt lgkmcnt(5)
	v_mfma_f32_32x32x16_bf16 v[50:65], v[82:85], v[122:125], v[50:65]
	s_waitcnt vmcnt(8)
	ds_write_b128 v0, v[142:145] offset:32256
	v_mfma_f32_32x32x16_bf16 v[2:17], v[98:101], v[114:117], v[2:17]
	v_mfma_f32_32x32x16_bf16 v[34:49], v[98:101], v[122:125], v[34:49]
	ds_read_b128 v[82:85], v173 offset:36928
	ds_read_b128 v[98:101], v173 offset:41536
	ds_read_b128 v[114:117], v174 offset:55360
	ds_read_b128 v[122:125], v174 offset:59968
	s_waitcnt lgkmcnt(7)
	v_mfma_f32_32x32x16_bf16 v[18:33], v[94:97], v[118:121], v[18:33]
	s_waitcnt lgkmcnt(6)
	v_mfma_f32_32x32x16_bf16 v[50:65], v[94:97], v[126:129], v[50:65]
	v_mfma_f32_32x32x16_bf16 v[2:17], v[102:105], v[118:121], v[2:17]
	v_mfma_f32_32x32x16_bf16 v[34:49], v[102:105], v[126:129], v[34:49]
	ds_read_b128 v[94:97], v173 offset:36960
	ds_read_b128 v[102:105], v173 offset:41568
	ds_read_b128 v[118:121], v174 offset:55392
	ds_read_b128 v[126:129], v174 offset:60000
	s_waitcnt lgkmcnt(5)
	v_mfma_f32_32x32x16_bf16 v[18:33], v[82:85], v[114:117], v[18:33]
	s_waitcnt lgkmcnt(4)
	v_mfma_f32_32x32x16_bf16 v[50:65], v[82:85], v[122:125], v[50:65]
	v_mfma_f32_32x32x16_bf16 v[2:17], v[98:101], v[114:117], v[2:17]
	v_mfma_f32_32x32x16_bf16 v[34:49], v[98:101], v[122:125], v[34:49]
	s_waitcnt lgkmcnt(1)
	v_mfma_f32_32x32x16_bf16 v[18:33], v[94:97], v[118:121], v[18:33]
	s_waitcnt lgkmcnt(0)
	v_mfma_f32_32x32x16_bf16 v[50:65], v[94:97], v[126:129], v[50:65]
	v_mfma_f32_32x32x16_bf16 v[2:17], v[102:105], v[118:121], v[2:17]
	v_mfma_f32_32x32x16_bf16 v[34:49], v[102:105], v[126:129], v[34:49]
	s_waitcnt lgkmcnt(0)
	s_setprio 0
	s_barrier
	s_setprio 2
	s_waitcnt vmcnt(7)
	ds_write_b128 v0, v[78:81] offset:36864
	s_waitcnt vmcnt(6)
	ds_write_b128 v0, v[86:89] offset:41472
	s_waitcnt vmcnt(5)
	ds_write_b128 v0, v[90:93] offset:46080
	s_waitcnt vmcnt(3)
	ds_write_b128 v0, v[66:69] offset:55296
	s_waitcnt vmcnt(2)
	ds_write_b128 v0, v[70:73] offset:59904
	s_waitcnt vmcnt(1)
	ds_write_b128 v0, v[74:77] offset:64512
	ds_read_b128 v[66:69], v173
	ds_read_b128 v[74:77], v173 offset:4608
	ds_read_b128 v[82:85], v174 offset:18432
	ds_read_b128 v[90:93], v174 offset:23040
	ds_read_b128 v[70:73], v173 offset:32
	ds_read_b128 v[78:81], v173 offset:4640
	ds_read_b128 v[86:89], v174 offset:18464
	ds_read_b128 v[94:97], v174 offset:23072
	s_waitcnt lgkmcnt(5)
	v_mfma_f32_32x32x16_bf16 v[18:33], v[66:69], v[82:85], v[18:33]
	s_waitcnt vmcnt(4)
	ds_write_b128 v0, v[106:109] offset:50688
	s_waitcnt lgkmcnt(5)
	v_mfma_f32_32x32x16_bf16 v[50:65], v[66:69], v[90:93], v[50:65]
	s_waitcnt vmcnt(0)
	ds_write_b128 v175, v[110:113] offset:13824
	v_mfma_f32_32x32x16_bf16 v[2:17], v[74:77], v[82:85], v[2:17]
	v_mfma_f32_32x32x16_bf16 v[34:49], v[74:77], v[90:93], v[34:49]
	ds_read_b128 v[66:69], v173 offset:64
	ds_read_b128 v[74:77], v173 offset:4672
	ds_read_b128 v[82:85], v174 offset:18496
	ds_read_b128 v[90:93], v174 offset:23104
	s_waitcnt lgkmcnt(7)
	v_mfma_f32_32x32x16_bf16 v[18:33], v[70:73], v[86:89], v[18:33]
	s_waitcnt lgkmcnt(6)
	v_mfma_f32_32x32x16_bf16 v[50:65], v[70:73], v[94:97], v[50:65]
	v_mfma_f32_32x32x16_bf16 v[2:17], v[78:81], v[86:89], v[2:17]
	v_mfma_f32_32x32x16_bf16 v[34:49], v[78:81], v[94:97], v[34:49]
	ds_read_b128 v[70:73], v173 offset:96
	ds_read_b128 v[78:81], v173 offset:4704
	ds_read_b128 v[86:89], v174 offset:18528
	ds_read_b128 v[94:97], v174 offset:23136
	s_waitcnt lgkmcnt(5)
	v_mfma_f32_32x32x16_bf16 v[18:33], v[66:69], v[82:85], v[18:33]
	s_waitcnt lgkmcnt(4)
	v_mfma_f32_32x32x16_bf16 v[50:65], v[66:69], v[90:93], v[50:65]
	v_mfma_f32_32x32x16_bf16 v[2:17], v[74:77], v[82:85], v[2:17]
	v_mfma_f32_32x32x16_bf16 v[34:49], v[74:77], v[90:93], v[34:49]
	s_waitcnt lgkmcnt(1)
	v_mfma_f32_32x32x16_bf16 v[18:33], v[70:73], v[86:89], v[18:33]
	s_waitcnt lgkmcnt(0)
	v_mfma_f32_32x32x16_bf16 v[50:65], v[70:73], v[94:97], v[50:65]
	v_mfma_f32_32x32x16_bf16 v[2:17], v[78:81], v[86:89], v[2:17]
	v_mfma_f32_32x32x16_bf16 v[34:49], v[78:81], v[94:97], v[34:49]
	s_waitcnt lgkmcnt(0)
	s_setprio 0
	s_barrier
	s_setprio 2
	ds_read_b128 v[66:69], v173 offset:36864
	ds_read_b128 v[70:73], v173 offset:36896
	ds_read_b128 v[74:77], v173 offset:41472
	ds_read_b128 v[78:81], v173 offset:41504
	ds_read_b128 v[82:85], v174 offset:55296
	ds_read_b128 v[86:89], v174 offset:55328
	ds_read_b128 v[90:93], v174 offset:59904
	ds_read_b128 v[94:97], v174 offset:59936
	s_waitcnt lgkmcnt(3)
	v_mfma_f32_32x32x16_bf16 v[18:33], v[66:69], v[82:85], v[18:33]
	s_waitcnt lgkmcnt(1)
	v_mfma_f32_32x32x16_bf16 v[50:65], v[66:69], v[90:93], v[50:65]
	v_mfma_f32_32x32x16_bf16 v[2:17], v[74:77], v[82:85], v[2:17]
	v_mfma_f32_32x32x16_bf16 v[34:49], v[74:77], v[90:93], v[34:49]
	ds_read_b128 v[66:69], v173 offset:36928
	ds_read_b128 v[74:77], v173 offset:41536
	ds_read_b128 v[82:85], v174 offset:55360
	ds_read_b128 v[90:93], v174 offset:59968
	v_mfma_f32_32x32x16_bf16 v[18:33], v[70:73], v[86:89], v[18:33]
	s_waitcnt lgkmcnt(4)
	v_mfma_f32_32x32x16_bf16 v[50:65], v[70:73], v[94:97], v[50:65]
	v_mfma_f32_32x32x16_bf16 v[2:17], v[78:81], v[86:89], v[2:17]
	v_mfma_f32_32x32x16_bf16 v[34:49], v[78:81], v[94:97], v[34:49]
	ds_read_b128 v[70:73], v173 offset:36960
	ds_read_b128 v[78:81], v173 offset:41568
	ds_read_b128 v[86:89], v174 offset:55392
	ds_read_b128 v[94:97], v174 offset:60000
	s_waitcnt lgkmcnt(5)
	v_mfma_f32_32x32x16_bf16 v[18:33], v[66:69], v[82:85], v[18:33]
	s_waitcnt lgkmcnt(4)
	v_mfma_f32_32x32x16_bf16 v[50:65], v[66:69], v[90:93], v[50:65]
	v_mfma_f32_32x32x16_bf16 v[2:17], v[74:77], v[82:85], v[2:17]
	v_mfma_f32_32x32x16_bf16 v[34:49], v[74:77], v[90:93], v[34:49]
	s_waitcnt lgkmcnt(1)
	v_mfma_f32_32x32x16_bf16 v[18:33], v[70:73], v[86:89], v[18:33]
	s_waitcnt lgkmcnt(0)
	v_mfma_f32_32x32x16_bf16 v[50:65], v[70:73], v[94:97], v[50:65]
	v_mfma_f32_32x32x16_bf16 v[2:17], v[78:81], v[86:89], v[2:17]
	v_mfma_f32_32x32x16_bf16 v[34:49], v[78:81], v[94:97], v[34:49]
	s_setprio 0
	v_cmp_ne_u32_e32 vcc, 24, v171
	s_barrier
	v_mov_b32 v0, v194
	s_and_b64 vcc, exec, vcc
	v_and_b32_e32 v74, 31, v0
	v_bfe_u32 v75, v0, 5, 1
	v_ashrrev_i32_e32 v76, 7, v0
	v_bfe_u32 v77, v0, 6, 1
	s_cbranch_vccz .LBB0_1382
	v_cmp_gt_u32_e32 vcc, 8, v168
	s_cbranch_vccnz .LBB0_1301
	v_cmp_lt_u32_e32 vcc, 15, v168
	s_cbranch_vccz .LBB0_1302
	v_cmp_lt_u32_e32 vcc, 31, v168
	s_cbranch_vccz .LBB0_1303
	v_cmp_lt_u32_e32 vcc, 47, v168
	s_cbranch_vccz .LBB0_1304
	v_cmp_lt_u32_e32 vcc, 55, v168
	v_cmp_lt_u32_e64 s[14:15], 31, v172
	s_cbranch_vccz .LBB0_1305
	v_cmp_lt_u32_e32 vcc, 63, v168
	s_cbranch_vccz .LBB0_1306
	s_movk_i32 s6, 0x50
	v_cmp_gt_u32_e32 vcc, s6, v168
	v_mov_b32_e32 v67, v1
	v_add_u32_e32 v68, 0xfffff800, v169
	v_cndmask_b32_e32 v0, v207, v208, vcc
	v_cndmask_b32_e32 v66, v209, v210, vcc
	v_lshl_add_u64 v[70:71], s[8:9], 0, v[66:67]
	s_mov_b64 s[12:13], 0
	v_mov_b64_e32 v[66:67], v[0:1]
	s_branch .LBB0_1307

.LBB0_1387:
	s_andn2_b64 vcc, exec, s[10:11]
	s_cbranch_vccnz .LBB0_1291
	v_mov_b32 v66, v194
	s_waitcnt vmcnt(63) expcnt(7) lgkmcnt(15)
	v_ashrrev_i32_e32 v68, 3, v66
	v_add_u32_e32 v2, v68, v169
	v_ashrrev_i32_e32 v3, 31, v2
	v_lshlrev_b64 v[2:3], 11, v[2:3]
	v_lshlrev_b32_e32 v0, 4, v66
	v_lshl_add_u64 v[2:3], s[50:51], 0, v[2:3]
	v_and_b32_e32 v0, 0x70, v0
	v_lshl_add_u64 v[150:151], v[2:3], 0, v[0:1]
	v_add_u32_e32 v2, v68, v167
	v_ashrrev_i32_e32 v3, 31, v2
	v_lshlrev_b64 v[2:3], 11, v[2:3]
	v_lshl_add_u64 v[2:3], s[52:53], 0, v[2:3]
	v_lshl_add_u64 v[158:159], v[2:3], 0, v[0:1]
	v_add_co_u32_e32 v160, vcc, s12, v158
	s_barrier
	s_nop 0
	v_addc_co_u32_e32 v161, vcc, 0, v159, vcc
	v_add_co_u32_e32 v162, vcc, s23, v158
	s_nop 1
	v_addc_co_u32_e32 v163, vcc, 0, v159, vcc
	v_add_co_u32_e32 v164, vcc, s21, v158
	s_nop 1
	v_addc_co_u32_e32 v165, vcc, 0, v159, vcc
	v_add_co_u32_e32 v152, vcc, s12, v150
	s_barrier
	global_load_dwordx4 v[2:5], v[158:159], off
	global_load_dwordx4 v[6:9], v[160:161], off
	global_load_dwordx4 v[10:13], v[162:163], off
	global_load_dwordx4 v[14:17], v[164:165], off
	global_load_dwordx4 v[18:21], v[150:151], off
	v_addc_co_u32_e32 v153, vcc, 0, v151, vcc
	v_add_co_u32_e32 v154, vcc, s23, v150
	global_load_dwordx4 v[22:25], v[152:153], off
	s_nop 0
	v_addc_co_u32_e32 v155, vcc, 0, v151, vcc
	v_add_co_u32_e32 v156, vcc, s21, v150
	global_load_dwordx4 v[26:29], v[154:155], off
	s_nop 0
	v_addc_co_u32_e32 v157, vcc, 0, v151, vcc
	global_load_dwordx4 v[30:33], v[156:157], off
	global_load_dwordx4 v[34:37], v[158:159], off offset:128
	global_load_dwordx4 v[38:41], v[160:161], off offset:128
	global_load_dwordx4 v[42:45], v[162:163], off offset:128
	global_load_dwordx4 v[46:49], v[164:165], off offset:128
	global_load_dwordx4 v[50:53], v[150:151], off offset:128
	global_load_dwordx4 v[54:57], v[152:153], off offset:128
	global_load_dwordx4 v[58:61], v[154:155], off offset:128
	global_load_dwordx4 v[62:65], v[156:157], off offset:128
	global_load_dwordx4 v[98:101], v[158:159], off offset:256
	global_load_dwordx4 v[102:105], v[160:161], off offset:256
	global_load_dwordx4 v[106:109], v[162:163], off offset:256
	global_load_dwordx4 v[110:113], v[164:165], off offset:256
	v_mul_lo_u32 v68, v68, s34
	v_add3_u32 v0, 16, v68, v0
	v_and_b32_e32 v67, 31, v66
	v_add_u32_e32 v175, 0xd800, v0
	s_waitcnt vmcnt(19)
	ds_write_b128 v0, v[2:5]
	s_waitcnt vmcnt(18)
	ds_write_b128 v0, v[6:9] offset:4608
	s_waitcnt vmcnt(17)
	ds_write_b128 v0, v[10:13] offset:9216
	s_waitcnt vmcnt(16)
	ds_write_b128 v0, v[14:17] offset:13824
	s_waitcnt vmcnt(15)
	ds_write_b128 v0, v[18:21] offset:18432
	s_waitcnt vmcnt(14)
	ds_write_b128 v0, v[22:25] offset:23040
	s_waitcnt vmcnt(13)
	ds_write_b128 v0, v[26:29] offset:27648
	s_waitcnt vmcnt(12)
	ds_write_b128 v0, v[30:33] offset:32256
	global_load_dwordx4 v[122:125], v[150:151], off offset:256
	global_load_dwordx4 v[126:129], v[152:153], off offset:256
	global_load_dwordx4 v[130:133], v[154:155], off offset:256
	global_load_dwordx4 v[134:137], v[156:157], off offset:256
	global_load_dwordx4 v[78:81], v[158:159], off offset:384
	global_load_dwordx4 v[86:89], v[160:161], off offset:384
	global_load_dwordx4 v[90:93], v[162:163], off offset:384
	global_load_dwordx4 v[94:97], v[164:165], off offset:384
	s_waitcnt lgkmcnt(0)
	s_barrier
	v_lshrrev_b32_e32 v2, 1, v66
	s_waitcnt vmcnt(19)
	ds_write_b128 v0, v[34:37] offset:36864
	s_waitcnt vmcnt(18)
	ds_write_b128 v0, v[38:41] offset:41472
	s_waitcnt vmcnt(17)
	ds_write_b128 v0, v[42:45] offset:46080
	s_waitcnt vmcnt(16)
	ds_write_b128 v0, v[46:49] offset:50688
	s_waitcnt vmcnt(15)
	ds_write_b128 v0, v[50:53] offset:55296
	s_waitcnt vmcnt(14)
	ds_write_b128 v0, v[54:57] offset:59904
	s_waitcnt vmcnt(13)
	ds_write_b128 v0, v[58:61] offset:64512
	s_waitcnt vmcnt(12)
	ds_write_b128 v175, v[62:65] offset:13824
	v_and_or_b32 v3, v2, s24, v67
	v_and_b32_e32 v4, 0x5f, v66
	global_load_dwordx4 v[114:117], v[150:151], off offset:384
	global_load_dwordx4 v[118:121], v[152:153], off offset:384
	global_load_dwordx4 v[138:141], v[154:155], off offset:384
	global_load_dwordx4 v[142:145], v[156:157], off offset:384
	global_load_dwordx4 v[66:69], v[158:159], off offset:512
	global_load_dwordx4 v[70:73], v[160:161], off offset:512
	global_load_dwordx4 v[74:77], v[162:163], off offset:512
	global_load_dwordx4 v[82:85], v[164:165], off offset:512
	v_mul_u32_u24_e32 v4, 0x48, v4
	v_mul_lo_u32 v3, v3, s34
	v_and_b32_e32 v2, 16, v2
	v_add3_u32 v173, 16, v3, v2
	v_lshlrev_b32_e32 v3, 1, v4
	v_add3_u32 v174, 16, v3, v2
	s_setprio 2
	ds_read_b128 v[2:5], v173
	ds_read_b128 v[146:149], v173 offset:32
	ds_read_b128 v[6:9], v173 offset:4608
	ds_read_b128 v[176:179], v173 offset:4640
	ds_read_b128 v[10:13], v174 offset:18432
	ds_read_b128 v[180:183], v174 offset:18464
	ds_read_b128 v[14:17], v174 offset:23040
	ds_read_b128 v[184:187], v174 offset:23072
	s_waitcnt lgkmcnt(3)
	v_mfma_f32_32x32x16_bf16 v[50:65], v[2:5], v[10:13], 0
	s_waitcnt lgkmcnt(1)
	v_mfma_f32_32x32x16_bf16 v[34:49], v[2:5], v[14:17], 0
	v_mfma_f32_32x32x16_bf16 v[18:33], v[6:9], v[10:13], 0
	v_mfma_f32_32x32x16_bf16 v[2:17], v[6:9], v[14:17], 0
	ds_read_b128 v[188:191], v173 offset:64
	ds_read_b128 v[212:215], v173 offset:4672
	ds_read_b128 v[216:219], v174 offset:18496
	ds_read_b128 v[220:223], v174 offset:23104
	v_mfma_f32_32x32x16_bf16 v[50:65], v[146:149], v[180:183], v[50:65]
	s_waitcnt lgkmcnt(4)
	v_mfma_f32_32x32x16_bf16 v[34:49], v[146:149], v[184:187], v[34:49]
	v_mfma_f32_32x32x16_bf16 v[18:33], v[176:179], v[180:183], v[18:33]
	v_mfma_f32_32x32x16_bf16 v[2:17], v[176:179], v[184:187], v[2:17]
	ds_read_b128 v[146:149], v173 offset:96
	ds_read_b128 v[176:179], v173 offset:4704
	ds_read_b128 v[180:183], v174 offset:18528
	ds_read_b128 v[184:187], v174 offset:23136
	s_waitcnt lgkmcnt(5)
	v_mfma_f32_32x32x16_bf16 v[50:65], v[188:191], v[216:219], v[50:65]
	s_waitcnt lgkmcnt(4)
	v_mfma_f32_32x32x16_bf16 v[34:49], v[188:191], v[220:223], v[34:49]
	v_mfma_f32_32x32x16_bf16 v[18:33], v[212:215], v[216:219], v[18:33]
	v_mfma_f32_32x32x16_bf16 v[2:17], v[212:215], v[220:223], v[2:17]
	s_waitcnt lgkmcnt(1)
	v_mfma_f32_32x32x16_bf16 v[50:65], v[146:149], v[180:183], v[50:65]
	s_waitcnt lgkmcnt(0)
	v_mfma_f32_32x32x16_bf16 v[34:49], v[146:149], v[184:187], v[34:49]
	v_mfma_f32_32x32x16_bf16 v[18:33], v[176:179], v[180:183], v[18:33]
	v_mfma_f32_32x32x16_bf16 v[2:17], v[176:179], v[184:187], v[2:17]
	s_setprio 0
	s_barrier
	s_setprio 2
	s_waitcnt vmcnt(13)
	ds_write_b128 v0, v[130:133] offset:27648
	ds_read_b128 v[130:133], v173 offset:36864
	ds_read_b128 v[180:183], v173 offset:41472
	ds_read_b128 v[188:191], v174 offset:55296
	ds_read_b128 v[216:219], v174 offset:59904
	ds_read_b128 v[176:179], v173 offset:36896
	ds_read_b128 v[184:187], v173 offset:41504
	ds_read_b128 v[212:215], v174 offset:55328
	ds_read_b128 v[220:223], v174 offset:59936
	s_waitcnt lgkmcnt(5)
	v_mfma_f32_32x32x16_bf16 v[50:65], v[130:133], v[188:191], v[50:65]
	s_waitcnt vmcnt(19)
	ds_write_b128 v0, v[98:101]
	s_waitcnt lgkmcnt(5)
	v_mfma_f32_32x32x16_bf16 v[34:49], v[130:133], v[216:219], v[34:49]
	s_waitcnt vmcnt(18)
	ds_write_b128 v0, v[102:105] offset:4608
	v_mfma_f32_32x32x16_bf16 v[18:33], v[180:183], v[188:191], v[18:33]
	s_waitcnt vmcnt(17)
	ds_write_b128 v0, v[106:109] offset:9216
	v_mfma_f32_32x32x16_bf16 v[2:17], v[180:183], v[216:219], v[2:17]
	s_waitcnt vmcnt(16)
	ds_write_b128 v0, v[110:113] offset:13824
	ds_read_b128 v[130:133], v173 offset:36928
	ds_read_b128 v[180:183], v173 offset:41536
	ds_read_b128 v[188:191], v174 offset:55360
	ds_read_b128 v[216:219], v174 offset:59968
	s_waitcnt lgkmcnt(9)
	v_mfma_f32_32x32x16_bf16 v[50:65], v[176:179], v[212:215], v[50:65]
	s_waitcnt vmcnt(15)
	ds_write_b128 v0, v[122:125] offset:18432
	s_waitcnt lgkmcnt(9)
	v_mfma_f32_32x32x16_bf16 v[34:49], v[176:179], v[220:223], v[34:49]
	s_waitcnt vmcnt(14)
	ds_write_b128 v0, v[126:129] offset:23040
	v_mfma_f32_32x32x16_bf16 v[18:33], v[184:187], v[212:215], v[18:33]
	s_waitcnt vmcnt(12)
	ds_write_b128 v0, v[134:137] offset:32256
	v_mfma_f32_32x32x16_bf16 v[2:17], v[184:187], v[220:223], v[2:17]
	ds_read_b128 v[176:179], v173 offset:36960
	ds_read_b128 v[184:187], v173 offset:41568
	ds_read_b128 v[212:215], v174 offset:55392
	ds_read_b128 v[220:223], v174 offset:60000
	s_waitcnt lgkmcnt(8)
	v_mfma_f32_32x32x16_bf16 v[50:65], v[130:133], v[188:191], v[50:65]
	global_load_dwordx4 v[122:125], v[150:151], off offset:512
	global_load_dwordx4 v[126:129], v[152:153], off offset:512
	s_waitcnt lgkmcnt(7)
	v_mfma_f32_32x32x16_bf16 v[34:49], v[130:133], v[216:219], v[34:49]
	global_load_dwordx4 v[134:137], v[154:155], off offset:512
	global_load_dwordx4 v[146:149], v[156:157], off offset:512
	v_mfma_f32_32x32x16_bf16 v[18:33], v[180:183], v[188:191], v[18:33]
	global_load_dwordx4 v[98:101], v[158:159], off offset:640
	global_load_dwordx4 v[102:105], v[160:161], off offset:640
	v_mfma_f32_32x32x16_bf16 v[2:17], v[180:183], v[216:219], v[2:17]
	global_load_dwordx4 v[106:109], v[162:163], off offset:640
	global_load_dwordx4 v[110:113], v[164:165], off offset:640
	s_waitcnt lgkmcnt(1)
	v_mfma_f32_32x32x16_bf16 v[50:65], v[176:179], v[212:215], v[50:65]
	s_waitcnt lgkmcnt(0)
	v_mfma_f32_32x32x16_bf16 v[34:49], v[176:179], v[220:223], v[34:49]
	v_mfma_f32_32x32x16_bf16 v[18:33], v[184:187], v[212:215], v[18:33]
	v_mfma_f32_32x32x16_bf16 v[2:17], v[184:187], v[220:223], v[2:17]
	s_waitcnt lgkmcnt(0)
	s_setprio 0
	s_barrier
	s_setprio 2
	s_waitcnt vmcnt(14)
	ds_write_b128 v0, v[118:121] offset:59904
	ds_read_b128 v[118:121], v173
	ds_read_b128 v[180:183], v173 offset:4608
	ds_read_b128 v[188:191], v174 offset:18432
	ds_read_b128 v[216:219], v174 offset:23040
	ds_read_b128 v[176:179], v173 offset:32
	ds_read_b128 v[184:187], v173 offset:4640
	ds_read_b128 v[212:215], v174 offset:18464
	ds_read_b128 v[220:223], v174 offset:23072
	s_waitcnt lgkmcnt(5)
	v_mfma_f32_32x32x16_bf16 v[50:65], v[118:121], v[188:191], v[50:65]
	s_waitcnt vmcnt(19)
	ds_write_b128 v0, v[78:81] offset:36864
	s_waitcnt lgkmcnt(5)
	v_mfma_f32_32x32x16_bf16 v[34:49], v[118:121], v[216:219], v[34:49]
	s_waitcnt vmcnt(18)
	ds_write_b128 v0, v[86:89] offset:41472
	v_mfma_f32_32x32x16_bf16 v[18:33], v[180:183], v[188:191], v[18:33]
	s_waitcnt vmcnt(17)
	ds_write_b128 v0, v[90:93] offset:46080
	v_mfma_f32_32x32x16_bf16 v[2:17], v[180:183], v[216:219], v[2:17]
	s_waitcnt vmcnt(16)
	ds_write_b128 v0, v[94:97] offset:50688
	ds_read_b128 v[118:121], v173 offset:64
	ds_read_b128 v[180:183], v173 offset:4672
	ds_read_b128 v[188:191], v174 offset:18496
	ds_read_b128 v[216:219], v174 offset:23104
	s_waitcnt lgkmcnt(9)
	v_mfma_f32_32x32x16_bf16 v[50:65], v[176:179], v[212:215], v[50:65]
	s_waitcnt vmcnt(15)
	ds_write_b128 v0, v[114:117] offset:55296
	s_waitcnt lgkmcnt(9)
	v_mfma_f32_32x32x16_bf16 v[34:49], v[176:179], v[220:223], v[34:49]
	s_waitcnt vmcnt(13)
	ds_write_b128 v0, v[138:141] offset:64512
	v_mfma_f32_32x32x16_bf16 v[18:33], v[184:187], v[212:215], v[18:33]
	s_waitcnt vmcnt(12)
	ds_write_b128 v175, v[142:145] offset:13824
	v_mfma_f32_32x32x16_bf16 v[2:17], v[184:187], v[220:223], v[2:17]
	ds_read_b128 v[176:179], v173 offset:96
	ds_read_b128 v[184:187], v173 offset:4704
	ds_read_b128 v[212:215], v174 offset:18528
	ds_read_b128 v[220:223], v174 offset:23136
	s_waitcnt lgkmcnt(8)
	v_mfma_f32_32x32x16_bf16 v[50:65], v[118:121], v[188:191], v[50:65]
	global_load_dwordx4 v[94:97], v[150:151], off offset:640
	global_load_dwordx4 v[130:133], v[152:153], off offset:640
	s_waitcnt lgkmcnt(7)
	v_mfma_f32_32x32x16_bf16 v[34:49], v[118:121], v[216:219], v[34:49]
	global_load_dwordx4 v[138:141], v[154:155], off offset:640
	global_load_dwordx4 v[142:145], v[156:157], off offset:640
	v_mfma_f32_32x32x16_bf16 v[18:33], v[180:183], v[188:191], v[18:33]
	global_load_dwordx4 v[78:81], v[158:159], off offset:768
	global_load_dwordx4 v[86:89], v[160:161], off offset:768
	v_mfma_f32_32x32x16_bf16 v[2:17], v[180:183], v[216:219], v[2:17]
	global_load_dwordx4 v[90:93], v[162:163], off offset:768
	global_load_dwordx4 v[114:117], v[164:165], off offset:768
	s_waitcnt lgkmcnt(1)
	v_mfma_f32_32x32x16_bf16 v[50:65], v[176:179], v[212:215], v[50:65]
	s_waitcnt lgkmcnt(0)
	v_mfma_f32_32x32x16_bf16 v[34:49], v[176:179], v[220:223], v[34:49]
	v_mfma_f32_32x32x16_bf16 v[18:33], v[184:187], v[212:215], v[18:33]
	v_mfma_f32_32x32x16_bf16 v[2:17], v[184:187], v[220:223], v[2:17]
	s_waitcnt lgkmcnt(0)
	s_setprio 0
	s_barrier
	s_setprio 2
	s_waitcnt vmcnt(16)
	ds_write_b128 v0, v[82:85] offset:13824
	ds_read_b128 v[82:85], v173 offset:36864
	ds_read_b128 v[180:183], v173 offset:41472
	ds_read_b128 v[188:191], v174 offset:55296
	ds_read_b128 v[216:219], v174 offset:59904
	ds_read_b128 v[176:179], v173 offset:36896
	ds_read_b128 v[184:187], v173 offset:41504
	ds_read_b128 v[212:215], v174 offset:55328
	ds_read_b128 v[220:223], v174 offset:59936
	s_waitcnt lgkmcnt(5)
	v_mfma_f32_32x32x16_bf16 v[50:65], v[82:85], v[188:191], v[50:65]
	s_waitcnt vmcnt(19)
	ds_write_b128 v0, v[66:69]
	s_waitcnt lgkmcnt(5)
	v_mfma_f32_32x32x16_bf16 v[34:49], v[82:85], v[216:219], v[34:49]
	s_waitcnt vmcnt(18)
	ds_write_b128 v0, v[70:73] offset:4608
	v_mfma_f32_32x32x16_bf16 v[18:33], v[180:183], v[188:191], v[18:33]
	s_waitcnt vmcnt(17)
	ds_write_b128 v0, v[74:77] offset:9216
	v_mfma_f32_32x32x16_bf16 v[2:17], v[180:183], v[216:219], v[2:17]
	s_waitcnt vmcnt(15)
	ds_write_b128 v0, v[122:125] offset:18432
	ds_read_b128 v[82:85], v173 offset:36928
	ds_read_b128 v[180:183], v173 offset:41536
	ds_read_b128 v[188:191], v174 offset:55360
	ds_read_b128 v[216:219], v174 offset:59968
	s_waitcnt lgkmcnt(9)
	v_mfma_f32_32x32x16_bf16 v[50:65], v[176:179], v[212:215], v[50:65]
	s_waitcnt vmcnt(14)
	ds_write_b128 v0, v[126:129] offset:23040
	s_waitcnt lgkmcnt(9)
	v_mfma_f32_32x32x16_bf16 v[34:49], v[176:179], v[220:223], v[34:49]
	s_waitcnt vmcnt(13)
	ds_write_b128 v0, v[134:137] offset:27648
	v_mfma_f32_32x32x16_bf16 v[18:33], v[184:187], v[212:215], v[18:33]
	s_waitcnt vmcnt(12)
	ds_write_b128 v0, v[146:149] offset:32256
	v_mfma_f32_32x32x16_bf16 v[2:17], v[184:187], v[220:223], v[2:17]
	ds_read_b128 v[176:179], v173 offset:36960
	ds_read_b128 v[184:187], v173 offset:41568
	ds_read_b128 v[212:215], v174 offset:55392
	ds_read_b128 v[220:223], v174 offset:60000
	s_waitcnt lgkmcnt(8)
	v_mfma_f32_32x32x16_bf16 v[50:65], v[82:85], v[188:191], v[50:65]
	global_load_dwordx4 v[122:125], v[150:151], off offset:768
	global_load_dwordx4 v[126:129], v[152:153], off offset:768
	s_waitcnt lgkmcnt(7)
	v_mfma_f32_32x32x16_bf16 v[34:49], v[82:85], v[216:219], v[34:49]
	global_load_dwordx4 v[134:137], v[154:155], off offset:768
	global_load_dwordx4 v[146:149], v[156:157], off offset:768
	v_mfma_f32_32x32x16_bf16 v[18:33], v[180:183], v[188:191], v[18:33]
	global_load_dwordx4 v[66:69], v[158:159], off offset:896
	global_load_dwordx4 v[70:73], v[160:161], off offset:896
	v_mfma_f32_32x32x16_bf16 v[2:17], v[180:183], v[216:219], v[2:17]
	global_load_dwordx4 v[74:77], v[162:163], off offset:896
	global_load_dwordx4 v[118:121], v[164:165], off offset:896
	s_waitcnt lgkmcnt(1)
	v_mfma_f32_32x32x16_bf16 v[50:65], v[176:179], v[212:215], v[50:65]
	s_waitcnt lgkmcnt(0)
	v_mfma_f32_32x32x16_bf16 v[34:49], v[176:179], v[220:223], v[34:49]
	v_mfma_f32_32x32x16_bf16 v[18:33], v[184:187], v[212:215], v[18:33]
	v_mfma_f32_32x32x16_bf16 v[2:17], v[184:187], v[220:223], v[2:17]
	s_waitcnt lgkmcnt(0)
	s_setprio 0
	s_barrier
	s_setprio 2
	s_waitcnt vmcnt(17)
	ds_write_b128 v0, v[106:109] offset:46080
	ds_read_b128 v[106:109], v173
	ds_read_b128 v[180:183], v173 offset:4608
	ds_read_b128 v[188:191], v174 offset:18432
	ds_read_b128 v[216:219], v174 offset:23040
	ds_read_b128 v[176:179], v173 offset:32
	ds_read_b128 v[184:187], v173 offset:4640
	ds_read_b128 v[212:215], v174 offset:18464
	ds_read_b128 v[220:223], v174 offset:23072
	s_waitcnt lgkmcnt(5)
	v_mfma_f32_32x32x16_bf16 v[50:65], v[106:109], v[188:191], v[50:65]
	s_waitcnt vmcnt(19)
	ds_write_b128 v0, v[98:101] offset:36864
	s_waitcnt lgkmcnt(5)
	v_mfma_f32_32x32x16_bf16 v[34:49], v[106:109], v[216:219], v[34:49]
	s_waitcnt vmcnt(18)
	ds_write_b128 v0, v[102:105] offset:41472
	v_mfma_f32_32x32x16_bf16 v[18:33], v[180:183], v[188:191], v[18:33]
	s_waitcnt vmcnt(16)
	ds_write_b128 v0, v[110:113] offset:50688
	v_mfma_f32_32x32x16_bf16 v[2:17], v[180:183], v[216:219], v[2:17]
	s_waitcnt vmcnt(15)
	ds_write_b128 v0, v[94:97] offset:55296
	ds_read_b128 v[106:109], v173 offset:64
	ds_read_b128 v[180:183], v173 offset:4672
	ds_read_b128 v[188:191], v174 offset:18496
	ds_read_b128 v[216:219], v174 offset:23104
	s_waitcnt lgkmcnt(9)
	v_mfma_f32_32x32x16_bf16 v[50:65], v[176:179], v[212:215], v[50:65]
	s_waitcnt vmcnt(14)
	ds_write_b128 v0, v[130:133] offset:59904
	s_waitcnt lgkmcnt(9)
	v_mfma_f32_32x32x16_bf16 v[34:49], v[176:179], v[220:223], v[34:49]
	s_waitcnt vmcnt(13)
	ds_write_b128 v0, v[138:141] offset:64512
	v_mfma_f32_32x32x16_bf16 v[18:33], v[184:187], v[212:215], v[18:33]
	s_waitcnt vmcnt(12)
	ds_write_b128 v175, v[142:145] offset:13824
	v_mfma_f32_32x32x16_bf16 v[2:17], v[184:187], v[220:223], v[2:17]
	ds_read_b128 v[176:179], v173 offset:96
	ds_read_b128 v[184:187], v173 offset:4704
	ds_read_b128 v[212:215], v174 offset:18528
	ds_read_b128 v[220:223], v174 offset:23136
	s_waitcnt lgkmcnt(8)
	v_mfma_f32_32x32x16_bf16 v[50:65], v[106:109], v[188:191], v[50:65]
	global_load_dwordx4 v[110:113], v[150:151], off offset:896
	global_load_dwordx4 v[130:133], v[152:153], off offset:896
	s_waitcnt lgkmcnt(7)
	v_mfma_f32_32x32x16_bf16 v[34:49], v[106:109], v[216:219], v[34:49]
	global_load_dwordx4 v[138:141], v[154:155], off offset:896
	global_load_dwordx4 v[142:145], v[156:157], off offset:896
	v_mfma_f32_32x32x16_bf16 v[18:33], v[180:183], v[188:191], v[18:33]
	global_load_dwordx4 v[82:85], v[158:159], off offset:1024
	global_load_dwordx4 v[94:97], v[160:161], off offset:1024
	v_mfma_f32_32x32x16_bf16 v[2:17], v[180:183], v[216:219], v[2:17]
	global_load_dwordx4 v[98:101], v[162:163], off offset:1024
	global_load_dwordx4 v[102:105], v[164:165], off offset:1024
	s_waitcnt lgkmcnt(1)
	v_mfma_f32_32x32x16_bf16 v[50:65], v[176:179], v[212:215], v[50:65]
	s_waitcnt lgkmcnt(0)
	v_mfma_f32_32x32x16_bf16 v[34:49], v[176:179], v[220:223], v[34:49]
	v_mfma_f32_32x32x16_bf16 v[18:33], v[184:187], v[212:215], v[18:33]
	v_mfma_f32_32x32x16_bf16 v[2:17], v[184:187], v[220:223], v[2:17]
	s_waitcnt lgkmcnt(0)
	s_setprio 0
	s_barrier
	s_setprio 2
	s_waitcnt vmcnt(14)
	ds_write_b128 v0, v[126:129] offset:23040
	ds_read_b128 v[126:129], v173 offset:36864
	ds_read_b128 v[180:183], v173 offset:41472
	ds_read_b128 v[188:191], v174 offset:55296
	ds_read_b128 v[216:219], v174 offset:59904
	ds_read_b128 v[176:179], v173 offset:36896
	ds_read_b128 v[184:187], v173 offset:41504
	ds_read_b128 v[212:215], v174 offset:55328
	ds_read_b128 v[220:223], v174 offset:59936
	s_waitcnt lgkmcnt(5)
	v_mfma_f32_32x32x16_bf16 v[50:65], v[126:129], v[188:191], v[50:65]
	s_waitcnt vmcnt(19)
	ds_write_b128 v0, v[78:81]
	s_waitcnt lgkmcnt(5)
	v_mfma_f32_32x32x16_bf16 v[34:49], v[126:129], v[216:219], v[34:49]
	s_waitcnt vmcnt(18)
	ds_write_b128 v0, v[86:89] offset:4608
	v_mfma_f32_32x32x16_bf16 v[18:33], v[180:183], v[188:191], v[18:33]
	s_waitcnt vmcnt(17)
	ds_write_b128 v0, v[90:93] offset:9216
	v_mfma_f32_32x32x16_bf16 v[2:17], v[180:183], v[216:219], v[2:17]
	s_waitcnt vmcnt(16)
	ds_write_b128 v0, v[114:117] offset:13824
	ds_read_b128 v[126:129], v173 offset:36928
	ds_read_b128 v[180:183], v173 offset:41536
	ds_read_b128 v[188:191], v174 offset:55360
	ds_read_b128 v[216:219], v174 offset:59968
	s_waitcnt lgkmcnt(9)
	v_mfma_f32_32x32x16_bf16 v[50:65], v[176:179], v[212:215], v[50:65]
	s_waitcnt vmcnt(15)
	ds_write_b128 v0, v[122:125] offset:18432
	s_waitcnt lgkmcnt(9)
	v_mfma_f32_32x32x16_bf16 v[34:49], v[176:179], v[220:223], v[34:49]
	s_waitcnt vmcnt(13)
	ds_write_b128 v0, v[134:137] offset:27648
	v_mfma_f32_32x32x16_bf16 v[18:33], v[184:187], v[212:215], v[18:33]
	s_waitcnt vmcnt(12)
	ds_write_b128 v0, v[146:149] offset:32256
	v_mfma_f32_32x32x16_bf16 v[2:17], v[184:187], v[220:223], v[2:17]
	ds_read_b128 v[176:179], v173 offset:36960
	ds_read_b128 v[184:187], v173 offset:41568
	ds_read_b128 v[212:215], v174 offset:55392
	ds_read_b128 v[220:223], v174 offset:60000
	s_waitcnt lgkmcnt(8)
	v_mfma_f32_32x32x16_bf16 v[50:65], v[126:129], v[188:191], v[50:65]
	global_load_dwordx4 v[114:117], v[150:151], off offset:1024
	global_load_dwordx4 v[122:125], v[152:153], off offset:1024
	s_waitcnt lgkmcnt(7)
	v_mfma_f32_32x32x16_bf16 v[34:49], v[126:129], v[216:219], v[34:49]
	global_load_dwordx4 v[134:137], v[154:155], off offset:1024
	global_load_dwordx4 v[146:149], v[156:157], off offset:1024
	v_mfma_f32_32x32x16_bf16 v[18:33], v[180:183], v[188:191], v[18:33]
	global_load_dwordx4 v[78:81], v[158:159], off offset:1152
	global_load_dwordx4 v[86:89], v[160:161], off offset:1152
	v_mfma_f32_32x32x16_bf16 v[2:17], v[180:183], v[216:219], v[2:17]
	global_load_dwordx4 v[90:93], v[162:163], off offset:1152
	global_load_dwordx4 v[106:109], v[164:165], off offset:1152
	s_waitcnt lgkmcnt(1)
	v_mfma_f32_32x32x16_bf16 v[50:65], v[176:179], v[212:215], v[50:65]
	s_waitcnt lgkmcnt(0)
	v_mfma_f32_32x32x16_bf16 v[34:49], v[176:179], v[220:223], v[34:49]
	v_mfma_f32_32x32x16_bf16 v[18:33], v[184:187], v[212:215], v[18:33]
	v_mfma_f32_32x32x16_bf16 v[2:17], v[184:187], v[220:223], v[2:17]
	s_waitcnt lgkmcnt(0)
	s_setprio 0
	s_barrier
	s_setprio 2
	s_waitcnt vmcnt(12)
	ds_write_b128 v175, v[142:145] offset:13824
	ds_read_b128 v[142:145], v173
	ds_read_b128 v[180:183], v173 offset:4608
	ds_read_b128 v[188:191], v174 offset:18432
	ds_read_b128 v[216:219], v174 offset:23040
	ds_read_b128 v[176:179], v173 offset:32
	ds_read_b128 v[184:187], v173 offset:4640
	ds_read_b128 v[212:215], v174 offset:18464
	ds_read_b128 v[220:223], v174 offset:23072
	s_waitcnt lgkmcnt(5)
	v_mfma_f32_32x32x16_bf16 v[50:65], v[142:145], v[188:191], v[50:65]
	s_waitcnt vmcnt(19)
	ds_write_b128 v0, v[66:69] offset:36864
	s_waitcnt lgkmcnt(5)
	v_mfma_f32_32x32x16_bf16 v[34:49], v[142:145], v[216:219], v[34:49]
	s_waitcnt vmcnt(18)
	ds_write_b128 v0, v[70:73] offset:41472
	v_mfma_f32_32x32x16_bf16 v[18:33], v[180:183], v[188:191], v[18:33]
	s_waitcnt vmcnt(17)
	ds_write_b128 v0, v[74:77] offset:46080
	v_mfma_f32_32x32x16_bf16 v[2:17], v[180:183], v[216:219], v[2:17]
	s_waitcnt vmcnt(16)
	ds_write_b128 v0, v[118:121] offset:50688
	ds_read_b128 v[142:145], v173 offset:64
	ds_read_b128 v[180:183], v173 offset:4672
	ds_read_b128 v[188:191], v174 offset:18496
	ds_read_b128 v[216:219], v174 offset:23104
	s_waitcnt lgkmcnt(9)
	v_mfma_f32_32x32x16_bf16 v[50:65], v[176:179], v[212:215], v[50:65]
	s_waitcnt vmcnt(15)
	ds_write_b128 v0, v[110:113] offset:55296
	s_waitcnt lgkmcnt(9)
	v_mfma_f32_32x32x16_bf16 v[34:49], v[176:179], v[220:223], v[34:49]
	s_waitcnt vmcnt(14)
	ds_write_b128 v0, v[130:133] offset:59904
	v_mfma_f32_32x32x16_bf16 v[18:33], v[184:187], v[212:215], v[18:33]
	s_waitcnt vmcnt(13)
	ds_write_b128 v0, v[138:141] offset:64512
	v_mfma_f32_32x32x16_bf16 v[2:17], v[184:187], v[220:223], v[2:17]
	ds_read_b128 v[176:179], v173 offset:96
	ds_read_b128 v[184:187], v173 offset:4704
	ds_read_b128 v[212:215], v174 offset:18528
	ds_read_b128 v[220:223], v174 offset:23136
	s_waitcnt lgkmcnt(8)
	v_mfma_f32_32x32x16_bf16 v[50:65], v[142:145], v[188:191], v[50:65]
	global_load_dwordx4 v[118:121], v[150:151], off offset:1152
	global_load_dwordx4 v[126:129], v[152:153], off offset:1152
	s_waitcnt lgkmcnt(7)
	v_mfma_f32_32x32x16_bf16 v[34:49], v[142:145], v[216:219], v[34:49]
	global_load_dwordx4 v[130:133], v[154:155], off offset:1152
	global_load_dwordx4 v[138:141], v[156:157], off offset:1152
	v_mfma_f32_32x32x16_bf16 v[18:33], v[180:183], v[188:191], v[18:33]
	global_load_dwordx4 v[66:69], v[158:159], off offset:1280
	global_load_dwordx4 v[70:73], v[160:161], off offset:1280
	v_mfma_f32_32x32x16_bf16 v[2:17], v[180:183], v[216:219], v[2:17]
	global_load_dwordx4 v[74:77], v[162:163], off offset:1280
	global_load_dwordx4 v[110:113], v[164:165], off offset:1280
	s_waitcnt lgkmcnt(1)
	v_mfma_f32_32x32x16_bf16 v[50:65], v[176:179], v[212:215], v[50:65]
	s_waitcnt lgkmcnt(0)
	v_mfma_f32_32x32x16_bf16 v[34:49], v[176:179], v[220:223], v[34:49]
	v_mfma_f32_32x32x16_bf16 v[18:33], v[184:187], v[212:215], v[18:33]
	v_mfma_f32_32x32x16_bf16 v[2:17], v[184:187], v[220:223], v[2:17]
	s_waitcnt lgkmcnt(0)
	s_setprio 0
	s_barrier
	s_setprio 2
	s_waitcnt vmcnt(12)
	ds_write_b128 v0, v[146:149] offset:32256
	ds_read_b128 v[146:149], v173 offset:36864
	ds_read_b128 v[180:183], v173 offset:41472
	ds_read_b128 v[188:191], v174 offset:55296
	ds_read_b128 v[216:219], v174 offset:59904
	ds_read_b128 v[176:179], v173 offset:36896
	ds_read_b128 v[184:187], v173 offset:41504
	ds_read_b128 v[212:215], v174 offset:55328
	ds_read_b128 v[220:223], v174 offset:59936
	s_waitcnt lgkmcnt(5)
	v_mfma_f32_32x32x16_bf16 v[50:65], v[146:149], v[188:191], v[50:65]
	s_waitcnt vmcnt(19)
	ds_write_b128 v0, v[82:85]
	s_waitcnt lgkmcnt(5)
	v_mfma_f32_32x32x16_bf16 v[34:49], v[146:149], v[216:219], v[34:49]
	s_waitcnt vmcnt(18)
	ds_write_b128 v0, v[94:97] offset:4608
	v_mfma_f32_32x32x16_bf16 v[18:33], v[180:183], v[188:191], v[18:33]
	s_waitcnt vmcnt(17)
	ds_write_b128 v0, v[98:101] offset:9216
	v_mfma_f32_32x32x16_bf16 v[2:17], v[180:183], v[216:219], v[2:17]
	s_waitcnt vmcnt(16)
	ds_write_b128 v0, v[102:105] offset:13824
	ds_read_b128 v[146:149], v173 offset:36928
	ds_read_b128 v[180:183], v173 offset:41536
	ds_read_b128 v[188:191], v174 offset:55360
	ds_read_b128 v[216:219], v174 offset:59968
	s_waitcnt lgkmcnt(9)
	v_mfma_f32_32x32x16_bf16 v[50:65], v[176:179], v[212:215], v[50:65]
	s_waitcnt vmcnt(15)
	ds_write_b128 v0, v[114:117] offset:18432
	s_waitcnt lgkmcnt(9)
	v_mfma_f32_32x32x16_bf16 v[34:49], v[176:179], v[220:223], v[34:49]
	s_waitcnt vmcnt(14)
	ds_write_b128 v0, v[122:125] offset:23040
	v_mfma_f32_32x32x16_bf16 v[18:33], v[184:187], v[212:215], v[18:33]
	s_waitcnt vmcnt(13)
	ds_write_b128 v0, v[134:137] offset:27648
	v_mfma_f32_32x32x16_bf16 v[2:17], v[184:187], v[220:223], v[2:17]
	ds_read_b128 v[176:179], v173 offset:36960
	ds_read_b128 v[184:187], v173 offset:41568
	ds_read_b128 v[212:215], v174 offset:55392
	ds_read_b128 v[220:223], v174 offset:60000
	s_waitcnt lgkmcnt(8)
	v_mfma_f32_32x32x16_bf16 v[50:65], v[146:149], v[188:191], v[50:65]
	global_load_dwordx4 v[114:117], v[150:151], off offset:1280
	global_load_dwordx4 v[122:125], v[152:153], off offset:1280
	s_waitcnt lgkmcnt(7)
	v_mfma_f32_32x32x16_bf16 v[34:49], v[146:149], v[216:219], v[34:49]
	global_load_dwordx4 v[134:137], v[154:155], off offset:1280
	global_load_dwordx4 v[142:145], v[156:157], off offset:1280
	v_mfma_f32_32x32x16_bf16 v[18:33], v[180:183], v[188:191], v[18:33]
	global_load_dwordx4 v[82:85], v[158:159], off offset:1408
	global_load_dwordx4 v[94:97], v[160:161], off offset:1408
	v_mfma_f32_32x32x16_bf16 v[2:17], v[180:183], v[216:219], v[2:17]
	global_load_dwordx4 v[98:101], v[162:163], off offset:1408
	global_load_dwordx4 v[102:105], v[164:165], off offset:1408
	s_waitcnt lgkmcnt(1)
	v_mfma_f32_32x32x16_bf16 v[50:65], v[176:179], v[212:215], v[50:65]
	s_waitcnt lgkmcnt(0)
	v_mfma_f32_32x32x16_bf16 v[34:49], v[176:179], v[220:223], v[34:49]
	v_mfma_f32_32x32x16_bf16 v[18:33], v[184:187], v[212:215], v[18:33]
	v_mfma_f32_32x32x16_bf16 v[2:17], v[184:187], v[220:223], v[2:17]
	s_waitcnt lgkmcnt(0)
	s_setprio 0
	s_barrier
	s_setprio 2
	ds_read_b128 v[146:149], v173
	ds_read_b128 v[180:183], v173 offset:4608
	ds_read_b128 v[188:191], v174 offset:18432
	ds_read_b128 v[216:219], v174 offset:23040
	ds_read_b128 v[176:179], v173 offset:32
	ds_read_b128 v[184:187], v173 offset:4640
	ds_read_b128 v[212:215], v174 offset:18464
	ds_read_b128 v[220:223], v174 offset:23072
	s_waitcnt lgkmcnt(5)
	v_mfma_f32_32x32x16_bf16 v[50:65], v[146:149], v[188:191], v[50:65]
	s_waitcnt vmcnt(19)
	ds_write_b128 v0, v[78:81] offset:36864
	s_waitcnt lgkmcnt(5)
	v_mfma_f32_32x32x16_bf16 v[34:49], v[146:149], v[216:219], v[34:49]
	s_waitcnt vmcnt(18)
	ds_write_b128 v0, v[86:89] offset:41472
	v_mfma_f32_32x32x16_bf16 v[18:33], v[180:183], v[188:191], v[18:33]
	s_waitcnt vmcnt(17)
	ds_write_b128 v0, v[90:93] offset:46080
	v_mfma_f32_32x32x16_bf16 v[2:17], v[180:183], v[216:219], v[2:17]
	s_waitcnt vmcnt(16)
	ds_write_b128 v0, v[106:109] offset:50688
	ds_read_b128 v[146:149], v173 offset:64
	ds_read_b128 v[180:183], v173 offset:4672
	ds_read_b128 v[188:191], v174 offset:18496
	ds_read_b128 v[216:219], v174 offset:23104
	s_waitcnt lgkmcnt(9)
	v_mfma_f32_32x32x16_bf16 v[50:65], v[176:179], v[212:215], v[50:65]
	s_waitcnt vmcnt(15)
	ds_write_b128 v0, v[118:121] offset:55296
	s_waitcnt lgkmcnt(9)
	v_mfma_f32_32x32x16_bf16 v[34:49], v[176:179], v[220:223], v[34:49]
	s_waitcnt vmcnt(14)
	ds_write_b128 v0, v[126:129] offset:59904
	v_mfma_f32_32x32x16_bf16 v[18:33], v[184:187], v[212:215], v[18:33]
	s_waitcnt vmcnt(13)
	ds_write_b128 v0, v[130:133] offset:64512
	v_mfma_f32_32x32x16_bf16 v[2:17], v[184:187], v[220:223], v[2:17]
	s_waitcnt vmcnt(12)
	ds_write_b128 v175, v[138:141] offset:13824
	ds_read_b128 v[176:179], v173 offset:96
	ds_read_b128 v[184:187], v173 offset:4704
	ds_read_b128 v[212:215], v174 offset:18528
	ds_read_b128 v[220:223], v174 offset:23136
	s_waitcnt lgkmcnt(9)
	v_mfma_f32_32x32x16_bf16 v[50:65], v[146:149], v[188:191], v[50:65]
	global_load_dwordx4 v[118:121], v[150:151], off offset:1408
	global_load_dwordx4 v[126:129], v[152:153], off offset:1408
	s_waitcnt lgkmcnt(8)
	v_mfma_f32_32x32x16_bf16 v[34:49], v[146:149], v[216:219], v[34:49]
	global_load_dwordx4 v[130:133], v[154:155], off offset:1408
	global_load_dwordx4 v[138:141], v[156:157], off offset:1408
	v_mfma_f32_32x32x16_bf16 v[18:33], v[180:183], v[188:191], v[18:33]
	global_load_dwordx4 v[78:81], v[158:159], off offset:1536
	global_load_dwordx4 v[86:89], v[160:161], off offset:1536
	v_mfma_f32_32x32x16_bf16 v[2:17], v[180:183], v[216:219], v[2:17]
	global_load_dwordx4 v[90:93], v[162:163], off offset:1536
	global_load_dwordx4 v[106:109], v[164:165], off offset:1536
	s_waitcnt lgkmcnt(1)
	v_mfma_f32_32x32x16_bf16 v[50:65], v[176:179], v[212:215], v[50:65]
	s_waitcnt lgkmcnt(0)
	v_mfma_f32_32x32x16_bf16 v[34:49], v[176:179], v[220:223], v[34:49]
	v_mfma_f32_32x32x16_bf16 v[18:33], v[184:187], v[212:215], v[18:33]
	v_mfma_f32_32x32x16_bf16 v[2:17], v[184:187], v[220:223], v[2:17]
	s_waitcnt lgkmcnt(0)
	s_setprio 0
	s_barrier
	s_setprio 2
	ds_read_b128 v[146:149], v173 offset:36864
	ds_read_b128 v[180:183], v173 offset:41472
	ds_read_b128 v[188:191], v174 offset:55296
	ds_read_b128 v[216:219], v174 offset:59904
	ds_read_b128 v[176:179], v173 offset:36896
	ds_read_b128 v[184:187], v173 offset:41504
	ds_read_b128 v[212:215], v174 offset:55328
	ds_read_b128 v[220:223], v174 offset:59936
	s_waitcnt lgkmcnt(5)
	v_mfma_f32_32x32x16_bf16 v[50:65], v[146:149], v[188:191], v[50:65]
	s_waitcnt vmcnt(19)
	ds_write_b128 v0, v[66:69]
	s_waitcnt lgkmcnt(5)
	v_mfma_f32_32x32x16_bf16 v[34:49], v[146:149], v[216:219], v[34:49]
	s_waitcnt vmcnt(18)
	ds_write_b128 v0, v[70:73] offset:4608
	v_mfma_f32_32x32x16_bf16 v[18:33], v[180:183], v[188:191], v[18:33]
	s_waitcnt vmcnt(17)
	ds_write_b128 v0, v[74:77] offset:9216
	v_mfma_f32_32x32x16_bf16 v[2:17], v[180:183], v[216:219], v[2:17]
	s_waitcnt vmcnt(16)
	ds_write_b128 v0, v[110:113] offset:13824
	ds_read_b128 v[146:149], v173 offset:36928
	ds_read_b128 v[180:183], v173 offset:41536
	ds_read_b128 v[188:191], v174 offset:55360
	ds_read_b128 v[216:219], v174 offset:59968
	s_waitcnt lgkmcnt(9)
	v_mfma_f32_32x32x16_bf16 v[50:65], v[176:179], v[212:215], v[50:65]
	s_waitcnt vmcnt(15)
	ds_write_b128 v0, v[114:117] offset:18432
	s_waitcnt lgkmcnt(9)
	v_mfma_f32_32x32x16_bf16 v[34:49], v[176:179], v[220:223], v[34:49]
	s_waitcnt vmcnt(14)
	ds_write_b128 v0, v[122:125] offset:23040
	v_mfma_f32_32x32x16_bf16 v[18:33], v[184:187], v[212:215], v[18:33]
	s_waitcnt vmcnt(13)
	ds_write_b128 v0, v[134:137] offset:27648
	v_mfma_f32_32x32x16_bf16 v[2:17], v[184:187], v[220:223], v[2:17]
	s_waitcnt vmcnt(12)
	ds_write_b128 v0, v[142:145] offset:32256
	ds_read_b128 v[176:179], v173 offset:36960
	ds_read_b128 v[184:187], v173 offset:41568
	ds_read_b128 v[212:215], v174 offset:55392
	ds_read_b128 v[220:223], v174 offset:60000
	s_waitcnt lgkmcnt(9)
	v_mfma_f32_32x32x16_bf16 v[50:65], v[146:149], v[188:191], v[50:65]
	global_load_dwordx4 v[114:117], v[150:151], off offset:1536
	global_load_dwordx4 v[122:125], v[152:153], off offset:1536
	s_waitcnt lgkmcnt(8)
	v_mfma_f32_32x32x16_bf16 v[34:49], v[146:149], v[216:219], v[34:49]
	global_load_dwordx4 v[134:137], v[154:155], off offset:1536
	global_load_dwordx4 v[142:145], v[156:157], off offset:1536
	v_mfma_f32_32x32x16_bf16 v[18:33], v[180:183], v[188:191], v[18:33]
	global_load_dwordx4 v[66:69], v[158:159], off offset:1664
	global_load_dwordx4 v[70:73], v[160:161], off offset:1664
	v_mfma_f32_32x32x16_bf16 v[2:17], v[180:183], v[216:219], v[2:17]
	global_load_dwordx4 v[74:77], v[162:163], off offset:1664
	global_load_dwordx4 v[110:113], v[164:165], off offset:1664
	s_waitcnt lgkmcnt(1)
	v_mfma_f32_32x32x16_bf16 v[50:65], v[176:179], v[212:215], v[50:65]
	s_waitcnt lgkmcnt(0)
	v_mfma_f32_32x32x16_bf16 v[34:49], v[176:179], v[220:223], v[34:49]
	v_mfma_f32_32x32x16_bf16 v[18:33], v[184:187], v[212:215], v[18:33]
	v_mfma_f32_32x32x16_bf16 v[2:17], v[184:187], v[220:223], v[2:17]
	s_waitcnt lgkmcnt(0)
	s_setprio 0
	s_barrier
	s_setprio 2
	ds_read_b128 v[146:149], v173
	ds_read_b128 v[180:183], v173 offset:4608
	ds_read_b128 v[188:191], v174 offset:18432
	ds_read_b128 v[216:219], v174 offset:23040
	ds_read_b128 v[176:179], v173 offset:32
	ds_read_b128 v[184:187], v173 offset:4640
	ds_read_b128 v[212:215], v174 offset:18464
	ds_read_b128 v[220:223], v174 offset:23072
	s_waitcnt lgkmcnt(5)
	v_mfma_f32_32x32x16_bf16 v[50:65], v[146:149], v[188:191], v[50:65]
	s_waitcnt vmcnt(19)
	ds_write_b128 v0, v[82:85] offset:36864
	s_waitcnt lgkmcnt(5)
	v_mfma_f32_32x32x16_bf16 v[34:49], v[146:149], v[216:219], v[34:49]
	s_waitcnt vmcnt(18)
	ds_write_b128 v0, v[94:97] offset:41472
	v_mfma_f32_32x32x16_bf16 v[18:33], v[180:183], v[188:191], v[18:33]
	s_waitcnt vmcnt(17)
	ds_write_b128 v0, v[98:101] offset:46080
	v_mfma_f32_32x32x16_bf16 v[2:17], v[180:183], v[216:219], v[2:17]
	s_waitcnt vmcnt(16)
	ds_write_b128 v0, v[102:105] offset:50688
	ds_read_b128 v[146:149], v173 offset:64
	ds_read_b128 v[180:183], v173 offset:4672
	ds_read_b128 v[188:191], v174 offset:18496
	ds_read_b128 v[216:219], v174 offset:23104
	s_waitcnt lgkmcnt(9)
	v_mfma_f32_32x32x16_bf16 v[50:65], v[176:179], v[212:215], v[50:65]
	s_waitcnt vmcnt(15)
	ds_write_b128 v0, v[118:121] offset:55296
	s_waitcnt lgkmcnt(9)
	v_mfma_f32_32x32x16_bf16 v[34:49], v[176:179], v[220:223], v[34:49]
	s_waitcnt vmcnt(14)
	ds_write_b128 v0, v[126:129] offset:59904
	v_mfma_f32_32x32x16_bf16 v[18:33], v[184:187], v[212:215], v[18:33]
	s_waitcnt vmcnt(13)
	ds_write_b128 v0, v[130:133] offset:64512
	v_mfma_f32_32x32x16_bf16 v[2:17], v[184:187], v[220:223], v[2:17]
	s_waitcnt vmcnt(12)
	ds_write_b128 v175, v[138:141] offset:13824
	ds_read_b128 v[176:179], v173 offset:96
	ds_read_b128 v[184:187], v173 offset:4704
	ds_read_b128 v[212:215], v174 offset:18528
	ds_read_b128 v[220:223], v174 offset:23136
	s_waitcnt lgkmcnt(9)
	v_mfma_f32_32x32x16_bf16 v[50:65], v[146:149], v[188:191], v[50:65]
	global_load_dwordx4 v[118:121], v[150:151], off offset:1664
	global_load_dwordx4 v[126:129], v[152:153], off offset:1664
	s_waitcnt lgkmcnt(8)
	v_mfma_f32_32x32x16_bf16 v[34:49], v[146:149], v[216:219], v[34:49]
	global_load_dwordx4 v[130:133], v[154:155], off offset:1664
	global_load_dwordx4 v[138:141], v[156:157], off offset:1664
	v_mfma_f32_32x32x16_bf16 v[18:33], v[180:183], v[188:191], v[18:33]
	global_load_dwordx4 v[82:85], v[158:159], off offset:1792
	global_load_dwordx4 v[94:97], v[160:161], off offset:1792
	v_mfma_f32_32x32x16_bf16 v[2:17], v[180:183], v[216:219], v[2:17]
	global_load_dwordx4 v[98:101], v[162:163], off offset:1792
	global_load_dwordx4 v[102:105], v[164:165], off offset:1792
	s_waitcnt lgkmcnt(1)
	v_mfma_f32_32x32x16_bf16 v[50:65], v[176:179], v[212:215], v[50:65]
	s_waitcnt lgkmcnt(0)
	v_mfma_f32_32x32x16_bf16 v[34:49], v[176:179], v[220:223], v[34:49]
	v_mfma_f32_32x32x16_bf16 v[18:33], v[184:187], v[212:215], v[18:33]
	v_mfma_f32_32x32x16_bf16 v[2:17], v[184:187], v[220:223], v[2:17]
	s_waitcnt lgkmcnt(0)
	s_setprio 0
	s_barrier
	s_waitcnt vmcnt(19)
	ds_write_b128 v0, v[78:81]
	s_waitcnt vmcnt(18)
	ds_write_b128 v0, v[86:89] offset:4608
	s_waitcnt vmcnt(17)
	ds_write_b128 v0, v[90:93] offset:9216
	s_waitcnt vmcnt(16)
	ds_write_b128 v0, v[106:109] offset:13824
	s_waitcnt vmcnt(15)
	ds_write_b128 v0, v[114:117] offset:18432
	s_waitcnt vmcnt(14)
	ds_write_b128 v0, v[122:125] offset:23040
	s_waitcnt vmcnt(13)
	ds_write_b128 v0, v[134:137] offset:27648
	s_waitcnt vmcnt(12)
	ds_write_b128 v0, v[142:145] offset:32256
	global_load_dwordx4 v[114:117], v[150:151], off offset:1792
	global_load_dwordx4 v[122:125], v[152:153], off offset:1792
	global_load_dwordx4 v[134:137], v[154:155], off offset:1792
	global_load_dwordx4 v[142:145], v[156:157], off offset:1792
	global_load_dwordx4 v[78:81], v[158:159], off offset:1920
	global_load_dwordx4 v[86:89], v[160:161], off offset:1920
	global_load_dwordx4 v[90:93], v[162:163], off offset:1920
	global_load_dwordx4 v[106:109], v[164:165], off offset:1920
	s_setprio 2
	ds_read_b128 v[146:149], v173 offset:36864
	ds_read_b128 v[158:161], v173 offset:36896
	ds_read_b128 v[162:165], v173 offset:41472
	ds_read_b128 v[176:179], v173 offset:41504
	ds_read_b128 v[180:183], v174 offset:55296
	ds_read_b128 v[184:187], v174 offset:55328
	ds_read_b128 v[188:191], v174 offset:59904
	ds_read_b128 v[212:215], v174 offset:59936
	s_waitcnt lgkmcnt(3)
	v_mfma_f32_32x32x16_bf16 v[50:65], v[146:149], v[180:183], v[50:65]
	s_waitcnt lgkmcnt(1)
	v_mfma_f32_32x32x16_bf16 v[34:49], v[146:149], v[188:191], v[34:49]
	v_mfma_f32_32x32x16_bf16 v[18:33], v[162:165], v[180:183], v[18:33]
	v_mfma_f32_32x32x16_bf16 v[2:17], v[162:165], v[188:191], v[2:17]
	ds_read_b128 v[146:149], v173 offset:36928
	ds_read_b128 v[162:165], v173 offset:41536
	ds_read_b128 v[180:183], v174 offset:55360
	ds_read_b128 v[188:191], v174 offset:59968
	v_mfma_f32_32x32x16_bf16 v[50:65], v[158:161], v[184:187], v[50:65]
	s_waitcnt lgkmcnt(4)
	v_mfma_f32_32x32x16_bf16 v[34:49], v[158:161], v[212:215], v[34:49]
	v_mfma_f32_32x32x16_bf16 v[18:33], v[176:179], v[184:187], v[18:33]
	v_mfma_f32_32x32x16_bf16 v[2:17], v[176:179], v[212:215], v[2:17]
	ds_read_b128 v[158:161], v173 offset:36960
	ds_read_b128 v[176:179], v173 offset:41568
	ds_read_b128 v[184:187], v174 offset:55392
	ds_read_b128 v[212:215], v174 offset:60000
	s_waitcnt lgkmcnt(5)
	v_mfma_f32_32x32x16_bf16 v[50:65], v[146:149], v[180:183], v[50:65]
	s_waitcnt lgkmcnt(4)
	v_mfma_f32_32x32x16_bf16 v[34:49], v[146:149], v[188:191], v[34:49]
	v_mfma_f32_32x32x16_bf16 v[18:33], v[162:165], v[180:183], v[18:33]
	v_mfma_f32_32x32x16_bf16 v[2:17], v[162:165], v[188:191], v[2:17]
	s_waitcnt lgkmcnt(1)
	v_mfma_f32_32x32x16_bf16 v[50:65], v[158:161], v[184:187], v[50:65]
	s_waitcnt lgkmcnt(0)
	v_mfma_f32_32x32x16_bf16 v[34:49], v[158:161], v[212:215], v[34:49]
	v_mfma_f32_32x32x16_bf16 v[18:33], v[176:179], v[184:187], v[18:33]
	v_mfma_f32_32x32x16_bf16 v[2:17], v[176:179], v[212:215], v[2:17]
	s_setprio 0
	s_barrier
	s_waitcnt vmcnt(19)
	ds_write_b128 v0, v[66:69] offset:36864
	s_waitcnt vmcnt(18)
	ds_write_b128 v0, v[70:73] offset:41472
	s_waitcnt vmcnt(17)
	ds_write_b128 v0, v[74:77] offset:46080
	s_waitcnt vmcnt(16)
	ds_write_b128 v0, v[110:113] offset:50688
	s_waitcnt vmcnt(15)
	ds_write_b128 v0, v[118:121] offset:55296
	s_waitcnt vmcnt(14)
	ds_write_b128 v0, v[126:129] offset:59904
	s_waitcnt vmcnt(13)
	ds_write_b128 v0, v[130:133] offset:64512
	s_waitcnt vmcnt(12)
	ds_write_b128 v175, v[138:141] offset:13824
	global_load_dwordx4 v[66:69], v[150:151], off offset:1920
	global_load_dwordx4 v[70:73], v[152:153], off offset:1920
	global_load_dwordx4 v[74:77], v[154:155], off offset:1920
	global_load_dwordx4 v[110:113], v[156:157], off offset:1920
	s_setprio 2
	ds_read_b128 v[118:121], v173
	ds_read_b128 v[126:129], v173 offset:32
	ds_read_b128 v[130:133], v173 offset:4608
	ds_read_b128 v[138:141], v173 offset:4640
	ds_read_b128 v[146:149], v174 offset:18432
	ds_read_b128 v[150:153], v174 offset:18464
	ds_read_b128 v[154:157], v174 offset:23040
	ds_read_b128 v[158:161], v174 offset:23072
	s_waitcnt lgkmcnt(3)
	v_mfma_f32_32x32x16_bf16 v[50:65], v[118:121], v[146:149], v[50:65]
	s_waitcnt lgkmcnt(1)
	v_mfma_f32_32x32x16_bf16 v[34:49], v[118:121], v[154:157], v[34:49]
	v_mfma_f32_32x32x16_bf16 v[18:33], v[130:133], v[146:149], v[18:33]
	v_mfma_f32_32x32x16_bf16 v[2:17], v[130:133], v[154:157], v[2:17]
	ds_read_b128 v[118:121], v173 offset:64
	ds_read_b128 v[130:133], v173 offset:4672
	ds_read_b128 v[146:149], v174 offset:18496
	ds_read_b128 v[154:157], v174 offset:23104
	v_mfma_f32_32x32x16_bf16 v[50:65], v[126:129], v[150:153], v[50:65]
	s_waitcnt lgkmcnt(4)
	v_mfma_f32_32x32x16_bf16 v[34:49], v[126:129], v[158:161], v[34:49]
	v_mfma_f32_32x32x16_bf16 v[18:33], v[138:141], v[150:153], v[18:33]
	v_mfma_f32_32x32x16_bf16 v[2:17], v[138:141], v[158:161], v[2:17]
	ds_read_b128 v[126:129], v173 offset:96
	ds_read_b128 v[138:141], v173 offset:4704
	ds_read_b128 v[150:153], v174 offset:18528
	ds_read_b128 v[158:161], v174 offset:23136
	s_waitcnt lgkmcnt(5)
	v_mfma_f32_32x32x16_bf16 v[50:65], v[118:121], v[146:149], v[50:65]
	s_waitcnt lgkmcnt(4)
	v_mfma_f32_32x32x16_bf16 v[34:49], v[118:121], v[154:157], v[34:49]
	v_mfma_f32_32x32x16_bf16 v[18:33], v[130:133], v[146:149], v[18:33]
	v_mfma_f32_32x32x16_bf16 v[2:17], v[130:133], v[154:157], v[2:17]
	s_waitcnt lgkmcnt(1)
	v_mfma_f32_32x32x16_bf16 v[50:65], v[126:129], v[150:153], v[50:65]
	s_waitcnt lgkmcnt(0)
	v_mfma_f32_32x32x16_bf16 v[34:49], v[126:129], v[158:161], v[34:49]
	v_mfma_f32_32x32x16_bf16 v[18:33], v[138:141], v[150:153], v[18:33]
	v_mfma_f32_32x32x16_bf16 v[2:17], v[138:141], v[158:161], v[2:17]
	s_setprio 0
	s_barrier
	s_setprio 2
	s_waitcnt vmcnt(15)
	ds_write_b128 v0, v[82:85]
	s_waitcnt vmcnt(14)
	ds_write_b128 v0, v[94:97] offset:4608
	s_waitcnt vmcnt(13)
	ds_write_b128 v0, v[98:101] offset:9216
	s_waitcnt vmcnt(12)
	ds_write_b128 v0, v[102:105] offset:13824
	s_waitcnt vmcnt(11)
	ds_write_b128 v0, v[114:117] offset:18432
	s_waitcnt vmcnt(10)
	ds_write_b128 v0, v[122:125] offset:23040
	ds_read_b128 v[82:85], v173 offset:36864
	ds_read_b128 v[98:101], v173 offset:41472
	ds_read_b128 v[114:117], v174 offset:55296
	ds_read_b128 v[122:125], v174 offset:59904
	ds_read_b128 v[94:97], v173 offset:36896
	ds_read_b128 v[102:105], v173 offset:41504
	ds_read_b128 v[118:121], v174 offset:55328
	ds_read_b128 v[126:129], v174 offset:59936
	s_waitcnt lgkmcnt(5)
	v_mfma_f32_32x32x16_bf16 v[50:65], v[82:85], v[114:117], v[50:65]
	s_waitcnt vmcnt(9)
	ds_write_b128 v0, v[134:137] offset:27648
	s_waitcnt lgkmcnt(5)
	v_mfma_f32_32x32x16_bf16 v[34:49], v[82:85], v[122:125], v[34:49]
	s_waitcnt vmcnt(8)
	ds_write_b128 v0, v[142:145] offset:32256
	v_mfma_f32_32x32x16_bf16 v[18:33], v[98:101], v[114:117], v[18:33]
	v_mfma_f32_32x32x16_bf16 v[2:17], v[98:101], v[122:125], v[2:17]
	ds_read_b128 v[82:85], v173 offset:36928
	ds_read_b128 v[98:101], v173 offset:41536
	ds_read_b128 v[114:117], v174 offset:55360
	ds_read_b128 v[122:125], v174 offset:59968
	s_waitcnt lgkmcnt(7)
	v_mfma_f32_32x32x16_bf16 v[50:65], v[94:97], v[118:121], v[50:65]
	s_waitcnt lgkmcnt(6)
	v_mfma_f32_32x32x16_bf16 v[34:49], v[94:97], v[126:129], v[34:49]
	v_mfma_f32_32x32x16_bf16 v[18:33], v[102:105], v[118:121], v[18:33]
	v_mfma_f32_32x32x16_bf16 v[2:17], v[102:105], v[126:129], v[2:17]
	ds_read_b128 v[94:97], v173 offset:36960
	ds_read_b128 v[102:105], v173 offset:41568
	ds_read_b128 v[118:121], v174 offset:55392
	ds_read_b128 v[126:129], v174 offset:60000
	s_waitcnt lgkmcnt(5)
	v_mfma_f32_32x32x16_bf16 v[50:65], v[82:85], v[114:117], v[50:65]
	s_waitcnt lgkmcnt(4)
	v_mfma_f32_32x32x16_bf16 v[34:49], v[82:85], v[122:125], v[34:49]
	v_mfma_f32_32x32x16_bf16 v[18:33], v[98:101], v[114:117], v[18:33]
	v_mfma_f32_32x32x16_bf16 v[2:17], v[98:101], v[122:125], v[2:17]
	s_waitcnt lgkmcnt(1)
	v_mfma_f32_32x32x16_bf16 v[50:65], v[94:97], v[118:121], v[50:65]
	s_waitcnt lgkmcnt(0)
	v_mfma_f32_32x32x16_bf16 v[34:49], v[94:97], v[126:129], v[34:49]
	v_mfma_f32_32x32x16_bf16 v[18:33], v[102:105], v[118:121], v[18:33]
	v_mfma_f32_32x32x16_bf16 v[2:17], v[102:105], v[126:129], v[2:17]
	s_waitcnt lgkmcnt(0)
	s_setprio 0
	s_barrier
	s_setprio 2
	s_waitcnt vmcnt(7)
	ds_write_b128 v0, v[78:81] offset:36864
	s_waitcnt vmcnt(6)
	ds_write_b128 v0, v[86:89] offset:41472
	s_waitcnt vmcnt(5)
	ds_write_b128 v0, v[90:93] offset:46080
	s_waitcnt vmcnt(3)
	ds_write_b128 v0, v[66:69] offset:55296
	s_waitcnt vmcnt(2)
	ds_write_b128 v0, v[70:73] offset:59904
	s_waitcnt vmcnt(1)
	ds_write_b128 v0, v[74:77] offset:64512
	ds_read_b128 v[66:69], v173
	ds_read_b128 v[74:77], v173 offset:4608
	ds_read_b128 v[82:85], v174 offset:18432
	ds_read_b128 v[90:93], v174 offset:23040
	ds_read_b128 v[70:73], v173 offset:32
	ds_read_b128 v[78:81], v173 offset:4640
	ds_read_b128 v[86:89], v174 offset:18464
	ds_read_b128 v[94:97], v174 offset:23072
	s_waitcnt lgkmcnt(5)
	v_mfma_f32_32x32x16_bf16 v[50:65], v[66:69], v[82:85], v[50:65]
	s_waitcnt vmcnt(4)
	ds_write_b128 v0, v[106:109] offset:50688
	s_waitcnt lgkmcnt(5)
	v_mfma_f32_32x32x16_bf16 v[34:49], v[66:69], v[90:93], v[34:49]
	s_waitcnt vmcnt(0)
	ds_write_b128 v175, v[110:113] offset:13824
	v_mfma_f32_32x32x16_bf16 v[18:33], v[74:77], v[82:85], v[18:33]
	v_mfma_f32_32x32x16_bf16 v[2:17], v[74:77], v[90:93], v[2:17]
	ds_read_b128 v[66:69], v173 offset:64
	ds_read_b128 v[74:77], v173 offset:4672
	ds_read_b128 v[82:85], v174 offset:18496
	ds_read_b128 v[90:93], v174 offset:23104
	s_waitcnt lgkmcnt(7)
	v_mfma_f32_32x32x16_bf16 v[50:65], v[70:73], v[86:89], v[50:65]
	s_waitcnt lgkmcnt(6)
	v_mfma_f32_32x32x16_bf16 v[34:49], v[70:73], v[94:97], v[34:49]
	v_mfma_f32_32x32x16_bf16 v[18:33], v[78:81], v[86:89], v[18:33]
	v_mfma_f32_32x32x16_bf16 v[2:17], v[78:81], v[94:97], v[2:17]
	ds_read_b128 v[70:73], v173 offset:96
	ds_read_b128 v[78:81], v173 offset:4704
	ds_read_b128 v[86:89], v174 offset:18528
	ds_read_b128 v[94:97], v174 offset:23136
	s_waitcnt lgkmcnt(5)
	v_mfma_f32_32x32x16_bf16 v[50:65], v[66:69], v[82:85], v[50:65]
	s_waitcnt lgkmcnt(4)
	v_mfma_f32_32x32x16_bf16 v[34:49], v[66:69], v[90:93], v[34:49]
	v_mfma_f32_32x32x16_bf16 v[18:33], v[74:77], v[82:85], v[18:33]
	v_mfma_f32_32x32x16_bf16 v[2:17], v[74:77], v[90:93], v[2:17]
	s_waitcnt lgkmcnt(1)
	v_mfma_f32_32x32x16_bf16 v[50:65], v[70:73], v[86:89], v[50:65]
	s_waitcnt lgkmcnt(0)
	v_mfma_f32_32x32x16_bf16 v[34:49], v[70:73], v[94:97], v[34:49]
	v_mfma_f32_32x32x16_bf16 v[18:33], v[78:81], v[86:89], v[18:33]
	v_mfma_f32_32x32x16_bf16 v[2:17], v[78:81], v[94:97], v[2:17]
	s_waitcnt lgkmcnt(0)
	s_setprio 0
	s_barrier
	s_setprio 2
	ds_read_b128 v[66:69], v173 offset:36864
	ds_read_b128 v[70:73], v173 offset:36896
	ds_read_b128 v[74:77], v173 offset:41472
	ds_read_b128 v[78:81], v173 offset:41504
	ds_read_b128 v[82:85], v174 offset:55296
	ds_read_b128 v[86:89], v174 offset:55328
	ds_read_b128 v[90:93], v174 offset:59904
	ds_read_b128 v[94:97], v174 offset:59936
	s_waitcnt lgkmcnt(3)
	v_mfma_f32_32x32x16_bf16 v[50:65], v[66:69], v[82:85], v[50:65]
	s_waitcnt lgkmcnt(1)
	v_mfma_f32_32x32x16_bf16 v[34:49], v[66:69], v[90:93], v[34:49]
	v_mfma_f32_32x32x16_bf16 v[18:33], v[74:77], v[82:85], v[18:33]
	v_mfma_f32_32x32x16_bf16 v[2:17], v[74:77], v[90:93], v[2:17]
	ds_read_b128 v[66:69], v173 offset:36928
	ds_read_b128 v[74:77], v173 offset:41536
	ds_read_b128 v[82:85], v174 offset:55360
	ds_read_b128 v[90:93], v174 offset:59968
	v_mfma_f32_32x32x16_bf16 v[50:65], v[70:73], v[86:89], v[50:65]
	s_waitcnt lgkmcnt(4)
	v_mfma_f32_32x32x16_bf16 v[34:49], v[70:73], v[94:97], v[34:49]
	v_mfma_f32_32x32x16_bf16 v[18:33], v[78:81], v[86:89], v[18:33]
	v_mfma_f32_32x32x16_bf16 v[2:17], v[78:81], v[94:97], v[2:17]
	ds_read_b128 v[70:73], v173 offset:36960
	ds_read_b128 v[78:81], v173 offset:41568
	ds_read_b128 v[86:89], v174 offset:55392
	ds_read_b128 v[94:97], v174 offset:60000
	s_waitcnt lgkmcnt(5)
	v_mfma_f32_32x32x16_bf16 v[50:65], v[66:69], v[82:85], v[50:65]
	s_waitcnt lgkmcnt(4)
	v_mfma_f32_32x32x16_bf16 v[34:49], v[66:69], v[90:93], v[34:49]
	v_mfma_f32_32x32x16_bf16 v[18:33], v[74:77], v[82:85], v[18:33]
	v_mfma_f32_32x32x16_bf16 v[2:17], v[74:77], v[90:93], v[2:17]
	s_waitcnt lgkmcnt(1)
	v_mfma_f32_32x32x16_bf16 v[50:65], v[70:73], v[86:89], v[50:65]
	s_waitcnt lgkmcnt(0)
	v_mfma_f32_32x32x16_bf16 v[34:49], v[70:73], v[94:97], v[34:49]
	v_mfma_f32_32x32x16_bf16 v[18:33], v[78:81], v[86:89], v[18:33]
	v_mfma_f32_32x32x16_bf16 v[2:17], v[78:81], v[94:97], v[2:17]
	s_setprio 0
	v_cmp_lt_u32_e32 vcc, 19, v168
	s_barrier
	v_mov_b32 v96, v194
	s_and_b64 vcc, exec, vcc
	v_and_b32_e32 v113, 31, v96
	v_bfe_u32 v112, v96, 5, 1
	v_ashrrev_i32_e32 v114, 7, v96
	v_bfe_u32 v115, v96, 6, 1
	s_mov_b64 s[10:11], -1
	s_cbranch_vccz .LBB0_2293
	s_load_dwordx2 s[80:81], s[48:49], 0x100
	v_cmp_lt_u32_e32 vcc, 51, v168
	v_cmp_gt_u32_e64 s[42:43], 32, v172
	s_cbranch_vccz .LBB0_1587
	s_movk_i32 s6, 0x43
	v_cmp_lt_u32_e32 vcc, s6, v168
	s_cbranch_vccz .LBB0_1521
	v_cmp_eq_u32_e32 vcc, 0, v115
	s_and_saveexec_b64 s[10:11], vcc
	s_cbranch_execz .LBB0_1520
	v_and_b32_e32 v0, 7, v96
	v_cvt_f32_ubyte0_e32 v68, v0
	v_mul_f32_e32 v0, 0xbfd49a78, v68
	s_mov_b32 s6, 0xc2fc0000
	v_cmp_gt_f32_e64 s[46:47], s6, v0
	v_and_b32_e32 v0, 8, v96
	v_lshl_add_u32 v77, v114, 6, v167
	v_cmp_eq_u32_e64 s[40:41], 0, v0
	v_lshlrev_b32_e32 v74, 2, v112
	v_lshlrev_b32_e32 v0, 1, v113
	v_ashrrev_i32_e32 v67, 7, v77
	v_or_b32_e32 v66, v77, v74
	v_lshl_add_u64 v[72:73], s[68:69], 0, v[0:1]
	v_cmp_gt_u32_e64 s[44:45], 16, v113
	s_mov_b64 s[12:13], -1
	s_and_b64 vcc, exec, s[42:43]
	v_and_b32_e32 v76, -2, v67
	v_lshlrev_b32_e32 v70, 2, v113
	s_cbranch_vccz .LBB0_1394
	v_ashrrev_i32_e32 v67, 31, v66
	v_lshlrev_b64 v[78:79], 6, v[66:67]
	v_cvt_pk_bf16_f32 v69, v50, s0
	v_lshl_add_u64 v[78:79], v[72:73], 0, v[78:79]
	global_store_short v[78:79], v69, off
	v_add_u32_e32 v78, s0, v76
	v_ashrrev_i32_e32 v79, 31, v78
	v_lshlrev_b64 v[78:79], 15, v[78:79]
	v_lshlrev_b32_e32 v67, 7, v66
	s_waitcnt lgkmcnt(0)
	v_lshl_add_u64 v[78:79], s[80:81], 0, v[78:79]
	v_and_b32_e32 v80, 0x6200, v67
	v_mov_b32_e32 v81, v1
	v_lshl_add_u64 v[78:79], v[78:79], 0, v[80:81]
	v_mov_b32_e32 v71, v1
	v_lshl_add_u64 v[78:79], v[78:79], 0, v[70:71]
	v_add_co_u32_e32 v78, vcc, 0x3800000, v78
	s_mov_b64 s[12:13], 0
	s_nop 0
	v_addc_co_u32_e32 v79, vcc, 0, v79, vcc
	global_store_dword v[78:79], v50, off

.LBB0_2301:
	s_lshr_b32 s2, s16, 3
	s_and_b32 s2, s2, 12
	v_readlane_b32 s6, v246, 16
	s_add_i32 s6, s2, s6
	s_and_b32 s2, s16, 3
	s_or_b32 s2, s6, s2
	s_lshl_b32 s10, s2, 7
	s_add_i32 s11, s10, 0xfffff000
	s_lshr_b32 s11, s11, 11
	s_add_i32 s11, s11, 1
	s_cmp_gt_u32 s6, 31
	s_cselect_b32 s6, s11, 0
	v_readlane_b32 s11, v246, 28
	s_add_i32 s6, s6, s11
	s_mul_hi_i32 s11, s6, 9
	s_mul_i32 s6, s6, 9
	s_add_u32 s48, s6, s12
	s_addc_u32 s49, s11, 0
	s_and_b32 s11, s15, 0x380
	v_mov_b32 v66, v194
	s_waitcnt vmcnt(0) lgkmcnt(0)
	v_mov_b64_e32 v[2:3], s[46:47]
	v_ashrrev_i32_e32 v67, 3, v66
	v_add_u32_e32 v0, s11, v67
	v_mad_i64_i32 v[2:3], s[18:19], v0, s4, v[2:3]
	v_lshlrev_b32_e32 v0, 4, v66
	v_and_b32_e32 v0, 0x70, v0
	v_lshl_add_u64 v[172:173], v[2:3], 0, v[0:1]
	v_add_u32_e32 v4, s10, v67
	v_mov_b64_e32 v[2:3], s[42:43]
	v_mad_i64_i32 v[2:3], s[18:19], v4, s4, v[2:3]
	v_lshl_add_u64 v[174:175], v[2:3], 0, v[0:1]
	s_mov_b32 s17, 0x2c000
	v_add_co_u32_e32 v182, vcc, s17, v174
	s_mov_b32 s18, 0x58000
	s_nop 0
	v_addc_co_u32_e32 v183, vcc, 0, v175, vcc
	v_add_co_u32_e32 v164, vcc, s5, v174
	s_mov_b32 s19, 0x59000
	s_nop 0
	v_addc_co_u32_e32 v165, vcc, 0, v175, vcc
	v_add_co_u32_e32 v184, vcc, s18, v174
	s_mov_b32 s6, 0x84000
	s_nop 0
	v_addc_co_u32_e32 v185, vcc, 0, v175, vcc
	v_add_co_u32_e32 v166, vcc, s19, v174
	s_mov_b32 s20, 0x85000
	s_nop 0
	v_addc_co_u32_e32 v167, vcc, 0, v175, vcc
	v_add_co_u32_e32 v186, vcc, s6, v174
	s_nop 1
	v_addc_co_u32_e32 v187, vcc, 0, v175, vcc
	v_add_co_u32_e32 v168, vcc, s20, v174
	s_barrier
	s_nop 0
	v_addc_co_u32_e32 v169, vcc, 0, v175, vcc
	v_add_co_u32_e32 v176, vcc, s17, v172
	s_nop 1
	v_addc_co_u32_e32 v177, vcc, 0, v173, vcc
	v_add_co_u32_e32 v158, vcc, s5, v172
	s_nop 1
	v_addc_co_u32_e32 v159, vcc, 0, v173, vcc
	v_add_co_u32_e32 v178, vcc, s18, v172
	s_barrier
	s_nop 0
	v_addc_co_u32_e32 v179, vcc, 0, v173, vcc
	v_add_co_u32_e32 v160, vcc, s19, v172
	global_load_dwordx4 v[2:5], v[174:175], off
	global_load_dwordx4 v[6:9], v[164:165], off offset:-4096
	global_load_dwordx4 v[10:13], v[166:167], off offset:-4096
	global_load_dwordx4 v[14:17], v[168:169], off offset:-4096
	global_load_dwordx4 v[18:21], v[172:173], off
	v_addc_co_u32_e32 v161, vcc, 0, v173, vcc
	v_add_co_u32_e32 v180, vcc, s6, v172
	global_load_dwordx4 v[22:25], v[158:159], off offset:-4096
	global_load_dwordx4 v[26:29], v[160:161], off offset:-4096
	v_addc_co_u32_e32 v181, vcc, 0, v173, vcc
	v_add_co_u32_e32 v162, vcc, s20, v172
	v_mul_lo_u32 v67, v67, s34
	s_nop 0
	v_addc_co_u32_e32 v163, vcc, 0, v173, vcc
	global_load_dwordx4 v[30:33], v[162:163], off offset:-4096
	global_load_dwordx4 v[34:37], v[174:175], off offset:128
	global_load_dwordx4 v[38:41], v[182:183], off offset:128
	global_load_dwordx4 v[42:45], v[184:185], off offset:128
	global_load_dwordx4 v[46:49], v[186:187], off offset:128
	global_load_dwordx4 v[50:53], v[172:173], off offset:128
	global_load_dwordx4 v[54:57], v[176:177], off offset:128
	global_load_dwordx4 v[58:61], v[178:179], off offset:128
	global_load_dwordx4 v[62:65], v[180:181], off offset:128
	global_load_dwordx4 v[94:97], v[174:175], off offset:256
	global_load_dwordx4 v[98:101], v[182:183], off offset:256
	global_load_dwordx4 v[102:105], v[184:185], off offset:256
	global_load_dwordx4 v[110:113], v[186:187], off offset:256
	v_add3_u32 v188, 16, v67, v0
	v_add_u32_e32 v189, 0xd800, v188
	v_and_b32_e32 v0, 31, v66
	s_waitcnt vmcnt(19)
	ds_write_b128 v188, v[2:5]
	s_waitcnt vmcnt(18)
	ds_write_b128 v188, v[6:9] offset:4608
	s_waitcnt vmcnt(17)
	ds_write_b128 v188, v[10:13] offset:9216
	s_waitcnt vmcnt(16)
	ds_write_b128 v188, v[14:17] offset:13824
	s_waitcnt vmcnt(15)
	ds_write_b128 v188, v[18:21] offset:18432
	s_waitcnt vmcnt(14)
	ds_write_b128 v188, v[22:25] offset:23040
	s_waitcnt vmcnt(13)
	ds_write_b128 v188, v[26:29] offset:27648
	s_waitcnt vmcnt(12)
	ds_write_b128 v188, v[30:33] offset:32256
	global_load_dwordx4 v[122:125], v[172:173], off offset:256
	global_load_dwordx4 v[134:137], v[176:177], off offset:256
	global_load_dwordx4 v[138:141], v[178:179], off offset:256
	global_load_dwordx4 v[142:145], v[180:181], off offset:256
	global_load_dwordx4 v[82:85], v[174:175], off offset:384
	global_load_dwordx4 v[86:89], v[182:183], off offset:384
	global_load_dwordx4 v[90:93], v[184:185], off offset:384
	global_load_dwordx4 v[106:109], v[186:187], off offset:384
	s_waitcnt lgkmcnt(0)
	s_barrier
	s_waitcnt vmcnt(19)
	ds_write_b128 v188, v[34:37] offset:36864
	s_waitcnt vmcnt(18)
	ds_write_b128 v188, v[38:41] offset:41472
	s_waitcnt vmcnt(17)
	ds_write_b128 v188, v[42:45] offset:46080
	s_waitcnt vmcnt(16)
	ds_write_b128 v188, v[46:49] offset:50688
	s_waitcnt vmcnt(15)
	ds_write_b128 v188, v[50:53] offset:55296
	s_waitcnt vmcnt(14)
	ds_write_b128 v188, v[54:57] offset:59904
	s_waitcnt vmcnt(13)
	ds_write_b128 v188, v[58:61] offset:64512
	s_waitcnt vmcnt(12)
	ds_write_b128 v189, v[62:65] offset:13824
	v_lshrrev_b32_e32 v2, 1, v66
	v_and_b32_e32 v3, 0x5f, v66
	global_load_dwordx4 v[114:117], v[172:173], off offset:384
	global_load_dwordx4 v[118:121], v[176:177], off offset:384
	global_load_dwordx4 v[126:129], v[178:179], off offset:384
	global_load_dwordx4 v[130:133], v[180:181], off offset:384
	global_load_dwordx4 v[66:69], v[174:175], off offset:512
	global_load_dwordx4 v[70:73], v[182:183], off offset:512
	global_load_dwordx4 v[74:77], v[184:185], off offset:512
	global_load_dwordx4 v[78:81], v[186:187], off offset:512
	v_and_or_b32 v0, v2, s64, v0
	v_mul_u32_u24_e32 v3, 0x48, v3
	v_mul_lo_u32 v0, v0, s34
	v_and_b32_e32 v2, 16, v2
	v_add3_u32 v0, 16, v0, v2
	v_lshlrev_b32_e32 v3, 1, v3
	v_add3_u32 v171, 16, v3, v2
	s_setprio 2
	ds_read_b128 v[2:5], v0
	ds_read_b128 v[146:149], v0 offset:32
	ds_read_b128 v[18:21], v0 offset:4608
	ds_read_b128 v[150:153], v0 offset:4640
	ds_read_b128 v[6:9], v171 offset:18432
	ds_read_b128 v[154:157], v171 offset:18464
	ds_read_b128 v[22:25], v171 offset:23040
	ds_read_b128 v[190:193], v171 offset:23072
	s_waitcnt lgkmcnt(3)
	v_mfma_f32_32x32x16_bf16 v[50:65], v[2:5], v[6:9], 0
	s_waitcnt lgkmcnt(1)
	v_mfma_f32_32x32x16_bf16 v[34:49], v[2:5], v[22:25], 0
	v_mfma_f32_32x32x16_bf16 v[2:17], v[18:21], v[6:9], 0
	v_mfma_f32_32x32x16_bf16 v[18:33], v[18:21], v[22:25], 0
	ds_read_b128 v[212:215], v0 offset:64
	ds_read_b128 v[216:219], v0 offset:4672
	ds_read_b128 v[220:223], v171 offset:18496
	ds_read_b128 v[224:227], v171 offset:23104
	s_waitcnt lgkmcnt(4)
	v_mfma_f32_32x32x16_bf16 v[34:49], v[146:149], v[190:193], v[34:49]
	v_mfma_f32_32x32x16_bf16 v[2:17], v[150:153], v[154:157], v[2:17]
	v_mfma_f32_32x32x16_bf16 v[18:33], v[150:153], v[190:193], v[18:33]
	v_mfma_f32_32x32x16_bf16 v[50:65], v[146:149], v[154:157], v[50:65]
	ds_read_b128 v[146:149], v0 offset:96
	ds_read_b128 v[150:153], v0 offset:4704
	ds_read_b128 v[154:157], v171 offset:18528
	ds_read_b128 v[190:193], v171 offset:23136
	s_waitcnt lgkmcnt(4)
	v_mfma_f32_32x32x16_bf16 v[34:49], v[212:215], v[224:227], v[34:49]
	v_mfma_f32_32x32x16_bf16 v[2:17], v[216:219], v[220:223], v[2:17]
	v_mfma_f32_32x32x16_bf16 v[18:33], v[216:219], v[224:227], v[18:33]
	v_mfma_f32_32x32x16_bf16 v[50:65], v[212:215], v[220:223], v[50:65]
	s_waitcnt lgkmcnt(0)
	v_mfma_f32_32x32x16_bf16 v[34:49], v[146:149], v[190:193], v[34:49]
	v_mfma_f32_32x32x16_bf16 v[2:17], v[150:153], v[154:157], v[2:17]
	v_mfma_f32_32x32x16_bf16 v[18:33], v[150:153], v[190:193], v[18:33]
	v_mfma_f32_32x32x16_bf16 v[50:65], v[146:149], v[154:157], v[50:65]
	s_setprio 0
	s_barrier
	s_setprio 2
	ds_read_b128 v[146:149], v0 offset:36864
	ds_read_b128 v[154:157], v0 offset:41472
	ds_read_b128 v[212:215], v171 offset:55296
	ds_read_b128 v[220:223], v171 offset:59904
	ds_read_b128 v[150:153], v0 offset:36896
	ds_read_b128 v[190:193], v0 offset:41504
	ds_read_b128 v[216:219], v171 offset:55328
	ds_read_b128 v[224:227], v171 offset:59936
	s_waitcnt lgkmcnt(4)
	v_mfma_f32_32x32x16_bf16 v[34:49], v[146:149], v[220:223], v[34:49]
	s_waitcnt vmcnt(19)
	ds_write_b128 v188, v[94:97]
	v_mfma_f32_32x32x16_bf16 v[2:17], v[154:157], v[212:215], v[2:17]
	s_waitcnt vmcnt(18)
	ds_write_b128 v188, v[98:101] offset:4608
	v_mfma_f32_32x32x16_bf16 v[18:33], v[154:157], v[220:223], v[18:33]
	s_waitcnt vmcnt(17)
	ds_write_b128 v188, v[102:105] offset:9216
	v_mfma_f32_32x32x16_bf16 v[50:65], v[146:149], v[212:215], v[50:65]
	s_waitcnt vmcnt(16)
	ds_write_b128 v188, v[110:113] offset:13824
	ds_read_b128 v[146:149], v0 offset:36928
	ds_read_b128 v[154:157], v0 offset:41536
	ds_read_b128 v[212:215], v171 offset:55360
	ds_read_b128 v[220:223], v171 offset:59968
	s_waitcnt lgkmcnt(8)
	v_mfma_f32_32x32x16_bf16 v[34:49], v[150:153], v[224:227], v[34:49]
	s_waitcnt vmcnt(15)
	ds_write_b128 v188, v[122:125] offset:18432
	v_mfma_f32_32x32x16_bf16 v[2:17], v[190:193], v[216:219], v[2:17]
	s_waitcnt vmcnt(14)
	ds_write_b128 v188, v[134:137] offset:23040
	v_mfma_f32_32x32x16_bf16 v[18:33], v[190:193], v[224:227], v[18:33]
	s_waitcnt vmcnt(13)
	ds_write_b128 v188, v[138:141] offset:27648
	v_mfma_f32_32x32x16_bf16 v[50:65], v[150:153], v[216:219], v[50:65]
	s_waitcnt vmcnt(12)
	ds_write_b128 v188, v[142:145] offset:32256
	ds_read_b128 v[150:153], v0 offset:36960
	ds_read_b128 v[190:193], v0 offset:41568
	ds_read_b128 v[216:219], v171 offset:55392
	ds_read_b128 v[224:227], v171 offset:60000
	s_waitcnt lgkmcnt(8)
	v_mfma_f32_32x32x16_bf16 v[34:49], v[146:149], v[220:223], v[34:49]
	global_load_dwordx4 v[122:125], v[172:173], off offset:512
	global_load_dwordx4 v[134:137], v[176:177], off offset:512
	v_mfma_f32_32x32x16_bf16 v[2:17], v[154:157], v[212:215], v[2:17]
	global_load_dwordx4 v[138:141], v[178:179], off offset:512
	global_load_dwordx4 v[142:145], v[180:181], off offset:512
	v_mfma_f32_32x32x16_bf16 v[18:33], v[154:157], v[220:223], v[18:33]
	global_load_dwordx4 v[94:97], v[174:175], off offset:640
	global_load_dwordx4 v[98:101], v[182:183], off offset:640
	v_mfma_f32_32x32x16_bf16 v[50:65], v[146:149], v[212:215], v[50:65]
	global_load_dwordx4 v[102:105], v[184:185], off offset:640
	global_load_dwordx4 v[110:113], v[186:187], off offset:640
	s_waitcnt lgkmcnt(0)
	v_mfma_f32_32x32x16_bf16 v[34:49], v[150:153], v[224:227], v[34:49]
	v_mfma_f32_32x32x16_bf16 v[2:17], v[190:193], v[216:219], v[2:17]
	v_mfma_f32_32x32x16_bf16 v[18:33], v[190:193], v[224:227], v[18:33]
	v_mfma_f32_32x32x16_bf16 v[50:65], v[150:153], v[216:219], v[50:65]
	s_waitcnt lgkmcnt(0)
	s_setprio 0
	s_barrier
	s_setprio 2
	s_waitcnt vmcnt(15)
	ds_write_b128 v188, v[114:117] offset:55296
	s_waitcnt vmcnt(12)
	ds_write_b128 v189, v[130:133] offset:13824
	ds_read_b128 v[114:117], v0
	ds_read_b128 v[154:157], v0 offset:4608
	ds_read_b128 v[212:215], v171 offset:18432
	ds_read_b128 v[220:223], v171 offset:23040
	ds_read_b128 v[130:133], v0 offset:32
	ds_read_b128 v[190:193], v0 offset:4640
	ds_read_b128 v[216:219], v171 offset:18464
	ds_read_b128 v[224:227], v171 offset:23072
	s_waitcnt lgkmcnt(4)
	v_mfma_f32_32x32x16_bf16 v[34:49], v[114:117], v[220:223], v[34:49]
	s_waitcnt vmcnt(19)
	ds_write_b128 v188, v[82:85] offset:36864
	v_mfma_f32_32x32x16_bf16 v[2:17], v[154:157], v[212:215], v[2:17]
	s_waitcnt vmcnt(18)
	ds_write_b128 v188, v[86:89] offset:41472
	v_mfma_f32_32x32x16_bf16 v[18:33], v[154:157], v[220:223], v[18:33]
	s_waitcnt vmcnt(17)
	ds_write_b128 v188, v[90:93] offset:46080
	v_mfma_f32_32x32x16_bf16 v[50:65], v[114:117], v[212:215], v[50:65]
	s_waitcnt vmcnt(16)
	ds_write_b128 v188, v[106:109] offset:50688
	ds_read_b128 v[114:117], v0 offset:64
	ds_read_b128 v[154:157], v0 offset:4672
	ds_read_b128 v[212:215], v171 offset:18496
	ds_read_b128 v[220:223], v171 offset:23104
	s_waitcnt lgkmcnt(8)
	v_mfma_f32_32x32x16_bf16 v[34:49], v[130:133], v[224:227], v[34:49]
	s_waitcnt vmcnt(14)
	ds_write_b128 v188, v[118:121] offset:59904
	v_mfma_f32_32x32x16_bf16 v[2:17], v[190:193], v[216:219], v[2:17]
	s_waitcnt vmcnt(13)
	ds_write_b128 v188, v[126:129] offset:64512
	v_mfma_f32_32x32x16_bf16 v[18:33], v[190:193], v[224:227], v[18:33]
	v_mfma_f32_32x32x16_bf16 v[50:65], v[130:133], v[216:219], v[50:65]
	ds_read_b128 v[130:133], v0 offset:96
	ds_read_b128 v[190:193], v0 offset:4704
	ds_read_b128 v[216:219], v171 offset:18528
	ds_read_b128 v[224:227], v171 offset:23136
	s_waitcnt lgkmcnt(6)
	v_mfma_f32_32x32x16_bf16 v[34:49], v[114:117], v[220:223], v[34:49]
	global_load_dwordx4 v[118:121], v[172:173], off offset:640
	global_load_dwordx4 v[126:129], v[176:177], off offset:640
	v_mfma_f32_32x32x16_bf16 v[2:17], v[154:157], v[212:215], v[2:17]
	global_load_dwordx4 v[146:149], v[178:179], off offset:640
	global_load_dwordx4 v[150:153], v[180:181], off offset:640
	v_mfma_f32_32x32x16_bf16 v[18:33], v[154:157], v[220:223], v[18:33]
	global_load_dwordx4 v[82:85], v[174:175], off offset:768
	global_load_dwordx4 v[86:89], v[182:183], off offset:768
	v_mfma_f32_32x32x16_bf16 v[50:65], v[114:117], v[212:215], v[50:65]
	global_load_dwordx4 v[90:93], v[184:185], off offset:768
	global_load_dwordx4 v[106:109], v[186:187], off offset:768
	s_waitcnt lgkmcnt(0)
	v_mfma_f32_32x32x16_bf16 v[34:49], v[130:133], v[224:227], v[34:49]
	v_mfma_f32_32x32x16_bf16 v[2:17], v[190:193], v[216:219], v[2:17]
	v_mfma_f32_32x32x16_bf16 v[18:33], v[190:193], v[224:227], v[18:33]
	v_mfma_f32_32x32x16_bf16 v[50:65], v[130:133], v[216:219], v[50:65]
	s_waitcnt lgkmcnt(0)
	s_setprio 0
	s_barrier
	s_setprio 2
	s_waitcnt vmcnt(16)
	ds_write_b128 v188, v[78:81] offset:13824
	s_waitcnt vmcnt(12)
	ds_write_b128 v188, v[142:145] offset:32256
	ds_read_b128 v[78:81], v0 offset:36864
	ds_read_b128 v[154:157], v0 offset:41472
	ds_read_b128 v[212:215], v171 offset:55296
	ds_read_b128 v[220:223], v171 offset:59904
	ds_read_b128 v[142:145], v0 offset:36896
	ds_read_b128 v[190:193], v0 offset:41504
	ds_read_b128 v[216:219], v171 offset:55328
	ds_read_b128 v[224:227], v171 offset:59936
	s_waitcnt lgkmcnt(4)
	v_mfma_f32_32x32x16_bf16 v[34:49], v[78:81], v[220:223], v[34:49]
	s_waitcnt vmcnt(19)
	ds_write_b128 v188, v[66:69]
	v_mfma_f32_32x32x16_bf16 v[2:17], v[154:157], v[212:215], v[2:17]
	s_waitcnt vmcnt(18)
	ds_write_b128 v188, v[70:73] offset:4608
	v_mfma_f32_32x32x16_bf16 v[18:33], v[154:157], v[220:223], v[18:33]
	s_waitcnt vmcnt(17)
	ds_write_b128 v188, v[74:77] offset:9216
	v_mfma_f32_32x32x16_bf16 v[50:65], v[78:81], v[212:215], v[50:65]
	s_waitcnt vmcnt(15)
	ds_write_b128 v188, v[122:125] offset:18432
	ds_read_b128 v[78:81], v0 offset:36928
	ds_read_b128 v[154:157], v0 offset:41536
	ds_read_b128 v[212:215], v171 offset:55360
	ds_read_b128 v[220:223], v171 offset:59968
	s_waitcnt lgkmcnt(8)
	v_mfma_f32_32x32x16_bf16 v[34:49], v[142:145], v[224:227], v[34:49]
	s_waitcnt vmcnt(14)
	ds_write_b128 v188, v[134:137] offset:23040
	v_mfma_f32_32x32x16_bf16 v[2:17], v[190:193], v[216:219], v[2:17]
	s_waitcnt vmcnt(13)
	ds_write_b128 v188, v[138:141] offset:27648
	v_mfma_f32_32x32x16_bf16 v[18:33], v[190:193], v[224:227], v[18:33]
	v_mfma_f32_32x32x16_bf16 v[50:65], v[142:145], v[216:219], v[50:65]
	ds_read_b128 v[142:145], v0 offset:36960
	ds_read_b128 v[190:193], v0 offset:41568
	ds_read_b128 v[216:219], v171 offset:55392
	ds_read_b128 v[224:227], v171 offset:60000
	s_waitcnt lgkmcnt(6)
	v_mfma_f32_32x32x16_bf16 v[34:49], v[78:81], v[220:223], v[34:49]
	global_load_dwordx4 v[122:125], v[172:173], off offset:768
	global_load_dwordx4 v[130:133], v[176:177], off offset:768
	v_mfma_f32_32x32x16_bf16 v[2:17], v[154:157], v[212:215], v[2:17]
	global_load_dwordx4 v[134:137], v[178:179], off offset:768
	global_load_dwordx4 v[138:141], v[180:181], off offset:768
	v_mfma_f32_32x32x16_bf16 v[18:33], v[154:157], v[220:223], v[18:33]
	global_load_dwordx4 v[66:69], v[174:175], off offset:896
	global_load_dwordx4 v[70:73], v[182:183], off offset:896
	v_mfma_f32_32x32x16_bf16 v[50:65], v[78:81], v[212:215], v[50:65]
	global_load_dwordx4 v[74:77], v[184:185], off offset:896
	global_load_dwordx4 v[114:117], v[186:187], off offset:896
	s_waitcnt lgkmcnt(0)
	v_mfma_f32_32x32x16_bf16 v[34:49], v[142:145], v[224:227], v[34:49]
	v_mfma_f32_32x32x16_bf16 v[2:17], v[190:193], v[216:219], v[2:17]
	v_mfma_f32_32x32x16_bf16 v[18:33], v[190:193], v[224:227], v[18:33]
	v_mfma_f32_32x32x16_bf16 v[50:65], v[142:145], v[216:219], v[50:65]
	s_waitcnt lgkmcnt(0)
	s_setprio 0
	s_barrier
	s_setprio 2
	s_waitcnt vmcnt(14)
	ds_write_b128 v188, v[126:129] offset:59904
	s_waitcnt vmcnt(12)
	ds_write_b128 v189, v[150:153] offset:13824
	ds_read_b128 v[126:129], v0
	ds_read_b128 v[154:157], v0 offset:4608
	ds_read_b128 v[212:215], v171 offset:18432
	ds_read_b128 v[220:223], v171 offset:23040
	ds_read_b128 v[150:153], v0 offset:32
	ds_read_b128 v[190:193], v0 offset:4640
	ds_read_b128 v[216:219], v171 offset:18464
	ds_read_b128 v[224:227], v171 offset:23072
	s_waitcnt lgkmcnt(4)
	v_mfma_f32_32x32x16_bf16 v[34:49], v[126:129], v[220:223], v[34:49]
	s_waitcnt vmcnt(19)
	ds_write_b128 v188, v[94:97] offset:36864
	v_mfma_f32_32x32x16_bf16 v[2:17], v[154:157], v[212:215], v[2:17]
	s_waitcnt vmcnt(18)
	ds_write_b128 v188, v[98:101] offset:41472
	v_mfma_f32_32x32x16_bf16 v[18:33], v[154:157], v[220:223], v[18:33]
	s_waitcnt vmcnt(17)
	ds_write_b128 v188, v[102:105] offset:46080
	v_mfma_f32_32x32x16_bf16 v[50:65], v[126:129], v[212:215], v[50:65]
	s_waitcnt vmcnt(16)
	ds_write_b128 v188, v[110:113] offset:50688
	ds_read_b128 v[126:129], v0 offset:64
	ds_read_b128 v[154:157], v0 offset:4672
	ds_read_b128 v[212:215], v171 offset:18496
	ds_read_b128 v[220:223], v171 offset:23104
	s_waitcnt lgkmcnt(8)
	v_mfma_f32_32x32x16_bf16 v[34:49], v[150:153], v[224:227], v[34:49]
	s_waitcnt vmcnt(15)
	ds_write_b128 v188, v[118:121] offset:55296
	v_mfma_f32_32x32x16_bf16 v[2:17], v[190:193], v[216:219], v[2:17]
	s_waitcnt vmcnt(13)
	ds_write_b128 v188, v[146:149] offset:64512
	v_mfma_f32_32x32x16_bf16 v[18:33], v[190:193], v[224:227], v[18:33]
	v_mfma_f32_32x32x16_bf16 v[50:65], v[150:153], v[216:219], v[50:65]
	ds_read_b128 v[150:153], v0 offset:96
	ds_read_b128 v[190:193], v0 offset:4704
	ds_read_b128 v[216:219], v171 offset:18528
	ds_read_b128 v[224:227], v171 offset:23136
	s_waitcnt lgkmcnt(6)
	v_mfma_f32_32x32x16_bf16 v[34:49], v[126:129], v[220:223], v[34:49]
	global_load_dwordx4 v[110:113], v[172:173], off offset:896
	global_load_dwordx4 v[118:121], v[176:177], off offset:896
	v_mfma_f32_32x32x16_bf16 v[2:17], v[154:157], v[212:215], v[2:17]
	global_load_dwordx4 v[142:145], v[178:179], off offset:896
	global_load_dwordx4 v[146:149], v[180:181], off offset:896
	v_mfma_f32_32x32x16_bf16 v[18:33], v[154:157], v[220:223], v[18:33]
	global_load_dwordx4 v[78:81], v[174:175], off offset:1024
	global_load_dwordx4 v[94:97], v[182:183], off offset:1024
	v_mfma_f32_32x32x16_bf16 v[50:65], v[126:129], v[212:215], v[50:65]
	global_load_dwordx4 v[98:101], v[184:185], off offset:1024
	global_load_dwordx4 v[102:105], v[186:187], off offset:1024
	s_waitcnt lgkmcnt(0)
	v_mfma_f32_32x32x16_bf16 v[34:49], v[150:153], v[224:227], v[34:49]
	v_mfma_f32_32x32x16_bf16 v[2:17], v[190:193], v[216:219], v[2:17]
	v_mfma_f32_32x32x16_bf16 v[18:33], v[190:193], v[224:227], v[18:33]
	v_mfma_f32_32x32x16_bf16 v[50:65], v[150:153], v[216:219], v[50:65]
	s_waitcnt lgkmcnt(0)
	s_setprio 0
	s_barrier
	s_setprio 2
	s_waitcnt vmcnt(12)
	ds_write_b128 v188, v[138:141] offset:32256
	ds_read_b128 v[138:141], v0 offset:36864
	ds_read_b128 v[154:157], v0 offset:41472
	ds_read_b128 v[212:215], v171 offset:55296
	ds_read_b128 v[220:223], v171 offset:59904
	ds_read_b128 v[150:153], v0 offset:36896
	ds_read_b128 v[190:193], v0 offset:41504
	ds_read_b128 v[216:219], v171 offset:55328
	ds_read_b128 v[224:227], v171 offset:59936
	s_waitcnt lgkmcnt(4)
	v_mfma_f32_32x32x16_bf16 v[34:49], v[138:141], v[220:223], v[34:49]
	s_waitcnt vmcnt(19)
	ds_write_b128 v188, v[82:85]
	v_mfma_f32_32x32x16_bf16 v[2:17], v[154:157], v[212:215], v[2:17]
	s_waitcnt vmcnt(18)
	ds_write_b128 v188, v[86:89] offset:4608
	v_mfma_f32_32x32x16_bf16 v[18:33], v[154:157], v[220:223], v[18:33]
	s_waitcnt vmcnt(17)
	ds_write_b128 v188, v[90:93] offset:9216
	v_mfma_f32_32x32x16_bf16 v[50:65], v[138:141], v[212:215], v[50:65]
	s_waitcnt vmcnt(16)
	ds_write_b128 v188, v[106:109] offset:13824
	ds_read_b128 v[138:141], v0 offset:36928
	ds_read_b128 v[154:157], v0 offset:41536
	ds_read_b128 v[212:215], v171 offset:55360
	ds_read_b128 v[220:223], v171 offset:59968
	s_waitcnt lgkmcnt(8)
	v_mfma_f32_32x32x16_bf16 v[34:49], v[150:153], v[224:227], v[34:49]
	s_waitcnt vmcnt(15)
	ds_write_b128 v188, v[122:125] offset:18432
	v_mfma_f32_32x32x16_bf16 v[2:17], v[190:193], v[216:219], v[2:17]
	s_waitcnt vmcnt(14)
	ds_write_b128 v188, v[130:133] offset:23040
	v_mfma_f32_32x32x16_bf16 v[18:33], v[190:193], v[224:227], v[18:33]
	s_waitcnt vmcnt(13)
	ds_write_b128 v188, v[134:137] offset:27648
	v_mfma_f32_32x32x16_bf16 v[50:65], v[150:153], v[216:219], v[50:65]
	ds_read_b128 v[150:153], v0 offset:36960
	ds_read_b128 v[190:193], v0 offset:41568
	ds_read_b128 v[216:219], v171 offset:55392
	ds_read_b128 v[224:227], v171 offset:60000
	s_waitcnt lgkmcnt(7)
	v_mfma_f32_32x32x16_bf16 v[34:49], v[138:141], v[220:223], v[34:49]
	global_load_dwordx4 v[122:125], v[172:173], off offset:1024
	global_load_dwordx4 v[126:129], v[176:177], off offset:1024
	v_mfma_f32_32x32x16_bf16 v[2:17], v[154:157], v[212:215], v[2:17]
	global_load_dwordx4 v[130:133], v[178:179], off offset:1024
	global_load_dwordx4 v[134:137], v[180:181], off offset:1024
	v_mfma_f32_32x32x16_bf16 v[18:33], v[154:157], v[220:223], v[18:33]
	global_load_dwordx4 v[82:85], v[174:175], off offset:1152
	global_load_dwordx4 v[86:89], v[182:183], off offset:1152
	v_mfma_f32_32x32x16_bf16 v[50:65], v[138:141], v[212:215], v[50:65]
	global_load_dwordx4 v[90:93], v[184:185], off offset:1152
	global_load_dwordx4 v[106:109], v[186:187], off offset:1152
	s_waitcnt lgkmcnt(0)
	v_mfma_f32_32x32x16_bf16 v[34:49], v[150:153], v[224:227], v[34:49]
	v_mfma_f32_32x32x16_bf16 v[2:17], v[190:193], v[216:219], v[2:17]
	v_mfma_f32_32x32x16_bf16 v[18:33], v[190:193], v[224:227], v[18:33]
	v_mfma_f32_32x32x16_bf16 v[50:65], v[150:153], v[216:219], v[50:65]
	s_waitcnt lgkmcnt(0)
	s_setprio 0
	s_barrier
	s_setprio 2
	s_waitcnt vmcnt(12)
	ds_write_b128 v189, v[146:149] offset:13824
	ds_read_b128 v[146:149], v0
	ds_read_b128 v[154:157], v0 offset:4608
	ds_read_b128 v[212:215], v171 offset:18432
	ds_read_b128 v[220:223], v171 offset:23040
	ds_read_b128 v[150:153], v0 offset:32
	ds_read_b128 v[190:193], v0 offset:4640
	ds_read_b128 v[216:219], v171 offset:18464
	ds_read_b128 v[224:227], v171 offset:23072
	s_waitcnt lgkmcnt(4)
	v_mfma_f32_32x32x16_bf16 v[34:49], v[146:149], v[220:223], v[34:49]
	s_waitcnt vmcnt(19)
	ds_write_b128 v188, v[66:69] offset:36864
	v_mfma_f32_32x32x16_bf16 v[2:17], v[154:157], v[212:215], v[2:17]
	s_waitcnt vmcnt(18)
	ds_write_b128 v188, v[70:73] offset:41472
	v_mfma_f32_32x32x16_bf16 v[18:33], v[154:157], v[220:223], v[18:33]
	s_waitcnt vmcnt(17)
	ds_write_b128 v188, v[74:77] offset:46080
	v_mfma_f32_32x32x16_bf16 v[50:65], v[146:149], v[212:215], v[50:65]
	s_waitcnt vmcnt(16)
	ds_write_b128 v188, v[114:117] offset:50688
	ds_read_b128 v[146:149], v0 offset:64
	ds_read_b128 v[154:157], v0 offset:4672
	ds_read_b128 v[212:215], v171 offset:18496
	ds_read_b128 v[220:223], v171 offset:23104
	s_waitcnt lgkmcnt(8)
	v_mfma_f32_32x32x16_bf16 v[34:49], v[150:153], v[224:227], v[34:49]
	s_waitcnt vmcnt(15)
	ds_write_b128 v188, v[110:113] offset:55296
	v_mfma_f32_32x32x16_bf16 v[2:17], v[190:193], v[216:219], v[2:17]
	s_waitcnt vmcnt(14)
	ds_write_b128 v188, v[118:121] offset:59904
	v_mfma_f32_32x32x16_bf16 v[18:33], v[190:193], v[224:227], v[18:33]
	s_waitcnt vmcnt(13)
	ds_write_b128 v188, v[142:145] offset:64512
	v_mfma_f32_32x32x16_bf16 v[50:65], v[150:153], v[216:219], v[50:65]
	ds_read_b128 v[150:153], v0 offset:96
	ds_read_b128 v[190:193], v0 offset:4704
	ds_read_b128 v[216:219], v171 offset:18528
	ds_read_b128 v[224:227], v171 offset:23136
	s_waitcnt lgkmcnt(7)
	v_mfma_f32_32x32x16_bf16 v[34:49], v[146:149], v[220:223], v[34:49]
	global_load_dwordx4 v[114:117], v[172:173], off offset:1152
	global_load_dwordx4 v[118:121], v[176:177], off offset:1152
	v_mfma_f32_32x32x16_bf16 v[2:17], v[154:157], v[212:215], v[2:17]
	global_load_dwordx4 v[138:141], v[178:179], off offset:1152
	global_load_dwordx4 v[142:145], v[180:181], off offset:1152
	v_mfma_f32_32x32x16_bf16 v[18:33], v[154:157], v[220:223], v[18:33]
	global_load_dwordx4 v[66:69], v[174:175], off offset:1280
	global_load_dwordx4 v[70:73], v[182:183], off offset:1280
	v_mfma_f32_32x32x16_bf16 v[50:65], v[146:149], v[212:215], v[50:65]
	global_load_dwordx4 v[74:77], v[184:185], off offset:1280
	global_load_dwordx4 v[110:113], v[186:187], off offset:1280
	s_waitcnt lgkmcnt(0)
	v_mfma_f32_32x32x16_bf16 v[34:49], v[150:153], v[224:227], v[34:49]
	v_mfma_f32_32x32x16_bf16 v[2:17], v[190:193], v[216:219], v[2:17]
	v_mfma_f32_32x32x16_bf16 v[18:33], v[190:193], v[224:227], v[18:33]
	v_mfma_f32_32x32x16_bf16 v[50:65], v[150:153], v[216:219], v[50:65]
	s_waitcnt lgkmcnt(0)
	s_setprio 0
	s_barrier
	s_setprio 2
	ds_read_b128 v[146:149], v0 offset:36864
	ds_read_b128 v[154:157], v0 offset:41472
	ds_read_b128 v[212:215], v171 offset:55296
	ds_read_b128 v[220:223], v171 offset:59904
	ds_read_b128 v[150:153], v0 offset:36896
	ds_read_b128 v[190:193], v0 offset:41504
	ds_read_b128 v[216:219], v171 offset:55328
	ds_read_b128 v[224:227], v171 offset:59936
	s_waitcnt lgkmcnt(4)
	v_mfma_f32_32x32x16_bf16 v[34:49], v[146:149], v[220:223], v[34:49]
	s_waitcnt vmcnt(19)
	ds_write_b128 v188, v[78:81]
	v_mfma_f32_32x32x16_bf16 v[2:17], v[154:157], v[212:215], v[2:17]
	s_waitcnt vmcnt(18)
	ds_write_b128 v188, v[94:97] offset:4608
	v_mfma_f32_32x32x16_bf16 v[18:33], v[154:157], v[220:223], v[18:33]
	s_waitcnt vmcnt(17)
	ds_write_b128 v188, v[98:101] offset:9216
	v_mfma_f32_32x32x16_bf16 v[50:65], v[146:149], v[212:215], v[50:65]
	s_waitcnt vmcnt(16)
	ds_write_b128 v188, v[102:105] offset:13824
	ds_read_b128 v[146:149], v0 offset:36928
	ds_read_b128 v[154:157], v0 offset:41536
	ds_read_b128 v[212:215], v171 offset:55360
	ds_read_b128 v[220:223], v171 offset:59968
	s_waitcnt lgkmcnt(8)
	v_mfma_f32_32x32x16_bf16 v[34:49], v[150:153], v[224:227], v[34:49]
	s_waitcnt vmcnt(15)
	ds_write_b128 v188, v[122:125] offset:18432
	v_mfma_f32_32x32x16_bf16 v[2:17], v[190:193], v[216:219], v[2:17]
	s_waitcnt vmcnt(14)
	ds_write_b128 v188, v[126:129] offset:23040
	v_mfma_f32_32x32x16_bf16 v[18:33], v[190:193], v[224:227], v[18:33]
	s_waitcnt vmcnt(13)
	ds_write_b128 v188, v[130:133] offset:27648
	v_mfma_f32_32x32x16_bf16 v[50:65], v[150:153], v[216:219], v[50:65]
	s_waitcnt vmcnt(12)
	ds_write_b128 v188, v[134:137] offset:32256
	ds_read_b128 v[150:153], v0 offset:36960
	ds_read_b128 v[190:193], v0 offset:41568
	ds_read_b128 v[216:219], v171 offset:55392
	ds_read_b128 v[224:227], v171 offset:60000
	s_waitcnt lgkmcnt(8)
	v_mfma_f32_32x32x16_bf16 v[34:49], v[146:149], v[220:223], v[34:49]
	global_load_dwordx4 v[122:125], v[172:173], off offset:1280
	global_load_dwordx4 v[126:129], v[176:177], off offset:1280
	v_mfma_f32_32x32x16_bf16 v[2:17], v[154:157], v[212:215], v[2:17]
	global_load_dwordx4 v[130:133], v[178:179], off offset:1280
	global_load_dwordx4 v[134:137], v[180:181], off offset:1280
	v_mfma_f32_32x32x16_bf16 v[18:33], v[154:157], v[220:223], v[18:33]
	global_load_dwordx4 v[78:81], v[174:175], off offset:1408
	global_load_dwordx4 v[94:97], v[182:183], off offset:1408
	v_mfma_f32_32x32x16_bf16 v[50:65], v[146:149], v[212:215], v[50:65]
	global_load_dwordx4 v[98:101], v[184:185], off offset:1408
	global_load_dwordx4 v[102:105], v[186:187], off offset:1408
	s_waitcnt lgkmcnt(0)
	v_mfma_f32_32x32x16_bf16 v[34:49], v[150:153], v[224:227], v[34:49]
	v_mfma_f32_32x32x16_bf16 v[2:17], v[190:193], v[216:219], v[2:17]
	v_mfma_f32_32x32x16_bf16 v[18:33], v[190:193], v[224:227], v[18:33]
	v_mfma_f32_32x32x16_bf16 v[50:65], v[150:153], v[216:219], v[50:65]
	s_waitcnt lgkmcnt(0)
	s_setprio 0
	s_barrier
	s_setprio 2
	ds_read_b128 v[146:149], v0
	ds_read_b128 v[154:157], v0 offset:4608
	ds_read_b128 v[212:215], v171 offset:18432
	ds_read_b128 v[220:223], v171 offset:23040
	ds_read_b128 v[150:153], v0 offset:32
	ds_read_b128 v[190:193], v0 offset:4640
	ds_read_b128 v[216:219], v171 offset:18464
	ds_read_b128 v[224:227], v171 offset:23072
	s_waitcnt lgkmcnt(4)
	v_mfma_f32_32x32x16_bf16 v[34:49], v[146:149], v[220:223], v[34:49]
	s_waitcnt vmcnt(19)
	ds_write_b128 v188, v[82:85] offset:36864
	v_mfma_f32_32x32x16_bf16 v[2:17], v[154:157], v[212:215], v[2:17]
	s_waitcnt vmcnt(18)
	ds_write_b128 v188, v[86:89] offset:41472
	v_mfma_f32_32x32x16_bf16 v[18:33], v[154:157], v[220:223], v[18:33]
	s_waitcnt vmcnt(17)
	ds_write_b128 v188, v[90:93] offset:46080
	v_mfma_f32_32x32x16_bf16 v[50:65], v[146:149], v[212:215], v[50:65]
	s_waitcnt vmcnt(16)
	ds_write_b128 v188, v[106:109] offset:50688
	ds_read_b128 v[146:149], v0 offset:64
	ds_read_b128 v[154:157], v0 offset:4672
	ds_read_b128 v[212:215], v171 offset:18496
	ds_read_b128 v[220:223], v171 offset:23104
	s_waitcnt lgkmcnt(8)
	v_mfma_f32_32x32x16_bf16 v[34:49], v[150:153], v[224:227], v[34:49]
	s_waitcnt vmcnt(15)
	ds_write_b128 v188, v[114:117] offset:55296
	v_mfma_f32_32x32x16_bf16 v[2:17], v[190:193], v[216:219], v[2:17]
	s_waitcnt vmcnt(14)
	ds_write_b128 v188, v[118:121] offset:59904
	v_mfma_f32_32x32x16_bf16 v[18:33], v[190:193], v[224:227], v[18:33]
	s_waitcnt vmcnt(13)
	ds_write_b128 v188, v[138:141] offset:64512
	v_mfma_f32_32x32x16_bf16 v[50:65], v[150:153], v[216:219], v[50:65]
	s_waitcnt vmcnt(12)
	ds_write_b128 v189, v[142:145] offset:13824
	ds_read_b128 v[150:153], v0 offset:96
	ds_read_b128 v[190:193], v0 offset:4704
	ds_read_b128 v[216:219], v171 offset:18528
	ds_read_b128 v[224:227], v171 offset:23136
	s_waitcnt lgkmcnt(8)
	v_mfma_f32_32x32x16_bf16 v[34:49], v[146:149], v[220:223], v[34:49]
	global_load_dwordx4 v[114:117], v[172:173], off offset:1408
	global_load_dwordx4 v[118:121], v[176:177], off offset:1408
	v_mfma_f32_32x32x16_bf16 v[2:17], v[154:157], v[212:215], v[2:17]
	global_load_dwordx4 v[138:141], v[178:179], off offset:1408
	global_load_dwordx4 v[142:145], v[180:181], off offset:1408
	v_mfma_f32_32x32x16_bf16 v[18:33], v[154:157], v[220:223], v[18:33]
	global_load_dwordx4 v[82:85], v[174:175], off offset:1536
	global_load_dwordx4 v[86:89], v[182:183], off offset:1536
	v_mfma_f32_32x32x16_bf16 v[50:65], v[146:149], v[212:215], v[50:65]
	global_load_dwordx4 v[90:93], v[184:185], off offset:1536
	global_load_dwordx4 v[106:109], v[186:187], off offset:1536
	s_waitcnt lgkmcnt(0)
	v_mfma_f32_32x32x16_bf16 v[34:49], v[150:153], v[224:227], v[34:49]
	v_mfma_f32_32x32x16_bf16 v[2:17], v[190:193], v[216:219], v[2:17]
	v_mfma_f32_32x32x16_bf16 v[18:33], v[190:193], v[224:227], v[18:33]
	v_mfma_f32_32x32x16_bf16 v[50:65], v[150:153], v[216:219], v[50:65]
	s_waitcnt lgkmcnt(0)
	s_setprio 0
	s_barrier
	s_setprio 2
	ds_read_b128 v[146:149], v0 offset:36864
	ds_read_b128 v[154:157], v0 offset:41472
	ds_read_b128 v[212:215], v171 offset:55296
	ds_read_b128 v[220:223], v171 offset:59904
	ds_read_b128 v[150:153], v0 offset:36896
	ds_read_b128 v[190:193], v0 offset:41504
	ds_read_b128 v[216:219], v171 offset:55328
	ds_read_b128 v[224:227], v171 offset:59936
	s_waitcnt lgkmcnt(4)
	v_mfma_f32_32x32x16_bf16 v[34:49], v[146:149], v[220:223], v[34:49]
	s_waitcnt vmcnt(19)
	ds_write_b128 v188, v[66:69]
	v_mfma_f32_32x32x16_bf16 v[2:17], v[154:157], v[212:215], v[2:17]
	s_waitcnt vmcnt(18)
	ds_write_b128 v188, v[70:73] offset:4608
	v_mfma_f32_32x32x16_bf16 v[18:33], v[154:157], v[220:223], v[18:33]
	s_waitcnt vmcnt(17)
	ds_write_b128 v188, v[74:77] offset:9216
	v_mfma_f32_32x32x16_bf16 v[50:65], v[146:149], v[212:215], v[50:65]
	s_waitcnt vmcnt(16)
	ds_write_b128 v188, v[110:113] offset:13824
	ds_read_b128 v[146:149], v0 offset:36928
	ds_read_b128 v[154:157], v0 offset:41536
	ds_read_b128 v[212:215], v171 offset:55360
	ds_read_b128 v[220:223], v171 offset:59968
	s_waitcnt lgkmcnt(8)
	v_mfma_f32_32x32x16_bf16 v[34:49], v[150:153], v[224:227], v[34:49]
	s_waitcnt vmcnt(15)
	ds_write_b128 v188, v[122:125] offset:18432
	v_mfma_f32_32x32x16_bf16 v[2:17], v[190:193], v[216:219], v[2:17]
	s_waitcnt vmcnt(14)
	ds_write_b128 v188, v[126:129] offset:23040
	v_mfma_f32_32x32x16_bf16 v[18:33], v[190:193], v[224:227], v[18:33]
	s_waitcnt vmcnt(13)
	ds_write_b128 v188, v[130:133] offset:27648
	v_mfma_f32_32x32x16_bf16 v[50:65], v[150:153], v[216:219], v[50:65]
	s_waitcnt vmcnt(12)
	ds_write_b128 v188, v[134:137] offset:32256
	ds_read_b128 v[150:153], v0 offset:36960
	ds_read_b128 v[190:193], v0 offset:41568
	ds_read_b128 v[216:219], v171 offset:55392
	ds_read_b128 v[224:227], v171 offset:60000
	s_waitcnt lgkmcnt(8)
	v_mfma_f32_32x32x16_bf16 v[34:49], v[146:149], v[220:223], v[34:49]
	global_load_dwordx4 v[122:125], v[172:173], off offset:1536
	global_load_dwordx4 v[126:129], v[176:177], off offset:1536
	v_mfma_f32_32x32x16_bf16 v[2:17], v[154:157], v[212:215], v[2:17]
	global_load_dwordx4 v[130:133], v[178:179], off offset:1536
	global_load_dwordx4 v[134:137], v[180:181], off offset:1536
	v_mfma_f32_32x32x16_bf16 v[18:33], v[154:157], v[220:223], v[18:33]
	global_load_dwordx4 v[66:69], v[174:175], off offset:1664
	global_load_dwordx4 v[70:73], v[182:183], off offset:1664
	v_mfma_f32_32x32x16_bf16 v[50:65], v[146:149], v[212:215], v[50:65]
	global_load_dwordx4 v[74:77], v[184:185], off offset:1664
	global_load_dwordx4 v[110:113], v[186:187], off offset:1664
	s_waitcnt lgkmcnt(0)
	v_mfma_f32_32x32x16_bf16 v[34:49], v[150:153], v[224:227], v[34:49]
	v_mfma_f32_32x32x16_bf16 v[2:17], v[190:193], v[216:219], v[2:17]
	v_mfma_f32_32x32x16_bf16 v[18:33], v[190:193], v[224:227], v[18:33]
	v_mfma_f32_32x32x16_bf16 v[50:65], v[150:153], v[216:219], v[50:65]
	s_waitcnt lgkmcnt(0)
	s_setprio 0
	s_barrier
	s_setprio 2
	ds_read_b128 v[146:149], v0
	ds_read_b128 v[154:157], v0 offset:4608
	ds_read_b128 v[212:215], v171 offset:18432
	ds_read_b128 v[220:223], v171 offset:23040
	ds_read_b128 v[150:153], v0 offset:32
	ds_read_b128 v[190:193], v0 offset:4640
	ds_read_b128 v[216:219], v171 offset:18464
	ds_read_b128 v[224:227], v171 offset:23072
	s_waitcnt lgkmcnt(4)
	v_mfma_f32_32x32x16_bf16 v[34:49], v[146:149], v[220:223], v[34:49]
	s_waitcnt vmcnt(19)
	ds_write_b128 v188, v[78:81] offset:36864
	v_mfma_f32_32x32x16_bf16 v[2:17], v[154:157], v[212:215], v[2:17]
	s_waitcnt vmcnt(18)
	ds_write_b128 v188, v[94:97] offset:41472
	v_mfma_f32_32x32x16_bf16 v[18:33], v[154:157], v[220:223], v[18:33]
	s_waitcnt vmcnt(17)
	ds_write_b128 v188, v[98:101] offset:46080
	v_mfma_f32_32x32x16_bf16 v[50:65], v[146:149], v[212:215], v[50:65]
	s_waitcnt vmcnt(16)
	ds_write_b128 v188, v[102:105] offset:50688
	ds_read_b128 v[146:149], v0 offset:64
	ds_read_b128 v[154:157], v0 offset:4672
	ds_read_b128 v[212:215], v171 offset:18496
	ds_read_b128 v[220:223], v171 offset:23104
	s_waitcnt lgkmcnt(8)
	v_mfma_f32_32x32x16_bf16 v[34:49], v[150:153], v[224:227], v[34:49]
	s_waitcnt vmcnt(15)
	ds_write_b128 v188, v[114:117] offset:55296
	v_mfma_f32_32x32x16_bf16 v[2:17], v[190:193], v[216:219], v[2:17]
	s_waitcnt vmcnt(14)
	ds_write_b128 v188, v[118:121] offset:59904
	v_mfma_f32_32x32x16_bf16 v[18:33], v[190:193], v[224:227], v[18:33]
	s_waitcnt vmcnt(13)
	ds_write_b128 v188, v[138:141] offset:64512
	v_mfma_f32_32x32x16_bf16 v[50:65], v[150:153], v[216:219], v[50:65]
	s_waitcnt vmcnt(12)
	ds_write_b128 v189, v[142:145] offset:13824
	ds_read_b128 v[150:153], v0 offset:96
	ds_read_b128 v[190:193], v0 offset:4704
	ds_read_b128 v[216:219], v171 offset:18528
	ds_read_b128 v[224:227], v171 offset:23136
	s_waitcnt lgkmcnt(8)
	v_mfma_f32_32x32x16_bf16 v[34:49], v[146:149], v[220:223], v[34:49]
	global_load_dwordx4 v[114:117], v[172:173], off offset:1664
	global_load_dwordx4 v[118:121], v[176:177], off offset:1664
	v_mfma_f32_32x32x16_bf16 v[2:17], v[154:157], v[212:215], v[2:17]
	global_load_dwordx4 v[138:141], v[178:179], off offset:1664
	global_load_dwordx4 v[142:145], v[180:181], off offset:1664
	v_mfma_f32_32x32x16_bf16 v[18:33], v[154:157], v[220:223], v[18:33]
	global_load_dwordx4 v[78:81], v[174:175], off offset:1792
	global_load_dwordx4 v[94:97], v[182:183], off offset:1792
	v_mfma_f32_32x32x16_bf16 v[50:65], v[146:149], v[212:215], v[50:65]
	global_load_dwordx4 v[98:101], v[184:185], off offset:1792
	global_load_dwordx4 v[102:105], v[186:187], off offset:1792
	s_waitcnt lgkmcnt(0)
	v_mfma_f32_32x32x16_bf16 v[34:49], v[150:153], v[224:227], v[34:49]
	v_mfma_f32_32x32x16_bf16 v[2:17], v[190:193], v[216:219], v[2:17]
	v_mfma_f32_32x32x16_bf16 v[18:33], v[190:193], v[224:227], v[18:33]
	v_mfma_f32_32x32x16_bf16 v[50:65], v[150:153], v[216:219], v[50:65]
	s_waitcnt lgkmcnt(0)
	s_setprio 0
	s_barrier
	s_setprio 2
	ds_read_b128 v[146:149], v0 offset:36864
	ds_read_b128 v[154:157], v0 offset:41472
	ds_read_b128 v[212:215], v171 offset:55296
	ds_read_b128 v[220:223], v171 offset:59904
	ds_read_b128 v[150:153], v0 offset:36896
	ds_read_b128 v[190:193], v0 offset:41504
	ds_read_b128 v[216:219], v171 offset:55328
	ds_read_b128 v[224:227], v171 offset:59936
	s_waitcnt lgkmcnt(4)
	v_mfma_f32_32x32x16_bf16 v[34:49], v[146:149], v[220:223], v[34:49]
	s_waitcnt vmcnt(19)
	ds_write_b128 v188, v[82:85]
	v_mfma_f32_32x32x16_bf16 v[2:17], v[154:157], v[212:215], v[2:17]
	s_waitcnt vmcnt(18)
	ds_write_b128 v188, v[86:89] offset:4608
	v_mfma_f32_32x32x16_bf16 v[18:33], v[154:157], v[220:223], v[18:33]
	s_waitcnt vmcnt(17)
	ds_write_b128 v188, v[90:93] offset:9216
	v_mfma_f32_32x32x16_bf16 v[50:65], v[146:149], v[212:215], v[50:65]
	s_waitcnt vmcnt(16)
	ds_write_b128 v188, v[106:109] offset:13824
	ds_read_b128 v[146:149], v0 offset:36928
	ds_read_b128 v[154:157], v0 offset:41536
	ds_read_b128 v[212:215], v171 offset:55360
	ds_read_b128 v[220:223], v171 offset:59968
	s_waitcnt lgkmcnt(8)
	v_mfma_f32_32x32x16_bf16 v[34:49], v[150:153], v[224:227], v[34:49]
	s_waitcnt vmcnt(15)
	ds_write_b128 v188, v[122:125] offset:18432
	v_mfma_f32_32x32x16_bf16 v[2:17], v[190:193], v[216:219], v[2:17]
	s_waitcnt vmcnt(14)
	ds_write_b128 v188, v[126:129] offset:23040
	v_mfma_f32_32x32x16_bf16 v[18:33], v[190:193], v[224:227], v[18:33]
	s_waitcnt vmcnt(13)
	ds_write_b128 v188, v[130:133] offset:27648
	v_mfma_f32_32x32x16_bf16 v[50:65], v[150:153], v[216:219], v[50:65]
	s_waitcnt vmcnt(12)
	ds_write_b128 v188, v[134:137] offset:32256
	ds_read_b128 v[150:153], v0 offset:36960
	ds_read_b128 v[190:193], v0 offset:41568
	ds_read_b128 v[216:219], v171 offset:55392
	ds_read_b128 v[224:227], v171 offset:60000
	s_waitcnt lgkmcnt(8)
	v_mfma_f32_32x32x16_bf16 v[34:49], v[146:149], v[220:223], v[34:49]
	global_load_dwordx4 v[122:125], v[172:173], off offset:1792
	global_load_dwordx4 v[126:129], v[176:177], off offset:1792
	v_mfma_f32_32x32x16_bf16 v[2:17], v[154:157], v[212:215], v[2:17]
	global_load_dwordx4 v[130:133], v[178:179], off offset:1792
	global_load_dwordx4 v[134:137], v[180:181], off offset:1792
	v_mfma_f32_32x32x16_bf16 v[18:33], v[154:157], v[220:223], v[18:33]
	global_load_dwordx4 v[82:85], v[174:175], off offset:1920
	global_load_dwordx4 v[86:89], v[182:183], off offset:1920
	v_mfma_f32_32x32x16_bf16 v[50:65], v[146:149], v[212:215], v[50:65]
	global_load_dwordx4 v[90:93], v[184:185], off offset:1920
	global_load_dwordx4 v[106:109], v[186:187], off offset:1920
	s_waitcnt lgkmcnt(0)
	v_mfma_f32_32x32x16_bf16 v[34:49], v[150:153], v[224:227], v[34:49]
	v_mfma_f32_32x32x16_bf16 v[2:17], v[190:193], v[216:219], v[2:17]
	v_mfma_f32_32x32x16_bf16 v[18:33], v[190:193], v[224:227], v[18:33]
	v_mfma_f32_32x32x16_bf16 v[50:65], v[150:153], v[216:219], v[50:65]
	s_waitcnt lgkmcnt(0)
	s_setprio 0
	s_barrier
	s_setprio 2
	ds_read_b128 v[146:149], v0
	ds_read_b128 v[154:157], v0 offset:4608
	ds_read_b128 v[212:215], v171 offset:18432
	ds_read_b128 v[220:223], v171 offset:23040
	ds_read_b128 v[150:153], v0 offset:32
	ds_read_b128 v[190:193], v0 offset:4640
	ds_read_b128 v[216:219], v171 offset:18464
	ds_read_b128 v[224:227], v171 offset:23072
	s_waitcnt lgkmcnt(4)
	v_mfma_f32_32x32x16_bf16 v[34:49], v[146:149], v[220:223], v[34:49]
	s_waitcnt vmcnt(19)
	ds_write_b128 v188, v[66:69] offset:36864
	v_mfma_f32_32x32x16_bf16 v[2:17], v[154:157], v[212:215], v[2:17]
	s_waitcnt vmcnt(18)
	ds_write_b128 v188, v[70:73] offset:41472
	v_mfma_f32_32x32x16_bf16 v[18:33], v[154:157], v[220:223], v[18:33]
	s_waitcnt vmcnt(17)
	ds_write_b128 v188, v[74:77] offset:46080
	v_mfma_f32_32x32x16_bf16 v[50:65], v[146:149], v[212:215], v[50:65]
	s_waitcnt vmcnt(16)
	ds_write_b128 v188, v[110:113] offset:50688
	ds_read_b128 v[146:149], v0 offset:64
	ds_read_b128 v[154:157], v0 offset:4672
	ds_read_b128 v[212:215], v171 offset:18496
	ds_read_b128 v[220:223], v171 offset:23104
	s_waitcnt lgkmcnt(8)
	v_mfma_f32_32x32x16_bf16 v[34:49], v[150:153], v[224:227], v[34:49]
	s_waitcnt vmcnt(15)
	ds_write_b128 v188, v[114:117] offset:55296
	v_mfma_f32_32x32x16_bf16 v[2:17], v[190:193], v[216:219], v[2:17]
	s_waitcnt vmcnt(14)
	ds_write_b128 v188, v[118:121] offset:59904
	v_mfma_f32_32x32x16_bf16 v[18:33], v[190:193], v[224:227], v[18:33]
	s_waitcnt vmcnt(13)
	ds_write_b128 v188, v[138:141] offset:64512
	v_mfma_f32_32x32x16_bf16 v[50:65], v[150:153], v[216:219], v[50:65]
	s_waitcnt vmcnt(12)
	ds_write_b128 v189, v[142:145] offset:13824
	ds_read_b128 v[150:153], v0 offset:96
	ds_read_b128 v[190:193], v0 offset:4704
	ds_read_b128 v[216:219], v171 offset:18528
	ds_read_b128 v[224:227], v171 offset:23136
	s_waitcnt lgkmcnt(8)
	v_mfma_f32_32x32x16_bf16 v[34:49], v[146:149], v[220:223], v[34:49]
	global_load_dwordx4 v[114:117], v[172:173], off offset:1920
	global_load_dwordx4 v[118:121], v[176:177], off offset:1920
	v_mfma_f32_32x32x16_bf16 v[2:17], v[154:157], v[212:215], v[2:17]
	global_load_dwordx4 v[138:141], v[178:179], off offset:1920
	global_load_dwordx4 v[142:145], v[180:181], off offset:1920
	v_mfma_f32_32x32x16_bf16 v[18:33], v[154:157], v[220:223], v[18:33]
	global_load_dwordx4 v[66:69], v[174:175], off offset:2048
	global_load_dwordx4 v[70:73], v[182:183], off offset:2048
	v_mfma_f32_32x32x16_bf16 v[50:65], v[146:149], v[212:215], v[50:65]
	global_load_dwordx4 v[74:77], v[184:185], off offset:2048
	global_load_dwordx4 v[110:113], v[186:187], off offset:2048
	s_waitcnt lgkmcnt(0)
	v_mfma_f32_32x32x16_bf16 v[34:49], v[150:153], v[224:227], v[34:49]
	v_mfma_f32_32x32x16_bf16 v[2:17], v[190:193], v[216:219], v[2:17]
	v_mfma_f32_32x32x16_bf16 v[18:33], v[190:193], v[224:227], v[18:33]
	v_mfma_f32_32x32x16_bf16 v[50:65], v[150:153], v[216:219], v[50:65]
	s_waitcnt lgkmcnt(0)
	s_setprio 0
	s_barrier
	s_setprio 2
	ds_read_b128 v[146:149], v0 offset:36864
	ds_read_b128 v[154:157], v0 offset:41472
	ds_read_b128 v[212:215], v171 offset:55296
	ds_read_b128 v[220:223], v171 offset:59904
	ds_read_b128 v[150:153], v0 offset:36896
	ds_read_b128 v[190:193], v0 offset:41504
	ds_read_b128 v[216:219], v171 offset:55328
	ds_read_b128 v[224:227], v171 offset:59936
	s_waitcnt lgkmcnt(4)
	v_mfma_f32_32x32x16_bf16 v[34:49], v[146:149], v[220:223], v[34:49]
	s_waitcnt vmcnt(19)
	ds_write_b128 v188, v[78:81]
	v_mfma_f32_32x32x16_bf16 v[2:17], v[154:157], v[212:215], v[2:17]
	s_waitcnt vmcnt(18)
	ds_write_b128 v188, v[94:97] offset:4608
	v_mfma_f32_32x32x16_bf16 v[18:33], v[154:157], v[220:223], v[18:33]
	s_waitcnt vmcnt(17)
	ds_write_b128 v188, v[98:101] offset:9216
	v_mfma_f32_32x32x16_bf16 v[50:65], v[146:149], v[212:215], v[50:65]
	s_waitcnt vmcnt(16)
	ds_write_b128 v188, v[102:105] offset:13824
	ds_read_b128 v[146:149], v0 offset:36928
	ds_read_b128 v[154:157], v0 offset:41536
	ds_read_b128 v[212:215], v171 offset:55360
	ds_read_b128 v[220:223], v171 offset:59968
	s_waitcnt lgkmcnt(8)
	v_mfma_f32_32x32x16_bf16 v[34:49], v[150:153], v[224:227], v[34:49]
	s_waitcnt vmcnt(15)
	ds_write_b128 v188, v[122:125] offset:18432
	v_mfma_f32_32x32x16_bf16 v[2:17], v[190:193], v[216:219], v[2:17]
	s_waitcnt vmcnt(14)
	ds_write_b128 v188, v[126:129] offset:23040
	v_mfma_f32_32x32x16_bf16 v[18:33], v[190:193], v[224:227], v[18:33]
	s_waitcnt vmcnt(13)
	ds_write_b128 v188, v[130:133] offset:27648
	v_mfma_f32_32x32x16_bf16 v[50:65], v[150:153], v[216:219], v[50:65]
	s_waitcnt vmcnt(12)
	ds_write_b128 v188, v[134:137] offset:32256
	ds_read_b128 v[150:153], v0 offset:36960
	ds_read_b128 v[190:193], v0 offset:41568
	ds_read_b128 v[216:219], v171 offset:55392
	ds_read_b128 v[224:227], v171 offset:60000
	s_waitcnt lgkmcnt(8)
	v_mfma_f32_32x32x16_bf16 v[34:49], v[146:149], v[220:223], v[34:49]
	global_load_dwordx4 v[122:125], v[172:173], off offset:2048
	global_load_dwordx4 v[126:129], v[176:177], off offset:2048
	v_mfma_f32_32x32x16_bf16 v[2:17], v[154:157], v[212:215], v[2:17]
	global_load_dwordx4 v[130:133], v[178:179], off offset:2048
	global_load_dwordx4 v[134:137], v[180:181], off offset:2048
	v_mfma_f32_32x32x16_bf16 v[18:33], v[154:157], v[220:223], v[18:33]
	global_load_dwordx4 v[78:81], v[174:175], off offset:2176
	global_load_dwordx4 v[94:97], v[182:183], off offset:2176
	v_mfma_f32_32x32x16_bf16 v[50:65], v[146:149], v[212:215], v[50:65]
	global_load_dwordx4 v[98:101], v[184:185], off offset:2176
	global_load_dwordx4 v[102:105], v[186:187], off offset:2176
	s_waitcnt lgkmcnt(0)
	v_mfma_f32_32x32x16_bf16 v[34:49], v[150:153], v[224:227], v[34:49]
	v_mfma_f32_32x32x16_bf16 v[2:17], v[190:193], v[216:219], v[2:17]
	v_mfma_f32_32x32x16_bf16 v[18:33], v[190:193], v[224:227], v[18:33]
	v_mfma_f32_32x32x16_bf16 v[50:65], v[150:153], v[216:219], v[50:65]
	s_waitcnt lgkmcnt(0)
	s_setprio 0
	s_barrier
	s_setprio 2
	ds_read_b128 v[146:149], v0
	ds_read_b128 v[154:157], v0 offset:4608
	ds_read_b128 v[212:215], v171 offset:18432
	ds_read_b128 v[220:223], v171 offset:23040
	ds_read_b128 v[150:153], v0 offset:32
	ds_read_b128 v[190:193], v0 offset:4640
	ds_read_b128 v[216:219], v171 offset:18464
	ds_read_b128 v[224:227], v171 offset:23072
	s_waitcnt lgkmcnt(4)
	v_mfma_f32_32x32x16_bf16 v[34:49], v[146:149], v[220:223], v[34:49]
	s_waitcnt vmcnt(19)
	ds_write_b128 v188, v[82:85] offset:36864
	v_mfma_f32_32x32x16_bf16 v[2:17], v[154:157], v[212:215], v[2:17]
	s_waitcnt vmcnt(18)
	ds_write_b128 v188, v[86:89] offset:41472
	v_mfma_f32_32x32x16_bf16 v[18:33], v[154:157], v[220:223], v[18:33]
	s_waitcnt vmcnt(17)
	ds_write_b128 v188, v[90:93] offset:46080
	v_mfma_f32_32x32x16_bf16 v[50:65], v[146:149], v[212:215], v[50:65]
	s_waitcnt vmcnt(16)
	ds_write_b128 v188, v[106:109] offset:50688
	ds_read_b128 v[146:149], v0 offset:64
	ds_read_b128 v[154:157], v0 offset:4672
	ds_read_b128 v[212:215], v171 offset:18496
	ds_read_b128 v[220:223], v171 offset:23104
	s_waitcnt lgkmcnt(8)
	v_mfma_f32_32x32x16_bf16 v[34:49], v[150:153], v[224:227], v[34:49]
	s_waitcnt vmcnt(15)
	ds_write_b128 v188, v[114:117] offset:55296
	v_mfma_f32_32x32x16_bf16 v[2:17], v[190:193], v[216:219], v[2:17]
	s_waitcnt vmcnt(14)
	ds_write_b128 v188, v[118:121] offset:59904
	v_mfma_f32_32x32x16_bf16 v[18:33], v[190:193], v[224:227], v[18:33]
	s_waitcnt vmcnt(13)
	ds_write_b128 v188, v[138:141] offset:64512
	v_mfma_f32_32x32x16_bf16 v[50:65], v[150:153], v[216:219], v[50:65]
	s_waitcnt vmcnt(12)
	ds_write_b128 v189, v[142:145] offset:13824
	ds_read_b128 v[150:153], v0 offset:96
	ds_read_b128 v[190:193], v0 offset:4704
	ds_read_b128 v[216:219], v171 offset:18528
	ds_read_b128 v[224:227], v171 offset:23136
	s_waitcnt lgkmcnt(8)
	v_mfma_f32_32x32x16_bf16 v[34:49], v[146:149], v[220:223], v[34:49]
	global_load_dwordx4 v[114:117], v[172:173], off offset:2176
	global_load_dwordx4 v[118:121], v[176:177], off offset:2176
	v_mfma_f32_32x32x16_bf16 v[2:17], v[154:157], v[212:215], v[2:17]
	global_load_dwordx4 v[138:141], v[178:179], off offset:2176
	global_load_dwordx4 v[142:145], v[180:181], off offset:2176
	v_mfma_f32_32x32x16_bf16 v[18:33], v[154:157], v[220:223], v[18:33]
	global_load_dwordx4 v[82:85], v[174:175], off offset:2304
	global_load_dwordx4 v[86:89], v[182:183], off offset:2304
	v_mfma_f32_32x32x16_bf16 v[50:65], v[146:149], v[212:215], v[50:65]
	global_load_dwordx4 v[90:93], v[184:185], off offset:2304
	global_load_dwordx4 v[106:109], v[186:187], off offset:2304
	s_waitcnt lgkmcnt(0)
	v_mfma_f32_32x32x16_bf16 v[34:49], v[150:153], v[224:227], v[34:49]
	v_mfma_f32_32x32x16_bf16 v[2:17], v[190:193], v[216:219], v[2:17]
	v_mfma_f32_32x32x16_bf16 v[18:33], v[190:193], v[224:227], v[18:33]
	v_mfma_f32_32x32x16_bf16 v[50:65], v[150:153], v[216:219], v[50:65]
	s_waitcnt lgkmcnt(0)
	s_setprio 0
	s_barrier
	s_setprio 2
	ds_read_b128 v[146:149], v0 offset:36864
	ds_read_b128 v[154:157], v0 offset:41472
	ds_read_b128 v[212:215], v171 offset:55296
	ds_read_b128 v[220:223], v171 offset:59904
	ds_read_b128 v[150:153], v0 offset:36896
	ds_read_b128 v[190:193], v0 offset:41504
	ds_read_b128 v[216:219], v171 offset:55328
	ds_read_b128 v[224:227], v171 offset:59936
	s_waitcnt lgkmcnt(4)
	v_mfma_f32_32x32x16_bf16 v[34:49], v[146:149], v[220:223], v[34:49]
	s_waitcnt vmcnt(19)
	ds_write_b128 v188, v[66:69]
	v_mfma_f32_32x32x16_bf16 v[2:17], v[154:157], v[212:215], v[2:17]
	s_waitcnt vmcnt(18)
	ds_write_b128 v188, v[70:73] offset:4608
	v_mfma_f32_32x32x16_bf16 v[18:33], v[154:157], v[220:223], v[18:33]
	s_waitcnt vmcnt(17)
	ds_write_b128 v188, v[74:77] offset:9216
	v_mfma_f32_32x32x16_bf16 v[50:65], v[146:149], v[212:215], v[50:65]
	s_waitcnt vmcnt(16)
	ds_write_b128 v188, v[110:113] offset:13824
	ds_read_b128 v[146:149], v0 offset:36928
	ds_read_b128 v[154:157], v0 offset:41536
	ds_read_b128 v[212:215], v171 offset:55360
	ds_read_b128 v[220:223], v171 offset:59968
	s_waitcnt lgkmcnt(8)
	v_mfma_f32_32x32x16_bf16 v[34:49], v[150:153], v[224:227], v[34:49]
	s_waitcnt vmcnt(15)
	ds_write_b128 v188, v[122:125] offset:18432
	v_mfma_f32_32x32x16_bf16 v[2:17], v[190:193], v[216:219], v[2:17]
	s_waitcnt vmcnt(14)
	ds_write_b128 v188, v[126:129] offset:23040
	v_mfma_f32_32x32x16_bf16 v[18:33], v[190:193], v[224:227], v[18:33]
	s_waitcnt vmcnt(13)
	ds_write_b128 v188, v[130:133] offset:27648
	v_mfma_f32_32x32x16_bf16 v[50:65], v[150:153], v[216:219], v[50:65]
	s_waitcnt vmcnt(12)
	ds_write_b128 v188, v[134:137] offset:32256
	ds_read_b128 v[150:153], v0 offset:36960
	ds_read_b128 v[190:193], v0 offset:41568
	ds_read_b128 v[216:219], v171 offset:55392
	ds_read_b128 v[224:227], v171 offset:60000
	s_waitcnt lgkmcnt(8)
	v_mfma_f32_32x32x16_bf16 v[34:49], v[146:149], v[220:223], v[34:49]
	global_load_dwordx4 v[122:125], v[172:173], off offset:2304
	global_load_dwordx4 v[126:129], v[176:177], off offset:2304
	v_mfma_f32_32x32x16_bf16 v[2:17], v[154:157], v[212:215], v[2:17]
	global_load_dwordx4 v[130:133], v[178:179], off offset:2304
	global_load_dwordx4 v[134:137], v[180:181], off offset:2304
	v_mfma_f32_32x32x16_bf16 v[18:33], v[154:157], v[220:223], v[18:33]
	global_load_dwordx4 v[66:69], v[174:175], off offset:2432
	global_load_dwordx4 v[70:73], v[182:183], off offset:2432
	v_mfma_f32_32x32x16_bf16 v[50:65], v[146:149], v[212:215], v[50:65]
	global_load_dwordx4 v[74:77], v[184:185], off offset:2432
	global_load_dwordx4 v[110:113], v[186:187], off offset:2432
	s_waitcnt lgkmcnt(0)
	v_mfma_f32_32x32x16_bf16 v[34:49], v[150:153], v[224:227], v[34:49]
	v_mfma_f32_32x32x16_bf16 v[2:17], v[190:193], v[216:219], v[2:17]
	v_mfma_f32_32x32x16_bf16 v[18:33], v[190:193], v[224:227], v[18:33]
	v_mfma_f32_32x32x16_bf16 v[50:65], v[150:153], v[216:219], v[50:65]
	s_waitcnt lgkmcnt(0)
	s_setprio 0
	s_barrier
	s_setprio 2
	ds_read_b128 v[146:149], v0
	ds_read_b128 v[154:157], v0 offset:4608
	ds_read_b128 v[212:215], v171 offset:18432
	ds_read_b128 v[220:223], v171 offset:23040
	ds_read_b128 v[150:153], v0 offset:32
	ds_read_b128 v[190:193], v0 offset:4640
	ds_read_b128 v[216:219], v171 offset:18464
	ds_read_b128 v[224:227], v171 offset:23072
	s_waitcnt lgkmcnt(4)
	v_mfma_f32_32x32x16_bf16 v[34:49], v[146:149], v[220:223], v[34:49]
	s_waitcnt vmcnt(19)
	ds_write_b128 v188, v[78:81] offset:36864
	v_mfma_f32_32x32x16_bf16 v[2:17], v[154:157], v[212:215], v[2:17]
	s_waitcnt vmcnt(18)
	ds_write_b128 v188, v[94:97] offset:41472
	v_mfma_f32_32x32x16_bf16 v[18:33], v[154:157], v[220:223], v[18:33]
	s_waitcnt vmcnt(17)
	ds_write_b128 v188, v[98:101] offset:46080
	v_mfma_f32_32x32x16_bf16 v[50:65], v[146:149], v[212:215], v[50:65]
	s_waitcnt vmcnt(16)
	ds_write_b128 v188, v[102:105] offset:50688
	ds_read_b128 v[146:149], v0 offset:64
	ds_read_b128 v[154:157], v0 offset:4672
	ds_read_b128 v[212:215], v171 offset:18496
	ds_read_b128 v[220:223], v171 offset:23104
	s_waitcnt lgkmcnt(8)
	v_mfma_f32_32x32x16_bf16 v[34:49], v[150:153], v[224:227], v[34:49]
	s_waitcnt vmcnt(15)
	ds_write_b128 v188, v[114:117] offset:55296
	v_mfma_f32_32x32x16_bf16 v[2:17], v[190:193], v[216:219], v[2:17]
	s_waitcnt vmcnt(14)
	ds_write_b128 v188, v[118:121] offset:59904
	v_mfma_f32_32x32x16_bf16 v[18:33], v[190:193], v[224:227], v[18:33]
	s_waitcnt vmcnt(13)
	ds_write_b128 v188, v[138:141] offset:64512
	v_mfma_f32_32x32x16_bf16 v[50:65], v[150:153], v[216:219], v[50:65]
	s_waitcnt vmcnt(12)
	ds_write_b128 v189, v[142:145] offset:13824
	ds_read_b128 v[150:153], v0 offset:96
	ds_read_b128 v[190:193], v0 offset:4704
	ds_read_b128 v[216:219], v171 offset:18528
	ds_read_b128 v[224:227], v171 offset:23136
	s_waitcnt lgkmcnt(8)
	v_mfma_f32_32x32x16_bf16 v[34:49], v[146:149], v[220:223], v[34:49]
	global_load_dwordx4 v[114:117], v[172:173], off offset:2432
	global_load_dwordx4 v[118:121], v[176:177], off offset:2432
	v_mfma_f32_32x32x16_bf16 v[2:17], v[154:157], v[212:215], v[2:17]
	global_load_dwordx4 v[138:141], v[178:179], off offset:2432
	global_load_dwordx4 v[142:145], v[180:181], off offset:2432
	v_mfma_f32_32x32x16_bf16 v[18:33], v[154:157], v[220:223], v[18:33]
	global_load_dwordx4 v[78:81], v[174:175], off offset:2560
	global_load_dwordx4 v[94:97], v[182:183], off offset:2560
	v_mfma_f32_32x32x16_bf16 v[50:65], v[146:149], v[212:215], v[50:65]
	global_load_dwordx4 v[98:101], v[184:185], off offset:2560
	global_load_dwordx4 v[102:105], v[186:187], off offset:2560
	s_waitcnt lgkmcnt(0)
	v_mfma_f32_32x32x16_bf16 v[34:49], v[150:153], v[224:227], v[34:49]
	v_mfma_f32_32x32x16_bf16 v[2:17], v[190:193], v[216:219], v[2:17]
	v_mfma_f32_32x32x16_bf16 v[18:33], v[190:193], v[224:227], v[18:33]
	v_mfma_f32_32x32x16_bf16 v[50:65], v[150:153], v[216:219], v[50:65]
	s_waitcnt lgkmcnt(0)
	s_setprio 0
	s_barrier
	s_setprio 2
	ds_read_b128 v[146:149], v0 offset:36864
	ds_read_b128 v[154:157], v0 offset:41472
	ds_read_b128 v[212:215], v171 offset:55296
	ds_read_b128 v[220:223], v171 offset:59904
	ds_read_b128 v[150:153], v0 offset:36896
	ds_read_b128 v[190:193], v0 offset:41504
	ds_read_b128 v[216:219], v171 offset:55328
	ds_read_b128 v[224:227], v171 offset:59936
	s_waitcnt lgkmcnt(4)
	v_mfma_f32_32x32x16_bf16 v[34:49], v[146:149], v[220:223], v[34:49]
	s_waitcnt vmcnt(19)
	ds_write_b128 v188, v[82:85]
	v_mfma_f32_32x32x16_bf16 v[2:17], v[154:157], v[212:215], v[2:17]
	s_waitcnt vmcnt(18)
	ds_write_b128 v188, v[86:89] offset:4608
	v_mfma_f32_32x32x16_bf16 v[18:33], v[154:157], v[220:223], v[18:33]
	s_waitcnt vmcnt(17)
	ds_write_b128 v188, v[90:93] offset:9216
	v_mfma_f32_32x32x16_bf16 v[50:65], v[146:149], v[212:215], v[50:65]
	s_waitcnt vmcnt(16)
	ds_write_b128 v188, v[106:109] offset:13824
	ds_read_b128 v[146:149], v0 offset:36928
	ds_read_b128 v[154:157], v0 offset:41536
	ds_read_b128 v[212:215], v171 offset:55360
	ds_read_b128 v[220:223], v171 offset:59968
	s_waitcnt lgkmcnt(8)
	v_mfma_f32_32x32x16_bf16 v[34:49], v[150:153], v[224:227], v[34:49]
	s_waitcnt vmcnt(15)
	ds_write_b128 v188, v[122:125] offset:18432
	v_mfma_f32_32x32x16_bf16 v[2:17], v[190:193], v[216:219], v[2:17]
	s_waitcnt vmcnt(14)
	ds_write_b128 v188, v[126:129] offset:23040
	v_mfma_f32_32x32x16_bf16 v[18:33], v[190:193], v[224:227], v[18:33]
	s_waitcnt vmcnt(13)
	ds_write_b128 v188, v[130:133] offset:27648
	v_mfma_f32_32x32x16_bf16 v[50:65], v[150:153], v[216:219], v[50:65]
	s_waitcnt vmcnt(12)
	ds_write_b128 v188, v[134:137] offset:32256
	ds_read_b128 v[150:153], v0 offset:36960
	ds_read_b128 v[190:193], v0 offset:41568
	ds_read_b128 v[216:219], v171 offset:55392
	ds_read_b128 v[224:227], v171 offset:60000
	s_waitcnt lgkmcnt(8)
	v_mfma_f32_32x32x16_bf16 v[34:49], v[146:149], v[220:223], v[34:49]
	global_load_dwordx4 v[122:125], v[172:173], off offset:2560
	global_load_dwordx4 v[126:129], v[176:177], off offset:2560
	v_mfma_f32_32x32x16_bf16 v[2:17], v[154:157], v[212:215], v[2:17]
	global_load_dwordx4 v[130:133], v[178:179], off offset:2560
	global_load_dwordx4 v[134:137], v[180:181], off offset:2560
	v_mfma_f32_32x32x16_bf16 v[18:33], v[154:157], v[220:223], v[18:33]
	global_load_dwordx4 v[82:85], v[174:175], off offset:2688
	global_load_dwordx4 v[86:89], v[182:183], off offset:2688
	v_mfma_f32_32x32x16_bf16 v[50:65], v[146:149], v[212:215], v[50:65]
	global_load_dwordx4 v[90:93], v[184:185], off offset:2688
	global_load_dwordx4 v[106:109], v[186:187], off offset:2688
	s_waitcnt lgkmcnt(0)
	v_mfma_f32_32x32x16_bf16 v[34:49], v[150:153], v[224:227], v[34:49]
	v_mfma_f32_32x32x16_bf16 v[2:17], v[190:193], v[216:219], v[2:17]
	v_mfma_f32_32x32x16_bf16 v[18:33], v[190:193], v[224:227], v[18:33]
	v_mfma_f32_32x32x16_bf16 v[50:65], v[150:153], v[216:219], v[50:65]
	s_waitcnt lgkmcnt(0)
	s_setprio 0
	s_barrier
	s_setprio 2
	ds_read_b128 v[146:149], v0
	ds_read_b128 v[154:157], v0 offset:4608
	ds_read_b128 v[212:215], v171 offset:18432
	ds_read_b128 v[220:223], v171 offset:23040
	ds_read_b128 v[150:153], v0 offset:32
	ds_read_b128 v[190:193], v0 offset:4640
	ds_read_b128 v[216:219], v171 offset:18464
	ds_read_b128 v[224:227], v171 offset:23072
	s_waitcnt lgkmcnt(4)
	v_mfma_f32_32x32x16_bf16 v[34:49], v[146:149], v[220:223], v[34:49]
	s_waitcnt vmcnt(19)
	ds_write_b128 v188, v[66:69] offset:36864
	v_mfma_f32_32x32x16_bf16 v[2:17], v[154:157], v[212:215], v[2:17]
	s_waitcnt vmcnt(18)
	ds_write_b128 v188, v[70:73] offset:41472
	v_mfma_f32_32x32x16_bf16 v[18:33], v[154:157], v[220:223], v[18:33]
	s_waitcnt vmcnt(17)
	ds_write_b128 v188, v[74:77] offset:46080
	v_mfma_f32_32x32x16_bf16 v[50:65], v[146:149], v[212:215], v[50:65]
	s_waitcnt vmcnt(16)
	ds_write_b128 v188, v[110:113] offset:50688
	ds_read_b128 v[146:149], v0 offset:64
	ds_read_b128 v[154:157], v0 offset:4672
	ds_read_b128 v[212:215], v171 offset:18496
	ds_read_b128 v[220:223], v171 offset:23104
	s_waitcnt lgkmcnt(8)
	v_mfma_f32_32x32x16_bf16 v[34:49], v[150:153], v[224:227], v[34:49]
	s_waitcnt vmcnt(15)
	ds_write_b128 v188, v[114:117] offset:55296
	v_mfma_f32_32x32x16_bf16 v[2:17], v[190:193], v[216:219], v[2:17]
	s_waitcnt vmcnt(14)
	ds_write_b128 v188, v[118:121] offset:59904
	v_mfma_f32_32x32x16_bf16 v[18:33], v[190:193], v[224:227], v[18:33]
	s_waitcnt vmcnt(13)
	ds_write_b128 v188, v[138:141] offset:64512
	v_mfma_f32_32x32x16_bf16 v[50:65], v[150:153], v[216:219], v[50:65]
	s_waitcnt vmcnt(12)
	ds_write_b128 v189, v[142:145] offset:13824
	ds_read_b128 v[150:153], v0 offset:96
	ds_read_b128 v[190:193], v0 offset:4704
	ds_read_b128 v[216:219], v171 offset:18528
	ds_read_b128 v[224:227], v171 offset:23136
	s_waitcnt lgkmcnt(8)
	v_mfma_f32_32x32x16_bf16 v[34:49], v[146:149], v[220:223], v[34:49]
	global_load_dwordx4 v[114:117], v[172:173], off offset:2688
	global_load_dwordx4 v[118:121], v[176:177], off offset:2688
	v_mfma_f32_32x32x16_bf16 v[2:17], v[154:157], v[212:215], v[2:17]
	global_load_dwordx4 v[138:141], v[178:179], off offset:2688
	global_load_dwordx4 v[142:145], v[180:181], off offset:2688
	v_mfma_f32_32x32x16_bf16 v[18:33], v[154:157], v[220:223], v[18:33]
	global_load_dwordx4 v[66:69], v[174:175], off offset:2816
	global_load_dwordx4 v[70:73], v[182:183], off offset:2816
	v_mfma_f32_32x32x16_bf16 v[50:65], v[146:149], v[212:215], v[50:65]
	global_load_dwordx4 v[74:77], v[184:185], off offset:2816
	global_load_dwordx4 v[110:113], v[186:187], off offset:2816
	s_waitcnt lgkmcnt(0)
	v_mfma_f32_32x32x16_bf16 v[34:49], v[150:153], v[224:227], v[34:49]
	v_mfma_f32_32x32x16_bf16 v[2:17], v[190:193], v[216:219], v[2:17]
	v_mfma_f32_32x32x16_bf16 v[18:33], v[190:193], v[224:227], v[18:33]
	v_mfma_f32_32x32x16_bf16 v[50:65], v[150:153], v[216:219], v[50:65]
	s_waitcnt lgkmcnt(0)
	s_setprio 0
	s_barrier
	s_setprio 2
	ds_read_b128 v[146:149], v0 offset:36864
	ds_read_b128 v[154:157], v0 offset:41472
	ds_read_b128 v[212:215], v171 offset:55296
	ds_read_b128 v[220:223], v171 offset:59904
	ds_read_b128 v[150:153], v0 offset:36896
	ds_read_b128 v[190:193], v0 offset:41504
	ds_read_b128 v[216:219], v171 offset:55328
	ds_read_b128 v[224:227], v171 offset:59936
	s_waitcnt lgkmcnt(4)
	v_mfma_f32_32x32x16_bf16 v[34:49], v[146:149], v[220:223], v[34:49]
	s_waitcnt vmcnt(19)
	ds_write_b128 v188, v[78:81]
	v_mfma_f32_32x32x16_bf16 v[2:17], v[154:157], v[212:215], v[2:17]
	s_waitcnt vmcnt(18)
	ds_write_b128 v188, v[94:97] offset:4608
	v_mfma_f32_32x32x16_bf16 v[18:33], v[154:157], v[220:223], v[18:33]
	s_waitcnt vmcnt(17)
	ds_write_b128 v188, v[98:101] offset:9216
	v_mfma_f32_32x32x16_bf16 v[50:65], v[146:149], v[212:215], v[50:65]
	s_waitcnt vmcnt(16)
	ds_write_b128 v188, v[102:105] offset:13824
	ds_read_b128 v[146:149], v0 offset:36928
	ds_read_b128 v[154:157], v0 offset:41536
	ds_read_b128 v[212:215], v171 offset:55360
	ds_read_b128 v[220:223], v171 offset:59968
	s_waitcnt lgkmcnt(8)
	v_mfma_f32_32x32x16_bf16 v[34:49], v[150:153], v[224:227], v[34:49]
	s_waitcnt vmcnt(15)
	ds_write_b128 v188, v[122:125] offset:18432
	v_mfma_f32_32x32x16_bf16 v[2:17], v[190:193], v[216:219], v[2:17]
	s_waitcnt vmcnt(14)
	ds_write_b128 v188, v[126:129] offset:23040
	v_mfma_f32_32x32x16_bf16 v[18:33], v[190:193], v[224:227], v[18:33]
	s_waitcnt vmcnt(13)
	ds_write_b128 v188, v[130:133] offset:27648
	v_mfma_f32_32x32x16_bf16 v[50:65], v[150:153], v[216:219], v[50:65]
	s_waitcnt vmcnt(12)
	ds_write_b128 v188, v[134:137] offset:32256
	ds_read_b128 v[150:153], v0 offset:36960
	ds_read_b128 v[190:193], v0 offset:41568
	ds_read_b128 v[216:219], v171 offset:55392
	ds_read_b128 v[224:227], v171 offset:60000
	s_waitcnt lgkmcnt(8)
	v_mfma_f32_32x32x16_bf16 v[34:49], v[146:149], v[220:223], v[34:49]
	global_load_dwordx4 v[122:125], v[172:173], off offset:2816
	global_load_dwordx4 v[126:129], v[176:177], off offset:2816
	v_mfma_f32_32x32x16_bf16 v[2:17], v[154:157], v[212:215], v[2:17]
	global_load_dwordx4 v[130:133], v[178:179], off offset:2816
	global_load_dwordx4 v[134:137], v[180:181], off offset:2816
	v_mfma_f32_32x32x16_bf16 v[18:33], v[154:157], v[220:223], v[18:33]
	global_load_dwordx4 v[78:81], v[174:175], off offset:2944
	global_load_dwordx4 v[94:97], v[182:183], off offset:2944
	v_mfma_f32_32x32x16_bf16 v[50:65], v[146:149], v[212:215], v[50:65]
	global_load_dwordx4 v[98:101], v[184:185], off offset:2944
	global_load_dwordx4 v[102:105], v[186:187], off offset:2944
	s_waitcnt lgkmcnt(0)
	v_mfma_f32_32x32x16_bf16 v[34:49], v[150:153], v[224:227], v[34:49]
	v_mfma_f32_32x32x16_bf16 v[2:17], v[190:193], v[216:219], v[2:17]
	v_mfma_f32_32x32x16_bf16 v[18:33], v[190:193], v[224:227], v[18:33]
	v_mfma_f32_32x32x16_bf16 v[50:65], v[150:153], v[216:219], v[50:65]
	s_waitcnt lgkmcnt(0)
	s_setprio 0
	s_barrier
	s_setprio 2
	ds_read_b128 v[146:149], v0
	ds_read_b128 v[154:157], v0 offset:4608
	ds_read_b128 v[212:215], v171 offset:18432
	ds_read_b128 v[220:223], v171 offset:23040
	ds_read_b128 v[150:153], v0 offset:32
	ds_read_b128 v[190:193], v0 offset:4640
	ds_read_b128 v[216:219], v171 offset:18464
	ds_read_b128 v[224:227], v171 offset:23072
	s_waitcnt lgkmcnt(4)
	v_mfma_f32_32x32x16_bf16 v[34:49], v[146:149], v[220:223], v[34:49]
	s_waitcnt vmcnt(19)
	ds_write_b128 v188, v[82:85] offset:36864
	v_mfma_f32_32x32x16_bf16 v[2:17], v[154:157], v[212:215], v[2:17]
	s_waitcnt vmcnt(18)
	ds_write_b128 v188, v[86:89] offset:41472
	v_mfma_f32_32x32x16_bf16 v[18:33], v[154:157], v[220:223], v[18:33]
	s_waitcnt vmcnt(17)
	ds_write_b128 v188, v[90:93] offset:46080
	v_mfma_f32_32x32x16_bf16 v[50:65], v[146:149], v[212:215], v[50:65]
	s_waitcnt vmcnt(16)
	ds_write_b128 v188, v[106:109] offset:50688
	ds_read_b128 v[146:149], v0 offset:64
	ds_read_b128 v[154:157], v0 offset:4672
	ds_read_b128 v[212:215], v171 offset:18496
	ds_read_b128 v[220:223], v171 offset:23104
	s_waitcnt lgkmcnt(8)
	v_mfma_f32_32x32x16_bf16 v[34:49], v[150:153], v[224:227], v[34:49]
	s_waitcnt vmcnt(15)
	ds_write_b128 v188, v[114:117] offset:55296
	v_mfma_f32_32x32x16_bf16 v[2:17], v[190:193], v[216:219], v[2:17]
	s_waitcnt vmcnt(14)
	ds_write_b128 v188, v[118:121] offset:59904
	v_mfma_f32_32x32x16_bf16 v[18:33], v[190:193], v[224:227], v[18:33]
	s_waitcnt vmcnt(13)
	ds_write_b128 v188, v[138:141] offset:64512
	v_mfma_f32_32x32x16_bf16 v[50:65], v[150:153], v[216:219], v[50:65]
	s_waitcnt vmcnt(12)
	ds_write_b128 v189, v[142:145] offset:13824
	ds_read_b128 v[150:153], v0 offset:96
	ds_read_b128 v[190:193], v0 offset:4704
	ds_read_b128 v[216:219], v171 offset:18528
	ds_read_b128 v[224:227], v171 offset:23136
	s_waitcnt lgkmcnt(8)
	v_mfma_f32_32x32x16_bf16 v[34:49], v[146:149], v[220:223], v[34:49]
	global_load_dwordx4 v[114:117], v[172:173], off offset:2944
	global_load_dwordx4 v[118:121], v[176:177], off offset:2944
	v_mfma_f32_32x32x16_bf16 v[2:17], v[154:157], v[212:215], v[2:17]
	global_load_dwordx4 v[138:141], v[178:179], off offset:2944
	global_load_dwordx4 v[142:145], v[180:181], off offset:2944
	v_mfma_f32_32x32x16_bf16 v[18:33], v[154:157], v[220:223], v[18:33]
	global_load_dwordx4 v[82:85], v[174:175], off offset:3072
	global_load_dwordx4 v[86:89], v[182:183], off offset:3072
	v_mfma_f32_32x32x16_bf16 v[50:65], v[146:149], v[212:215], v[50:65]
	global_load_dwordx4 v[90:93], v[184:185], off offset:3072
	global_load_dwordx4 v[106:109], v[186:187], off offset:3072
	s_waitcnt lgkmcnt(0)
	v_mfma_f32_32x32x16_bf16 v[34:49], v[150:153], v[224:227], v[34:49]
	v_mfma_f32_32x32x16_bf16 v[2:17], v[190:193], v[216:219], v[2:17]
	v_mfma_f32_32x32x16_bf16 v[18:33], v[190:193], v[224:227], v[18:33]
	v_mfma_f32_32x32x16_bf16 v[50:65], v[150:153], v[216:219], v[50:65]
	s_waitcnt lgkmcnt(0)
	s_setprio 0
	s_barrier
	s_setprio 2
	ds_read_b128 v[146:149], v0 offset:36864
	ds_read_b128 v[154:157], v0 offset:41472
	ds_read_b128 v[212:215], v171 offset:55296
	ds_read_b128 v[220:223], v171 offset:59904
	ds_read_b128 v[150:153], v0 offset:36896
	ds_read_b128 v[190:193], v0 offset:41504
	ds_read_b128 v[216:219], v171 offset:55328
	ds_read_b128 v[224:227], v171 offset:59936
	s_waitcnt lgkmcnt(4)
	v_mfma_f32_32x32x16_bf16 v[34:49], v[146:149], v[220:223], v[34:49]
	s_waitcnt vmcnt(19)
	ds_write_b128 v188, v[66:69]
	v_mfma_f32_32x32x16_bf16 v[2:17], v[154:157], v[212:215], v[2:17]
	s_waitcnt vmcnt(18)
	ds_write_b128 v188, v[70:73] offset:4608
	v_mfma_f32_32x32x16_bf16 v[18:33], v[154:157], v[220:223], v[18:33]
	s_waitcnt vmcnt(17)
	ds_write_b128 v188, v[74:77] offset:9216
	v_mfma_f32_32x32x16_bf16 v[50:65], v[146:149], v[212:215], v[50:65]
	s_waitcnt vmcnt(16)
	ds_write_b128 v188, v[110:113] offset:13824
	ds_read_b128 v[146:149], v0 offset:36928
	ds_read_b128 v[154:157], v0 offset:41536
	ds_read_b128 v[212:215], v171 offset:55360
	ds_read_b128 v[220:223], v171 offset:59968
	s_waitcnt lgkmcnt(8)
	v_mfma_f32_32x32x16_bf16 v[34:49], v[150:153], v[224:227], v[34:49]
	s_waitcnt vmcnt(15)
	ds_write_b128 v188, v[122:125] offset:18432
	v_mfma_f32_32x32x16_bf16 v[2:17], v[190:193], v[216:219], v[2:17]
	s_waitcnt vmcnt(14)
	ds_write_b128 v188, v[126:129] offset:23040
	v_mfma_f32_32x32x16_bf16 v[18:33], v[190:193], v[224:227], v[18:33]
	s_waitcnt vmcnt(13)
	ds_write_b128 v188, v[130:133] offset:27648
	v_mfma_f32_32x32x16_bf16 v[50:65], v[150:153], v[216:219], v[50:65]
	s_waitcnt vmcnt(12)
	ds_write_b128 v188, v[134:137] offset:32256
	ds_read_b128 v[150:153], v0 offset:36960
	ds_read_b128 v[190:193], v0 offset:41568
	ds_read_b128 v[216:219], v171 offset:55392
	ds_read_b128 v[224:227], v171 offset:60000
	s_waitcnt lgkmcnt(8)
	v_mfma_f32_32x32x16_bf16 v[34:49], v[146:149], v[220:223], v[34:49]
	global_load_dwordx4 v[122:125], v[172:173], off offset:3072
	global_load_dwordx4 v[126:129], v[176:177], off offset:3072
	v_mfma_f32_32x32x16_bf16 v[2:17], v[154:157], v[212:215], v[2:17]
	global_load_dwordx4 v[130:133], v[178:179], off offset:3072
	global_load_dwordx4 v[134:137], v[180:181], off offset:3072
	v_mfma_f32_32x32x16_bf16 v[18:33], v[154:157], v[220:223], v[18:33]
	global_load_dwordx4 v[66:69], v[174:175], off offset:3200
	global_load_dwordx4 v[70:73], v[182:183], off offset:3200
	v_mfma_f32_32x32x16_bf16 v[50:65], v[146:149], v[212:215], v[50:65]
	global_load_dwordx4 v[74:77], v[184:185], off offset:3200
	global_load_dwordx4 v[110:113], v[186:187], off offset:3200
	s_waitcnt lgkmcnt(0)
	v_mfma_f32_32x32x16_bf16 v[34:49], v[150:153], v[224:227], v[34:49]
	v_mfma_f32_32x32x16_bf16 v[2:17], v[190:193], v[216:219], v[2:17]
	v_mfma_f32_32x32x16_bf16 v[18:33], v[190:193], v[224:227], v[18:33]
	v_mfma_f32_32x32x16_bf16 v[50:65], v[150:153], v[216:219], v[50:65]
	s_waitcnt lgkmcnt(0)
	s_setprio 0
	s_barrier
	s_setprio 2
	ds_read_b128 v[146:149], v0
	ds_read_b128 v[154:157], v0 offset:4608
	ds_read_b128 v[212:215], v171 offset:18432
	ds_read_b128 v[220:223], v171 offset:23040
	ds_read_b128 v[150:153], v0 offset:32
	ds_read_b128 v[190:193], v0 offset:4640
	ds_read_b128 v[216:219], v171 offset:18464
	ds_read_b128 v[224:227], v171 offset:23072
	s_waitcnt lgkmcnt(4)
	v_mfma_f32_32x32x16_bf16 v[34:49], v[146:149], v[220:223], v[34:49]
	s_waitcnt vmcnt(19)
	ds_write_b128 v188, v[78:81] offset:36864
	v_mfma_f32_32x32x16_bf16 v[2:17], v[154:157], v[212:215], v[2:17]
	s_waitcnt vmcnt(18)
	ds_write_b128 v188, v[94:97] offset:41472
	v_mfma_f32_32x32x16_bf16 v[18:33], v[154:157], v[220:223], v[18:33]
	s_waitcnt vmcnt(17)
	ds_write_b128 v188, v[98:101] offset:46080
	v_mfma_f32_32x32x16_bf16 v[50:65], v[146:149], v[212:215], v[50:65]
	s_waitcnt vmcnt(16)
	ds_write_b128 v188, v[102:105] offset:50688
	ds_read_b128 v[146:149], v0 offset:64
	ds_read_b128 v[154:157], v0 offset:4672
	ds_read_b128 v[212:215], v171 offset:18496
	ds_read_b128 v[220:223], v171 offset:23104
	s_waitcnt lgkmcnt(8)
	v_mfma_f32_32x32x16_bf16 v[34:49], v[150:153], v[224:227], v[34:49]
	s_waitcnt vmcnt(15)
	ds_write_b128 v188, v[114:117] offset:55296
	v_mfma_f32_32x32x16_bf16 v[2:17], v[190:193], v[216:219], v[2:17]
	s_waitcnt vmcnt(14)
	ds_write_b128 v188, v[118:121] offset:59904
	v_mfma_f32_32x32x16_bf16 v[18:33], v[190:193], v[224:227], v[18:33]
	s_waitcnt vmcnt(13)
	ds_write_b128 v188, v[138:141] offset:64512
	v_mfma_f32_32x32x16_bf16 v[50:65], v[150:153], v[216:219], v[50:65]
	s_waitcnt vmcnt(12)
	ds_write_b128 v189, v[142:145] offset:13824
	ds_read_b128 v[150:153], v0 offset:96
	ds_read_b128 v[190:193], v0 offset:4704
	ds_read_b128 v[216:219], v171 offset:18528
	ds_read_b128 v[224:227], v171 offset:23136
	s_waitcnt lgkmcnt(8)
	v_mfma_f32_32x32x16_bf16 v[34:49], v[146:149], v[220:223], v[34:49]
	global_load_dwordx4 v[114:117], v[172:173], off offset:3200
	global_load_dwordx4 v[118:121], v[176:177], off offset:3200
	v_mfma_f32_32x32x16_bf16 v[2:17], v[154:157], v[212:215], v[2:17]
	global_load_dwordx4 v[138:141], v[178:179], off offset:3200
	global_load_dwordx4 v[142:145], v[180:181], off offset:3200
	v_mfma_f32_32x32x16_bf16 v[18:33], v[154:157], v[220:223], v[18:33]
	global_load_dwordx4 v[78:81], v[174:175], off offset:3328
	global_load_dwordx4 v[94:97], v[182:183], off offset:3328
	v_mfma_f32_32x32x16_bf16 v[50:65], v[146:149], v[212:215], v[50:65]
	global_load_dwordx4 v[98:101], v[184:185], off offset:3328
	global_load_dwordx4 v[102:105], v[186:187], off offset:3328
	s_waitcnt lgkmcnt(0)
	v_mfma_f32_32x32x16_bf16 v[34:49], v[150:153], v[224:227], v[34:49]
	v_mfma_f32_32x32x16_bf16 v[2:17], v[190:193], v[216:219], v[2:17]
	v_mfma_f32_32x32x16_bf16 v[18:33], v[190:193], v[224:227], v[18:33]
	v_mfma_f32_32x32x16_bf16 v[50:65], v[150:153], v[216:219], v[50:65]
	s_waitcnt lgkmcnt(0)
	s_setprio 0
	s_barrier
	s_setprio 2
	ds_read_b128 v[146:149], v0 offset:36864
	ds_read_b128 v[154:157], v0 offset:41472
	ds_read_b128 v[212:215], v171 offset:55296
	ds_read_b128 v[220:223], v171 offset:59904
	ds_read_b128 v[150:153], v0 offset:36896
	ds_read_b128 v[190:193], v0 offset:41504
	ds_read_b128 v[216:219], v171 offset:55328
	ds_read_b128 v[224:227], v171 offset:59936
	s_waitcnt lgkmcnt(4)
	v_mfma_f32_32x32x16_bf16 v[34:49], v[146:149], v[220:223], v[34:49]
	s_waitcnt vmcnt(19)
	ds_write_b128 v188, v[82:85]
	v_mfma_f32_32x32x16_bf16 v[2:17], v[154:157], v[212:215], v[2:17]
	s_waitcnt vmcnt(18)
	ds_write_b128 v188, v[86:89] offset:4608
	v_mfma_f32_32x32x16_bf16 v[18:33], v[154:157], v[220:223], v[18:33]
	s_waitcnt vmcnt(17)
	ds_write_b128 v188, v[90:93] offset:9216
	v_mfma_f32_32x32x16_bf16 v[50:65], v[146:149], v[212:215], v[50:65]
	s_waitcnt vmcnt(16)
	ds_write_b128 v188, v[106:109] offset:13824
	ds_read_b128 v[146:149], v0 offset:36928
	ds_read_b128 v[154:157], v0 offset:41536
	ds_read_b128 v[212:215], v171 offset:55360
	ds_read_b128 v[220:223], v171 offset:59968
	s_waitcnt lgkmcnt(8)
	v_mfma_f32_32x32x16_bf16 v[34:49], v[150:153], v[224:227], v[34:49]
	s_waitcnt vmcnt(15)
	ds_write_b128 v188, v[122:125] offset:18432
	v_mfma_f32_32x32x16_bf16 v[2:17], v[190:193], v[216:219], v[2:17]
	s_waitcnt vmcnt(14)
	ds_write_b128 v188, v[126:129] offset:23040
	v_mfma_f32_32x32x16_bf16 v[18:33], v[190:193], v[224:227], v[18:33]
	s_waitcnt vmcnt(13)
	ds_write_b128 v188, v[130:133] offset:27648
	v_mfma_f32_32x32x16_bf16 v[50:65], v[150:153], v[216:219], v[50:65]
	s_waitcnt vmcnt(12)
	ds_write_b128 v188, v[134:137] offset:32256
	ds_read_b128 v[150:153], v0 offset:36960
	ds_read_b128 v[190:193], v0 offset:41568
	ds_read_b128 v[216:219], v171 offset:55392
	ds_read_b128 v[224:227], v171 offset:60000
	s_waitcnt lgkmcnt(8)
	v_mfma_f32_32x32x16_bf16 v[34:49], v[146:149], v[220:223], v[34:49]
	global_load_dwordx4 v[122:125], v[172:173], off offset:3328
	global_load_dwordx4 v[126:129], v[176:177], off offset:3328
	v_mfma_f32_32x32x16_bf16 v[2:17], v[154:157], v[212:215], v[2:17]
	global_load_dwordx4 v[130:133], v[178:179], off offset:3328
	global_load_dwordx4 v[134:137], v[180:181], off offset:3328
	v_mfma_f32_32x32x16_bf16 v[18:33], v[154:157], v[220:223], v[18:33]
	global_load_dwordx4 v[82:85], v[174:175], off offset:3456
	global_load_dwordx4 v[86:89], v[182:183], off offset:3456
	v_mfma_f32_32x32x16_bf16 v[50:65], v[146:149], v[212:215], v[50:65]
	global_load_dwordx4 v[90:93], v[184:185], off offset:3456
	global_load_dwordx4 v[106:109], v[186:187], off offset:3456
	s_waitcnt lgkmcnt(0)
	v_mfma_f32_32x32x16_bf16 v[34:49], v[150:153], v[224:227], v[34:49]
	v_mfma_f32_32x32x16_bf16 v[2:17], v[190:193], v[216:219], v[2:17]
	v_mfma_f32_32x32x16_bf16 v[18:33], v[190:193], v[224:227], v[18:33]
	v_mfma_f32_32x32x16_bf16 v[50:65], v[150:153], v[216:219], v[50:65]
	s_waitcnt lgkmcnt(0)
	s_setprio 0
	s_barrier
	s_setprio 2
	ds_read_b128 v[146:149], v0
	ds_read_b128 v[154:157], v0 offset:4608
	ds_read_b128 v[212:215], v171 offset:18432
	ds_read_b128 v[220:223], v171 offset:23040
	ds_read_b128 v[150:153], v0 offset:32
	ds_read_b128 v[190:193], v0 offset:4640
	ds_read_b128 v[216:219], v171 offset:18464
	ds_read_b128 v[224:227], v171 offset:23072
	s_waitcnt lgkmcnt(4)
	v_mfma_f32_32x32x16_bf16 v[34:49], v[146:149], v[220:223], v[34:49]
	s_waitcnt vmcnt(19)
	ds_write_b128 v188, v[66:69] offset:36864
	v_mfma_f32_32x32x16_bf16 v[2:17], v[154:157], v[212:215], v[2:17]
	s_waitcnt vmcnt(18)
	ds_write_b128 v188, v[70:73] offset:41472
	v_mfma_f32_32x32x16_bf16 v[18:33], v[154:157], v[220:223], v[18:33]
	s_waitcnt vmcnt(17)
	ds_write_b128 v188, v[74:77] offset:46080
	v_mfma_f32_32x32x16_bf16 v[50:65], v[146:149], v[212:215], v[50:65]
	s_waitcnt vmcnt(16)
	ds_write_b128 v188, v[110:113] offset:50688
	ds_read_b128 v[146:149], v0 offset:64
	ds_read_b128 v[154:157], v0 offset:4672
	ds_read_b128 v[212:215], v171 offset:18496
	ds_read_b128 v[220:223], v171 offset:23104
	s_waitcnt lgkmcnt(8)
	v_mfma_f32_32x32x16_bf16 v[34:49], v[150:153], v[224:227], v[34:49]
	s_waitcnt vmcnt(15)
	ds_write_b128 v188, v[114:117] offset:55296
	v_mfma_f32_32x32x16_bf16 v[2:17], v[190:193], v[216:219], v[2:17]
	s_waitcnt vmcnt(14)
	ds_write_b128 v188, v[118:121] offset:59904
	v_mfma_f32_32x32x16_bf16 v[18:33], v[190:193], v[224:227], v[18:33]
	s_waitcnt vmcnt(13)
	ds_write_b128 v188, v[138:141] offset:64512
	v_mfma_f32_32x32x16_bf16 v[50:65], v[150:153], v[216:219], v[50:65]
	s_waitcnt vmcnt(12)
	ds_write_b128 v189, v[142:145] offset:13824
	ds_read_b128 v[150:153], v0 offset:96
	ds_read_b128 v[190:193], v0 offset:4704
	ds_read_b128 v[216:219], v171 offset:18528
	ds_read_b128 v[224:227], v171 offset:23136
	s_waitcnt lgkmcnt(8)
	v_mfma_f32_32x32x16_bf16 v[34:49], v[146:149], v[220:223], v[34:49]
	global_load_dwordx4 v[114:117], v[172:173], off offset:3456
	global_load_dwordx4 v[118:121], v[176:177], off offset:3456
	v_mfma_f32_32x32x16_bf16 v[2:17], v[154:157], v[212:215], v[2:17]
	global_load_dwordx4 v[138:141], v[178:179], off offset:3456
	global_load_dwordx4 v[142:145], v[180:181], off offset:3456
	v_mfma_f32_32x32x16_bf16 v[18:33], v[154:157], v[220:223], v[18:33]
	global_load_dwordx4 v[66:69], v[174:175], off offset:3584
	global_load_dwordx4 v[70:73], v[182:183], off offset:3584
	v_mfma_f32_32x32x16_bf16 v[50:65], v[146:149], v[212:215], v[50:65]
	global_load_dwordx4 v[74:77], v[184:185], off offset:3584
	global_load_dwordx4 v[110:113], v[186:187], off offset:3584
	s_waitcnt lgkmcnt(0)
	v_mfma_f32_32x32x16_bf16 v[34:49], v[150:153], v[224:227], v[34:49]
	v_mfma_f32_32x32x16_bf16 v[2:17], v[190:193], v[216:219], v[2:17]
	v_mfma_f32_32x32x16_bf16 v[18:33], v[190:193], v[224:227], v[18:33]
	v_mfma_f32_32x32x16_bf16 v[50:65], v[150:153], v[216:219], v[50:65]
	s_waitcnt lgkmcnt(0)
	s_setprio 0
	s_barrier
	s_setprio 2
	s_waitcnt vmcnt(13)
	ds_write_b128 v188, v[130:133] offset:27648
	s_waitcnt vmcnt(12)
	ds_write_b128 v188, v[134:137] offset:32256
	ds_read_b128 v[130:133], v0 offset:36864
	ds_read_b128 v[154:157], v0 offset:41472
	ds_read_b128 v[212:215], v171 offset:55296
	ds_read_b128 v[220:223], v171 offset:59904
	ds_read_b128 v[134:137], v0 offset:36896
	ds_read_b128 v[190:193], v0 offset:41504
	ds_read_b128 v[216:219], v171 offset:55328
	ds_read_b128 v[224:227], v171 offset:59936
	s_waitcnt lgkmcnt(4)
	v_mfma_f32_32x32x16_bf16 v[34:49], v[130:133], v[220:223], v[34:49]
	s_waitcnt vmcnt(19)
	ds_write_b128 v188, v[78:81]
	v_mfma_f32_32x32x16_bf16 v[2:17], v[154:157], v[212:215], v[2:17]
	s_waitcnt vmcnt(18)
	ds_write_b128 v188, v[94:97] offset:4608
	v_mfma_f32_32x32x16_bf16 v[18:33], v[154:157], v[220:223], v[18:33]
	s_waitcnt vmcnt(17)
	ds_write_b128 v188, v[98:101] offset:9216
	v_mfma_f32_32x32x16_bf16 v[50:65], v[130:133], v[212:215], v[50:65]
	s_waitcnt vmcnt(16)
	ds_write_b128 v188, v[102:105] offset:13824
	ds_read_b128 v[130:133], v0 offset:36928
	ds_read_b128 v[154:157], v0 offset:41536
	ds_read_b128 v[212:215], v171 offset:55360
	ds_read_b128 v[220:223], v171 offset:59968
	s_waitcnt lgkmcnt(8)
	v_mfma_f32_32x32x16_bf16 v[34:49], v[134:137], v[224:227], v[34:49]
	s_waitcnt vmcnt(15)
	ds_write_b128 v188, v[122:125] offset:18432
	v_mfma_f32_32x32x16_bf16 v[2:17], v[190:193], v[216:219], v[2:17]
	s_waitcnt vmcnt(14)
	ds_write_b128 v188, v[126:129] offset:23040
	v_mfma_f32_32x32x16_bf16 v[18:33], v[190:193], v[224:227], v[18:33]
	v_mfma_f32_32x32x16_bf16 v[50:65], v[134:137], v[216:219], v[50:65]
	ds_read_b128 v[134:137], v0 offset:36960
	ds_read_b128 v[190:193], v0 offset:41568
	ds_read_b128 v[216:219], v171 offset:55392
	ds_read_b128 v[224:227], v171 offset:60000
	s_waitcnt lgkmcnt(6)
	v_mfma_f32_32x32x16_bf16 v[34:49], v[130:133], v[220:223], v[34:49]
	global_load_dwordx4 v[122:125], v[172:173], off offset:3584
	global_load_dwordx4 v[126:129], v[176:177], off offset:3584
	v_mfma_f32_32x32x16_bf16 v[2:17], v[154:157], v[212:215], v[2:17]
	global_load_dwordx4 v[146:149], v[178:179], off offset:3584
	global_load_dwordx4 v[150:153], v[180:181], off offset:3584
	v_mfma_f32_32x32x16_bf16 v[18:33], v[154:157], v[220:223], v[18:33]
	global_load_dwordx4 v[78:81], v[174:175], off offset:3712
	global_load_dwordx4 v[94:97], v[182:183], off offset:3712
	v_mfma_f32_32x32x16_bf16 v[50:65], v[130:133], v[212:215], v[50:65]
	global_load_dwordx4 v[98:101], v[184:185], off offset:3712
	global_load_dwordx4 v[102:105], v[186:187], off offset:3712
	s_waitcnt lgkmcnt(0)
	v_mfma_f32_32x32x16_bf16 v[34:49], v[134:137], v[224:227], v[34:49]
	v_mfma_f32_32x32x16_bf16 v[2:17], v[190:193], v[216:219], v[2:17]
	v_mfma_f32_32x32x16_bf16 v[18:33], v[190:193], v[224:227], v[18:33]
	v_mfma_f32_32x32x16_bf16 v[50:65], v[134:137], v[216:219], v[50:65]
	s_waitcnt lgkmcnt(0)
	s_setprio 0
	s_barrier
	s_setprio 2
	s_waitcnt vmcnt(16)
	ds_write_b128 v188, v[106:109] offset:50688
	s_waitcnt vmcnt(15)
	ds_write_b128 v188, v[114:117] offset:55296
	s_waitcnt vmcnt(13)
	ds_write_b128 v188, v[138:141] offset:64512
	ds_read_b128 v[106:109], v0
	ds_read_b128 v[138:141], v0 offset:4608
	ds_read_b128 v[212:215], v171 offset:18432
	ds_read_b128 v[220:223], v171 offset:23040
	ds_read_b128 v[114:117], v0 offset:32
	ds_read_b128 v[190:193], v0 offset:4640
	ds_read_b128 v[216:219], v171 offset:18464
	ds_read_b128 v[224:227], v171 offset:23072
	s_waitcnt lgkmcnt(4)
	v_mfma_f32_32x32x16_bf16 v[34:49], v[106:109], v[220:223], v[34:49]
	s_waitcnt vmcnt(19)
	ds_write_b128 v188, v[82:85] offset:36864
	v_mfma_f32_32x32x16_bf16 v[2:17], v[138:141], v[212:215], v[2:17]
	s_waitcnt vmcnt(18)
	ds_write_b128 v188, v[86:89] offset:41472
	v_mfma_f32_32x32x16_bf16 v[18:33], v[138:141], v[220:223], v[18:33]
	s_waitcnt vmcnt(17)
	ds_write_b128 v188, v[90:93] offset:46080
	v_mfma_f32_32x32x16_bf16 v[50:65], v[106:109], v[212:215], v[50:65]
	s_waitcnt vmcnt(14)
	ds_write_b128 v188, v[118:121] offset:59904
	ds_read_b128 v[106:109], v0 offset:64
	ds_read_b128 v[138:141], v0 offset:4672
	ds_read_b128 v[212:215], v171 offset:18496
	ds_read_b128 v[220:223], v171 offset:23104
	s_waitcnt lgkmcnt(8)
	v_mfma_f32_32x32x16_bf16 v[34:49], v[114:117], v[224:227], v[34:49]
	s_waitcnt vmcnt(12)
	ds_write_b128 v189, v[142:145] offset:13824
	v_mfma_f32_32x32x16_bf16 v[2:17], v[190:193], v[216:219], v[2:17]
	v_mfma_f32_32x32x16_bf16 v[18:33], v[190:193], v[224:227], v[18:33]
	v_mfma_f32_32x32x16_bf16 v[50:65], v[114:117], v[216:219], v[50:65]
	ds_read_b128 v[114:117], v0 offset:96
	ds_read_b128 v[190:193], v0 offset:4704
	ds_read_b128 v[216:219], v171 offset:18528
	ds_read_b128 v[224:227], v171 offset:23136
	s_waitcnt lgkmcnt(5)
	v_mfma_f32_32x32x16_bf16 v[34:49], v[106:109], v[220:223], v[34:49]
	global_load_dwordx4 v[130:133], v[172:173], off offset:3712
	global_load_dwordx4 v[134:137], v[176:177], off offset:3712
	v_mfma_f32_32x32x16_bf16 v[2:17], v[138:141], v[212:215], v[2:17]
	global_load_dwordx4 v[142:145], v[178:179], off offset:3712
	global_load_dwordx4 v[154:157], v[180:181], off offset:3712
	v_mfma_f32_32x32x16_bf16 v[18:33], v[138:141], v[220:223], v[18:33]
	global_load_dwordx4 v[82:85], v[174:175], off offset:3840
	global_load_dwordx4 v[86:89], v[182:183], off offset:3840
	v_mfma_f32_32x32x16_bf16 v[50:65], v[106:109], v[212:215], v[50:65]
	global_load_dwordx4 v[90:93], v[184:185], off offset:3840
	global_load_dwordx4 v[118:121], v[186:187], off offset:3840
	s_waitcnt lgkmcnt(0)
	v_mfma_f32_32x32x16_bf16 v[34:49], v[114:117], v[224:227], v[34:49]
	v_mfma_f32_32x32x16_bf16 v[2:17], v[190:193], v[216:219], v[2:17]
	v_mfma_f32_32x32x16_bf16 v[18:33], v[190:193], v[224:227], v[18:33]
	v_mfma_f32_32x32x16_bf16 v[50:65], v[114:117], v[216:219], v[50:65]
	s_waitcnt lgkmcnt(0)
	s_setprio 0
	s_barrier
	s_waitcnt vmcnt(19)
	ds_write_b128 v188, v[66:69]
	s_waitcnt vmcnt(18)
	ds_write_b128 v188, v[70:73] offset:4608
	s_waitcnt vmcnt(17)
	ds_write_b128 v188, v[74:77] offset:9216
	s_waitcnt vmcnt(16)
	ds_write_b128 v188, v[110:113] offset:13824
	s_waitcnt vmcnt(15)
	ds_write_b128 v188, v[122:125] offset:18432
	s_waitcnt vmcnt(14)
	ds_write_b128 v188, v[126:129] offset:23040
	s_waitcnt vmcnt(13)
	ds_write_b128 v188, v[146:149] offset:27648
	s_waitcnt vmcnt(12)
	ds_write_b128 v188, v[150:153] offset:32256
	global_load_dwordx4 v[126:129], v[172:173], off offset:3840
	global_load_dwordx4 v[138:141], v[176:177], off offset:3840
	global_load_dwordx4 v[146:149], v[178:179], off offset:3840
	global_load_dwordx4 v[150:153], v[180:181], off offset:3840
	global_load_dwordx4 v[106:109], v[174:175], off offset:3968
	global_load_dwordx4 v[110:113], v[182:183], off offset:3968
	global_load_dwordx4 v[114:117], v[184:185], off offset:3968
	global_load_dwordx4 v[122:125], v[186:187], off offset:3968
	s_setprio 2
	ds_read_b128 v[66:69], v0 offset:36864
	ds_read_b128 v[70:73], v0 offset:36896
	ds_read_b128 v[74:77], v0 offset:41472
	ds_read_b128 v[182:185], v0 offset:41504
	ds_read_b128 v[190:193], v171 offset:55296
	ds_read_b128 v[212:215], v171 offset:55328
	ds_read_b128 v[216:219], v171 offset:59904
	ds_read_b128 v[220:223], v171 offset:59936
	s_waitcnt lgkmcnt(1)
	v_mfma_f32_32x32x16_bf16 v[34:49], v[66:69], v[216:219], v[34:49]
	v_mfma_f32_32x32x16_bf16 v[2:17], v[74:77], v[190:193], v[2:17]
	v_mfma_f32_32x32x16_bf16 v[18:33], v[74:77], v[216:219], v[18:33]
	v_mfma_f32_32x32x16_bf16 v[50:65], v[66:69], v[190:193], v[50:65]
	ds_read_b128 v[66:69], v0 offset:36928
	ds_read_b128 v[74:77], v0 offset:41536
	ds_read_b128 v[190:193], v171 offset:55360
	ds_read_b128 v[216:219], v171 offset:59968
	s_waitcnt lgkmcnt(4)
	v_mfma_f32_32x32x16_bf16 v[34:49], v[70:73], v[220:223], v[34:49]
	v_mfma_f32_32x32x16_bf16 v[2:17], v[182:185], v[212:215], v[2:17]
	v_mfma_f32_32x32x16_bf16 v[18:33], v[182:185], v[220:223], v[18:33]
	v_mfma_f32_32x32x16_bf16 v[50:65], v[70:73], v[212:215], v[50:65]
	ds_read_b128 v[70:73], v0 offset:36960
	ds_read_b128 v[182:185], v0 offset:41568
	ds_read_b128 v[212:215], v171 offset:55392
	ds_read_b128 v[220:223], v171 offset:60000
	s_waitcnt lgkmcnt(4)
	v_mfma_f32_32x32x16_bf16 v[34:49], v[66:69], v[216:219], v[34:49]
	v_mfma_f32_32x32x16_bf16 v[2:17], v[74:77], v[190:193], v[2:17]
	v_mfma_f32_32x32x16_bf16 v[18:33], v[74:77], v[216:219], v[18:33]
	v_mfma_f32_32x32x16_bf16 v[50:65], v[66:69], v[190:193], v[50:65]
	s_waitcnt lgkmcnt(0)
	v_mfma_f32_32x32x16_bf16 v[34:49], v[70:73], v[220:223], v[34:49]
	v_mfma_f32_32x32x16_bf16 v[2:17], v[182:185], v[212:215], v[2:17]
	v_mfma_f32_32x32x16_bf16 v[18:33], v[182:185], v[220:223], v[18:33]
	v_mfma_f32_32x32x16_bf16 v[50:65], v[70:73], v[212:215], v[50:65]
	s_setprio 0
	s_movk_i32 s6, 0x1000
	s_barrier
	s_waitcnt vmcnt(19)
	ds_write_b128 v188, v[78:81] offset:36864
	s_waitcnt vmcnt(18)
	ds_write_b128 v188, v[94:97] offset:41472
	s_waitcnt vmcnt(17)
	ds_write_b128 v188, v[98:101] offset:46080
	s_waitcnt vmcnt(16)
	ds_write_b128 v188, v[102:105] offset:50688
	s_waitcnt vmcnt(15)
	ds_write_b128 v188, v[130:133] offset:55296
	s_waitcnt vmcnt(14)
	ds_write_b128 v188, v[134:137] offset:59904
	s_waitcnt vmcnt(13)
	ds_write_b128 v188, v[142:145] offset:64512
	s_waitcnt vmcnt(12)
	ds_write_b128 v189, v[154:157] offset:13824
	v_add_co_u32_e32 v154, vcc, s6, v174
	global_load_dwordx4 v[94:97], v[172:173], off offset:3968
	global_load_dwordx4 v[98:101], v[176:177], off offset:3968
	global_load_dwordx4 v[102:105], v[178:179], off offset:3968
	global_load_dwordx4 v[134:137], v[180:181], off offset:3968
	v_addc_co_u32_e32 v155, vcc, 0, v175, vcc
	global_load_dwordx4 v[66:69], v[154:155], off
	global_load_dwordx4 v[70:73], v[164:165], off
	global_load_dwordx4 v[74:77], v[166:167], off
	global_load_dwordx4 v[78:81], v[168:169], off
	s_setprio 2
	ds_read_b128 v[130:133], v0
	ds_read_b128 v[142:145], v0 offset:32
	ds_read_b128 v[174:177], v0 offset:4608
	ds_read_b128 v[178:181], v0 offset:4640
	ds_read_b128 v[182:185], v171 offset:18432
	ds_read_b128 v[190:193], v171 offset:18464
	ds_read_b128 v[212:215], v171 offset:23040
	ds_read_b128 v[216:219], v171 offset:23072
	s_waitcnt lgkmcnt(1)
	v_mfma_f32_32x32x16_bf16 v[34:49], v[130:133], v[212:215], v[34:49]
	v_mfma_f32_32x32x16_bf16 v[2:17], v[174:177], v[182:185], v[2:17]
	v_mfma_f32_32x32x16_bf16 v[18:33], v[174:177], v[212:215], v[18:33]
	v_mfma_f32_32x32x16_bf16 v[50:65], v[130:133], v[182:185], v[50:65]
	ds_read_b128 v[130:133], v0 offset:64
	ds_read_b128 v[174:177], v0 offset:4672
	ds_read_b128 v[182:185], v171 offset:18496
	ds_read_b128 v[212:215], v171 offset:23104
	s_waitcnt lgkmcnt(4)
	v_mfma_f32_32x32x16_bf16 v[34:49], v[142:145], v[216:219], v[34:49]
	v_mfma_f32_32x32x16_bf16 v[2:17], v[178:181], v[190:193], v[2:17]
	v_mfma_f32_32x32x16_bf16 v[18:33], v[178:181], v[216:219], v[18:33]
	v_mfma_f32_32x32x16_bf16 v[50:65], v[142:145], v[190:193], v[50:65]
	ds_read_b128 v[142:145], v0 offset:96
	ds_read_b128 v[178:181], v0 offset:4704
	ds_read_b128 v[190:193], v171 offset:18528
	ds_read_b128 v[216:219], v171 offset:23136
	s_waitcnt lgkmcnt(4)
	v_mfma_f32_32x32x16_bf16 v[34:49], v[130:133], v[212:215], v[34:49]
	v_mfma_f32_32x32x16_bf16 v[2:17], v[174:177], v[182:185], v[2:17]
	v_mfma_f32_32x32x16_bf16 v[18:33], v[174:177], v[212:215], v[18:33]
	v_mfma_f32_32x32x16_bf16 v[50:65], v[130:133], v[182:185], v[50:65]
	s_waitcnt lgkmcnt(0)
	v_mfma_f32_32x32x16_bf16 v[34:49], v[142:145], v[216:219], v[34:49]
	v_mfma_f32_32x32x16_bf16 v[2:17], v[178:181], v[190:193], v[2:17]
	v_mfma_f32_32x32x16_bf16 v[18:33], v[178:181], v[216:219], v[18:33]
	v_mfma_f32_32x32x16_bf16 v[50:65], v[142:145], v[190:193], v[50:65]
	s_setprio 0
	s_barrier
	s_waitcnt vmcnt(19)
	ds_write_b128 v188, v[82:85]
	s_waitcnt vmcnt(18)
	ds_write_b128 v188, v[86:89] offset:4608
	s_waitcnt vmcnt(17)
	ds_write_b128 v188, v[90:93] offset:9216
	s_waitcnt vmcnt(16)
	ds_write_b128 v188, v[118:121] offset:13824
	s_waitcnt vmcnt(15)
	ds_write_b128 v188, v[126:129] offset:18432
	s_waitcnt vmcnt(14)
	ds_write_b128 v188, v[138:141] offset:23040
	s_waitcnt vmcnt(13)
	ds_write_b128 v188, v[146:149] offset:27648
	s_waitcnt vmcnt(12)
	ds_write_b128 v188, v[150:153] offset:32256
	v_add_co_u32_e32 v150, vcc, s6, v172
	s_nop 1
	v_addc_co_u32_e32 v151, vcc, 0, v173, vcc
	global_load_dwordx4 v[126:129], v[150:151], off
	global_load_dwordx4 v[130:133], v[158:159], off
	global_load_dwordx4 v[138:141], v[160:161], off
	global_load_dwordx4 v[142:145], v[162:163], off
	global_load_dwordx4 v[82:85], v[154:155], off offset:128
	global_load_dwordx4 v[86:89], v[164:165], off offset:128
	global_load_dwordx4 v[90:93], v[166:167], off offset:128
	global_load_dwordx4 v[118:121], v[168:169], off offset:128
	s_setprio 2
	ds_read_b128 v[146:149], v0 offset:36864
	ds_read_b128 v[172:175], v0 offset:36896
	ds_read_b128 v[176:179], v0 offset:41472
	ds_read_b128 v[180:183], v0 offset:41504
	ds_read_b128 v[184:187], v171 offset:55296
	ds_read_b128 v[190:193], v171 offset:55328
	ds_read_b128 v[212:215], v171 offset:59904
	ds_read_b128 v[216:219], v171 offset:59936
	s_waitcnt lgkmcnt(1)
	v_mfma_f32_32x32x16_bf16 v[34:49], v[146:149], v[212:215], v[34:49]
	v_mfma_f32_32x32x16_bf16 v[2:17], v[176:179], v[184:187], v[2:17]
	v_mfma_f32_32x32x16_bf16 v[18:33], v[176:179], v[212:215], v[18:33]
	v_mfma_f32_32x32x16_bf16 v[50:65], v[146:149], v[184:187], v[50:65]
	ds_read_b128 v[146:149], v0 offset:36928
	ds_read_b128 v[176:179], v0 offset:41536
	ds_read_b128 v[184:187], v171 offset:55360
	ds_read_b128 v[212:215], v171 offset:59968
	s_waitcnt lgkmcnt(4)
	v_mfma_f32_32x32x16_bf16 v[34:49], v[172:175], v[216:219], v[34:49]
	v_mfma_f32_32x32x16_bf16 v[2:17], v[180:183], v[190:193], v[2:17]
	v_mfma_f32_32x32x16_bf16 v[18:33], v[180:183], v[216:219], v[18:33]
	v_mfma_f32_32x32x16_bf16 v[50:65], v[172:175], v[190:193], v[50:65]
	ds_read_b128 v[172:175], v0 offset:36960
	ds_read_b128 v[180:183], v0 offset:41568
	ds_read_b128 v[190:193], v171 offset:55392
	ds_read_b128 v[216:219], v171 offset:60000
	s_waitcnt lgkmcnt(4)
	v_mfma_f32_32x32x16_bf16 v[34:49], v[146:149], v[212:215], v[34:49]
	v_mfma_f32_32x32x16_bf16 v[2:17], v[176:179], v[184:187], v[2:17]
	v_mfma_f32_32x32x16_bf16 v[18:33], v[176:179], v[212:215], v[18:33]
	v_mfma_f32_32x32x16_bf16 v[50:65], v[146:149], v[184:187], v[50:65]
	s_waitcnt lgkmcnt(0)
	v_mfma_f32_32x32x16_bf16 v[34:49], v[172:175], v[216:219], v[34:49]
	v_mfma_f32_32x32x16_bf16 v[2:17], v[180:183], v[190:193], v[2:17]
	v_mfma_f32_32x32x16_bf16 v[18:33], v[180:183], v[216:219], v[18:33]
	v_mfma_f32_32x32x16_bf16 v[50:65], v[172:175], v[190:193], v[50:65]
	s_setprio 0
	s_barrier
	s_setprio 2
	s_waitcnt vmcnt(18)
	ds_write_b128 v188, v[110:113] offset:41472
	ds_read_b128 v[110:113], v0
	ds_read_b128 v[176:179], v0 offset:4608
	ds_read_b128 v[184:187], v171 offset:18432
	ds_read_b128 v[212:215], v171 offset:23040
	ds_read_b128 v[172:175], v0 offset:32
	ds_read_b128 v[180:183], v0 offset:4640
	ds_read_b128 v[190:193], v171 offset:18464
	ds_read_b128 v[216:219], v171 offset:23072
	s_waitcnt lgkmcnt(4)
	v_mfma_f32_32x32x16_bf16 v[34:49], v[110:113], v[212:215], v[34:49]
	s_waitcnt vmcnt(19)
	ds_write_b128 v188, v[106:109] offset:36864
	v_mfma_f32_32x32x16_bf16 v[2:17], v[176:179], v[184:187], v[2:17]
	s_waitcnt vmcnt(17)
	ds_write_b128 v188, v[114:117] offset:46080
	v_mfma_f32_32x32x16_bf16 v[18:33], v[176:179], v[212:215], v[18:33]
	s_waitcnt vmcnt(16)
	ds_write_b128 v188, v[122:125] offset:50688
	v_mfma_f32_32x32x16_bf16 v[50:65], v[110:113], v[184:187], v[50:65]
	s_waitcnt vmcnt(15)
	ds_write_b128 v188, v[94:97] offset:55296
	ds_read_b128 v[110:113], v0 offset:64
	ds_read_b128 v[176:179], v0 offset:4672
	ds_read_b128 v[184:187], v171 offset:18496
	ds_read_b128 v[212:215], v171 offset:23104
	s_waitcnt lgkmcnt(8)
	v_mfma_f32_32x32x16_bf16 v[34:49], v[172:175], v[216:219], v[34:49]
	s_waitcnt vmcnt(14)
	ds_write_b128 v188, v[98:101] offset:59904
	v_mfma_f32_32x32x16_bf16 v[2:17], v[180:183], v[190:193], v[2:17]
	s_waitcnt vmcnt(13)
	ds_write_b128 v188, v[102:105] offset:64512
	v_mfma_f32_32x32x16_bf16 v[18:33], v[180:183], v[216:219], v[18:33]
	s_waitcnt vmcnt(12)
	ds_write_b128 v189, v[134:137] offset:13824
	v_mfma_f32_32x32x16_bf16 v[50:65], v[172:175], v[190:193], v[50:65]
	ds_read_b128 v[172:175], v0 offset:96
	ds_read_b128 v[180:183], v0 offset:4704
	ds_read_b128 v[190:193], v171 offset:18528
	ds_read_b128 v[216:219], v171 offset:23136
	s_waitcnt lgkmcnt(7)
	v_mfma_f32_32x32x16_bf16 v[34:49], v[110:113], v[212:215], v[34:49]
	global_load_dwordx4 v[114:117], v[150:151], off offset:128
	global_load_dwordx4 v[122:125], v[158:159], off offset:128
	v_mfma_f32_32x32x16_bf16 v[2:17], v[176:179], v[184:187], v[2:17]
	global_load_dwordx4 v[134:137], v[160:161], off offset:128
	global_load_dwordx4 v[146:149], v[162:163], off offset:128
	v_mfma_f32_32x32x16_bf16 v[18:33], v[176:179], v[212:215], v[18:33]
	global_load_dwordx4 v[94:97], v[154:155], off offset:256
	global_load_dwordx4 v[98:101], v[164:165], off offset:256
	v_mfma_f32_32x32x16_bf16 v[50:65], v[110:113], v[184:187], v[50:65]
	global_load_dwordx4 v[102:105], v[166:167], off offset:256
	global_load_dwordx4 v[106:109], v[168:169], off offset:256
	s_waitcnt lgkmcnt(0)
	v_mfma_f32_32x32x16_bf16 v[34:49], v[172:175], v[216:219], v[34:49]
	v_mfma_f32_32x32x16_bf16 v[2:17], v[180:183], v[190:193], v[2:17]
	v_mfma_f32_32x32x16_bf16 v[18:33], v[180:183], v[216:219], v[18:33]
	v_mfma_f32_32x32x16_bf16 v[50:65], v[172:175], v[190:193], v[50:65]
	s_waitcnt lgkmcnt(0)
	s_setprio 0
	s_barrier
	s_setprio 2
	s_waitcnt vmcnt(16)
	ds_write_b128 v188, v[78:81] offset:13824
	ds_read_b128 v[78:81], v0 offset:36864
	ds_read_b128 v[176:179], v0 offset:41472
	ds_read_b128 v[184:187], v171 offset:55296
	ds_read_b128 v[212:215], v171 offset:59904
	ds_read_b128 v[172:175], v0 offset:36896
	ds_read_b128 v[180:183], v0 offset:41504
	ds_read_b128 v[190:193], v171 offset:55328
	ds_read_b128 v[216:219], v171 offset:59936
	s_waitcnt lgkmcnt(4)
	v_mfma_f32_32x32x16_bf16 v[34:49], v[78:81], v[212:215], v[34:49]
	s_waitcnt vmcnt(19)
	ds_write_b128 v188, v[66:69]
	v_mfma_f32_32x32x16_bf16 v[2:17], v[176:179], v[184:187], v[2:17]
	s_waitcnt vmcnt(18)
	ds_write_b128 v188, v[70:73] offset:4608
	v_mfma_f32_32x32x16_bf16 v[18:33], v[176:179], v[212:215], v[18:33]
	s_waitcnt vmcnt(17)
	ds_write_b128 v188, v[74:77] offset:9216
	v_mfma_f32_32x32x16_bf16 v[50:65], v[78:81], v[184:187], v[50:65]
	s_waitcnt vmcnt(15)
	ds_write_b128 v188, v[126:129] offset:18432
	ds_read_b128 v[78:81], v0 offset:36928
	ds_read_b128 v[176:179], v0 offset:41536
	ds_read_b128 v[184:187], v171 offset:55360
	ds_read_b128 v[212:215], v171 offset:59968
	s_waitcnt lgkmcnt(8)
	v_mfma_f32_32x32x16_bf16 v[34:49], v[172:175], v[216:219], v[34:49]
	s_waitcnt vmcnt(14)
	ds_write_b128 v188, v[130:133] offset:23040
	v_mfma_f32_32x32x16_bf16 v[2:17], v[180:183], v[190:193], v[2:17]
	s_waitcnt vmcnt(13)
	ds_write_b128 v188, v[138:141] offset:27648
	v_mfma_f32_32x32x16_bf16 v[18:33], v[180:183], v[216:219], v[18:33]
	s_waitcnt vmcnt(12)
	ds_write_b128 v188, v[142:145] offset:32256
	v_mfma_f32_32x32x16_bf16 v[50:65], v[172:175], v[190:193], v[50:65]
	ds_read_b128 v[172:175], v0 offset:36960
	ds_read_b128 v[180:183], v0 offset:41568
	ds_read_b128 v[190:193], v171 offset:55392
	ds_read_b128 v[216:219], v171 offset:60000
	s_waitcnt lgkmcnt(7)
	v_mfma_f32_32x32x16_bf16 v[34:49], v[78:81], v[212:215], v[34:49]
	global_load_dwordx4 v[126:129], v[150:151], off offset:256
	global_load_dwordx4 v[130:133], v[158:159], off offset:256
	v_mfma_f32_32x32x16_bf16 v[2:17], v[176:179], v[184:187], v[2:17]
	global_load_dwordx4 v[138:141], v[160:161], off offset:256
	global_load_dwordx4 v[142:145], v[162:163], off offset:256
	v_mfma_f32_32x32x16_bf16 v[18:33], v[176:179], v[212:215], v[18:33]
	global_load_dwordx4 v[66:69], v[154:155], off offset:384
	global_load_dwordx4 v[70:73], v[164:165], off offset:384
	v_mfma_f32_32x32x16_bf16 v[50:65], v[78:81], v[184:187], v[50:65]
	global_load_dwordx4 v[74:77], v[166:167], off offset:384
	global_load_dwordx4 v[110:113], v[168:169], off offset:384
	s_waitcnt lgkmcnt(0)
	v_mfma_f32_32x32x16_bf16 v[34:49], v[172:175], v[216:219], v[34:49]
	v_mfma_f32_32x32x16_bf16 v[2:17], v[180:183], v[190:193], v[2:17]
	v_mfma_f32_32x32x16_bf16 v[18:33], v[180:183], v[216:219], v[18:33]
	v_mfma_f32_32x32x16_bf16 v[50:65], v[172:175], v[190:193], v[50:65]
	s_waitcnt lgkmcnt(0)
	s_setprio 0
	s_barrier
	s_setprio 2
	s_waitcnt vmcnt(17)
	ds_write_b128 v188, v[90:93] offset:46080
	ds_read_b128 v[90:93], v0
	ds_read_b128 v[176:179], v0 offset:4608
	ds_read_b128 v[184:187], v171 offset:18432
	ds_read_b128 v[212:215], v171 offset:23040
	ds_read_b128 v[172:175], v0 offset:32
	ds_read_b128 v[180:183], v0 offset:4640
	ds_read_b128 v[190:193], v171 offset:18464
	ds_read_b128 v[216:219], v171 offset:23072
	s_waitcnt lgkmcnt(4)
	v_mfma_f32_32x32x16_bf16 v[34:49], v[90:93], v[212:215], v[34:49]
	s_waitcnt vmcnt(19)
	ds_write_b128 v188, v[82:85] offset:36864
	v_mfma_f32_32x32x16_bf16 v[2:17], v[176:179], v[184:187], v[2:17]
	s_waitcnt vmcnt(18)
	ds_write_b128 v188, v[86:89] offset:41472
	v_mfma_f32_32x32x16_bf16 v[18:33], v[176:179], v[212:215], v[18:33]
	s_waitcnt vmcnt(16)
	ds_write_b128 v188, v[118:121] offset:50688
	v_mfma_f32_32x32x16_bf16 v[50:65], v[90:93], v[184:187], v[50:65]
	s_waitcnt vmcnt(15)
	ds_write_b128 v188, v[114:117] offset:55296
	ds_read_b128 v[90:93], v0 offset:64
	ds_read_b128 v[176:179], v0 offset:4672
	ds_read_b128 v[184:187], v171 offset:18496
	ds_read_b128 v[212:215], v171 offset:23104
	s_waitcnt lgkmcnt(8)
	v_mfma_f32_32x32x16_bf16 v[34:49], v[172:175], v[216:219], v[34:49]
	s_waitcnt vmcnt(14)
	ds_write_b128 v188, v[122:125] offset:59904
	v_mfma_f32_32x32x16_bf16 v[2:17], v[180:183], v[190:193], v[2:17]
	s_waitcnt vmcnt(13)
	ds_write_b128 v188, v[134:137] offset:64512
	v_mfma_f32_32x32x16_bf16 v[18:33], v[180:183], v[216:219], v[18:33]
	s_waitcnt vmcnt(12)
	ds_write_b128 v189, v[146:149] offset:13824
	v_mfma_f32_32x32x16_bf16 v[50:65], v[172:175], v[190:193], v[50:65]
	ds_read_b128 v[172:175], v0 offset:96
	ds_read_b128 v[180:183], v0 offset:4704
	ds_read_b128 v[190:193], v171 offset:18528
	ds_read_b128 v[216:219], v171 offset:23136
	s_waitcnt lgkmcnt(7)
	v_mfma_f32_32x32x16_bf16 v[34:49], v[90:93], v[212:215], v[34:49]
	global_load_dwordx4 v[118:121], v[150:151], off offset:384
	global_load_dwordx4 v[122:125], v[158:159], off offset:384
	v_mfma_f32_32x32x16_bf16 v[2:17], v[176:179], v[184:187], v[2:17]
	global_load_dwordx4 v[134:137], v[160:161], off offset:384
	global_load_dwordx4 v[146:149], v[162:163], off offset:384
	v_mfma_f32_32x32x16_bf16 v[18:33], v[176:179], v[212:215], v[18:33]
	global_load_dwordx4 v[78:81], v[154:155], off offset:512
	global_load_dwordx4 v[82:85], v[164:165], off offset:512
	v_mfma_f32_32x32x16_bf16 v[50:65], v[90:93], v[184:187], v[50:65]
	global_load_dwordx4 v[86:89], v[166:167], off offset:512
	global_load_dwordx4 v[114:117], v[168:169], off offset:512
	s_waitcnt lgkmcnt(0)
	v_mfma_f32_32x32x16_bf16 v[34:49], v[172:175], v[216:219], v[34:49]
	v_mfma_f32_32x32x16_bf16 v[2:17], v[180:183], v[190:193], v[2:17]
	v_mfma_f32_32x32x16_bf16 v[18:33], v[180:183], v[216:219], v[18:33]
	v_mfma_f32_32x32x16_bf16 v[50:65], v[172:175], v[190:193], v[50:65]
	s_waitcnt lgkmcnt(0)
	s_setprio 0
	s_barrier
	s_setprio 2
	s_waitcnt vmcnt(16)
	ds_write_b128 v188, v[106:109] offset:13824
	ds_read_b128 v[106:109], v0 offset:36864
	ds_read_b128 v[176:179], v0 offset:41472
	ds_read_b128 v[184:187], v171 offset:55296
	ds_read_b128 v[212:215], v171 offset:59904
	ds_read_b128 v[172:175], v0 offset:36896
	ds_read_b128 v[180:183], v0 offset:41504
	ds_read_b128 v[190:193], v171 offset:55328
	ds_read_b128 v[216:219], v171 offset:59936
	s_waitcnt lgkmcnt(4)
	v_mfma_f32_32x32x16_bf16 v[34:49], v[106:109], v[212:215], v[34:49]
	s_waitcnt vmcnt(19)
	ds_write_b128 v188, v[94:97]
	v_mfma_f32_32x32x16_bf16 v[2:17], v[176:179], v[184:187], v[2:17]
	s_waitcnt vmcnt(18)
	ds_write_b128 v188, v[98:101] offset:4608
	v_mfma_f32_32x32x16_bf16 v[18:33], v[176:179], v[212:215], v[18:33]
	s_waitcnt vmcnt(17)
	ds_write_b128 v188, v[102:105] offset:9216
	v_mfma_f32_32x32x16_bf16 v[50:65], v[106:109], v[184:187], v[50:65]
	s_waitcnt vmcnt(15)
	ds_write_b128 v188, v[126:129] offset:18432
	ds_read_b128 v[106:109], v0 offset:36928
	ds_read_b128 v[176:179], v0 offset:41536
	ds_read_b128 v[184:187], v171 offset:55360
	ds_read_b128 v[212:215], v171 offset:59968
	s_waitcnt lgkmcnt(8)
	v_mfma_f32_32x32x16_bf16 v[34:49], v[172:175], v[216:219], v[34:49]
	s_waitcnt vmcnt(14)
	ds_write_b128 v188, v[130:133] offset:23040
	v_mfma_f32_32x32x16_bf16 v[2:17], v[180:183], v[190:193], v[2:17]
	s_waitcnt vmcnt(13)
	ds_write_b128 v188, v[138:141] offset:27648
	v_mfma_f32_32x32x16_bf16 v[18:33], v[180:183], v[216:219], v[18:33]
	s_waitcnt vmcnt(12)
	ds_write_b128 v188, v[142:145] offset:32256
	v_mfma_f32_32x32x16_bf16 v[50:65], v[172:175], v[190:193], v[50:65]
	ds_read_b128 v[172:175], v0 offset:36960
	ds_read_b128 v[180:183], v0 offset:41568
	ds_read_b128 v[190:193], v171 offset:55392
	ds_read_b128 v[216:219], v171 offset:60000
	s_waitcnt lgkmcnt(7)
	v_mfma_f32_32x32x16_bf16 v[34:49], v[106:109], v[212:215], v[34:49]
	global_load_dwordx4 v[126:129], v[150:151], off offset:512
	global_load_dwordx4 v[130:133], v[158:159], off offset:512
	v_mfma_f32_32x32x16_bf16 v[2:17], v[176:179], v[184:187], v[2:17]
	global_load_dwordx4 v[138:141], v[160:161], off offset:512
	global_load_dwordx4 v[142:145], v[162:163], off offset:512
	v_mfma_f32_32x32x16_bf16 v[18:33], v[176:179], v[212:215], v[18:33]
	global_load_dwordx4 v[90:93], v[154:155], off offset:640
	global_load_dwordx4 v[94:97], v[164:165], off offset:640
	v_mfma_f32_32x32x16_bf16 v[50:65], v[106:109], v[184:187], v[50:65]
	global_load_dwordx4 v[98:101], v[166:167], off offset:640
	global_load_dwordx4 v[102:105], v[168:169], off offset:640
	s_waitcnt lgkmcnt(0)
	v_mfma_f32_32x32x16_bf16 v[34:49], v[172:175], v[216:219], v[34:49]
	v_mfma_f32_32x32x16_bf16 v[2:17], v[180:183], v[190:193], v[2:17]
	v_mfma_f32_32x32x16_bf16 v[18:33], v[180:183], v[216:219], v[18:33]
	v_mfma_f32_32x32x16_bf16 v[50:65], v[172:175], v[190:193], v[50:65]
	s_waitcnt lgkmcnt(0)
	s_setprio 0
	s_barrier
	s_setprio 2
	s_waitcnt vmcnt(16)
	ds_write_b128 v188, v[110:113] offset:50688
	ds_read_b128 v[110:113], v0
	ds_read_b128 v[176:179], v0 offset:4608
	ds_read_b128 v[184:187], v171 offset:18432
	ds_read_b128 v[212:215], v171 offset:23040
	ds_read_b128 v[172:175], v0 offset:32
	ds_read_b128 v[180:183], v0 offset:4640
	ds_read_b128 v[190:193], v171 offset:18464
	ds_read_b128 v[216:219], v171 offset:23072
	s_waitcnt lgkmcnt(4)
	v_mfma_f32_32x32x16_bf16 v[34:49], v[110:113], v[212:215], v[34:49]
	s_waitcnt vmcnt(19)
	ds_write_b128 v188, v[66:69] offset:36864
	v_mfma_f32_32x32x16_bf16 v[2:17], v[176:179], v[184:187], v[2:17]
	s_waitcnt vmcnt(18)
	ds_write_b128 v188, v[70:73] offset:41472
	v_mfma_f32_32x32x16_bf16 v[18:33], v[176:179], v[212:215], v[18:33]
	s_waitcnt vmcnt(17)
	ds_write_b128 v188, v[74:77] offset:46080
	v_mfma_f32_32x32x16_bf16 v[50:65], v[110:113], v[184:187], v[50:65]
	s_waitcnt vmcnt(15)
	ds_write_b128 v188, v[118:121] offset:55296
	ds_read_b128 v[110:113], v0 offset:64
	ds_read_b128 v[176:179], v0 offset:4672
	ds_read_b128 v[184:187], v171 offset:18496
	ds_read_b128 v[212:215], v171 offset:23104
	s_waitcnt lgkmcnt(8)
	v_mfma_f32_32x32x16_bf16 v[34:49], v[172:175], v[216:219], v[34:49]
	s_waitcnt vmcnt(14)
	ds_write_b128 v188, v[122:125] offset:59904
	v_mfma_f32_32x32x16_bf16 v[2:17], v[180:183], v[190:193], v[2:17]
	s_waitcnt vmcnt(13)
	ds_write_b128 v188, v[134:137] offset:64512
	v_mfma_f32_32x32x16_bf16 v[18:33], v[180:183], v[216:219], v[18:33]
	s_waitcnt vmcnt(12)
	ds_write_b128 v189, v[146:149] offset:13824
	v_mfma_f32_32x32x16_bf16 v[50:65], v[172:175], v[190:193], v[50:65]
	ds_read_b128 v[172:175], v0 offset:96
	ds_read_b128 v[180:183], v0 offset:4704
	ds_read_b128 v[190:193], v171 offset:18528
	ds_read_b128 v[216:219], v171 offset:23136
	s_waitcnt lgkmcnt(7)
	v_mfma_f32_32x32x16_bf16 v[34:49], v[110:113], v[212:215], v[34:49]
	global_load_dwordx4 v[118:121], v[150:151], off offset:640
	global_load_dwordx4 v[122:125], v[158:159], off offset:640
	v_mfma_f32_32x32x16_bf16 v[2:17], v[176:179], v[184:187], v[2:17]
	global_load_dwordx4 v[134:137], v[160:161], off offset:640
	global_load_dwordx4 v[146:149], v[162:163], off offset:640
	v_mfma_f32_32x32x16_bf16 v[18:33], v[176:179], v[212:215], v[18:33]
	global_load_dwordx4 v[66:69], v[154:155], off offset:768
	global_load_dwordx4 v[70:73], v[164:165], off offset:768
	v_mfma_f32_32x32x16_bf16 v[50:65], v[110:113], v[184:187], v[50:65]
	global_load_dwordx4 v[74:77], v[166:167], off offset:768
	global_load_dwordx4 v[106:109], v[168:169], off offset:768
	s_waitcnt lgkmcnt(0)
	v_mfma_f32_32x32x16_bf16 v[34:49], v[172:175], v[216:219], v[34:49]
	v_mfma_f32_32x32x16_bf16 v[2:17], v[180:183], v[190:193], v[2:17]
	v_mfma_f32_32x32x16_bf16 v[18:33], v[180:183], v[216:219], v[18:33]
	v_mfma_f32_32x32x16_bf16 v[50:65], v[172:175], v[190:193], v[50:65]
	s_waitcnt lgkmcnt(0)
	s_setprio 0
	s_barrier
	s_setprio 2
	s_waitcnt vmcnt(12)
	ds_write_b128 v188, v[142:145] offset:32256
	ds_read_b128 v[142:145], v0 offset:36864
	ds_read_b128 v[176:179], v0 offset:41472
	ds_read_b128 v[184:187], v171 offset:55296
	ds_read_b128 v[212:215], v171 offset:59904
	ds_read_b128 v[172:175], v0 offset:36896
	ds_read_b128 v[180:183], v0 offset:41504
	ds_read_b128 v[190:193], v171 offset:55328
	ds_read_b128 v[216:219], v171 offset:59936
	s_waitcnt lgkmcnt(4)
	v_mfma_f32_32x32x16_bf16 v[34:49], v[142:145], v[212:215], v[34:49]
	s_waitcnt vmcnt(19)
	ds_write_b128 v188, v[78:81]
	v_mfma_f32_32x32x16_bf16 v[2:17], v[176:179], v[184:187], v[2:17]
	s_waitcnt vmcnt(18)
	ds_write_b128 v188, v[82:85] offset:4608
	v_mfma_f32_32x32x16_bf16 v[18:33], v[176:179], v[212:215], v[18:33]
	s_waitcnt vmcnt(17)
	ds_write_b128 v188, v[86:89] offset:9216
	v_mfma_f32_32x32x16_bf16 v[50:65], v[142:145], v[184:187], v[50:65]
	s_waitcnt vmcnt(16)
	ds_write_b128 v188, v[114:117] offset:13824
	ds_read_b128 v[142:145], v0 offset:36928
	ds_read_b128 v[176:179], v0 offset:41536
	ds_read_b128 v[184:187], v171 offset:55360
	ds_read_b128 v[212:215], v171 offset:59968
	s_waitcnt lgkmcnt(8)
	v_mfma_f32_32x32x16_bf16 v[34:49], v[172:175], v[216:219], v[34:49]
	s_waitcnt vmcnt(15)
	ds_write_b128 v188, v[126:129] offset:18432
	v_mfma_f32_32x32x16_bf16 v[2:17], v[180:183], v[190:193], v[2:17]
	s_waitcnt vmcnt(14)
	ds_write_b128 v188, v[130:133] offset:23040
	v_mfma_f32_32x32x16_bf16 v[18:33], v[180:183], v[216:219], v[18:33]
	s_waitcnt vmcnt(13)
	ds_write_b128 v188, v[138:141] offset:27648
	v_mfma_f32_32x32x16_bf16 v[50:65], v[172:175], v[190:193], v[50:65]
	ds_read_b128 v[172:175], v0 offset:36960
	ds_read_b128 v[180:183], v0 offset:41568
	ds_read_b128 v[190:193], v171 offset:55392
	ds_read_b128 v[216:219], v171 offset:60000
	s_waitcnt lgkmcnt(7)
	v_mfma_f32_32x32x16_bf16 v[34:49], v[142:145], v[212:215], v[34:49]
	global_load_dwordx4 v[114:117], v[150:151], off offset:768
	global_load_dwordx4 v[126:129], v[158:159], off offset:768
	v_mfma_f32_32x32x16_bf16 v[2:17], v[176:179], v[184:187], v[2:17]
	global_load_dwordx4 v[130:133], v[160:161], off offset:768
	global_load_dwordx4 v[138:141], v[162:163], off offset:768
	v_mfma_f32_32x32x16_bf16 v[18:33], v[176:179], v[212:215], v[18:33]
	global_load_dwordx4 v[78:81], v[154:155], off offset:896
	global_load_dwordx4 v[82:85], v[164:165], off offset:896
	v_mfma_f32_32x32x16_bf16 v[50:65], v[142:145], v[184:187], v[50:65]
	global_load_dwordx4 v[86:89], v[166:167], off offset:896
	global_load_dwordx4 v[110:113], v[168:169], off offset:896
	s_waitcnt lgkmcnt(0)
	v_mfma_f32_32x32x16_bf16 v[34:49], v[172:175], v[216:219], v[34:49]
	v_mfma_f32_32x32x16_bf16 v[2:17], v[180:183], v[190:193], v[2:17]
	v_mfma_f32_32x32x16_bf16 v[18:33], v[180:183], v[216:219], v[18:33]
	v_mfma_f32_32x32x16_bf16 v[50:65], v[172:175], v[190:193], v[50:65]
	s_waitcnt lgkmcnt(0)
	s_setprio 0
	s_barrier
	s_setprio 2
	s_waitcnt vmcnt(12)
	ds_write_b128 v189, v[146:149] offset:13824
	ds_read_b128 v[146:149], v0
	ds_read_b128 v[176:179], v0 offset:4608
	ds_read_b128 v[184:187], v171 offset:18432
	ds_read_b128 v[212:215], v171 offset:23040
	ds_read_b128 v[172:175], v0 offset:32
	ds_read_b128 v[180:183], v0 offset:4640
	ds_read_b128 v[190:193], v171 offset:18464
	ds_read_b128 v[216:219], v171 offset:23072
	s_waitcnt lgkmcnt(4)
	v_mfma_f32_32x32x16_bf16 v[34:49], v[146:149], v[212:215], v[34:49]
	s_waitcnt vmcnt(19)
	ds_write_b128 v188, v[90:93] offset:36864
	v_mfma_f32_32x32x16_bf16 v[2:17], v[176:179], v[184:187], v[2:17]
	s_waitcnt vmcnt(18)
	ds_write_b128 v188, v[94:97] offset:41472
	v_mfma_f32_32x32x16_bf16 v[18:33], v[176:179], v[212:215], v[18:33]
	s_waitcnt vmcnt(17)
	ds_write_b128 v188, v[98:101] offset:46080
	v_mfma_f32_32x32x16_bf16 v[50:65], v[146:149], v[184:187], v[50:65]
	s_waitcnt vmcnt(16)
	ds_write_b128 v188, v[102:105] offset:50688
	ds_read_b128 v[146:149], v0 offset:64
	ds_read_b128 v[176:179], v0 offset:4672
	ds_read_b128 v[184:187], v171 offset:18496
	ds_read_b128 v[212:215], v171 offset:23104
	s_waitcnt lgkmcnt(8)
	v_mfma_f32_32x32x16_bf16 v[34:49], v[172:175], v[216:219], v[34:49]
	s_waitcnt vmcnt(15)
	ds_write_b128 v188, v[118:121] offset:55296
	v_mfma_f32_32x32x16_bf16 v[2:17], v[180:183], v[190:193], v[2:17]
	s_waitcnt vmcnt(14)
	ds_write_b128 v188, v[122:125] offset:59904
	v_mfma_f32_32x32x16_bf16 v[18:33], v[180:183], v[216:219], v[18:33]
	s_waitcnt vmcnt(13)
	ds_write_b128 v188, v[134:137] offset:64512
	v_mfma_f32_32x32x16_bf16 v[50:65], v[172:175], v[190:193], v[50:65]
	ds_read_b128 v[172:175], v0 offset:96
	ds_read_b128 v[180:183], v0 offset:4704
	ds_read_b128 v[190:193], v171 offset:18528
	ds_read_b128 v[216:219], v171 offset:23136
	s_waitcnt lgkmcnt(7)
	v_mfma_f32_32x32x16_bf16 v[34:49], v[146:149], v[212:215], v[34:49]
	global_load_dwordx4 v[118:121], v[150:151], off offset:896
	global_load_dwordx4 v[122:125], v[158:159], off offset:896
	v_mfma_f32_32x32x16_bf16 v[2:17], v[176:179], v[184:187], v[2:17]
	global_load_dwordx4 v[134:137], v[160:161], off offset:896
	global_load_dwordx4 v[142:145], v[162:163], off offset:896
	v_mfma_f32_32x32x16_bf16 v[18:33], v[176:179], v[212:215], v[18:33]
	global_load_dwordx4 v[90:93], v[154:155], off offset:1024
	global_load_dwordx4 v[94:97], v[164:165], off offset:1024
	v_mfma_f32_32x32x16_bf16 v[50:65], v[146:149], v[184:187], v[50:65]
	global_load_dwordx4 v[98:101], v[166:167], off offset:1024
	global_load_dwordx4 v[102:105], v[168:169], off offset:1024
	s_waitcnt lgkmcnt(0)
	v_mfma_f32_32x32x16_bf16 v[34:49], v[172:175], v[216:219], v[34:49]
	v_mfma_f32_32x32x16_bf16 v[2:17], v[180:183], v[190:193], v[2:17]
	v_mfma_f32_32x32x16_bf16 v[18:33], v[180:183], v[216:219], v[18:33]
	v_mfma_f32_32x32x16_bf16 v[50:65], v[172:175], v[190:193], v[50:65]
	s_waitcnt lgkmcnt(0)
	s_setprio 0
	s_barrier
	s_setprio 2
	ds_read_b128 v[146:149], v0 offset:36864
	ds_read_b128 v[176:179], v0 offset:41472
	ds_read_b128 v[184:187], v171 offset:55296
	ds_read_b128 v[212:215], v171 offset:59904
	ds_read_b128 v[172:175], v0 offset:36896
	ds_read_b128 v[180:183], v0 offset:41504
	ds_read_b128 v[190:193], v171 offset:55328
	ds_read_b128 v[216:219], v171 offset:59936
	s_waitcnt lgkmcnt(4)
	v_mfma_f32_32x32x16_bf16 v[34:49], v[146:149], v[212:215], v[34:49]
	s_waitcnt vmcnt(19)
	ds_write_b128 v188, v[66:69]
	v_mfma_f32_32x32x16_bf16 v[2:17], v[176:179], v[184:187], v[2:17]
	s_waitcnt vmcnt(18)
	ds_write_b128 v188, v[70:73] offset:4608
	v_mfma_f32_32x32x16_bf16 v[18:33], v[176:179], v[212:215], v[18:33]
	s_waitcnt vmcnt(17)
	ds_write_b128 v188, v[74:77] offset:9216
	v_mfma_f32_32x32x16_bf16 v[50:65], v[146:149], v[184:187], v[50:65]
	s_waitcnt vmcnt(16)
	ds_write_b128 v188, v[106:109] offset:13824
	ds_read_b128 v[146:149], v0 offset:36928
	ds_read_b128 v[176:179], v0 offset:41536
	ds_read_b128 v[184:187], v171 offset:55360
	ds_read_b128 v[212:215], v171 offset:59968
	s_waitcnt lgkmcnt(8)
	v_mfma_f32_32x32x16_bf16 v[34:49], v[172:175], v[216:219], v[34:49]
	s_waitcnt vmcnt(15)
	ds_write_b128 v188, v[114:117] offset:18432
	v_mfma_f32_32x32x16_bf16 v[2:17], v[180:183], v[190:193], v[2:17]
	s_waitcnt vmcnt(14)
	ds_write_b128 v188, v[126:129] offset:23040
	v_mfma_f32_32x32x16_bf16 v[18:33], v[180:183], v[216:219], v[18:33]
	s_waitcnt vmcnt(13)
	ds_write_b128 v188, v[130:133] offset:27648
	v_mfma_f32_32x32x16_bf16 v[50:65], v[172:175], v[190:193], v[50:65]
	s_waitcnt vmcnt(12)
	ds_write_b128 v188, v[138:141] offset:32256
	ds_read_b128 v[172:175], v0 offset:36960
	ds_read_b128 v[180:183], v0 offset:41568
	ds_read_b128 v[190:193], v171 offset:55392
	ds_read_b128 v[216:219], v171 offset:60000
	s_waitcnt lgkmcnt(8)
	v_mfma_f32_32x32x16_bf16 v[34:49], v[146:149], v[212:215], v[34:49]
	global_load_dwordx4 v[114:117], v[150:151], off offset:1024
	global_load_dwordx4 v[126:129], v[158:159], off offset:1024
	v_mfma_f32_32x32x16_bf16 v[2:17], v[176:179], v[184:187], v[2:17]
	global_load_dwordx4 v[130:133], v[160:161], off offset:1024
	global_load_dwordx4 v[138:141], v[162:163], off offset:1024
	v_mfma_f32_32x32x16_bf16 v[18:33], v[176:179], v[212:215], v[18:33]
	global_load_dwordx4 v[66:69], v[154:155], off offset:1152
	global_load_dwordx4 v[70:73], v[164:165], off offset:1152
	v_mfma_f32_32x32x16_bf16 v[50:65], v[146:149], v[184:187], v[50:65]
	global_load_dwordx4 v[74:77], v[166:167], off offset:1152
	global_load_dwordx4 v[106:109], v[168:169], off offset:1152
	s_waitcnt lgkmcnt(0)
	v_mfma_f32_32x32x16_bf16 v[34:49], v[172:175], v[216:219], v[34:49]
	v_mfma_f32_32x32x16_bf16 v[2:17], v[180:183], v[190:193], v[2:17]
	v_mfma_f32_32x32x16_bf16 v[18:33], v[180:183], v[216:219], v[18:33]
	v_mfma_f32_32x32x16_bf16 v[50:65], v[172:175], v[190:193], v[50:65]
	s_waitcnt lgkmcnt(0)
	s_setprio 0
	s_barrier
	s_setprio 2
	ds_read_b128 v[146:149], v0
	ds_read_b128 v[176:179], v0 offset:4608
	ds_read_b128 v[184:187], v171 offset:18432
	ds_read_b128 v[212:215], v171 offset:23040
	ds_read_b128 v[172:175], v0 offset:32
	ds_read_b128 v[180:183], v0 offset:4640
	ds_read_b128 v[190:193], v171 offset:18464
	ds_read_b128 v[216:219], v171 offset:23072
	s_waitcnt lgkmcnt(4)
	v_mfma_f32_32x32x16_bf16 v[34:49], v[146:149], v[212:215], v[34:49]
	s_waitcnt vmcnt(19)
	ds_write_b128 v188, v[78:81] offset:36864
	v_mfma_f32_32x32x16_bf16 v[2:17], v[176:179], v[184:187], v[2:17]
	s_waitcnt vmcnt(18)
	ds_write_b128 v188, v[82:85] offset:41472
	v_mfma_f32_32x32x16_bf16 v[18:33], v[176:179], v[212:215], v[18:33]
	s_waitcnt vmcnt(17)
	ds_write_b128 v188, v[86:89] offset:46080
	v_mfma_f32_32x32x16_bf16 v[50:65], v[146:149], v[184:187], v[50:65]
	s_waitcnt vmcnt(16)
	ds_write_b128 v188, v[110:113] offset:50688
	ds_read_b128 v[146:149], v0 offset:64
	ds_read_b128 v[176:179], v0 offset:4672
	ds_read_b128 v[184:187], v171 offset:18496
	ds_read_b128 v[212:215], v171 offset:23104
	s_waitcnt lgkmcnt(8)
	v_mfma_f32_32x32x16_bf16 v[34:49], v[172:175], v[216:219], v[34:49]
	s_waitcnt vmcnt(15)
	ds_write_b128 v188, v[118:121] offset:55296
	v_mfma_f32_32x32x16_bf16 v[2:17], v[180:183], v[190:193], v[2:17]
	s_waitcnt vmcnt(14)
	ds_write_b128 v188, v[122:125] offset:59904
	v_mfma_f32_32x32x16_bf16 v[18:33], v[180:183], v[216:219], v[18:33]
	s_waitcnt vmcnt(13)
	ds_write_b128 v188, v[134:137] offset:64512
	v_mfma_f32_32x32x16_bf16 v[50:65], v[172:175], v[190:193], v[50:65]
	s_waitcnt vmcnt(12)
	ds_write_b128 v189, v[142:145] offset:13824
	ds_read_b128 v[172:175], v0 offset:96
	ds_read_b128 v[180:183], v0 offset:4704
	ds_read_b128 v[190:193], v171 offset:18528
	ds_read_b128 v[216:219], v171 offset:23136
	s_waitcnt lgkmcnt(8)
	v_mfma_f32_32x32x16_bf16 v[34:49], v[146:149], v[212:215], v[34:49]
	global_load_dwordx4 v[118:121], v[150:151], off offset:1152
	global_load_dwordx4 v[122:125], v[158:159], off offset:1152
	v_mfma_f32_32x32x16_bf16 v[2:17], v[176:179], v[184:187], v[2:17]
	global_load_dwordx4 v[134:137], v[160:161], off offset:1152
	global_load_dwordx4 v[142:145], v[162:163], off offset:1152
	v_mfma_f32_32x32x16_bf16 v[18:33], v[176:179], v[212:215], v[18:33]
	global_load_dwordx4 v[78:81], v[154:155], off offset:1280
	global_load_dwordx4 v[82:85], v[164:165], off offset:1280
	v_mfma_f32_32x32x16_bf16 v[50:65], v[146:149], v[184:187], v[50:65]
	global_load_dwordx4 v[86:89], v[166:167], off offset:1280
	global_load_dwordx4 v[110:113], v[168:169], off offset:1280
	s_waitcnt lgkmcnt(0)
	v_mfma_f32_32x32x16_bf16 v[34:49], v[172:175], v[216:219], v[34:49]
	v_mfma_f32_32x32x16_bf16 v[2:17], v[180:183], v[190:193], v[2:17]
	v_mfma_f32_32x32x16_bf16 v[18:33], v[180:183], v[216:219], v[18:33]
	v_mfma_f32_32x32x16_bf16 v[50:65], v[172:175], v[190:193], v[50:65]
	s_waitcnt lgkmcnt(0)
	s_setprio 0
	s_barrier
	s_waitcnt vmcnt(19)
	ds_write_b128 v188, v[90:93]
	s_waitcnt vmcnt(18)
	ds_write_b128 v188, v[94:97] offset:4608
	s_waitcnt vmcnt(17)
	ds_write_b128 v188, v[98:101] offset:9216
	s_waitcnt vmcnt(16)
	ds_write_b128 v188, v[102:105] offset:13824
	s_waitcnt vmcnt(15)
	ds_write_b128 v188, v[114:117] offset:18432
	s_waitcnt vmcnt(14)
	ds_write_b128 v188, v[126:129] offset:23040
	s_waitcnt vmcnt(13)
	ds_write_b128 v188, v[130:133] offset:27648
	s_waitcnt vmcnt(12)
	ds_write_b128 v188, v[138:141] offset:32256
	global_load_dwordx4 v[114:117], v[150:151], off offset:1280
	global_load_dwordx4 v[126:129], v[158:159], off offset:1280
	global_load_dwordx4 v[130:133], v[160:161], off offset:1280
	global_load_dwordx4 v[138:141], v[162:163], off offset:1280
	global_load_dwordx4 v[90:93], v[154:155], off offset:1408
	global_load_dwordx4 v[94:97], v[164:165], off offset:1408
	global_load_dwordx4 v[98:101], v[166:167], off offset:1408
	global_load_dwordx4 v[102:105], v[168:169], off offset:1408
	s_setprio 2
	ds_read_b128 v[146:149], v0 offset:36864
	ds_read_b128 v[152:155], v0 offset:36896
	ds_read_b128 v[164:167], v0 offset:41472
	ds_read_b128 v[172:175], v0 offset:41504
	ds_read_b128 v[176:179], v171 offset:55296
	ds_read_b128 v[180:183], v171 offset:55328
	ds_read_b128 v[184:187], v171 offset:59904
	ds_read_b128 v[190:193], v171 offset:59936
	s_waitcnt lgkmcnt(1)
	v_mfma_f32_32x32x16_bf16 v[34:49], v[146:149], v[184:187], v[34:49]
	v_mfma_f32_32x32x16_bf16 v[2:17], v[164:167], v[176:179], v[2:17]
	v_mfma_f32_32x32x16_bf16 v[18:33], v[164:167], v[184:187], v[18:33]
	v_mfma_f32_32x32x16_bf16 v[50:65], v[146:149], v[176:179], v[50:65]
	ds_read_b128 v[146:149], v0 offset:36928
	ds_read_b128 v[164:167], v0 offset:41536
	ds_read_b128 v[176:179], v171 offset:55360
	ds_read_b128 v[184:187], v171 offset:59968
	s_waitcnt lgkmcnt(4)
	v_mfma_f32_32x32x16_bf16 v[34:49], v[152:155], v[190:193], v[34:49]
	v_mfma_f32_32x32x16_bf16 v[2:17], v[172:175], v[180:183], v[2:17]
	v_mfma_f32_32x32x16_bf16 v[18:33], v[172:175], v[190:193], v[18:33]
	v_mfma_f32_32x32x16_bf16 v[50:65], v[152:155], v[180:183], v[50:65]
	ds_read_b128 v[152:155], v0 offset:36960
	ds_read_b128 v[172:175], v0 offset:41568
	ds_read_b128 v[180:183], v171 offset:55392
	ds_read_b128 v[190:193], v171 offset:60000
	s_waitcnt lgkmcnt(4)
	v_mfma_f32_32x32x16_bf16 v[34:49], v[146:149], v[184:187], v[34:49]
	v_mfma_f32_32x32x16_bf16 v[2:17], v[164:167], v[176:179], v[2:17]
	v_mfma_f32_32x32x16_bf16 v[18:33], v[164:167], v[184:187], v[18:33]
	v_mfma_f32_32x32x16_bf16 v[50:65], v[146:149], v[176:179], v[50:65]
	s_waitcnt lgkmcnt(0)
	v_mfma_f32_32x32x16_bf16 v[34:49], v[152:155], v[190:193], v[34:49]
	v_mfma_f32_32x32x16_bf16 v[2:17], v[172:175], v[180:183], v[2:17]
	v_mfma_f32_32x32x16_bf16 v[18:33], v[172:175], v[190:193], v[18:33]
	v_mfma_f32_32x32x16_bf16 v[50:65], v[152:155], v[180:183], v[50:65]
	s_setprio 0
	s_barrier
	s_waitcnt vmcnt(19)
	ds_write_b128 v188, v[66:69] offset:36864
	s_waitcnt vmcnt(18)
	ds_write_b128 v188, v[70:73] offset:41472
	s_waitcnt vmcnt(17)
	ds_write_b128 v188, v[74:77] offset:46080
	s_waitcnt vmcnt(16)
	ds_write_b128 v188, v[106:109] offset:50688
	s_waitcnt vmcnt(15)
	ds_write_b128 v188, v[118:121] offset:55296
	s_waitcnt vmcnt(14)
	ds_write_b128 v188, v[122:125] offset:59904
	s_waitcnt vmcnt(13)
	ds_write_b128 v188, v[134:137] offset:64512
	s_waitcnt vmcnt(12)
	ds_write_b128 v189, v[142:145] offset:13824
	global_load_dwordx4 v[66:69], v[150:151], off offset:1408
	global_load_dwordx4 v[70:73], v[158:159], off offset:1408
	global_load_dwordx4 v[74:77], v[160:161], off offset:1408
	global_load_dwordx4 v[106:109], v[162:163], off offset:1408
	s_setprio 2
	ds_read_b128 v[118:121], v0
	ds_read_b128 v[122:125], v0 offset:32
	ds_read_b128 v[134:137], v0 offset:4608
	ds_read_b128 v[142:145], v0 offset:4640
	ds_read_b128 v[146:149], v171 offset:18432
	ds_read_b128 v[150:153], v171 offset:18464
	ds_read_b128 v[154:157], v171 offset:23040
	ds_read_b128 v[158:161], v171 offset:23072
	s_waitcnt lgkmcnt(1)
	v_mfma_f32_32x32x16_bf16 v[34:49], v[118:121], v[154:157], v[34:49]
	v_mfma_f32_32x32x16_bf16 v[2:17], v[134:137], v[146:149], v[2:17]
	v_mfma_f32_32x32x16_bf16 v[18:33], v[134:137], v[154:157], v[18:33]
	v_mfma_f32_32x32x16_bf16 v[50:65], v[118:121], v[146:149], v[50:65]
	ds_read_b128 v[118:121], v0 offset:64
	ds_read_b128 v[134:137], v0 offset:4672
	ds_read_b128 v[146:149], v171 offset:18496
	ds_read_b128 v[154:157], v171 offset:23104
	s_waitcnt lgkmcnt(4)
	v_mfma_f32_32x32x16_bf16 v[34:49], v[122:125], v[158:161], v[34:49]
	v_mfma_f32_32x32x16_bf16 v[2:17], v[142:145], v[150:153], v[2:17]
	v_mfma_f32_32x32x16_bf16 v[18:33], v[142:145], v[158:161], v[18:33]
	v_mfma_f32_32x32x16_bf16 v[50:65], v[122:125], v[150:153], v[50:65]
	ds_read_b128 v[122:125], v0 offset:96
	ds_read_b128 v[142:145], v0 offset:4704
	ds_read_b128 v[150:153], v171 offset:18528
	ds_read_b128 v[158:161], v171 offset:23136
	s_waitcnt lgkmcnt(4)
	v_mfma_f32_32x32x16_bf16 v[34:49], v[118:121], v[154:157], v[34:49]
	v_mfma_f32_32x32x16_bf16 v[2:17], v[134:137], v[146:149], v[2:17]
	v_mfma_f32_32x32x16_bf16 v[18:33], v[134:137], v[154:157], v[18:33]
	v_mfma_f32_32x32x16_bf16 v[50:65], v[118:121], v[146:149], v[50:65]
	s_waitcnt lgkmcnt(0)
	v_mfma_f32_32x32x16_bf16 v[34:49], v[122:125], v[158:161], v[34:49]
	v_mfma_f32_32x32x16_bf16 v[2:17], v[142:145], v[150:153], v[2:17]
	v_mfma_f32_32x32x16_bf16 v[18:33], v[142:145], v[158:161], v[18:33]
	v_mfma_f32_32x32x16_bf16 v[50:65], v[122:125], v[150:153], v[50:65]
	s_setprio 0
	s_barrier
	s_setprio 2
	s_waitcnt vmcnt(15)
	ds_write_b128 v188, v[78:81]
	s_waitcnt vmcnt(14)
	ds_write_b128 v188, v[82:85] offset:4608
	s_waitcnt vmcnt(13)
	ds_write_b128 v188, v[86:89] offset:9216
	s_waitcnt vmcnt(12)
	ds_write_b128 v188, v[110:113] offset:13824
	s_waitcnt vmcnt(11)
	ds_write_b128 v188, v[114:117] offset:18432
	s_waitcnt vmcnt(10)
	ds_write_b128 v188, v[126:129] offset:23040
	ds_read_b128 v[78:81], v0 offset:36864
	ds_read_b128 v[86:89], v0 offset:41472
	ds_read_b128 v[114:117], v171 offset:55296
	ds_read_b128 v[122:125], v171 offset:59904
	ds_read_b128 v[82:85], v0 offset:36896
	ds_read_b128 v[110:113], v0 offset:41504
	ds_read_b128 v[118:121], v171 offset:55328
	ds_read_b128 v[126:129], v171 offset:59936
	s_waitcnt lgkmcnt(4)
	v_mfma_f32_32x32x16_bf16 v[34:49], v[78:81], v[122:125], v[34:49]
	s_waitcnt vmcnt(9)
	ds_write_b128 v188, v[130:133] offset:27648
	v_mfma_f32_32x32x16_bf16 v[2:17], v[86:89], v[114:117], v[2:17]
	s_waitcnt vmcnt(8)
	ds_write_b128 v188, v[138:141] offset:32256
	v_mfma_f32_32x32x16_bf16 v[18:33], v[86:89], v[122:125], v[18:33]
	v_mfma_f32_32x32x16_bf16 v[50:65], v[78:81], v[114:117], v[50:65]
	ds_read_b128 v[78:81], v0 offset:36928
	ds_read_b128 v[86:89], v0 offset:41536
	ds_read_b128 v[114:117], v171 offset:55360
	ds_read_b128 v[122:125], v171 offset:59968
	s_waitcnt lgkmcnt(6)
	v_mfma_f32_32x32x16_bf16 v[34:49], v[82:85], v[126:129], v[34:49]
	v_mfma_f32_32x32x16_bf16 v[2:17], v[110:113], v[118:121], v[2:17]
	v_mfma_f32_32x32x16_bf16 v[18:33], v[110:113], v[126:129], v[18:33]
	v_mfma_f32_32x32x16_bf16 v[50:65], v[82:85], v[118:121], v[50:65]
	ds_read_b128 v[82:85], v0 offset:36960
	ds_read_b128 v[110:113], v0 offset:41568
	ds_read_b128 v[118:121], v171 offset:55392
	ds_read_b128 v[126:129], v171 offset:60000
	s_waitcnt lgkmcnt(4)
	v_mfma_f32_32x32x16_bf16 v[34:49], v[78:81], v[122:125], v[34:49]
	v_mfma_f32_32x32x16_bf16 v[2:17], v[86:89], v[114:117], v[2:17]
	v_mfma_f32_32x32x16_bf16 v[18:33], v[86:89], v[122:125], v[18:33]
	v_mfma_f32_32x32x16_bf16 v[50:65], v[78:81], v[114:117], v[50:65]
	s_waitcnt lgkmcnt(0)
	v_mfma_f32_32x32x16_bf16 v[34:49], v[82:85], v[126:129], v[34:49]
	v_mfma_f32_32x32x16_bf16 v[2:17], v[110:113], v[118:121], v[2:17]
	v_mfma_f32_32x32x16_bf16 v[18:33], v[110:113], v[126:129], v[18:33]
	v_mfma_f32_32x32x16_bf16 v[50:65], v[82:85], v[118:121], v[50:65]
	s_waitcnt lgkmcnt(0)
	s_setprio 0
	s_barrier
	s_setprio 2
	s_waitcnt vmcnt(7)
	ds_write_b128 v188, v[90:93] offset:36864
	s_waitcnt vmcnt(6)
	ds_write_b128 v188, v[94:97] offset:41472
	s_waitcnt vmcnt(3)
	ds_write_b128 v188, v[66:69] offset:55296
	s_waitcnt vmcnt(2)
	ds_write_b128 v188, v[70:73] offset:59904
	s_waitcnt vmcnt(1)
	ds_write_b128 v188, v[74:77] offset:64512
	ds_read_b128 v[66:69], v0
	ds_read_b128 v[74:77], v0 offset:4608
	ds_read_b128 v[82:85], v171 offset:18432
	ds_read_b128 v[90:93], v171 offset:23040
	ds_read_b128 v[70:73], v0 offset:32
	ds_read_b128 v[78:81], v0 offset:4640
	ds_read_b128 v[86:89], v171 offset:18464
	ds_read_b128 v[94:97], v171 offset:23072
	s_waitcnt lgkmcnt(4)
	v_mfma_f32_32x32x16_bf16 v[34:49], v[66:69], v[90:93], v[34:49]
	s_waitcnt vmcnt(5)
	ds_write_b128 v188, v[98:101] offset:46080
	v_mfma_f32_32x32x16_bf16 v[2:17], v[74:77], v[82:85], v[2:17]
	s_waitcnt vmcnt(4)
	ds_write_b128 v188, v[102:105] offset:50688
	v_mfma_f32_32x32x16_bf16 v[18:33], v[74:77], v[90:93], v[18:33]
	s_waitcnt vmcnt(0)
	ds_write_b128 v189, v[106:109] offset:13824
	v_mfma_f32_32x32x16_bf16 v[50:65], v[66:69], v[82:85], v[50:65]
	ds_read_b128 v[66:69], v0 offset:64
	ds_read_b128 v[74:77], v0 offset:4672
	ds_read_b128 v[82:85], v171 offset:18496
	ds_read_b128 v[90:93], v171 offset:23104
	s_waitcnt lgkmcnt(7)
	v_mfma_f32_32x32x16_bf16 v[34:49], v[70:73], v[94:97], v[34:49]
	v_mfma_f32_32x32x16_bf16 v[2:17], v[78:81], v[86:89], v[2:17]
	v_mfma_f32_32x32x16_bf16 v[18:33], v[78:81], v[94:97], v[18:33]
	v_mfma_f32_32x32x16_bf16 v[50:65], v[70:73], v[86:89], v[50:65]
	ds_read_b128 v[70:73], v0 offset:96
	ds_read_b128 v[78:81], v0 offset:4704
	ds_read_b128 v[86:89], v171 offset:18528
	ds_read_b128 v[94:97], v171 offset:23136
	s_waitcnt lgkmcnt(4)
	v_mfma_f32_32x32x16_bf16 v[34:49], v[66:69], v[90:93], v[34:49]
	v_mfma_f32_32x32x16_bf16 v[2:17], v[74:77], v[82:85], v[2:17]
	v_mfma_f32_32x32x16_bf16 v[18:33], v[74:77], v[90:93], v[18:33]
	v_mfma_f32_32x32x16_bf16 v[50:65], v[66:69], v[82:85], v[50:65]
	s_waitcnt lgkmcnt(0)
	v_mfma_f32_32x32x16_bf16 v[34:49], v[70:73], v[94:97], v[34:49]
	v_mfma_f32_32x32x16_bf16 v[2:17], v[78:81], v[86:89], v[2:17]
	v_mfma_f32_32x32x16_bf16 v[18:33], v[78:81], v[94:97], v[18:33]
	v_mfma_f32_32x32x16_bf16 v[50:65], v[70:73], v[86:89], v[50:65]
	s_waitcnt lgkmcnt(0)
	s_setprio 0
	s_barrier
	s_setprio 2
	ds_read_b128 v[66:69], v0 offset:36864
	ds_read_b128 v[70:73], v0 offset:36896
	ds_read_b128 v[74:77], v0 offset:41472
	ds_read_b128 v[78:81], v0 offset:41504
	ds_read_b128 v[82:85], v171 offset:55296
	ds_read_b128 v[86:89], v171 offset:55328
	ds_read_b128 v[90:93], v171 offset:59904
	ds_read_b128 v[94:97], v171 offset:59936
	s_waitcnt lgkmcnt(1)
	v_mfma_f32_32x32x16_bf16 v[34:49], v[66:69], v[90:93], v[34:49]
	v_mfma_f32_32x32x16_bf16 v[2:17], v[74:77], v[82:85], v[2:17]
	v_mfma_f32_32x32x16_bf16 v[18:33], v[74:77], v[90:93], v[18:33]
	v_mfma_f32_32x32x16_bf16 v[50:65], v[66:69], v[82:85], v[50:65]
	ds_read_b128 v[66:69], v0 offset:36928
	ds_read_b128 v[74:77], v0 offset:41536
	ds_read_b128 v[82:85], v171 offset:55360
	ds_read_b128 v[90:93], v171 offset:59968
	s_waitcnt lgkmcnt(4)
	v_mfma_f32_32x32x16_bf16 v[34:49], v[70:73], v[94:97], v[34:49]
	v_mfma_f32_32x32x16_bf16 v[2:17], v[78:81], v[86:89], v[2:17]
	v_mfma_f32_32x32x16_bf16 v[18:33], v[78:81], v[94:97], v[18:33]
	v_mfma_f32_32x32x16_bf16 v[50:65], v[70:73], v[86:89], v[50:65]
	ds_read_b128 v[70:73], v0 offset:36960
	ds_read_b128 v[78:81], v0 offset:41568
	ds_read_b128 v[86:89], v171 offset:55392
	ds_read_b128 v[94:97], v171 offset:60000
	s_waitcnt lgkmcnt(4)
	v_mfma_f32_32x32x16_bf16 v[34:49], v[66:69], v[90:93], v[34:49]
	v_mfma_f32_32x32x16_bf16 v[2:17], v[74:77], v[82:85], v[2:17]
	v_mfma_f32_32x32x16_bf16 v[18:33], v[74:77], v[90:93], v[18:33]
	v_mfma_f32_32x32x16_bf16 v[50:65], v[66:69], v[82:85], v[50:65]
	s_waitcnt lgkmcnt(0)
	v_mfma_f32_32x32x16_bf16 v[34:49], v[70:73], v[94:97], v[34:49]
	v_mfma_f32_32x32x16_bf16 v[2:17], v[78:81], v[86:89], v[2:17]
	v_mfma_f32_32x32x16_bf16 v[18:33], v[78:81], v[94:97], v[18:33]
	v_mfma_f32_32x32x16_bf16 v[50:65], v[70:73], v[86:89], v[50:65]
	s_setprio 0
	s_barrier
	v_mov_b32 v66, v194
	s_lshl_b64 s[18:19], s[48:49], 12
	v_and_b32_e32 v69, 31, v66
	v_bfe_u32 v169, v66, 5, 1
	v_and_or_b32 v171, v66, 64, s11
	v_ashrrev_i32_e32 v66, 1, v66
	v_and_b32_e32 v68, 0xffffffc0, v66
	v_add_u32_e32 v66, s10, v68
	v_ashrrev_i32_e32 v67, 31, v66
	s_add_u32 s18, s13, s18
	v_or_b32_e32 v0, v171, v69
	v_lshlrev_b64 v[66:67], 12, v[66:67]
	s_addc_u32 s19, s14, s19
	v_lshlrev_b32_e32 v0, 2, v0
	v_lshl_add_u64 v[66:67], s[40:41], 0, v[66:67]
	global_load_dword v108, v0, s[18:19]
	global_load_dword v110, v0, s[18:19] offset:128
	v_lshl_add_u64 v[66:67], v[66:67], 0, v[0:1]
	v_lshlrev_b32_e32 v0, 14, v169
	v_lshl_add_u64 v[66:67], v[66:67], 0, v[0:1]
	v_add_co_u32_e32 v72, vcc, s6, v66
	s_movk_i32 s6, 0x2000
	s_nop 0
	v_addc_co_u32_e32 v73, vcc, 0, v67, vcc
	v_add_co_u32_e32 v70, vcc, s6, v66
	s_movk_i32 s6, 0x3000
	s_nop 0
	v_addc_co_u32_e32 v71, vcc, 0, v67, vcc
	v_add_co_u32_e32 v74, vcc, s6, v66
	s_mov_b32 s6, 0x8000
	s_nop 0
	v_addc_co_u32_e32 v75, vcc, 0, v67, vcc
	v_add_co_u32_e32 v78, vcc, s6, v66
	s_mov_b32 s6, 0xa000
	s_nop 0
	v_addc_co_u32_e32 v79, vcc, 0, v67, vcc
	v_add_co_u32_e32 v76, vcc, s31, v66
	global_load_dword v172, v[66:67], off
	global_load_dword v173, v[66:67], off offset:128
	v_addc_co_u32_e32 v77, vcc, 0, v67, vcc
	v_add_co_u32_e32 v82, vcc, s6, v66
	s_mov_b32 s6, 0xb000
	s_nop 0
	v_addc_co_u32_e32 v83, vcc, 0, v67, vcc
	v_add_co_u32_e32 v80, vcc, s6, v66
	s_mov_b32 s6, 0x10000
	s_nop 0
	v_addc_co_u32_e32 v81, vcc, 0, v67, vcc
	v_add_co_u32_e32 v86, vcc, s6, v66
	s_mov_b32 s6, 0x11000
	s_nop 0
	v_addc_co_u32_e32 v87, vcc, 0, v67, vcc
	v_add_co_u32_e32 v84, vcc, s6, v66
	s_mov_b32 s6, 0x13000
	s_nop 0
	v_addc_co_u32_e32 v85, vcc, 0, v67, vcc
	v_add_co_u32_e32 v90, vcc, s30, v66
	global_load_dword v167, v[70:71], off offset:-4096
	global_load_dword v168, v[72:73], off offset:128
	global_load_dword v165, v[70:71], off
	global_load_dword v166, v[70:71], off offset:128
	v_addc_co_u32_e32 v91, vcc, 0, v67, vcc
	v_add_co_u32_e32 v88, vcc, s6, v66
	s_mov_b32 s6, 0x18000
	s_nop 0
	v_addc_co_u32_e32 v89, vcc, 0, v67, vcc
	v_add_co_u32_e32 v94, vcc, s6, v66
	s_mov_b32 s6, 0x19000
	s_nop 0
	v_addc_co_u32_e32 v95, vcc, 0, v67, vcc
	v_add_co_u32_e32 v92, vcc, s6, v66
	s_mov_b32 s6, 0x1a000
	s_nop 0
	v_addc_co_u32_e32 v93, vcc, 0, v67, vcc
	v_add_co_u32_e32 v98, vcc, s6, v66
	s_mov_b32 s6, 0x21000
	s_nop 0
	v_addc_co_u32_e32 v99, vcc, 0, v67, vcc
	v_add_co_u32_e32 v96, vcc, s25, v66
	global_load_dword v163, v[74:75], off
	global_load_dword v164, v[74:75], off offset:128
	v_addc_co_u32_e32 v97, vcc, 0, v67, vcc
	v_add_co_u32_e32 v100, vcc, s63, v66
	global_load_dword v161, v[76:77], off offset:-4096
	global_load_dword v162, v[78:79], off offset:128
	global_load_dword v155, v[76:77], off
	global_load_dword v157, v[76:77], off offset:128
	v_addc_co_u32_e32 v101, vcc, 0, v67, vcc
	v_add_co_u32_e32 v102, vcc, s6, v66
	s_mov_b32 s6, 0x22000
	s_nop 0
	v_addc_co_u32_e32 v103, vcc, 0, v67, vcc
	global_load_dword v154, v[80:81], off offset:-4096
	global_load_dword v156, v[82:83], off offset:128
	global_load_dword v148, v[80:81], off
	global_load_dword v150, v[80:81], off offset:128
	global_load_dword v147, v[84:85], off offset:-4096
	global_load_dword v158, v[86:87], off offset:128
	global_load_dword v149, v[84:85], off
	global_load_dword v151, v[84:85], off offset:128
	global_load_dword v152, v[88:89], off offset:-4096
	global_load_dword v153, v[90:91], off offset:128
	global_load_dword v145, v[88:89], off
	global_load_dword v146, v[88:89], off offset:128
	global_load_dword v143, v[92:93], off offset:-4096
	global_load_dword v144, v[94:95], off offset:128
	global_load_dword v139, v[92:93], off
	global_load_dword v140, v[92:93], off offset:128
	global_load_dword v141, v[96:97], off offset:-4096
	global_load_dword v142, v[98:99], off offset:128
	global_load_dword v137, v[96:97], off
	global_load_dword v138, v[96:97], off offset:128
	global_load_dword v135, v[102:103], off offset:-4096
	global_load_dword v136, v[100:101], off offset:128
	global_load_dword v132, v[102:103], off
	global_load_dword v134, v[102:103], off offset:128
	v_add_co_u32_e32 v100, vcc, s6, v66
	s_mov_b32 s6, 0x23000
	s_nop 0
	v_addc_co_u32_e32 v101, vcc, 0, v67, vcc
	v_add_co_u32_e32 v102, vcc, s6, v66
	s_mov_b32 s6, 0x28000
	s_nop 0
	v_addc_co_u32_e32 v103, vcc, 0, v67, vcc
	global_load_dword v131, v[102:103], off offset:-4096
	global_load_dword v133, v[100:101], off offset:128
	global_load_dword v126, v[102:103], off
	global_load_dword v128, v[102:103], off offset:128
	v_add_co_u32_e32 v100, vcc, s6, v66
	s_mov_b32 s6, 0x29000
	s_nop 0
	v_addc_co_u32_e32 v101, vcc, 0, v67, vcc
	v_add_co_u32_e32 v102, vcc, s6, v66
	s_mov_b32 s6, 0x2a000
	s_nop 0
	v_addc_co_u32_e32 v103, vcc, 0, v67, vcc
	global_load_dword v129, v[102:103], off offset:-4096
	global_load_dword v130, v[100:101], off offset:128
	global_load_dword v125, v[102:103], off
	global_load_dword v127, v[102:103], off offset:128
	v_add_co_u32_e32 v100, vcc, s6, v66
	s_mov_b32 s6, 0x2b000
	s_nop 0
	v_addc_co_u32_e32 v101, vcc, 0, v67, vcc
	v_add_co_u32_e32 v102, vcc, s6, v66
	s_mov_b32 s6, 0x31000
	s_nop 0
	v_addc_co_u32_e32 v103, vcc, 0, v67, vcc
	global_load_dword v122, v[102:103], off offset:-4096
	global_load_dword v123, v[100:101], off offset:128
	global_load_dword v116, v[102:103], off
	global_load_dword v118, v[102:103], off offset:128
	v_add_co_u32_e32 v100, vcc, s59, v66
	s_waitcnt vmcnt(49)
	v_mul_f32_e32 v159, 0.5, v108
	v_addc_co_u32_e32 v101, vcc, 0, v67, vcc
	v_add_co_u32_e32 v102, vcc, s6, v66
	s_mov_b32 s6, 0x32000
	s_nop 0
	v_addc_co_u32_e32 v103, vcc, 0, v67, vcc
	global_load_dword v114, v[102:103], off offset:-4096
	global_load_dword v124, v[100:101], off offset:128
	global_load_dword v117, v[102:103], off
	global_load_dword v119, v[102:103], off offset:128
	v_add_co_u32_e32 v100, vcc, s6, v66
	s_mov_b32 s6, 0x33000
	s_nop 0
	v_addc_co_u32_e32 v101, vcc, 0, v67, vcc
	v_add_co_u32_e32 v102, vcc, s6, v66
	s_mov_b32 s6, 0x38000
	s_nop 0
	v_addc_co_u32_e32 v103, vcc, 0, v67, vcc
	global_load_dword v120, v[102:103], off offset:-4096
	global_load_dword v121, v[100:101], off offset:128
	global_load_dword v109, v[102:103], off
	global_load_dword v111, v[102:103], off offset:128
	v_add_co_u32_e32 v100, vcc, s6, v66
	s_mov_b32 s6, 0x39000
	s_nop 0
	v_addc_co_u32_e32 v101, vcc, 0, v67, vcc
	v_add_co_u32_e32 v102, vcc, s6, v66
	s_mov_b32 s6, 0x3a000
	s_nop 0
	v_addc_co_u32_e32 v103, vcc, 0, v67, vcc
	v_add_co_u32_e32 v112, vcc, s6, v66
	s_mov_b32 s6, 0x3b000
	s_nop 0
	v_addc_co_u32_e32 v113, vcc, 0, v67, vcc
	v_add_co_u32_e32 v174, vcc, s6, v66
	global_load_dword v104, v[102:103], off offset:-4096
	global_load_dword v106, v[100:101], off offset:128
	s_nop 0
	global_load_dword v101, v[102:103], off
	s_nop 0
	global_load_dword v102, v[102:103], off offset:128
	v_addc_co_u32_e32 v175, vcc, 0, v67, vcc
	global_load_dword v100, v[174:175], off offset:-4096
	global_load_dword v107, v[112:113], off offset:128
	global_load_dword v103, v[174:175], off
	global_load_dword v105, v[174:175], off offset:128
	s_waitcnt vmcnt(62)
	v_mul_f32_e32 v160, 0.5, v110
	v_and_b32_e32 v108, 64, v200
	v_xor_b32_e32 v0, 16, v200
	v_add_u32_e32 v115, 64, v108
	v_cmp_lt_i32_e32 vcc, v0, v115
	v_fmac_f32_e32 v173, v34, v160
	v_fmac_f32_e32 v172, v50, v159
	v_cndmask_b32_e32 v0, v200, v0, vcc
	v_mul_f32_e32 v34, v173, v173
	v_lshlrev_b32_e32 v108, 2, v0
	v_fmac_f32_e32 v34, v172, v172
	s_waitcnt vmcnt(60)
	v_fmac_f32_e32 v168, v35, v160
	ds_bpermute_b32 v35, v108, v34
	v_xor_b32_e32 v0, 8, v200
	v_cmp_lt_i32_e32 vcc, v0, v115
	s_waitcnt vmcnt(58)
	v_fmac_f32_e32 v166, v36, v160
	s_waitcnt vmcnt(56)
	v_fmac_f32_e32 v164, v37, v160
	v_cndmask_b32_e32 v0, v200, v0, vcc
	v_lshlrev_b32_e32 v110, 2, v0
	s_waitcnt lgkmcnt(0)
	v_add_f32_e32 v34, v34, v35
	ds_bpermute_b32 v35, v110, v34
	v_xor_b32_e32 v0, 4, v200
	v_cmp_lt_i32_e32 vcc, v0, v115
	s_lshl_b32 s2, s2, 9
	v_lshlrev_b32_e32 v169, 2, v169
	v_cndmask_b32_e32 v0, v200, v0, vcc
	v_lshlrev_b32_e32 v112, 2, v0
	s_waitcnt lgkmcnt(0)
	v_add_f32_e32 v34, v34, v35
	ds_bpermute_b32 v35, v112, v34
	v_xor_b32_e32 v0, 2, v200
	v_cmp_lt_i32_e32 vcc, v0, v115
	v_fmac_f32_e32 v167, v51, v159
	v_fmac_f32_e32 v165, v52, v159
	v_cndmask_b32_e32 v0, v200, v0, vcc
	v_lshlrev_b32_e32 v113, 2, v0
	s_waitcnt lgkmcnt(0)
	v_add_f32_e32 v36, v34, v35
	ds_bpermute_b32 v37, v113, v36
	v_xor_b32_e32 v0, 1, v200
	v_cmp_lt_i32_e32 vcc, v0, v115
	v_fmac_f32_e32 v163, v53, v159
	s_waitcnt vmcnt(55)
	v_fmac_f32_e32 v161, v54, v159
	v_cndmask_b32_e32 v0, v200, v0, vcc
	v_lshlrev_b32_e32 v115, 2, v0
	s_waitcnt lgkmcnt(0)
	v_add_f32_e32 v36, v36, v37
	v_lshrrev_b32_e32 v0, 6, v171
	ds_bpermute_b32 v37, v115, v36
	v_mul_u32_u24_e32 v0, 0xc000, v0
	v_lshl_add_u64 v[34:35], s[44:45], 0, v[0:1]
	v_cmp_eq_u32_e32 vcc, 0, v69
	v_ashrrev_i32_e32 v69, 31, v68
	v_lshl_add_u64 v[34:35], v[34:35], 0, s[2:3]
	s_waitcnt vmcnt(54)
	v_fmac_f32_e32 v162, v38, v160
	s_waitcnt vmcnt(53)
	v_fmac_f32_e32 v155, v55, v159
	s_waitcnt vmcnt(52)
	v_fmac_f32_e32 v157, v39, v160
	s_waitcnt vmcnt(51)
	v_fmac_f32_e32 v154, v56, v159
	s_waitcnt vmcnt(50)
	v_fmac_f32_e32 v156, v40, v160
	s_waitcnt vmcnt(49)
	v_fmac_f32_e32 v148, v57, v159
	s_waitcnt vmcnt(48)
	v_fmac_f32_e32 v150, v41, v160
	s_waitcnt vmcnt(47)
	v_fmac_f32_e32 v147, v58, v159
	s_waitcnt vmcnt(46)
	v_fmac_f32_e32 v158, v42, v160
	s_waitcnt vmcnt(45)
	v_fmac_f32_e32 v149, v59, v159
	s_waitcnt vmcnt(44)
	v_fmac_f32_e32 v151, v43, v160
	s_waitcnt vmcnt(43)
	v_fmac_f32_e32 v152, v60, v159
	s_waitcnt vmcnt(42)
	v_fmac_f32_e32 v153, v44, v160
	s_waitcnt vmcnt(41)
	v_fmac_f32_e32 v145, v61, v159
	s_waitcnt vmcnt(40)
	v_fmac_f32_e32 v146, v45, v160
	s_waitcnt vmcnt(39)
	v_fmac_f32_e32 v143, v62, v159
	s_waitcnt vmcnt(38)
	v_fmac_f32_e32 v144, v46, v160
	s_waitcnt vmcnt(37)
	v_fmac_f32_e32 v139, v63, v159
	s_waitcnt vmcnt(36)
	v_fmac_f32_e32 v140, v47, v160
	s_waitcnt vmcnt(35)
	v_fmac_f32_e32 v141, v64, v159
	s_waitcnt vmcnt(34)
	v_fmac_f32_e32 v142, v48, v160
	s_waitcnt vmcnt(33)
	v_fmac_f32_e32 v137, v65, v159
	s_waitcnt vmcnt(32)
	v_fmac_f32_e32 v138, v49, v160
	v_lshl_add_u64 v[34:35], v[68:69], 2, v[34:35]
	v_lshlrev_b32_e32 v0, 2, v169
	global_store_dword v[66:67], v172, off
	global_store_dword v[66:67], v173, off offset:128
	global_store_dword v[70:71], v167, off offset:-4096
	global_store_dword v[72:73], v168, off offset:128
	global_store_dword v[70:71], v165, off
	global_store_dword v[70:71], v166, off offset:128
	global_store_dword v[74:75], v163, off
	global_store_dword v[74:75], v164, off offset:128
	global_store_dword v[76:77], v161, off offset:-4096
	global_store_dword v[78:79], v162, off offset:128
	global_store_dword v[76:77], v155, off
	global_store_dword v[76:77], v157, off offset:128
	global_store_dword v[80:81], v154, off offset:-4096
	global_store_dword v[82:83], v156, off offset:128
	global_store_dword v[80:81], v148, off
	global_store_dword v[80:81], v150, off offset:128
	global_store_dword v[84:85], v147, off offset:-4096
	global_store_dword v[86:87], v158, off offset:128
	global_store_dword v[84:85], v149, off
	global_store_dword v[84:85], v151, off offset:128
	global_store_dword v[88:89], v152, off offset:-4096
	global_store_dword v[90:91], v153, off offset:128
	global_store_dword v[88:89], v145, off
	global_store_dword v[88:89], v146, off offset:128
	global_store_dword v[92:93], v143, off offset:-4096
	global_store_dword v[94:95], v144, off offset:128
	global_store_dword v[92:93], v139, off
	global_store_dword v[92:93], v140, off offset:128
	global_store_dword v[96:97], v141, off offset:-4096
	global_store_dword v[98:99], v142, off offset:128
	global_store_dword v[96:97], v137, off
	global_store_dword v[96:97], v138, off offset:128
	s_and_saveexec_b64 s[10:11], vcc
	s_cbranch_execz .LBB0_2303
	v_lshl_add_u64 v[38:39], v[34:35], 0, v[0:1]
	s_waitcnt lgkmcnt(0)
	v_add_f32_e32 v36, v36, v37
	global_store_dword v[38:39], v36, off

.LBB0_2770:
	s_and_b32 s6, s2, 0xffff
	s_mul_i32 s6, s6, 0xba2f
	s_lshr_b32 s6, s6, 23
	s_mul_i32 s12, s6, 0xb0
	s_sub_i32 s12, s2, s12
	s_lshl_b32 s6, s6, 2
	s_and_b32 s13, s12, 0xffff
	s_add_i32 s6, s35, s6
	s_and_b32 s12, s12, 3
	s_or_b32 s6, s6, s12
	s_lshl_b32 s12, s13, 5
	s_and_b32 s12, s12, 0x1f80
	v_mov_b32 v66, v194
	s_lshl_b32 s6, s6, 7
	v_ashrrev_i32_e32 v68, 3, v66
	s_waitcnt vmcnt(0)
	v_add_u32_e32 v2, s12, v68
	v_ashrrev_i32_e32 v3, 31, v2
	v_lshlrev_b64 v[2:3], 11, v[2:3]
	v_lshlrev_b32_e32 v0, 4, v66
	v_lshl_add_u64 v[2:3], s[0:1], 0, v[2:3]
	v_and_b32_e32 v0, 0x70, v0
	v_lshl_add_u64 v[150:151], v[2:3], 0, v[0:1]
	v_add_u32_e32 v2, s6, v68
	v_ashrrev_i32_e32 v3, 31, v2
	v_lshlrev_b64 v[2:3], 11, v[2:3]
	v_lshl_add_u64 v[2:3], s[10:11], 0, v[2:3]
	v_lshl_add_u64 v[158:159], v[2:3], 0, v[0:1]
	v_add_co_u32_e32 v160, vcc, s14, v158
	s_nop 1
	v_addc_co_u32_e32 v161, vcc, 0, v159, vcc
	v_add_co_u32_e32 v162, vcc, s63, v158
	s_barrier
	s_nop 0
	v_addc_co_u32_e32 v163, vcc, 0, v159, vcc
	v_add_co_u32_e32 v164, vcc, s59, v158
	s_nop 1
	v_addc_co_u32_e32 v165, vcc, 0, v159, vcc
	v_add_co_u32_e32 v152, vcc, s14, v150
	s_barrier
	global_load_dwordx4 v[2:5], v[158:159], off
	global_load_dwordx4 v[6:9], v[160:161], off
	global_load_dwordx4 v[10:13], v[162:163], off
	global_load_dwordx4 v[14:17], v[164:165], off
	global_load_dwordx4 v[18:21], v[150:151], off
	v_addc_co_u32_e32 v153, vcc, 0, v151, vcc
	v_add_co_u32_e32 v154, vcc, s63, v150
	global_load_dwordx4 v[22:25], v[152:153], off
	s_nop 0
	v_addc_co_u32_e32 v155, vcc, 0, v151, vcc
	v_add_co_u32_e32 v156, vcc, s59, v150
	global_load_dwordx4 v[26:29], v[154:155], off
	s_nop 0
	v_addc_co_u32_e32 v157, vcc, 0, v151, vcc
	global_load_dwordx4 v[30:33], v[156:157], off
	global_load_dwordx4 v[34:37], v[158:159], off offset:128
	global_load_dwordx4 v[38:41], v[160:161], off offset:128
	global_load_dwordx4 v[42:45], v[162:163], off offset:128
	global_load_dwordx4 v[46:49], v[164:165], off offset:128
	global_load_dwordx4 v[50:53], v[150:151], off offset:128
	global_load_dwordx4 v[54:57], v[152:153], off offset:128
	global_load_dwordx4 v[58:61], v[154:155], off offset:128
	global_load_dwordx4 v[62:65], v[156:157], off offset:128
	global_load_dwordx4 v[98:101], v[158:159], off offset:256
	global_load_dwordx4 v[102:105], v[160:161], off offset:256
	global_load_dwordx4 v[106:109], v[162:163], off offset:256
	global_load_dwordx4 v[110:113], v[164:165], off offset:256
	v_mul_lo_u32 v68, v68, s34
	v_add3_u32 v0, 16, v68, v0
	v_and_b32_e32 v67, 31, v66
	v_add_u32_e32 v168, 0xd800, v0
	s_waitcnt vmcnt(19)
	ds_write_b128 v0, v[2:5]
	s_waitcnt vmcnt(18)
	ds_write_b128 v0, v[6:9] offset:4608
	s_waitcnt vmcnt(17)
	ds_write_b128 v0, v[10:13] offset:9216
	s_waitcnt vmcnt(16)
	ds_write_b128 v0, v[14:17] offset:13824
	s_waitcnt vmcnt(15)
	ds_write_b128 v0, v[18:21] offset:18432
	s_waitcnt vmcnt(14)
	ds_write_b128 v0, v[22:25] offset:23040
	s_waitcnt vmcnt(13)
	ds_write_b128 v0, v[26:29] offset:27648
	s_waitcnt vmcnt(12)
	ds_write_b128 v0, v[30:33] offset:32256
	global_load_dwordx4 v[122:125], v[150:151], off offset:256
	global_load_dwordx4 v[126:129], v[152:153], off offset:256
	global_load_dwordx4 v[130:133], v[154:155], off offset:256
	global_load_dwordx4 v[134:137], v[156:157], off offset:256
	global_load_dwordx4 v[78:81], v[158:159], off offset:384
	global_load_dwordx4 v[86:89], v[160:161], off offset:384
	global_load_dwordx4 v[90:93], v[162:163], off offset:384
	global_load_dwordx4 v[94:97], v[164:165], off offset:384
	s_waitcnt lgkmcnt(0)
	s_barrier
	v_lshrrev_b32_e32 v2, 1, v66
	s_waitcnt vmcnt(19)
	ds_write_b128 v0, v[34:37] offset:36864
	s_waitcnt vmcnt(18)
	ds_write_b128 v0, v[38:41] offset:41472
	s_waitcnt vmcnt(17)
	ds_write_b128 v0, v[42:45] offset:46080
	s_waitcnt vmcnt(16)
	ds_write_b128 v0, v[46:49] offset:50688
	s_waitcnt vmcnt(15)
	ds_write_b128 v0, v[50:53] offset:55296
	s_waitcnt vmcnt(14)
	ds_write_b128 v0, v[54:57] offset:59904
	s_waitcnt vmcnt(13)
	ds_write_b128 v0, v[58:61] offset:64512
	s_waitcnt vmcnt(12)
	ds_write_b128 v168, v[62:65] offset:13824
	v_and_or_b32 v3, v2, s64, v67
	v_and_b32_e32 v4, 0x5f, v66
	global_load_dwordx4 v[114:117], v[150:151], off offset:384
	global_load_dwordx4 v[118:121], v[152:153], off offset:384
	global_load_dwordx4 v[138:141], v[154:155], off offset:384
	global_load_dwordx4 v[142:145], v[156:157], off offset:384
	global_load_dwordx4 v[66:69], v[158:159], off offset:512
	global_load_dwordx4 v[70:73], v[160:161], off offset:512
	global_load_dwordx4 v[74:77], v[162:163], off offset:512
	global_load_dwordx4 v[82:85], v[164:165], off offset:512
	v_mul_u32_u24_e32 v4, 0x48, v4
	v_mul_lo_u32 v3, v3, s34
	v_and_b32_e32 v2, 16, v2
	v_add3_u32 v166, 16, v3, v2
	v_lshlrev_b32_e32 v3, 1, v4
	v_add3_u32 v167, 16, v3, v2
	s_setprio 2
	ds_read_b128 v[2:5], v166
	ds_read_b128 v[146:149], v166 offset:32
	ds_read_b128 v[18:21], v166 offset:4608
	ds_read_b128 v[172:175], v166 offset:4640
	ds_read_b128 v[6:9], v167 offset:18432
	ds_read_b128 v[176:179], v167 offset:18464
	ds_read_b128 v[22:25], v167 offset:23040
	ds_read_b128 v[180:183], v167 offset:23072
	s_waitcnt lgkmcnt(3)
	v_mfma_f32_32x32x16_bf16 v[34:49], v[2:5], v[6:9], 0
	s_waitcnt lgkmcnt(1)
	v_mfma_f32_32x32x16_bf16 v[50:65], v[2:5], v[22:25], 0
	v_mfma_f32_32x32x16_bf16 v[2:17], v[18:21], v[6:9], 0
	v_mfma_f32_32x32x16_bf16 v[18:33], v[18:21], v[22:25], 0
	ds_read_b128 v[184:187], v166 offset:64
	ds_read_b128 v[188:191], v166 offset:4672
	ds_read_b128 v[212:215], v167 offset:18496
	ds_read_b128 v[216:219], v167 offset:23104
	v_mfma_f32_32x32x16_bf16 v[34:49], v[146:149], v[176:179], v[34:49]
	s_waitcnt lgkmcnt(4)
	v_mfma_f32_32x32x16_bf16 v[50:65], v[146:149], v[180:183], v[50:65]
	v_mfma_f32_32x32x16_bf16 v[2:17], v[172:175], v[176:179], v[2:17]
	v_mfma_f32_32x32x16_bf16 v[18:33], v[172:175], v[180:183], v[18:33]
	ds_read_b128 v[146:149], v166 offset:96
	ds_read_b128 v[172:175], v166 offset:4704
	ds_read_b128 v[176:179], v167 offset:18528
	ds_read_b128 v[180:183], v167 offset:23136
	s_waitcnt lgkmcnt(5)
	v_mfma_f32_32x32x16_bf16 v[34:49], v[184:187], v[212:215], v[34:49]
	s_waitcnt lgkmcnt(4)
	v_mfma_f32_32x32x16_bf16 v[50:65], v[184:187], v[216:219], v[50:65]
	v_mfma_f32_32x32x16_bf16 v[2:17], v[188:191], v[212:215], v[2:17]
	v_mfma_f32_32x32x16_bf16 v[18:33], v[188:191], v[216:219], v[18:33]
	s_waitcnt lgkmcnt(1)
	v_mfma_f32_32x32x16_bf16 v[34:49], v[146:149], v[176:179], v[34:49]
	s_waitcnt lgkmcnt(0)
	v_mfma_f32_32x32x16_bf16 v[50:65], v[146:149], v[180:183], v[50:65]
	v_mfma_f32_32x32x16_bf16 v[2:17], v[172:175], v[176:179], v[2:17]
	v_mfma_f32_32x32x16_bf16 v[18:33], v[172:175], v[180:183], v[18:33]
	s_setprio 0
	s_barrier
	s_setprio 2
	s_waitcnt vmcnt(13)
	ds_write_b128 v0, v[130:133] offset:27648
	ds_read_b128 v[130:133], v166 offset:36864
	ds_read_b128 v[176:179], v166 offset:41472
	ds_read_b128 v[184:187], v167 offset:55296
	ds_read_b128 v[212:215], v167 offset:59904
	ds_read_b128 v[172:175], v166 offset:36896
	ds_read_b128 v[180:183], v166 offset:41504
	ds_read_b128 v[188:191], v167 offset:55328
	ds_read_b128 v[216:219], v167 offset:59936
	s_waitcnt lgkmcnt(5)
	v_mfma_f32_32x32x16_bf16 v[34:49], v[130:133], v[184:187], v[34:49]
	s_waitcnt vmcnt(19)
	ds_write_b128 v0, v[98:101]
	s_waitcnt lgkmcnt(5)
	v_mfma_f32_32x32x16_bf16 v[50:65], v[130:133], v[212:215], v[50:65]
	s_waitcnt vmcnt(18)
	ds_write_b128 v0, v[102:105] offset:4608
	v_mfma_f32_32x32x16_bf16 v[2:17], v[176:179], v[184:187], v[2:17]
	s_waitcnt vmcnt(17)
	ds_write_b128 v0, v[106:109] offset:9216
	v_mfma_f32_32x32x16_bf16 v[18:33], v[176:179], v[212:215], v[18:33]
	s_waitcnt vmcnt(16)
	ds_write_b128 v0, v[110:113] offset:13824
	ds_read_b128 v[130:133], v166 offset:36928
	ds_read_b128 v[176:179], v166 offset:41536
	ds_read_b128 v[184:187], v167 offset:55360
	ds_read_b128 v[212:215], v167 offset:59968
	s_waitcnt lgkmcnt(9)
	v_mfma_f32_32x32x16_bf16 v[34:49], v[172:175], v[188:191], v[34:49]
	s_waitcnt vmcnt(15)
	ds_write_b128 v0, v[122:125] offset:18432
	s_waitcnt lgkmcnt(9)
	v_mfma_f32_32x32x16_bf16 v[50:65], v[172:175], v[216:219], v[50:65]
	s_waitcnt vmcnt(14)
	ds_write_b128 v0, v[126:129] offset:23040
	v_mfma_f32_32x32x16_bf16 v[2:17], v[180:183], v[188:191], v[2:17]
	s_waitcnt vmcnt(12)
	ds_write_b128 v0, v[134:137] offset:32256
	v_mfma_f32_32x32x16_bf16 v[18:33], v[180:183], v[216:219], v[18:33]
	ds_read_b128 v[172:175], v166 offset:36960
	ds_read_b128 v[180:183], v166 offset:41568
	ds_read_b128 v[188:191], v167 offset:55392
	ds_read_b128 v[216:219], v167 offset:60000
	s_waitcnt lgkmcnt(8)
	v_mfma_f32_32x32x16_bf16 v[34:49], v[130:133], v[184:187], v[34:49]
	global_load_dwordx4 v[122:125], v[150:151], off offset:512
	global_load_dwordx4 v[126:129], v[152:153], off offset:512
	s_waitcnt lgkmcnt(7)
	v_mfma_f32_32x32x16_bf16 v[50:65], v[130:133], v[212:215], v[50:65]
	global_load_dwordx4 v[134:137], v[154:155], off offset:512
	global_load_dwordx4 v[146:149], v[156:157], off offset:512
	v_mfma_f32_32x32x16_bf16 v[2:17], v[176:179], v[184:187], v[2:17]
	global_load_dwordx4 v[98:101], v[158:159], off offset:640
	global_load_dwordx4 v[102:105], v[160:161], off offset:640
	v_mfma_f32_32x32x16_bf16 v[18:33], v[176:179], v[212:215], v[18:33]
	global_load_dwordx4 v[106:109], v[162:163], off offset:640
	global_load_dwordx4 v[110:113], v[164:165], off offset:640
	s_waitcnt lgkmcnt(1)
	v_mfma_f32_32x32x16_bf16 v[34:49], v[172:175], v[188:191], v[34:49]
	s_waitcnt lgkmcnt(0)
	v_mfma_f32_32x32x16_bf16 v[50:65], v[172:175], v[216:219], v[50:65]
	v_mfma_f32_32x32x16_bf16 v[2:17], v[180:183], v[188:191], v[2:17]
	v_mfma_f32_32x32x16_bf16 v[18:33], v[180:183], v[216:219], v[18:33]
	s_waitcnt lgkmcnt(0)
	s_setprio 0
	s_barrier
	s_setprio 2
	s_waitcnt vmcnt(14)
	ds_write_b128 v0, v[118:121] offset:59904
	ds_read_b128 v[118:121], v166
	ds_read_b128 v[176:179], v166 offset:4608
	ds_read_b128 v[184:187], v167 offset:18432
	ds_read_b128 v[212:215], v167 offset:23040
	ds_read_b128 v[172:175], v166 offset:32
	ds_read_b128 v[180:183], v166 offset:4640
	ds_read_b128 v[188:191], v167 offset:18464
	ds_read_b128 v[216:219], v167 offset:23072
	s_waitcnt lgkmcnt(5)
	v_mfma_f32_32x32x16_bf16 v[34:49], v[118:121], v[184:187], v[34:49]
	s_waitcnt vmcnt(19)
	ds_write_b128 v0, v[78:81] offset:36864
	s_waitcnt lgkmcnt(5)
	v_mfma_f32_32x32x16_bf16 v[50:65], v[118:121], v[212:215], v[50:65]
	s_waitcnt vmcnt(18)
	ds_write_b128 v0, v[86:89] offset:41472
	v_mfma_f32_32x32x16_bf16 v[2:17], v[176:179], v[184:187], v[2:17]
	s_waitcnt vmcnt(17)
	ds_write_b128 v0, v[90:93] offset:46080
	v_mfma_f32_32x32x16_bf16 v[18:33], v[176:179], v[212:215], v[18:33]
	s_waitcnt vmcnt(16)
	ds_write_b128 v0, v[94:97] offset:50688
	ds_read_b128 v[118:121], v166 offset:64
	ds_read_b128 v[176:179], v166 offset:4672
	ds_read_b128 v[184:187], v167 offset:18496
	ds_read_b128 v[212:215], v167 offset:23104
	s_waitcnt lgkmcnt(9)
	v_mfma_f32_32x32x16_bf16 v[34:49], v[172:175], v[188:191], v[34:49]
	s_waitcnt vmcnt(15)
	ds_write_b128 v0, v[114:117] offset:55296
	s_waitcnt lgkmcnt(9)
	v_mfma_f32_32x32x16_bf16 v[50:65], v[172:175], v[216:219], v[50:65]
	s_waitcnt vmcnt(13)
	ds_write_b128 v0, v[138:141] offset:64512
	v_mfma_f32_32x32x16_bf16 v[2:17], v[180:183], v[188:191], v[2:17]
	s_waitcnt vmcnt(12)
	ds_write_b128 v168, v[142:145] offset:13824
	v_mfma_f32_32x32x16_bf16 v[18:33], v[180:183], v[216:219], v[18:33]
	ds_read_b128 v[172:175], v166 offset:96
	ds_read_b128 v[180:183], v166 offset:4704
	ds_read_b128 v[188:191], v167 offset:18528
	ds_read_b128 v[216:219], v167 offset:23136
	s_waitcnt lgkmcnt(8)
	v_mfma_f32_32x32x16_bf16 v[34:49], v[118:121], v[184:187], v[34:49]
	global_load_dwordx4 v[94:97], v[150:151], off offset:640
	global_load_dwordx4 v[130:133], v[152:153], off offset:640
	s_waitcnt lgkmcnt(7)
	v_mfma_f32_32x32x16_bf16 v[50:65], v[118:121], v[212:215], v[50:65]
	global_load_dwordx4 v[138:141], v[154:155], off offset:640
	global_load_dwordx4 v[142:145], v[156:157], off offset:640
	v_mfma_f32_32x32x16_bf16 v[2:17], v[176:179], v[184:187], v[2:17]
	global_load_dwordx4 v[78:81], v[158:159], off offset:768
	global_load_dwordx4 v[86:89], v[160:161], off offset:768
	v_mfma_f32_32x32x16_bf16 v[18:33], v[176:179], v[212:215], v[18:33]
	global_load_dwordx4 v[90:93], v[162:163], off offset:768
	global_load_dwordx4 v[114:117], v[164:165], off offset:768
	s_waitcnt lgkmcnt(1)
	v_mfma_f32_32x32x16_bf16 v[34:49], v[172:175], v[188:191], v[34:49]
	s_waitcnt lgkmcnt(0)
	v_mfma_f32_32x32x16_bf16 v[50:65], v[172:175], v[216:219], v[50:65]
	v_mfma_f32_32x32x16_bf16 v[2:17], v[180:183], v[188:191], v[2:17]
	v_mfma_f32_32x32x16_bf16 v[18:33], v[180:183], v[216:219], v[18:33]
	s_waitcnt lgkmcnt(0)
	s_setprio 0
	s_barrier
	s_setprio 2
	s_waitcnt vmcnt(16)
	ds_write_b128 v0, v[82:85] offset:13824
	ds_read_b128 v[82:85], v166 offset:36864
	ds_read_b128 v[176:179], v166 offset:41472
	ds_read_b128 v[184:187], v167 offset:55296
	ds_read_b128 v[212:215], v167 offset:59904
	ds_read_b128 v[172:175], v166 offset:36896
	ds_read_b128 v[180:183], v166 offset:41504
	ds_read_b128 v[188:191], v167 offset:55328
	ds_read_b128 v[216:219], v167 offset:59936
	s_waitcnt lgkmcnt(5)
	v_mfma_f32_32x32x16_bf16 v[34:49], v[82:85], v[184:187], v[34:49]
	s_waitcnt vmcnt(19)
	ds_write_b128 v0, v[66:69]
	s_waitcnt lgkmcnt(5)
	v_mfma_f32_32x32x16_bf16 v[50:65], v[82:85], v[212:215], v[50:65]
	s_waitcnt vmcnt(18)
	ds_write_b128 v0, v[70:73] offset:4608
	v_mfma_f32_32x32x16_bf16 v[2:17], v[176:179], v[184:187], v[2:17]
	s_waitcnt vmcnt(17)
	ds_write_b128 v0, v[74:77] offset:9216
	v_mfma_f32_32x32x16_bf16 v[18:33], v[176:179], v[212:215], v[18:33]
	s_waitcnt vmcnt(15)
	ds_write_b128 v0, v[122:125] offset:18432
	ds_read_b128 v[82:85], v166 offset:36928
	ds_read_b128 v[176:179], v166 offset:41536
	ds_read_b128 v[184:187], v167 offset:55360
	ds_read_b128 v[212:215], v167 offset:59968
	s_waitcnt lgkmcnt(9)
	v_mfma_f32_32x32x16_bf16 v[34:49], v[172:175], v[188:191], v[34:49]
	s_waitcnt vmcnt(14)
	ds_write_b128 v0, v[126:129] offset:23040
	s_waitcnt lgkmcnt(9)
	v_mfma_f32_32x32x16_bf16 v[50:65], v[172:175], v[216:219], v[50:65]
	s_waitcnt vmcnt(13)
	ds_write_b128 v0, v[134:137] offset:27648
	v_mfma_f32_32x32x16_bf16 v[2:17], v[180:183], v[188:191], v[2:17]
	s_waitcnt vmcnt(12)
	ds_write_b128 v0, v[146:149] offset:32256
	v_mfma_f32_32x32x16_bf16 v[18:33], v[180:183], v[216:219], v[18:33]
	ds_read_b128 v[172:175], v166 offset:36960
	ds_read_b128 v[180:183], v166 offset:41568
	ds_read_b128 v[188:191], v167 offset:55392
	ds_read_b128 v[216:219], v167 offset:60000
	s_waitcnt lgkmcnt(8)
	v_mfma_f32_32x32x16_bf16 v[34:49], v[82:85], v[184:187], v[34:49]
	global_load_dwordx4 v[122:125], v[150:151], off offset:768
	global_load_dwordx4 v[126:129], v[152:153], off offset:768
	s_waitcnt lgkmcnt(7)
	v_mfma_f32_32x32x16_bf16 v[50:65], v[82:85], v[212:215], v[50:65]
	global_load_dwordx4 v[134:137], v[154:155], off offset:768
	global_load_dwordx4 v[146:149], v[156:157], off offset:768
	v_mfma_f32_32x32x16_bf16 v[2:17], v[176:179], v[184:187], v[2:17]
	global_load_dwordx4 v[66:69], v[158:159], off offset:896
	global_load_dwordx4 v[70:73], v[160:161], off offset:896
	v_mfma_f32_32x32x16_bf16 v[18:33], v[176:179], v[212:215], v[18:33]
	global_load_dwordx4 v[74:77], v[162:163], off offset:896
	global_load_dwordx4 v[118:121], v[164:165], off offset:896
	s_waitcnt lgkmcnt(1)
	v_mfma_f32_32x32x16_bf16 v[34:49], v[172:175], v[188:191], v[34:49]
	s_waitcnt lgkmcnt(0)
	v_mfma_f32_32x32x16_bf16 v[50:65], v[172:175], v[216:219], v[50:65]
	v_mfma_f32_32x32x16_bf16 v[2:17], v[180:183], v[188:191], v[2:17]
	v_mfma_f32_32x32x16_bf16 v[18:33], v[180:183], v[216:219], v[18:33]
	s_waitcnt lgkmcnt(0)
	s_setprio 0
	s_barrier
	s_setprio 2
	s_waitcnt vmcnt(17)
	ds_write_b128 v0, v[106:109] offset:46080
	ds_read_b128 v[106:109], v166
	ds_read_b128 v[176:179], v166 offset:4608
	ds_read_b128 v[184:187], v167 offset:18432
	ds_read_b128 v[212:215], v167 offset:23040
	ds_read_b128 v[172:175], v166 offset:32
	ds_read_b128 v[180:183], v166 offset:4640
	ds_read_b128 v[188:191], v167 offset:18464
	ds_read_b128 v[216:219], v167 offset:23072
	s_waitcnt lgkmcnt(5)
	v_mfma_f32_32x32x16_bf16 v[34:49], v[106:109], v[184:187], v[34:49]
	s_waitcnt vmcnt(19)
	ds_write_b128 v0, v[98:101] offset:36864
	s_waitcnt lgkmcnt(5)
	v_mfma_f32_32x32x16_bf16 v[50:65], v[106:109], v[212:215], v[50:65]
	s_waitcnt vmcnt(18)
	ds_write_b128 v0, v[102:105] offset:41472
	v_mfma_f32_32x32x16_bf16 v[2:17], v[176:179], v[184:187], v[2:17]
	s_waitcnt vmcnt(16)
	ds_write_b128 v0, v[110:113] offset:50688
	v_mfma_f32_32x32x16_bf16 v[18:33], v[176:179], v[212:215], v[18:33]
	s_waitcnt vmcnt(15)
	ds_write_b128 v0, v[94:97] offset:55296
	ds_read_b128 v[106:109], v166 offset:64
	ds_read_b128 v[176:179], v166 offset:4672
	ds_read_b128 v[184:187], v167 offset:18496
	ds_read_b128 v[212:215], v167 offset:23104
	s_waitcnt lgkmcnt(9)
	v_mfma_f32_32x32x16_bf16 v[34:49], v[172:175], v[188:191], v[34:49]
	s_waitcnt vmcnt(14)
	ds_write_b128 v0, v[130:133] offset:59904
	s_waitcnt lgkmcnt(9)
	v_mfma_f32_32x32x16_bf16 v[50:65], v[172:175], v[216:219], v[50:65]
	s_waitcnt vmcnt(13)
	ds_write_b128 v0, v[138:141] offset:64512
	v_mfma_f32_32x32x16_bf16 v[2:17], v[180:183], v[188:191], v[2:17]
	s_waitcnt vmcnt(12)
	ds_write_b128 v168, v[142:145] offset:13824
	v_mfma_f32_32x32x16_bf16 v[18:33], v[180:183], v[216:219], v[18:33]
	ds_read_b128 v[172:175], v166 offset:96
	ds_read_b128 v[180:183], v166 offset:4704
	ds_read_b128 v[188:191], v167 offset:18528
	ds_read_b128 v[216:219], v167 offset:23136
	s_waitcnt lgkmcnt(8)
	v_mfma_f32_32x32x16_bf16 v[34:49], v[106:109], v[184:187], v[34:49]
	global_load_dwordx4 v[110:113], v[150:151], off offset:896
	global_load_dwordx4 v[130:133], v[152:153], off offset:896
	s_waitcnt lgkmcnt(7)
	v_mfma_f32_32x32x16_bf16 v[50:65], v[106:109], v[212:215], v[50:65]
	global_load_dwordx4 v[138:141], v[154:155], off offset:896
	global_load_dwordx4 v[142:145], v[156:157], off offset:896
	v_mfma_f32_32x32x16_bf16 v[2:17], v[176:179], v[184:187], v[2:17]
	global_load_dwordx4 v[82:85], v[158:159], off offset:1024
	global_load_dwordx4 v[94:97], v[160:161], off offset:1024
	v_mfma_f32_32x32x16_bf16 v[18:33], v[176:179], v[212:215], v[18:33]
	global_load_dwordx4 v[98:101], v[162:163], off offset:1024
	global_load_dwordx4 v[102:105], v[164:165], off offset:1024
	s_waitcnt lgkmcnt(1)
	v_mfma_f32_32x32x16_bf16 v[34:49], v[172:175], v[188:191], v[34:49]
	s_waitcnt lgkmcnt(0)
	v_mfma_f32_32x32x16_bf16 v[50:65], v[172:175], v[216:219], v[50:65]
	v_mfma_f32_32x32x16_bf16 v[2:17], v[180:183], v[188:191], v[2:17]
	v_mfma_f32_32x32x16_bf16 v[18:33], v[180:183], v[216:219], v[18:33]
	s_waitcnt lgkmcnt(0)
	s_setprio 0
	s_barrier
	s_setprio 2
	s_waitcnt vmcnt(14)
	ds_write_b128 v0, v[126:129] offset:23040
	ds_read_b128 v[126:129], v166 offset:36864
	ds_read_b128 v[176:179], v166 offset:41472
	ds_read_b128 v[184:187], v167 offset:55296
	ds_read_b128 v[212:215], v167 offset:59904
	ds_read_b128 v[172:175], v166 offset:36896
	ds_read_b128 v[180:183], v166 offset:41504
	ds_read_b128 v[188:191], v167 offset:55328
	ds_read_b128 v[216:219], v167 offset:59936
	s_waitcnt lgkmcnt(5)
	v_mfma_f32_32x32x16_bf16 v[34:49], v[126:129], v[184:187], v[34:49]
	s_waitcnt vmcnt(19)
	ds_write_b128 v0, v[78:81]
	s_waitcnt lgkmcnt(5)
	v_mfma_f32_32x32x16_bf16 v[50:65], v[126:129], v[212:215], v[50:65]
	s_waitcnt vmcnt(18)
	ds_write_b128 v0, v[86:89] offset:4608
	v_mfma_f32_32x32x16_bf16 v[2:17], v[176:179], v[184:187], v[2:17]
	s_waitcnt vmcnt(17)
	ds_write_b128 v0, v[90:93] offset:9216
	v_mfma_f32_32x32x16_bf16 v[18:33], v[176:179], v[212:215], v[18:33]
	s_waitcnt vmcnt(16)
	ds_write_b128 v0, v[114:117] offset:13824
	ds_read_b128 v[126:129], v166 offset:36928
	ds_read_b128 v[176:179], v166 offset:41536
	ds_read_b128 v[184:187], v167 offset:55360
	ds_read_b128 v[212:215], v167 offset:59968
	s_waitcnt lgkmcnt(9)
	v_mfma_f32_32x32x16_bf16 v[34:49], v[172:175], v[188:191], v[34:49]
	s_waitcnt vmcnt(15)
	ds_write_b128 v0, v[122:125] offset:18432
	s_waitcnt lgkmcnt(9)
	v_mfma_f32_32x32x16_bf16 v[50:65], v[172:175], v[216:219], v[50:65]
	s_waitcnt vmcnt(13)
	ds_write_b128 v0, v[134:137] offset:27648
	v_mfma_f32_32x32x16_bf16 v[2:17], v[180:183], v[188:191], v[2:17]
	s_waitcnt vmcnt(12)
	ds_write_b128 v0, v[146:149] offset:32256
	v_mfma_f32_32x32x16_bf16 v[18:33], v[180:183], v[216:219], v[18:33]
	ds_read_b128 v[172:175], v166 offset:36960
	ds_read_b128 v[180:183], v166 offset:41568
	ds_read_b128 v[188:191], v167 offset:55392
	ds_read_b128 v[216:219], v167 offset:60000
	s_waitcnt lgkmcnt(8)
	v_mfma_f32_32x32x16_bf16 v[34:49], v[126:129], v[184:187], v[34:49]
	global_load_dwordx4 v[114:117], v[150:151], off offset:1024
	global_load_dwordx4 v[122:125], v[152:153], off offset:1024
	s_waitcnt lgkmcnt(7)
	v_mfma_f32_32x32x16_bf16 v[50:65], v[126:129], v[212:215], v[50:65]
	global_load_dwordx4 v[134:137], v[154:155], off offset:1024
	global_load_dwordx4 v[146:149], v[156:157], off offset:1024
	v_mfma_f32_32x32x16_bf16 v[2:17], v[176:179], v[184:187], v[2:17]
	global_load_dwordx4 v[78:81], v[158:159], off offset:1152
	global_load_dwordx4 v[86:89], v[160:161], off offset:1152
	v_mfma_f32_32x32x16_bf16 v[18:33], v[176:179], v[212:215], v[18:33]
	global_load_dwordx4 v[90:93], v[162:163], off offset:1152
	global_load_dwordx4 v[106:109], v[164:165], off offset:1152
	s_waitcnt lgkmcnt(1)
	v_mfma_f32_32x32x16_bf16 v[34:49], v[172:175], v[188:191], v[34:49]
	s_waitcnt lgkmcnt(0)
	v_mfma_f32_32x32x16_bf16 v[50:65], v[172:175], v[216:219], v[50:65]
	v_mfma_f32_32x32x16_bf16 v[2:17], v[180:183], v[188:191], v[2:17]
	v_mfma_f32_32x32x16_bf16 v[18:33], v[180:183], v[216:219], v[18:33]
	s_waitcnt lgkmcnt(0)
	s_setprio 0
	s_barrier
	s_setprio 2
	s_waitcnt vmcnt(12)
	ds_write_b128 v168, v[142:145] offset:13824
	ds_read_b128 v[142:145], v166
	ds_read_b128 v[176:179], v166 offset:4608
	ds_read_b128 v[184:187], v167 offset:18432
	ds_read_b128 v[212:215], v167 offset:23040
	ds_read_b128 v[172:175], v166 offset:32
	ds_read_b128 v[180:183], v166 offset:4640
	ds_read_b128 v[188:191], v167 offset:18464
	ds_read_b128 v[216:219], v167 offset:23072
	s_waitcnt lgkmcnt(5)
	v_mfma_f32_32x32x16_bf16 v[34:49], v[142:145], v[184:187], v[34:49]
	s_waitcnt vmcnt(19)
	ds_write_b128 v0, v[66:69] offset:36864
	s_waitcnt lgkmcnt(5)
	v_mfma_f32_32x32x16_bf16 v[50:65], v[142:145], v[212:215], v[50:65]
	s_waitcnt vmcnt(18)
	ds_write_b128 v0, v[70:73] offset:41472
	v_mfma_f32_32x32x16_bf16 v[2:17], v[176:179], v[184:187], v[2:17]
	s_waitcnt vmcnt(17)
	ds_write_b128 v0, v[74:77] offset:46080
	v_mfma_f32_32x32x16_bf16 v[18:33], v[176:179], v[212:215], v[18:33]
	s_waitcnt vmcnt(16)
	ds_write_b128 v0, v[118:121] offset:50688
	ds_read_b128 v[142:145], v166 offset:64
	ds_read_b128 v[176:179], v166 offset:4672
	ds_read_b128 v[184:187], v167 offset:18496
	ds_read_b128 v[212:215], v167 offset:23104
	s_waitcnt lgkmcnt(9)
	v_mfma_f32_32x32x16_bf16 v[34:49], v[172:175], v[188:191], v[34:49]
	s_waitcnt vmcnt(15)
	ds_write_b128 v0, v[110:113] offset:55296
	s_waitcnt lgkmcnt(9)
	v_mfma_f32_32x32x16_bf16 v[50:65], v[172:175], v[216:219], v[50:65]
	s_waitcnt vmcnt(14)
	ds_write_b128 v0, v[130:133] offset:59904
	v_mfma_f32_32x32x16_bf16 v[2:17], v[180:183], v[188:191], v[2:17]
	s_waitcnt vmcnt(13)
	ds_write_b128 v0, v[138:141] offset:64512
	v_mfma_f32_32x32x16_bf16 v[18:33], v[180:183], v[216:219], v[18:33]
	ds_read_b128 v[172:175], v166 offset:96
	ds_read_b128 v[180:183], v166 offset:4704
	ds_read_b128 v[188:191], v167 offset:18528
	ds_read_b128 v[216:219], v167 offset:23136
	s_waitcnt lgkmcnt(8)
	v_mfma_f32_32x32x16_bf16 v[34:49], v[142:145], v[184:187], v[34:49]
	global_load_dwordx4 v[118:121], v[150:151], off offset:1152
	global_load_dwordx4 v[126:129], v[152:153], off offset:1152
	s_waitcnt lgkmcnt(7)
	v_mfma_f32_32x32x16_bf16 v[50:65], v[142:145], v[212:215], v[50:65]
	global_load_dwordx4 v[130:133], v[154:155], off offset:1152
	global_load_dwordx4 v[138:141], v[156:157], off offset:1152
	v_mfma_f32_32x32x16_bf16 v[2:17], v[176:179], v[184:187], v[2:17]
	global_load_dwordx4 v[66:69], v[158:159], off offset:1280
	global_load_dwordx4 v[70:73], v[160:161], off offset:1280
	v_mfma_f32_32x32x16_bf16 v[18:33], v[176:179], v[212:215], v[18:33]
	global_load_dwordx4 v[74:77], v[162:163], off offset:1280
	global_load_dwordx4 v[110:113], v[164:165], off offset:1280
	s_waitcnt lgkmcnt(1)
	v_mfma_f32_32x32x16_bf16 v[34:49], v[172:175], v[188:191], v[34:49]
	s_waitcnt lgkmcnt(0)
	v_mfma_f32_32x32x16_bf16 v[50:65], v[172:175], v[216:219], v[50:65]
	v_mfma_f32_32x32x16_bf16 v[2:17], v[180:183], v[188:191], v[2:17]
	v_mfma_f32_32x32x16_bf16 v[18:33], v[180:183], v[216:219], v[18:33]
	s_waitcnt lgkmcnt(0)
	s_setprio 0
	s_barrier
	s_setprio 2
	s_waitcnt vmcnt(12)
	ds_write_b128 v0, v[146:149] offset:32256
	ds_read_b128 v[146:149], v166 offset:36864
	ds_read_b128 v[176:179], v166 offset:41472
	ds_read_b128 v[184:187], v167 offset:55296
	ds_read_b128 v[212:215], v167 offset:59904
	ds_read_b128 v[172:175], v166 offset:36896
	ds_read_b128 v[180:183], v166 offset:41504
	ds_read_b128 v[188:191], v167 offset:55328
	ds_read_b128 v[216:219], v167 offset:59936
	s_waitcnt lgkmcnt(5)
	v_mfma_f32_32x32x16_bf16 v[34:49], v[146:149], v[184:187], v[34:49]
	s_waitcnt vmcnt(19)
	ds_write_b128 v0, v[82:85]
	s_waitcnt lgkmcnt(5)
	v_mfma_f32_32x32x16_bf16 v[50:65], v[146:149], v[212:215], v[50:65]
	s_waitcnt vmcnt(18)
	ds_write_b128 v0, v[94:97] offset:4608
	v_mfma_f32_32x32x16_bf16 v[2:17], v[176:179], v[184:187], v[2:17]
	s_waitcnt vmcnt(17)
	ds_write_b128 v0, v[98:101] offset:9216
	v_mfma_f32_32x32x16_bf16 v[18:33], v[176:179], v[212:215], v[18:33]
	s_waitcnt vmcnt(16)
	ds_write_b128 v0, v[102:105] offset:13824
	ds_read_b128 v[146:149], v166 offset:36928
	ds_read_b128 v[176:179], v166 offset:41536
	ds_read_b128 v[184:187], v167 offset:55360
	ds_read_b128 v[212:215], v167 offset:59968
	s_waitcnt lgkmcnt(9)
	v_mfma_f32_32x32x16_bf16 v[34:49], v[172:175], v[188:191], v[34:49]
	s_waitcnt vmcnt(15)
	ds_write_b128 v0, v[114:117] offset:18432
	s_waitcnt lgkmcnt(9)
	v_mfma_f32_32x32x16_bf16 v[50:65], v[172:175], v[216:219], v[50:65]
	s_waitcnt vmcnt(14)
	ds_write_b128 v0, v[122:125] offset:23040
	v_mfma_f32_32x32x16_bf16 v[2:17], v[180:183], v[188:191], v[2:17]
	s_waitcnt vmcnt(13)
	ds_write_b128 v0, v[134:137] offset:27648
	v_mfma_f32_32x32x16_bf16 v[18:33], v[180:183], v[216:219], v[18:33]
	ds_read_b128 v[172:175], v166 offset:36960
	ds_read_b128 v[180:183], v166 offset:41568
	ds_read_b128 v[188:191], v167 offset:55392
	ds_read_b128 v[216:219], v167 offset:60000
	s_waitcnt lgkmcnt(8)
	v_mfma_f32_32x32x16_bf16 v[34:49], v[146:149], v[184:187], v[34:49]
	global_load_dwordx4 v[114:117], v[150:151], off offset:1280
	global_load_dwordx4 v[122:125], v[152:153], off offset:1280
	s_waitcnt lgkmcnt(7)
	v_mfma_f32_32x32x16_bf16 v[50:65], v[146:149], v[212:215], v[50:65]
	global_load_dwordx4 v[134:137], v[154:155], off offset:1280
	global_load_dwordx4 v[142:145], v[156:157], off offset:1280
	v_mfma_f32_32x32x16_bf16 v[2:17], v[176:179], v[184:187], v[2:17]
	global_load_dwordx4 v[82:85], v[158:159], off offset:1408
	global_load_dwordx4 v[94:97], v[160:161], off offset:1408
	v_mfma_f32_32x32x16_bf16 v[18:33], v[176:179], v[212:215], v[18:33]
	global_load_dwordx4 v[98:101], v[162:163], off offset:1408
	global_load_dwordx4 v[102:105], v[164:165], off offset:1408
	s_waitcnt lgkmcnt(1)
	v_mfma_f32_32x32x16_bf16 v[34:49], v[172:175], v[188:191], v[34:49]
	s_waitcnt lgkmcnt(0)
	v_mfma_f32_32x32x16_bf16 v[50:65], v[172:175], v[216:219], v[50:65]
	v_mfma_f32_32x32x16_bf16 v[2:17], v[180:183], v[188:191], v[2:17]
	v_mfma_f32_32x32x16_bf16 v[18:33], v[180:183], v[216:219], v[18:33]
	s_waitcnt lgkmcnt(0)
	s_setprio 0
	s_barrier
	s_setprio 2
	ds_read_b128 v[146:149], v166
	ds_read_b128 v[176:179], v166 offset:4608
	ds_read_b128 v[184:187], v167 offset:18432
	ds_read_b128 v[212:215], v167 offset:23040
	ds_read_b128 v[172:175], v166 offset:32
	ds_read_b128 v[180:183], v166 offset:4640
	ds_read_b128 v[188:191], v167 offset:18464
	ds_read_b128 v[216:219], v167 offset:23072
	s_waitcnt lgkmcnt(5)
	v_mfma_f32_32x32x16_bf16 v[34:49], v[146:149], v[184:187], v[34:49]
	s_waitcnt vmcnt(19)
	ds_write_b128 v0, v[78:81] offset:36864
	s_waitcnt lgkmcnt(5)
	v_mfma_f32_32x32x16_bf16 v[50:65], v[146:149], v[212:215], v[50:65]
	s_waitcnt vmcnt(18)
	ds_write_b128 v0, v[86:89] offset:41472
	v_mfma_f32_32x32x16_bf16 v[2:17], v[176:179], v[184:187], v[2:17]
	s_waitcnt vmcnt(17)
	ds_write_b128 v0, v[90:93] offset:46080
	v_mfma_f32_32x32x16_bf16 v[18:33], v[176:179], v[212:215], v[18:33]
	s_waitcnt vmcnt(16)
	ds_write_b128 v0, v[106:109] offset:50688
	ds_read_b128 v[146:149], v166 offset:64
	ds_read_b128 v[176:179], v166 offset:4672
	ds_read_b128 v[184:187], v167 offset:18496
	ds_read_b128 v[212:215], v167 offset:23104
	s_waitcnt lgkmcnt(9)
	v_mfma_f32_32x32x16_bf16 v[34:49], v[172:175], v[188:191], v[34:49]
	s_waitcnt vmcnt(15)
	ds_write_b128 v0, v[118:121] offset:55296
	s_waitcnt lgkmcnt(9)
	v_mfma_f32_32x32x16_bf16 v[50:65], v[172:175], v[216:219], v[50:65]
	s_waitcnt vmcnt(14)
	ds_write_b128 v0, v[126:129] offset:59904
	v_mfma_f32_32x32x16_bf16 v[2:17], v[180:183], v[188:191], v[2:17]
	s_waitcnt vmcnt(13)
	ds_write_b128 v0, v[130:133] offset:64512
	v_mfma_f32_32x32x16_bf16 v[18:33], v[180:183], v[216:219], v[18:33]
	s_waitcnt vmcnt(12)
	ds_write_b128 v168, v[138:141] offset:13824
	ds_read_b128 v[172:175], v166 offset:96
	ds_read_b128 v[180:183], v166 offset:4704
	ds_read_b128 v[188:191], v167 offset:18528
	ds_read_b128 v[216:219], v167 offset:23136
	s_waitcnt lgkmcnt(9)
	v_mfma_f32_32x32x16_bf16 v[34:49], v[146:149], v[184:187], v[34:49]
	global_load_dwordx4 v[118:121], v[150:151], off offset:1408
	global_load_dwordx4 v[126:129], v[152:153], off offset:1408
	s_waitcnt lgkmcnt(8)
	v_mfma_f32_32x32x16_bf16 v[50:65], v[146:149], v[212:215], v[50:65]
	global_load_dwordx4 v[130:133], v[154:155], off offset:1408
	global_load_dwordx4 v[138:141], v[156:157], off offset:1408
	v_mfma_f32_32x32x16_bf16 v[2:17], v[176:179], v[184:187], v[2:17]
	global_load_dwordx4 v[78:81], v[158:159], off offset:1536
	global_load_dwordx4 v[86:89], v[160:161], off offset:1536
	v_mfma_f32_32x32x16_bf16 v[18:33], v[176:179], v[212:215], v[18:33]
	global_load_dwordx4 v[90:93], v[162:163], off offset:1536
	global_load_dwordx4 v[106:109], v[164:165], off offset:1536
	s_waitcnt lgkmcnt(1)
	v_mfma_f32_32x32x16_bf16 v[34:49], v[172:175], v[188:191], v[34:49]
	s_waitcnt lgkmcnt(0)
	v_mfma_f32_32x32x16_bf16 v[50:65], v[172:175], v[216:219], v[50:65]
	v_mfma_f32_32x32x16_bf16 v[2:17], v[180:183], v[188:191], v[2:17]
	v_mfma_f32_32x32x16_bf16 v[18:33], v[180:183], v[216:219], v[18:33]
	s_waitcnt lgkmcnt(0)
	s_setprio 0
	s_barrier
	s_setprio 2
	ds_read_b128 v[146:149], v166 offset:36864
	ds_read_b128 v[176:179], v166 offset:41472
	ds_read_b128 v[184:187], v167 offset:55296
	ds_read_b128 v[212:215], v167 offset:59904
	ds_read_b128 v[172:175], v166 offset:36896
	ds_read_b128 v[180:183], v166 offset:41504
	ds_read_b128 v[188:191], v167 offset:55328
	ds_read_b128 v[216:219], v167 offset:59936
	s_waitcnt lgkmcnt(5)
	v_mfma_f32_32x32x16_bf16 v[34:49], v[146:149], v[184:187], v[34:49]
	s_waitcnt vmcnt(19)
	ds_write_b128 v0, v[66:69]
	s_waitcnt lgkmcnt(5)
	v_mfma_f32_32x32x16_bf16 v[50:65], v[146:149], v[212:215], v[50:65]
	s_waitcnt vmcnt(18)
	ds_write_b128 v0, v[70:73] offset:4608
	v_mfma_f32_32x32x16_bf16 v[2:17], v[176:179], v[184:187], v[2:17]
	s_waitcnt vmcnt(17)
	ds_write_b128 v0, v[74:77] offset:9216
	v_mfma_f32_32x32x16_bf16 v[18:33], v[176:179], v[212:215], v[18:33]
	s_waitcnt vmcnt(16)
	ds_write_b128 v0, v[110:113] offset:13824
	ds_read_b128 v[146:149], v166 offset:36928
	ds_read_b128 v[176:179], v166 offset:41536
	ds_read_b128 v[184:187], v167 offset:55360
	ds_read_b128 v[212:215], v167 offset:59968
	s_waitcnt lgkmcnt(9)
	v_mfma_f32_32x32x16_bf16 v[34:49], v[172:175], v[188:191], v[34:49]
	s_waitcnt vmcnt(15)
	ds_write_b128 v0, v[114:117] offset:18432
	s_waitcnt lgkmcnt(9)
	v_mfma_f32_32x32x16_bf16 v[50:65], v[172:175], v[216:219], v[50:65]
	s_waitcnt vmcnt(14)
	ds_write_b128 v0, v[122:125] offset:23040
	v_mfma_f32_32x32x16_bf16 v[2:17], v[180:183], v[188:191], v[2:17]
	s_waitcnt vmcnt(13)
	ds_write_b128 v0, v[134:137] offset:27648
	v_mfma_f32_32x32x16_bf16 v[18:33], v[180:183], v[216:219], v[18:33]
	s_waitcnt vmcnt(12)
	ds_write_b128 v0, v[142:145] offset:32256
	ds_read_b128 v[172:175], v166 offset:36960
	ds_read_b128 v[180:183], v166 offset:41568
	ds_read_b128 v[188:191], v167 offset:55392
	ds_read_b128 v[216:219], v167 offset:60000
	s_waitcnt lgkmcnt(9)
	v_mfma_f32_32x32x16_bf16 v[34:49], v[146:149], v[184:187], v[34:49]
	global_load_dwordx4 v[114:117], v[150:151], off offset:1536
	global_load_dwordx4 v[122:125], v[152:153], off offset:1536
	s_waitcnt lgkmcnt(8)
	v_mfma_f32_32x32x16_bf16 v[50:65], v[146:149], v[212:215], v[50:65]
	global_load_dwordx4 v[134:137], v[154:155], off offset:1536
	global_load_dwordx4 v[142:145], v[156:157], off offset:1536
	v_mfma_f32_32x32x16_bf16 v[2:17], v[176:179], v[184:187], v[2:17]
	global_load_dwordx4 v[66:69], v[158:159], off offset:1664
	global_load_dwordx4 v[70:73], v[160:161], off offset:1664
	v_mfma_f32_32x32x16_bf16 v[18:33], v[176:179], v[212:215], v[18:33]
	global_load_dwordx4 v[74:77], v[162:163], off offset:1664
	global_load_dwordx4 v[110:113], v[164:165], off offset:1664
	s_waitcnt lgkmcnt(1)
	v_mfma_f32_32x32x16_bf16 v[34:49], v[172:175], v[188:191], v[34:49]
	s_waitcnt lgkmcnt(0)
	v_mfma_f32_32x32x16_bf16 v[50:65], v[172:175], v[216:219], v[50:65]
	v_mfma_f32_32x32x16_bf16 v[2:17], v[180:183], v[188:191], v[2:17]
	v_mfma_f32_32x32x16_bf16 v[18:33], v[180:183], v[216:219], v[18:33]
	s_waitcnt lgkmcnt(0)
	s_setprio 0
	s_barrier
	s_setprio 2
	ds_read_b128 v[146:149], v166
	ds_read_b128 v[176:179], v166 offset:4608
	ds_read_b128 v[184:187], v167 offset:18432
	ds_read_b128 v[212:215], v167 offset:23040
	ds_read_b128 v[172:175], v166 offset:32
	ds_read_b128 v[180:183], v166 offset:4640
	ds_read_b128 v[188:191], v167 offset:18464
	ds_read_b128 v[216:219], v167 offset:23072
	s_waitcnt lgkmcnt(5)
	v_mfma_f32_32x32x16_bf16 v[34:49], v[146:149], v[184:187], v[34:49]
	s_waitcnt vmcnt(19)
	ds_write_b128 v0, v[82:85] offset:36864
	s_waitcnt lgkmcnt(5)
	v_mfma_f32_32x32x16_bf16 v[50:65], v[146:149], v[212:215], v[50:65]
	s_waitcnt vmcnt(18)
	ds_write_b128 v0, v[94:97] offset:41472
	v_mfma_f32_32x32x16_bf16 v[2:17], v[176:179], v[184:187], v[2:17]
	s_waitcnt vmcnt(17)
	ds_write_b128 v0, v[98:101] offset:46080
	v_mfma_f32_32x32x16_bf16 v[18:33], v[176:179], v[212:215], v[18:33]
	s_waitcnt vmcnt(16)
	ds_write_b128 v0, v[102:105] offset:50688
	ds_read_b128 v[146:149], v166 offset:64
	ds_read_b128 v[176:179], v166 offset:4672
	ds_read_b128 v[184:187], v167 offset:18496
	ds_read_b128 v[212:215], v167 offset:23104
	s_waitcnt lgkmcnt(9)
	v_mfma_f32_32x32x16_bf16 v[34:49], v[172:175], v[188:191], v[34:49]
	s_waitcnt vmcnt(15)
	ds_write_b128 v0, v[118:121] offset:55296
	s_waitcnt lgkmcnt(9)
	v_mfma_f32_32x32x16_bf16 v[50:65], v[172:175], v[216:219], v[50:65]
	s_waitcnt vmcnt(14)
	ds_write_b128 v0, v[126:129] offset:59904
	v_mfma_f32_32x32x16_bf16 v[2:17], v[180:183], v[188:191], v[2:17]
	s_waitcnt vmcnt(13)
	ds_write_b128 v0, v[130:133] offset:64512
	v_mfma_f32_32x32x16_bf16 v[18:33], v[180:183], v[216:219], v[18:33]
	s_waitcnt vmcnt(12)
	ds_write_b128 v168, v[138:141] offset:13824
	ds_read_b128 v[172:175], v166 offset:96
	ds_read_b128 v[180:183], v166 offset:4704
	ds_read_b128 v[188:191], v167 offset:18528
	ds_read_b128 v[216:219], v167 offset:23136
	s_waitcnt lgkmcnt(9)
	v_mfma_f32_32x32x16_bf16 v[34:49], v[146:149], v[184:187], v[34:49]
	global_load_dwordx4 v[118:121], v[150:151], off offset:1664
	global_load_dwordx4 v[126:129], v[152:153], off offset:1664
	s_waitcnt lgkmcnt(8)
	v_mfma_f32_32x32x16_bf16 v[50:65], v[146:149], v[212:215], v[50:65]
	global_load_dwordx4 v[130:133], v[154:155], off offset:1664
	global_load_dwordx4 v[138:141], v[156:157], off offset:1664
	v_mfma_f32_32x32x16_bf16 v[2:17], v[176:179], v[184:187], v[2:17]
	global_load_dwordx4 v[82:85], v[158:159], off offset:1792
	global_load_dwordx4 v[94:97], v[160:161], off offset:1792
	v_mfma_f32_32x32x16_bf16 v[18:33], v[176:179], v[212:215], v[18:33]
	global_load_dwordx4 v[98:101], v[162:163], off offset:1792
	global_load_dwordx4 v[102:105], v[164:165], off offset:1792
	s_waitcnt lgkmcnt(1)
	v_mfma_f32_32x32x16_bf16 v[34:49], v[172:175], v[188:191], v[34:49]
	s_waitcnt lgkmcnt(0)
	v_mfma_f32_32x32x16_bf16 v[50:65], v[172:175], v[216:219], v[50:65]
	v_mfma_f32_32x32x16_bf16 v[2:17], v[180:183], v[188:191], v[2:17]
	v_mfma_f32_32x32x16_bf16 v[18:33], v[180:183], v[216:219], v[18:33]
	s_waitcnt lgkmcnt(0)
	s_setprio 0
	s_barrier
	s_waitcnt vmcnt(19)
	ds_write_b128 v0, v[78:81]
	s_waitcnt vmcnt(18)
	ds_write_b128 v0, v[86:89] offset:4608
	s_waitcnt vmcnt(17)
	ds_write_b128 v0, v[90:93] offset:9216
	s_waitcnt vmcnt(16)
	ds_write_b128 v0, v[106:109] offset:13824
	s_waitcnt vmcnt(15)
	ds_write_b128 v0, v[114:117] offset:18432
	s_waitcnt vmcnt(14)
	ds_write_b128 v0, v[122:125] offset:23040
	s_waitcnt vmcnt(13)
	ds_write_b128 v0, v[134:137] offset:27648
	s_waitcnt vmcnt(12)
	ds_write_b128 v0, v[142:145] offset:32256
	global_load_dwordx4 v[114:117], v[150:151], off offset:1792
	global_load_dwordx4 v[122:125], v[152:153], off offset:1792
	global_load_dwordx4 v[134:137], v[154:155], off offset:1792
	global_load_dwordx4 v[142:145], v[156:157], off offset:1792
	global_load_dwordx4 v[78:81], v[158:159], off offset:1920
	global_load_dwordx4 v[86:89], v[160:161], off offset:1920
	global_load_dwordx4 v[90:93], v[162:163], off offset:1920
	global_load_dwordx4 v[106:109], v[164:165], off offset:1920
	s_setprio 2
	ds_read_b128 v[146:149], v166 offset:36864
	ds_read_b128 v[158:161], v166 offset:36896
	ds_read_b128 v[162:165], v166 offset:41472
	ds_read_b128 v[172:175], v166 offset:41504
	ds_read_b128 v[176:179], v167 offset:55296
	ds_read_b128 v[180:183], v167 offset:55328
	ds_read_b128 v[184:187], v167 offset:59904
	ds_read_b128 v[188:191], v167 offset:59936
	s_waitcnt lgkmcnt(3)
	v_mfma_f32_32x32x16_bf16 v[34:49], v[146:149], v[176:179], v[34:49]
	s_waitcnt lgkmcnt(1)
	v_mfma_f32_32x32x16_bf16 v[50:65], v[146:149], v[184:187], v[50:65]
	v_mfma_f32_32x32x16_bf16 v[2:17], v[162:165], v[176:179], v[2:17]
	v_mfma_f32_32x32x16_bf16 v[18:33], v[162:165], v[184:187], v[18:33]
	ds_read_b128 v[146:149], v166 offset:36928
	ds_read_b128 v[162:165], v166 offset:41536
	ds_read_b128 v[176:179], v167 offset:55360
	ds_read_b128 v[184:187], v167 offset:59968
	v_mfma_f32_32x32x16_bf16 v[34:49], v[158:161], v[180:183], v[34:49]
	s_waitcnt lgkmcnt(4)
	v_mfma_f32_32x32x16_bf16 v[50:65], v[158:161], v[188:191], v[50:65]
	v_mfma_f32_32x32x16_bf16 v[2:17], v[172:175], v[180:183], v[2:17]
	v_mfma_f32_32x32x16_bf16 v[18:33], v[172:175], v[188:191], v[18:33]
	ds_read_b128 v[158:161], v166 offset:36960
	ds_read_b128 v[172:175], v166 offset:41568
	ds_read_b128 v[180:183], v167 offset:55392
	ds_read_b128 v[188:191], v167 offset:60000
	s_waitcnt lgkmcnt(5)
	v_mfma_f32_32x32x16_bf16 v[34:49], v[146:149], v[176:179], v[34:49]
	s_waitcnt lgkmcnt(4)
	v_mfma_f32_32x32x16_bf16 v[50:65], v[146:149], v[184:187], v[50:65]
	v_mfma_f32_32x32x16_bf16 v[2:17], v[162:165], v[176:179], v[2:17]
	v_mfma_f32_32x32x16_bf16 v[18:33], v[162:165], v[184:187], v[18:33]
	s_waitcnt lgkmcnt(1)
	v_mfma_f32_32x32x16_bf16 v[34:49], v[158:161], v[180:183], v[34:49]
	s_waitcnt lgkmcnt(0)
	v_mfma_f32_32x32x16_bf16 v[50:65], v[158:161], v[188:191], v[50:65]
	v_mfma_f32_32x32x16_bf16 v[2:17], v[172:175], v[180:183], v[2:17]
	v_mfma_f32_32x32x16_bf16 v[18:33], v[172:175], v[188:191], v[18:33]
	s_setprio 0
	s_barrier
	s_waitcnt vmcnt(19)
	ds_write_b128 v0, v[66:69] offset:36864
	s_waitcnt vmcnt(18)
	ds_write_b128 v0, v[70:73] offset:41472
	s_waitcnt vmcnt(17)
	ds_write_b128 v0, v[74:77] offset:46080
	s_waitcnt vmcnt(16)
	ds_write_b128 v0, v[110:113] offset:50688
	s_waitcnt vmcnt(15)
	ds_write_b128 v0, v[118:121] offset:55296
	s_waitcnt vmcnt(14)
	ds_write_b128 v0, v[126:129] offset:59904
	s_waitcnt vmcnt(13)
	ds_write_b128 v0, v[130:133] offset:64512
	s_waitcnt vmcnt(12)
	ds_write_b128 v168, v[138:141] offset:13824
	global_load_dwordx4 v[66:69], v[150:151], off offset:1920
	global_load_dwordx4 v[70:73], v[152:153], off offset:1920
	global_load_dwordx4 v[74:77], v[154:155], off offset:1920
	global_load_dwordx4 v[110:113], v[156:157], off offset:1920
	s_setprio 2
	ds_read_b128 v[118:121], v166
	ds_read_b128 v[126:129], v166 offset:32
	ds_read_b128 v[130:133], v166 offset:4608
	ds_read_b128 v[138:141], v166 offset:4640
	ds_read_b128 v[146:149], v167 offset:18432
	ds_read_b128 v[150:153], v167 offset:18464
	ds_read_b128 v[154:157], v167 offset:23040
	ds_read_b128 v[158:161], v167 offset:23072
	s_waitcnt lgkmcnt(3)
	v_mfma_f32_32x32x16_bf16 v[34:49], v[118:121], v[146:149], v[34:49]
	s_waitcnt lgkmcnt(1)
	v_mfma_f32_32x32x16_bf16 v[50:65], v[118:121], v[154:157], v[50:65]
	v_mfma_f32_32x32x16_bf16 v[2:17], v[130:133], v[146:149], v[2:17]
	v_mfma_f32_32x32x16_bf16 v[18:33], v[130:133], v[154:157], v[18:33]
	ds_read_b128 v[118:121], v166 offset:64
	ds_read_b128 v[130:133], v166 offset:4672
	ds_read_b128 v[146:149], v167 offset:18496
	ds_read_b128 v[154:157], v167 offset:23104
	v_mfma_f32_32x32x16_bf16 v[34:49], v[126:129], v[150:153], v[34:49]
	s_waitcnt lgkmcnt(4)
	v_mfma_f32_32x32x16_bf16 v[50:65], v[126:129], v[158:161], v[50:65]
	v_mfma_f32_32x32x16_bf16 v[2:17], v[138:141], v[150:153], v[2:17]
	v_mfma_f32_32x32x16_bf16 v[18:33], v[138:141], v[158:161], v[18:33]
	ds_read_b128 v[126:129], v166 offset:96
	ds_read_b128 v[138:141], v166 offset:4704
	ds_read_b128 v[150:153], v167 offset:18528
	ds_read_b128 v[158:161], v167 offset:23136
	s_waitcnt lgkmcnt(5)
	v_mfma_f32_32x32x16_bf16 v[34:49], v[118:121], v[146:149], v[34:49]
	s_waitcnt lgkmcnt(4)
	v_mfma_f32_32x32x16_bf16 v[50:65], v[118:121], v[154:157], v[50:65]
	v_mfma_f32_32x32x16_bf16 v[2:17], v[130:133], v[146:149], v[2:17]
	v_mfma_f32_32x32x16_bf16 v[18:33], v[130:133], v[154:157], v[18:33]
	s_waitcnt lgkmcnt(1)
	v_mfma_f32_32x32x16_bf16 v[34:49], v[126:129], v[150:153], v[34:49]
	s_waitcnt lgkmcnt(0)
	v_mfma_f32_32x32x16_bf16 v[50:65], v[126:129], v[158:161], v[50:65]
	v_mfma_f32_32x32x16_bf16 v[2:17], v[138:141], v[150:153], v[2:17]
	v_mfma_f32_32x32x16_bf16 v[18:33], v[138:141], v[158:161], v[18:33]
	s_setprio 0
	s_barrier
	s_setprio 2
	s_waitcnt vmcnt(15)
	ds_write_b128 v0, v[82:85]
	s_waitcnt vmcnt(14)
	ds_write_b128 v0, v[94:97] offset:4608
	s_waitcnt vmcnt(13)
	ds_write_b128 v0, v[98:101] offset:9216
	s_waitcnt vmcnt(12)
	ds_write_b128 v0, v[102:105] offset:13824
	s_waitcnt vmcnt(11)
	ds_write_b128 v0, v[114:117] offset:18432
	s_waitcnt vmcnt(10)
	ds_write_b128 v0, v[122:125] offset:23040
	ds_read_b128 v[82:85], v166 offset:36864
	ds_read_b128 v[98:101], v166 offset:41472
	ds_read_b128 v[114:117], v167 offset:55296
	ds_read_b128 v[122:125], v167 offset:59904
	ds_read_b128 v[94:97], v166 offset:36896
	ds_read_b128 v[102:105], v166 offset:41504
	ds_read_b128 v[118:121], v167 offset:55328
	ds_read_b128 v[126:129], v167 offset:59936
	s_waitcnt lgkmcnt(5)
	v_mfma_f32_32x32x16_bf16 v[34:49], v[82:85], v[114:117], v[34:49]
	s_waitcnt vmcnt(9)
	ds_write_b128 v0, v[134:137] offset:27648
	s_waitcnt lgkmcnt(5)
	v_mfma_f32_32x32x16_bf16 v[50:65], v[82:85], v[122:125], v[50:65]
	s_waitcnt vmcnt(8)
	ds_write_b128 v0, v[142:145] offset:32256
	v_mfma_f32_32x32x16_bf16 v[2:17], v[98:101], v[114:117], v[2:17]
	v_mfma_f32_32x32x16_bf16 v[18:33], v[98:101], v[122:125], v[18:33]
	ds_read_b128 v[82:85], v166 offset:36928
	ds_read_b128 v[98:101], v166 offset:41536
	ds_read_b128 v[114:117], v167 offset:55360
	ds_read_b128 v[122:125], v167 offset:59968
	s_waitcnt lgkmcnt(7)
	v_mfma_f32_32x32x16_bf16 v[34:49], v[94:97], v[118:121], v[34:49]
	s_waitcnt lgkmcnt(6)
	v_mfma_f32_32x32x16_bf16 v[50:65], v[94:97], v[126:129], v[50:65]
	v_mfma_f32_32x32x16_bf16 v[2:17], v[102:105], v[118:121], v[2:17]
	v_mfma_f32_32x32x16_bf16 v[18:33], v[102:105], v[126:129], v[18:33]
	ds_read_b128 v[94:97], v166 offset:36960
	ds_read_b128 v[102:105], v166 offset:41568
	ds_read_b128 v[118:121], v167 offset:55392
	ds_read_b128 v[126:129], v167 offset:60000
	s_waitcnt lgkmcnt(5)
	v_mfma_f32_32x32x16_bf16 v[34:49], v[82:85], v[114:117], v[34:49]
	s_waitcnt lgkmcnt(4)
	v_mfma_f32_32x32x16_bf16 v[50:65], v[82:85], v[122:125], v[50:65]
	v_mfma_f32_32x32x16_bf16 v[2:17], v[98:101], v[114:117], v[2:17]
	v_mfma_f32_32x32x16_bf16 v[18:33], v[98:101], v[122:125], v[18:33]
	s_waitcnt lgkmcnt(1)
	v_mfma_f32_32x32x16_bf16 v[34:49], v[94:97], v[118:121], v[34:49]
	s_waitcnt lgkmcnt(0)
	v_mfma_f32_32x32x16_bf16 v[50:65], v[94:97], v[126:129], v[50:65]
	v_mfma_f32_32x32x16_bf16 v[2:17], v[102:105], v[118:121], v[2:17]
	v_mfma_f32_32x32x16_bf16 v[18:33], v[102:105], v[126:129], v[18:33]
	s_waitcnt lgkmcnt(0)
	s_setprio 0
	s_barrier
	s_setprio 2
	s_waitcnt vmcnt(7)
	ds_write_b128 v0, v[78:81] offset:36864
	s_waitcnt vmcnt(6)
	ds_write_b128 v0, v[86:89] offset:41472
	s_waitcnt vmcnt(5)
	ds_write_b128 v0, v[90:93] offset:46080
	s_waitcnt vmcnt(3)
	ds_write_b128 v0, v[66:69] offset:55296
	s_waitcnt vmcnt(2)
	ds_write_b128 v0, v[70:73] offset:59904
	s_waitcnt vmcnt(1)
	ds_write_b128 v0, v[74:77] offset:64512
	ds_read_b128 v[66:69], v166
	ds_read_b128 v[74:77], v166 offset:4608
	ds_read_b128 v[82:85], v167 offset:18432
	ds_read_b128 v[90:93], v167 offset:23040
	ds_read_b128 v[70:73], v166 offset:32
	ds_read_b128 v[78:81], v166 offset:4640
	ds_read_b128 v[86:89], v167 offset:18464
	ds_read_b128 v[94:97], v167 offset:23072
	s_waitcnt lgkmcnt(5)
	v_mfma_f32_32x32x16_bf16 v[34:49], v[66:69], v[82:85], v[34:49]
	s_waitcnt vmcnt(4)
	ds_write_b128 v0, v[106:109] offset:50688
	s_waitcnt lgkmcnt(5)
	v_mfma_f32_32x32x16_bf16 v[50:65], v[66:69], v[90:93], v[50:65]
	s_waitcnt vmcnt(0)
	ds_write_b128 v168, v[110:113] offset:13824
	v_mfma_f32_32x32x16_bf16 v[2:17], v[74:77], v[82:85], v[2:17]
	v_mfma_f32_32x32x16_bf16 v[18:33], v[74:77], v[90:93], v[18:33]
	ds_read_b128 v[66:69], v166 offset:64
	ds_read_b128 v[74:77], v166 offset:4672
	ds_read_b128 v[82:85], v167 offset:18496
	ds_read_b128 v[90:93], v167 offset:23104
	s_waitcnt lgkmcnt(7)
	v_mfma_f32_32x32x16_bf16 v[34:49], v[70:73], v[86:89], v[34:49]
	s_waitcnt lgkmcnt(6)
	v_mfma_f32_32x32x16_bf16 v[50:65], v[70:73], v[94:97], v[50:65]
	v_mfma_f32_32x32x16_bf16 v[2:17], v[78:81], v[86:89], v[2:17]
	v_mfma_f32_32x32x16_bf16 v[18:33], v[78:81], v[94:97], v[18:33]
	ds_read_b128 v[70:73], v166 offset:96
	ds_read_b128 v[78:81], v166 offset:4704
	ds_read_b128 v[86:89], v167 offset:18528
	ds_read_b128 v[94:97], v167 offset:23136
	s_waitcnt lgkmcnt(5)
	v_mfma_f32_32x32x16_bf16 v[34:49], v[66:69], v[82:85], v[34:49]
	s_waitcnt lgkmcnt(4)
	v_mfma_f32_32x32x16_bf16 v[50:65], v[66:69], v[90:93], v[50:65]
	v_mfma_f32_32x32x16_bf16 v[2:17], v[74:77], v[82:85], v[2:17]
	v_mfma_f32_32x32x16_bf16 v[18:33], v[74:77], v[90:93], v[18:33]
	s_waitcnt lgkmcnt(1)
	v_mfma_f32_32x32x16_bf16 v[34:49], v[70:73], v[86:89], v[34:49]
	s_waitcnt lgkmcnt(0)
	v_mfma_f32_32x32x16_bf16 v[50:65], v[70:73], v[94:97], v[50:65]
	v_mfma_f32_32x32x16_bf16 v[2:17], v[78:81], v[86:89], v[2:17]
	v_mfma_f32_32x32x16_bf16 v[18:33], v[78:81], v[94:97], v[18:33]
	s_waitcnt lgkmcnt(0)
	s_setprio 0
	s_barrier
	s_setprio 2
	ds_read_b128 v[66:69], v166 offset:36864
	ds_read_b128 v[70:73], v166 offset:36896
	ds_read_b128 v[74:77], v166 offset:41472
	ds_read_b128 v[78:81], v166 offset:41504
	ds_read_b128 v[82:85], v167 offset:55296
	ds_read_b128 v[86:89], v167 offset:55328
	ds_read_b128 v[90:93], v167 offset:59904
	ds_read_b128 v[94:97], v167 offset:59936
	s_waitcnt lgkmcnt(3)
	v_mfma_f32_32x32x16_bf16 v[34:49], v[66:69], v[82:85], v[34:49]
	s_waitcnt lgkmcnt(1)
	v_mfma_f32_32x32x16_bf16 v[50:65], v[66:69], v[90:93], v[50:65]
	v_mfma_f32_32x32x16_bf16 v[2:17], v[74:77], v[82:85], v[2:17]
	v_mfma_f32_32x32x16_bf16 v[18:33], v[74:77], v[90:93], v[18:33]
	ds_read_b128 v[66:69], v166 offset:36928
	ds_read_b128 v[74:77], v166 offset:41536
	ds_read_b128 v[82:85], v167 offset:55360
	ds_read_b128 v[90:93], v167 offset:59968
	v_mfma_f32_32x32x16_bf16 v[34:49], v[70:73], v[86:89], v[34:49]
	s_waitcnt lgkmcnt(4)
	v_mfma_f32_32x32x16_bf16 v[50:65], v[70:73], v[94:97], v[50:65]
	v_mfma_f32_32x32x16_bf16 v[2:17], v[78:81], v[86:89], v[2:17]
	v_mfma_f32_32x32x16_bf16 v[18:33], v[78:81], v[94:97], v[18:33]
	ds_read_b128 v[70:73], v166 offset:36960
	ds_read_b128 v[78:81], v166 offset:41568
	ds_read_b128 v[86:89], v167 offset:55392
	ds_read_b128 v[94:97], v167 offset:60000
	s_waitcnt lgkmcnt(5)
	v_mfma_f32_32x32x16_bf16 v[34:49], v[66:69], v[82:85], v[34:49]
	s_waitcnt lgkmcnt(4)
	v_mfma_f32_32x32x16_bf16 v[50:65], v[66:69], v[90:93], v[50:65]
	v_mfma_f32_32x32x16_bf16 v[2:17], v[74:77], v[82:85], v[2:17]
	v_mfma_f32_32x32x16_bf16 v[18:33], v[74:77], v[90:93], v[18:33]
	s_waitcnt lgkmcnt(1)
	v_mfma_f32_32x32x16_bf16 v[34:49], v[70:73], v[86:89], v[34:49]
	s_waitcnt lgkmcnt(0)
	v_mfma_f32_32x32x16_bf16 v[50:65], v[70:73], v[94:97], v[50:65]
	v_mfma_f32_32x32x16_bf16 v[2:17], v[78:81], v[86:89], v[2:17]
	v_mfma_f32_32x32x16_bf16 v[18:33], v[78:81], v[94:97], v[18:33]
	s_setprio 0
	s_barrier
	v_mov_b32 v0, v194
	s_lshr_b32 s12, s12, 1
	v_lshrrev_b32_e32 v67, 1, v0
	v_and_b32_e32 v66, 31, v0
	v_and_b32_e32 v67, 32, v67
	s_nop 1
	v_mul_f32_e32 v68, 0xbfb8aa3b, v34
	v_exp_f32_e32 v68, v68
	v_or3_b32 v69, v66, s12, v67
	v_ashrrev_i32_e32 v66, 1, v0
	v_and_b32_e32 v66, 0xffffffc0, v66
	s_nop 0
	v_lshrrev_b32_e32 v0, 3, v0
	v_add_f32_e32 v67, 1.0, v68
	v_rcp_f32_e32 v67, v67
	v_add_u32_e32 v66, s6, v66
	v_and_or_b32 v68, v0, 4, v66
	s_nop 0
	s_add_i32 s2, s2, s33
	v_mul_f32_e32 v0, v34, v67
	v_mul_f32_e32 v0, v50, v0
	v_cvt_pk_bf16_f32 v34, v0, s0
	v_mov_b64_e32 v[66:67], s[8:9]
	v_mul_f32_e32 v0, 0xbfb8aa3b, v35
	v_mad_i64_i32 v[70:71], s[12:13], v68, s4, v[66:67]
	v_exp_f32_e32 v50, v0
	v_lshlrev_b32_e32 v0, 1, v69
	v_lshl_add_u64 v[70:71], v[70:71], 0, v[0:1]
	global_store_short v[70:71], v34, off
	s_nop 0
	s_cmpk_gt_u32 s2, 0x20f
	v_add_f32_e32 v34, 1.0, v50
	v_rcp_f32_e32 v34, v34
	s_nop 0
	v_or_b32_e32 v50, 1, v68
	v_mul_f32_e32 v34, v35, v34
	v_mul_f32_e32 v34, v51, v34
	v_cvt_pk_bf16_f32 v51, v34, s0
	v_mul_f32_e32 v34, 0xbfb8aa3b, v36
	v_exp_f32_e32 v69, v34
	v_mad_i64_i32 v[34:35], s[12:13], v50, s4, v[66:67]
	v_lshl_add_u64 v[34:35], v[34:35], 0, v[0:1]
	global_store_short v[34:35], v51, off
	s_nop 0
	v_or_b32_e32 v35, 2, v68
	v_add_f32_e32 v34, 1.0, v69
	v_rcp_f32_e32 v34, v34
	s_nop 0
	s_nop 0
	v_mul_f32_e32 v34, v36, v34
	v_mul_f32_e32 v34, v52, v34
	v_cvt_pk_bf16_f32 v36, v34, s0
	v_mul_f32_e32 v34, 0xbfb8aa3b, v37
	v_exp_f32_e32 v50, v34
	v_mad_i64_i32 v[34:35], s[12:13], v35, s4, v[66:67]
	v_lshl_add_u64 v[34:35], v[34:35], 0, v[0:1]
	global_store_short v[34:35], v36, off
	s_nop 0
	v_or_b32_e32 v35, 3, v68
	v_add_f32_e32 v34, 1.0, v50
	v_rcp_f32_e32 v34, v34
	s_nop 0
	s_nop 0
	v_mul_f32_e32 v34, v37, v34
	v_mul_f32_e32 v34, v53, v34
	v_cvt_pk_bf16_f32 v36, v34, s0
	v_mul_f32_e32 v34, 0xbfb8aa3b, v38
	v_exp_f32_e32 v37, v34
	v_mad_i64_i32 v[34:35], s[12:13], v35, s4, v[66:67]
	v_lshl_add_u64 v[34:35], v[34:35], 0, v[0:1]
	global_store_short v[34:35], v36, off
	s_nop 0
	v_or_b32_e32 v35, 8, v68
	v_add_f32_e32 v34, 1.0, v37
	v_rcp_f32_e32 v34, v34
	s_nop 0
	s_nop 0
	v_mul_f32_e32 v34, v38, v34
	v_mul_f32_e32 v34, v54, v34
	v_cvt_pk_bf16_f32 v36, v34, s0
	v_mul_f32_e32 v34, 0xbfb8aa3b, v39
	v_exp_f32_e32 v37, v34
	v_mad_i64_i32 v[34:35], s[12:13], v35, s4, v[66:67]
	v_lshl_add_u64 v[34:35], v[34:35], 0, v[0:1]
	global_store_short v[34:35], v36, off
	s_nop 0
	v_or_b32_e32 v35, 9, v68
	v_add_f32_e32 v34, 1.0, v37
	v_rcp_f32_e32 v34, v34
	s_nop 0
	s_nop 0
	v_mul_f32_e32 v34, v39, v34
	v_mul_f32_e32 v34, v55, v34
	v_cvt_pk_bf16_f32 v36, v34, s0
	v_mul_f32_e32 v34, 0xbfb8aa3b, v40
	v_exp_f32_e32 v37, v34
	v_mad_i64_i32 v[34:35], s[12:13], v35, s4, v[66:67]
	v_lshl_add_u64 v[34:35], v[34:35], 0, v[0:1]
	global_store_short v[34:35], v36, off
	s_nop 0
	v_or_b32_e32 v35, 10, v68
	v_add_f32_e32 v34, 1.0, v37
	v_rcp_f32_e32 v34, v34
	s_nop 0
	s_nop 0
	v_mul_f32_e32 v34, v40, v34
	v_mul_f32_e32 v34, v56, v34
	v_cvt_pk_bf16_f32 v36, v34, s0
	v_mul_f32_e32 v34, 0xbfb8aa3b, v41
	v_exp_f32_e32 v37, v34
	v_mad_i64_i32 v[34:35], s[12:13], v35, s4, v[66:67]
	v_lshl_add_u64 v[34:35], v[34:35], 0, v[0:1]
	global_store_short v[34:35], v36, off
	s_nop 0
	v_or_b32_e32 v35, 11, v68
	v_add_f32_e32 v34, 1.0, v37
	v_rcp_f32_e32 v34, v34
	s_nop 0
	s_nop 0
	v_mul_f32_e32 v34, v41, v34
	v_mul_f32_e32 v34, v57, v34
	v_cvt_pk_bf16_f32 v36, v34, s0
	v_mul_f32_e32 v34, 0xbfb8aa3b, v42
	v_exp_f32_e32 v37, v34
	v_mad_i64_i32 v[34:35], s[12:13], v35, s4, v[66:67]
	v_lshl_add_u64 v[34:35], v[34:35], 0, v[0:1]
	global_store_short v[34:35], v36, off
	s_nop 0
	v_or_b32_e32 v35, 16, v68
	v_add_f32_e32 v34, 1.0, v37
	v_rcp_f32_e32 v34, v34
	s_nop 0
	s_nop 0
	v_mul_f32_e32 v34, v42, v34
	v_mul_f32_e32 v34, v58, v34
	v_cvt_pk_bf16_f32 v36, v34, s0
	v_mul_f32_e32 v34, 0xbfb8aa3b, v43
	v_exp_f32_e32 v37, v34
	v_mad_i64_i32 v[34:35], s[12:13], v35, s4, v[66:67]
	v_lshl_add_u64 v[34:35], v[34:35], 0, v[0:1]
	global_store_short v[34:35], v36, off
	s_nop 0
	v_or_b32_e32 v35, 17, v68
	v_add_f32_e32 v34, 1.0, v37
	v_rcp_f32_e32 v34, v34
	s_nop 0
	s_nop 0
	v_mul_f32_e32 v34, v43, v34
	v_mul_f32_e32 v34, v59, v34
	v_cvt_pk_bf16_f32 v36, v34, s0
	v_mul_f32_e32 v34, 0xbfb8aa3b, v44
	v_exp_f32_e32 v37, v34
	v_mad_i64_i32 v[34:35], s[12:13], v35, s4, v[66:67]
	v_lshl_add_u64 v[34:35], v[34:35], 0, v[0:1]
	global_store_short v[34:35], v36, off
	s_nop 0
	v_or_b32_e32 v35, 18, v68
	v_add_f32_e32 v34, 1.0, v37
	v_rcp_f32_e32 v34, v34
	s_nop 0
	s_nop 0
	v_mul_f32_e32 v34, v44, v34
	v_mul_f32_e32 v34, v60, v34
	v_cvt_pk_bf16_f32 v36, v34, s0
	v_mul_f32_e32 v34, 0xbfb8aa3b, v45
	v_exp_f32_e32 v37, v34
	v_mad_i64_i32 v[34:35], s[12:13], v35, s4, v[66:67]
	v_lshl_add_u64 v[34:35], v[34:35], 0, v[0:1]
	global_store_short v[34:35], v36, off
	s_nop 0
	v_or_b32_e32 v35, 19, v68
	v_add_f32_e32 v34, 1.0, v37
	v_rcp_f32_e32 v34, v34
	s_nop 0
	s_nop 0
	v_mul_f32_e32 v34, v45, v34
	v_mul_f32_e32 v34, v61, v34
	v_cvt_pk_bf16_f32 v36, v34, s0
	v_mul_f32_e32 v34, 0xbfb8aa3b, v46
	v_exp_f32_e32 v37, v34
	v_mad_i64_i32 v[34:35], s[12:13], v35, s4, v[66:67]
	v_lshl_add_u64 v[34:35], v[34:35], 0, v[0:1]
	global_store_short v[34:35], v36, off
	s_nop 0
	v_or_b32_e32 v35, 24, v68
	v_add_f32_e32 v34, 1.0, v37
	v_rcp_f32_e32 v34, v34
	s_nop 0
	s_nop 0
	v_mul_f32_e32 v34, v46, v34
	v_mul_f32_e32 v34, v62, v34
	v_cvt_pk_bf16_f32 v36, v34, s0
	v_mul_f32_e32 v34, 0xbfb8aa3b, v47
	v_exp_f32_e32 v37, v34
	v_mad_i64_i32 v[34:35], s[12:13], v35, s4, v[66:67]
	v_lshl_add_u64 v[34:35], v[34:35], 0, v[0:1]
	global_store_short v[34:35], v36, off
	s_nop 0
	v_or_b32_e32 v35, 25, v68
	v_add_f32_e32 v34, 1.0, v37
	v_rcp_f32_e32 v34, v34
	s_nop 0
	s_nop 0
	v_mul_f32_e32 v34, v47, v34
	v_mul_f32_e32 v34, v63, v34
	v_cvt_pk_bf16_f32 v36, v34, s0
	v_mul_f32_e32 v34, 0xbfb8aa3b, v48
	v_exp_f32_e32 v37, v34
	v_mad_i64_i32 v[34:35], s[12:13], v35, s4, v[66:67]
	v_lshl_add_u64 v[34:35], v[34:35], 0, v[0:1]
	global_store_short v[34:35], v36, off
	s_nop 0
	v_or_b32_e32 v35, 26, v68
	v_add_f32_e32 v34, 1.0, v37
	v_rcp_f32_e32 v34, v34
	s_nop 0
	s_nop 0
	v_mul_f32_e32 v34, v48, v34
	v_mul_f32_e32 v34, v64, v34
	v_cvt_pk_bf16_f32 v36, v34, s0
	v_mul_f32_e32 v34, 0xbfb8aa3b, v49
	v_exp_f32_e32 v37, v34
	v_mad_i64_i32 v[34:35], s[12:13], v35, s4, v[66:67]
	v_lshl_add_u64 v[34:35], v[34:35], 0, v[0:1]
	global_store_short v[34:35], v36, off
	s_nop 0
	v_or_b32_e32 v35, 27, v68
	v_add_f32_e32 v34, 1.0, v37
	v_rcp_f32_e32 v34, v34
	s_nop 0
	s_nop 0
	v_mul_f32_e32 v34, v49, v34
	v_mul_f32_e32 v34, v65, v34
	v_cvt_pk_bf16_f32 v36, v34, s0
	v_mul_f32_e32 v34, 0xbfb8aa3b, v2
	v_exp_f32_e32 v37, v34
	v_mad_i64_i32 v[34:35], s[12:13], v35, s4, v[66:67]
	v_lshl_add_u64 v[34:35], v[34:35], 0, v[0:1]
	global_store_short v[34:35], v36, off
	s_nop 0
	v_or_b32_e32 v35, 32, v68
	v_add_f32_e32 v34, 1.0, v37
	v_rcp_f32_e32 v34, v34
	s_nop 0
	s_nop 0
	v_mul_f32_e32 v2, v2, v34
	v_mul_f32_e32 v2, v18, v2
	v_mul_f32_e32 v18, 0xbfb8aa3b, v3
	v_mad_i64_i32 v[34:35], s[12:13], v35, s4, v[66:67]
	v_cvt_pk_bf16_f32 v2, v2, s0
	v_exp_f32_e32 v18, v18
	v_lshl_add_u64 v[34:35], v[34:35], 0, v[0:1]
	global_store_short v[34:35], v2, off
	s_nop 0
	s_nop 0
	v_add_f32_e32 v2, 1.0, v18
	v_rcp_f32_e32 v2, v2
	s_nop 0
	v_or_b32_e32 v18, 33, v68
	v_mul_f32_e32 v2, v3, v2
	v_mul_f32_e32 v2, v19, v2
	v_cvt_pk_bf16_f32 v19, v2, s0
	v_mul_f32_e32 v2, 0xbfb8aa3b, v4
	v_exp_f32_e32 v34, v2
	v_mad_i64_i32 v[2:3], s[12:13], v18, s4, v[66:67]
	v_lshl_add_u64 v[2:3], v[2:3], 0, v[0:1]
	global_store_short v[2:3], v19, off
	s_nop 0
	v_or_b32_e32 v3, 34, v68
	v_add_f32_e32 v2, 1.0, v34
	v_rcp_f32_e32 v2, v2
	s_nop 0
	s_nop 0
	v_mul_f32_e32 v2, v4, v2
	v_mul_f32_e32 v2, v20, v2
	v_cvt_pk_bf16_f32 v4, v2, s0
	v_mul_f32_e32 v2, 0xbfb8aa3b, v5
	v_exp_f32_e32 v18, v2
	v_mad_i64_i32 v[2:3], s[12:13], v3, s4, v[66:67]
	v_lshl_add_u64 v[2:3], v[2:3], 0, v[0:1]
	global_store_short v[2:3], v4, off
	s_nop 0
	v_or_b32_e32 v3, 35, v68
	v_add_f32_e32 v2, 1.0, v18
	v_rcp_f32_e32 v2, v2
	s_nop 0
	s_nop 0
	v_mul_f32_e32 v2, v5, v2
	v_mul_f32_e32 v2, v21, v2
	v_cvt_pk_bf16_f32 v4, v2, s0
	v_mul_f32_e32 v2, 0xbfb8aa3b, v6
	v_exp_f32_e32 v5, v2
	v_mad_i64_i32 v[2:3], s[12:13], v3, s4, v[66:67]
	v_lshl_add_u64 v[2:3], v[2:3], 0, v[0:1]
	global_store_short v[2:3], v4, off
	s_nop 0
	v_or_b32_e32 v3, 40, v68
	v_add_f32_e32 v2, 1.0, v5
	v_rcp_f32_e32 v2, v2
	s_nop 0
	s_nop 0
	v_mul_f32_e32 v2, v6, v2
	v_mul_f32_e32 v2, v22, v2
	v_cvt_pk_bf16_f32 v4, v2, s0
	v_mul_f32_e32 v2, 0xbfb8aa3b, v7
	v_exp_f32_e32 v5, v2
	v_mad_i64_i32 v[2:3], s[12:13], v3, s4, v[66:67]
	v_lshl_add_u64 v[2:3], v[2:3], 0, v[0:1]
	global_store_short v[2:3], v4, off
	s_nop 0
	v_or_b32_e32 v3, 41, v68
	v_add_f32_e32 v2, 1.0, v5
	v_rcp_f32_e32 v2, v2
	s_nop 0
	s_nop 0
	v_mul_f32_e32 v2, v7, v2
	v_mul_f32_e32 v2, v23, v2
	v_cvt_pk_bf16_f32 v4, v2, s0
	v_mul_f32_e32 v2, 0xbfb8aa3b, v8
	v_exp_f32_e32 v5, v2
	v_mad_i64_i32 v[2:3], s[12:13], v3, s4, v[66:67]
	v_lshl_add_u64 v[2:3], v[2:3], 0, v[0:1]
	global_store_short v[2:3], v4, off
	s_nop 0
	v_or_b32_e32 v3, 42, v68
	v_add_f32_e32 v2, 1.0, v5
	v_rcp_f32_e32 v2, v2
	s_nop 0
	s_nop 0
	v_mul_f32_e32 v2, v8, v2
	v_mul_f32_e32 v2, v24, v2
	v_cvt_pk_bf16_f32 v4, v2, s0
	v_mul_f32_e32 v2, 0xbfb8aa3b, v9
	v_exp_f32_e32 v5, v2
	v_mad_i64_i32 v[2:3], s[12:13], v3, s4, v[66:67]
	v_lshl_add_u64 v[2:3], v[2:3], 0, v[0:1]
	global_store_short v[2:3], v4, off
	s_nop 0
	v_or_b32_e32 v3, 43, v68
	v_add_f32_e32 v2, 1.0, v5
	v_rcp_f32_e32 v2, v2
	s_nop 0
	s_nop 0
	v_mul_f32_e32 v2, v9, v2
	v_mul_f32_e32 v2, v25, v2
	v_cvt_pk_bf16_f32 v4, v2, s0
	v_mul_f32_e32 v2, 0xbfb8aa3b, v10
	v_exp_f32_e32 v5, v2
	v_mad_i64_i32 v[2:3], s[12:13], v3, s4, v[66:67]
	v_lshl_add_u64 v[2:3], v[2:3], 0, v[0:1]
	global_store_short v[2:3], v4, off
	s_nop 0
	v_or_b32_e32 v3, 48, v68
	v_add_f32_e32 v2, 1.0, v5
	v_rcp_f32_e32 v2, v2
	s_nop 0
	s_nop 0
	v_mul_f32_e32 v2, v10, v2
	v_mul_f32_e32 v2, v26, v2
	v_cvt_pk_bf16_f32 v4, v2, s0
	v_mul_f32_e32 v2, 0xbfb8aa3b, v11
	v_exp_f32_e32 v5, v2
	v_mad_i64_i32 v[2:3], s[12:13], v3, s4, v[66:67]
	v_lshl_add_u64 v[2:3], v[2:3], 0, v[0:1]
	global_store_short v[2:3], v4, off
	s_nop 0
	v_or_b32_e32 v3, 49, v68
	v_add_f32_e32 v2, 1.0, v5
	v_rcp_f32_e32 v2, v2
	s_nop 0
	s_nop 0
	v_mul_f32_e32 v2, v11, v2
	v_mul_f32_e32 v2, v27, v2
	v_cvt_pk_bf16_f32 v4, v2, s0
	v_mul_f32_e32 v2, 0xbfb8aa3b, v12
	v_exp_f32_e32 v5, v2
	v_mad_i64_i32 v[2:3], s[12:13], v3, s4, v[66:67]
	v_lshl_add_u64 v[2:3], v[2:3], 0, v[0:1]
	global_store_short v[2:3], v4, off
	s_nop 0
	v_or_b32_e32 v3, 50, v68
	v_add_f32_e32 v2, 1.0, v5
	v_rcp_f32_e32 v2, v2
	s_nop 0
	s_nop 0
	v_mul_f32_e32 v2, v12, v2
	v_mul_f32_e32 v2, v28, v2
	v_cvt_pk_bf16_f32 v4, v2, s0
	v_mul_f32_e32 v2, 0xbfb8aa3b, v13
	v_exp_f32_e32 v5, v2
	v_mad_i64_i32 v[2:3], s[12:13], v3, s4, v[66:67]
	v_lshl_add_u64 v[2:3], v[2:3], 0, v[0:1]
	global_store_short v[2:3], v4, off
	s_nop 0
	v_or_b32_e32 v3, 51, v68
	v_add_f32_e32 v2, 1.0, v5
	v_rcp_f32_e32 v2, v2
	s_nop 0
	s_nop 0
	v_mul_f32_e32 v2, v13, v2
	v_mul_f32_e32 v2, v29, v2
	v_cvt_pk_bf16_f32 v4, v2, s0
	v_mul_f32_e32 v2, 0xbfb8aa3b, v14
	v_exp_f32_e32 v5, v2
	v_mad_i64_i32 v[2:3], s[12:13], v3, s4, v[66:67]
	v_lshl_add_u64 v[2:3], v[2:3], 0, v[0:1]
	global_store_short v[2:3], v4, off
	s_nop 0
	v_or_b32_e32 v3, 56, v68
	v_add_f32_e32 v2, 1.0, v5
	v_rcp_f32_e32 v2, v2
	s_nop 0
	s_nop 0
	v_mul_f32_e32 v2, v14, v2
	v_mul_f32_e32 v2, v30, v2
	v_cvt_pk_bf16_f32 v4, v2, s0
	v_mul_f32_e32 v2, 0xbfb8aa3b, v15
	v_exp_f32_e32 v5, v2
	v_mad_i64_i32 v[2:3], s[12:13], v3, s4, v[66:67]
	v_lshl_add_u64 v[2:3], v[2:3], 0, v[0:1]
	global_store_short v[2:3], v4, off
	s_nop 0
	v_or_b32_e32 v3, 57, v68
	v_add_f32_e32 v2, 1.0, v5
	v_rcp_f32_e32 v2, v2
	s_nop 0
	s_nop 0
	v_mul_f32_e32 v2, v15, v2
	v_mul_f32_e32 v2, v31, v2
	v_cvt_pk_bf16_f32 v4, v2, s0
	v_mul_f32_e32 v2, 0xbfb8aa3b, v16
	v_exp_f32_e32 v5, v2
	v_mad_i64_i32 v[2:3], s[12:13], v3, s4, v[66:67]
	v_lshl_add_u64 v[2:3], v[2:3], 0, v[0:1]
	global_store_short v[2:3], v4, off
	s_nop 0
	v_or_b32_e32 v3, 58, v68
	v_add_f32_e32 v2, 1.0, v5
	v_rcp_f32_e32 v2, v2
	s_nop 0
	s_nop 0
	v_mul_f32_e32 v2, v16, v2
	v_mul_f32_e32 v2, v32, v2
	v_cvt_pk_bf16_f32 v4, v2, s0
	v_mul_f32_e32 v2, 0xbfb8aa3b, v17
	v_exp_f32_e32 v5, v2
	v_mad_i64_i32 v[2:3], s[12:13], v3, s4, v[66:67]
	v_lshl_add_u64 v[2:3], v[2:3], 0, v[0:1]
	global_store_short v[2:3], v4, off
	s_nop 0
	v_or_b32_e32 v3, 59, v68
	v_add_f32_e32 v2, 1.0, v5
	v_rcp_f32_e32 v2, v2
	s_nop 0
	s_nop 0
	v_mul_f32_e32 v2, v17, v2
	v_mul_f32_e32 v2, v33, v2
	v_cvt_pk_bf16_f32 v4, v2, s0
	v_mad_i64_i32 v[2:3], s[12:13], v3, s4, v[66:67]
	v_lshl_add_u64 v[2:3], v[2:3], 0, v[0:1]
	global_store_short v[2:3], v4, off
	s_cbranch_scc0 .LBB0_2770
	s_getpc_b64 s[98:99]
